# GEMM K-loops: per-segment s_setprio toggles removed
# speedup vs baseline: 1.0089x; 1.0057x over previous
; #define PG8_STAGE(bufoff, gbase, voff) do { _Pragma("unroll") for (int _i = 0; _i < 2; ++_i) \
;         __builtin_amdgcn_global_load_lds((const unsigned*)((const char*)(gbase) + (voff)[_i]), (PG8_LAS unsigned*)(lds + (bufoff) + ldsw + _i * 8192), 16, 0, 0); } while (0)
; #define PG8_LDA(dst, b, h) do { _Pragma("unroll") for (int m = 0; m < 4; ++m) _Pragma("unroll") for (int k = 0; k < 2; ++k) dst[m][k] = *(const PG8_LAS bf16x8*)(lds + PG8_SA(b, h) + aoff + m * 2048 + k * 1024); } while (0)
; #define PG8_LDB(dst, b, h) do { _Pragma("unroll") for (int n = 0; n < 2; ++n) _Pragma("unroll") for (int k = 0; k < 2; ++k) dst[n][k] = *(const PG8_LAS bf16x8*)(lds + PG8_SB(b, h) + boff + n * 2048 + k * 1024); } while (0)
; #define PG8_MMA(ai, bj, At, Bt) do { __builtin_amdgcn_s_setprio(1); _Pragma("unroll") for (int m = 0; m < 4; ++m) _Pragma("unroll") for (int n = 0; n < 2; ++n) _Pragma("unroll") for (int k = 0; k < 2; ++k) \
;         acc[ai][bj][m][n] = __builtin_amdgcn_mfma_f32_16x16x32_bf16(Bt[n][k], At[m][k], acc[ai][bj][m][n], 0, 0, 0); __builtin_amdgcn_s_setprio(0); } while (0)
; #define PG8_WAIT_V(n) asm volatile("s_waitcnt vmcnt(" #n ")" ::: "memory")
; #define PG8_WAIT_L(n) asm volatile("s_waitcnt lgkmcnt(" #n ")" ::: "memory")
; #define PG8_BAR __builtin_amdgcn_s_barrier()
; #define PG8_SCHED __builtin_amdgcn_sched_barrier(0)
; template <class Epi, class Sched, bool STAMP = false>
; __device__ __forceinline__ void gemm_phase(PG8_LAS unsigned char* lds, const Gemm g, const Sched& S, const Epi& E, unsigned long long* stamps) {
;     ...
;             PG8_LDB(B0, 0, 0); PG8_SCHED; PG8_LDA(At, 0, 0); PG8_STAGE(PG8_SA(1, 1), a1 + hstep, voffA);
;             PG8_WAIT_L(8); PG8_BAR; PG8_WAIT_L(0); PG8_MMA(0, 0, At, B0); PG8_BAR; PG8_SCHED;
;             PG8_LDB(B1, 0, 1); PG8_STAGE(PG8_SB(0, 0), b2, voffB);
;             PG8_BAR; PG8_WAIT_L(0); PG8_MMA(0, 1, At, B1); PG8_BAR;
;             PG8_LDA(At, 0, 1); PG8_STAGE(PG8_SA(0, 0), a2, voffA);
;             PG8_BAR; PG8_WAIT_L(0); PG8_MMA(1, 0, At, B0); PG8_BAR; PG8_SCHED;
;             PG8_STAGE(PG8_SB(0, 1), b2 + hstep, voffB);
;             PG8_WAIT_V(6); PG8_BAR; PG8_MMA(1, 1, At, B1); PG8_BAR;
.LBB0_44:
	s_add_u32 s14, s24, 0xfffc0080
	s_addc_u32 s15, s25, -1
	s_add_i32 s16, 0, 0x10000
	v_add_u32_e32 v169, s16, v166
	ds_read_b128 v[158:161], v169
	ds_read_b128 v[162:165], v169 offset:1024
	ds_read_b128 v[170:173], v169 offset:2048
	ds_read_b128 v[174:177], v169 offset:3072
	s_cmp_eq_u32 s61, 12
	s_cselect_b32 s31, s7, s15
	s_cselect_b32 s30, s57, s14
	s_cselect_b32 s27, s5, s60
	s_cselect_b32 s26, s58, s59
	v_lshl_add_u64 v[182:183], s[24:25], 0, v[154:155]
	s_add_i32 m0, s23, 0xc000
	ds_read_b128 v[178:181], v168
	ds_read_b128 v[192:195], v168 offset:1024
	ds_read_b128 v[196:199], v168 offset:2048
	ds_read_b128 v[200:203], v168 offset:3072
	ds_read_b128 v[204:207], v168 offset:4096
	ds_read_b128 v[208:211], v168 offset:5120
	ds_read_b128 v[212:215], v168 offset:6144
	ds_read_b128 v[216:219], v168 offset:7168
	global_load_lds_dwordx4 v[182:183], off
	v_lshl_add_u64 v[182:183], s[24:25], 0, v[156:157]
	s_add_i32 m0, s23, 0xe000
	s_nop 0
	global_load_lds_dwordx4 v[182:183], off
	s_waitcnt lgkmcnt(8)
	s_barrier
	s_waitcnt lgkmcnt(0)
	s_waitcnt lgkmcnt(0)
	v_mfma_f32_16x16x32_bf16 v[124:127], v[158:161], v[178:181], v[124:127]
	v_mfma_f32_16x16x32_bf16 v[120:123], v[170:173], v[178:181], v[120:123]
	v_mfma_f32_16x16x32_bf16 v[108:111], v[158:161], v[196:199], v[108:111]
	v_mfma_f32_16x16x32_bf16 v[104:107], v[170:173], v[196:199], v[104:107]
	v_mfma_f32_16x16x32_bf16 v[92:95], v[158:161], v[204:207], v[92:95]
	v_mfma_f32_16x16x32_bf16 v[88:91], v[170:173], v[204:207], v[88:91]
	v_mfma_f32_16x16x32_bf16 v[76:79], v[158:161], v[212:215], v[76:79]
	v_mfma_f32_16x16x32_bf16 v[72:75], v[170:173], v[212:215], v[72:75]
	v_mfma_f32_16x16x32_bf16 v[124:127], v[162:165], v[192:195], v[124:127]
	v_mfma_f32_16x16x32_bf16 v[120:123], v[174:177], v[192:195], v[120:123]
	v_mfma_f32_16x16x32_bf16 v[108:111], v[162:165], v[200:203], v[108:111]
	v_mfma_f32_16x16x32_bf16 v[104:107], v[174:177], v[200:203], v[104:107]
	v_mfma_f32_16x16x32_bf16 v[92:95], v[162:165], v[208:211], v[92:95]
	v_mfma_f32_16x16x32_bf16 v[88:91], v[174:177], v[208:211], v[88:91]
	v_mfma_f32_16x16x32_bf16 v[76:79], v[162:165], v[216:219], v[76:79]
	v_mfma_f32_16x16x32_bf16 v[72:75], v[174:177], v[216:219], v[72:75]
	s_barrier
	s_add_i32 s17, 0, 0x14000
	s_add_i32 s14, s16, s43
	v_add_u32_e32 v169, s17, v166
	v_lshl_add_u64 v[182:183], s[26:27], 0, v[128:129]
	s_mov_b32 m0, s14
	ds_read_b128 v[220:223], v169
	ds_read_b128 v[224:227], v169 offset:1024
	ds_read_b128 v[228:231], v169 offset:2048
	ds_read_b128 v[232:235], v169 offset:3072
	global_load_lds_dwordx4 v[182:183], off
	v_lshl_add_u64 v[236:237], s[26:27], 0, v[148:149]
	s_add_i32 m0, s14, 0x2000
	s_nop 0
	global_load_lds_dwordx4 v[236:237], off
	s_barrier
	s_waitcnt lgkmcnt(0)
	s_waitcnt lgkmcnt(0)
	v_mfma_f32_16x16x32_bf16 v[116:119], v[220:223], v[178:181], v[116:119]
	v_mfma_f32_16x16x32_bf16 v[112:115], v[228:231], v[178:181], v[112:115]
	v_mfma_f32_16x16x32_bf16 v[100:103], v[220:223], v[196:199], v[100:103]
	v_mfma_f32_16x16x32_bf16 v[96:99], v[228:231], v[196:199], v[96:99]
	v_mfma_f32_16x16x32_bf16 v[84:87], v[220:223], v[204:207], v[84:87]
	v_mfma_f32_16x16x32_bf16 v[80:83], v[228:231], v[204:207], v[80:83]
	v_mfma_f32_16x16x32_bf16 v[68:71], v[220:223], v[212:215], v[68:71]
	v_mfma_f32_16x16x32_bf16 v[64:67], v[228:231], v[212:215], v[64:67]
	v_mfma_f32_16x16x32_bf16 v[116:119], v[224:227], v[192:195], v[116:119]
	v_mfma_f32_16x16x32_bf16 v[112:115], v[232:235], v[192:195], v[112:115]
	v_mfma_f32_16x16x32_bf16 v[100:103], v[224:227], v[200:203], v[100:103]
	v_mfma_f32_16x16x32_bf16 v[96:99], v[232:235], v[200:203], v[96:99]
	v_mfma_f32_16x16x32_bf16 v[84:87], v[224:227], v[208:211], v[84:87]
	v_mfma_f32_16x16x32_bf16 v[80:83], v[232:235], v[208:211], v[80:83]
	v_mfma_f32_16x16x32_bf16 v[68:71], v[224:227], v[216:219], v[68:71]
	v_mfma_f32_16x16x32_bf16 v[64:67], v[232:235], v[216:219], v[64:67]
	s_mov_b32 m0, s23
	v_lshl_add_u64 v[238:239], s[30:31], 0, v[152:153]
	s_barrier
	ds_read_b128 v[178:181], v168 offset:16384
	ds_read_b128 v[192:195], v168 offset:17408
	ds_read_b128 v[196:199], v168 offset:18432
	ds_read_b128 v[200:203], v168 offset:19456
	ds_read_b128 v[204:207], v168 offset:20480
	ds_read_b128 v[208:211], v168 offset:21504
	ds_read_b128 v[212:215], v168 offset:22528
	ds_read_b128 v[216:219], v168 offset:23552
	global_load_lds_dwordx4 v[238:239], off
	v_lshl_add_u64 v[240:241], s[30:31], 0, v[150:151]
	s_mov_b32 m0, s45
	s_nop 0
	global_load_lds_dwordx4 v[240:241], off
	s_barrier
	s_waitcnt lgkmcnt(0)
	s_waitcnt lgkmcnt(0)
	v_mfma_f32_16x16x32_bf16 v[60:63], v[158:161], v[178:181], v[60:63]
	v_mfma_f32_16x16x32_bf16 v[56:59], v[170:173], v[178:181], v[56:59]
	v_mfma_f32_16x16x32_bf16 v[44:47], v[158:161], v[196:199], v[44:47]
	v_mfma_f32_16x16x32_bf16 v[40:43], v[170:173], v[196:199], v[40:43]
	v_mfma_f32_16x16x32_bf16 v[28:31], v[158:161], v[204:207], v[28:31]
	v_mfma_f32_16x16x32_bf16 v[24:27], v[170:173], v[204:207], v[24:27]
	v_mfma_f32_16x16x32_bf16 v[12:15], v[158:161], v[212:215], v[12:15]
	v_mfma_f32_16x16x32_bf16 v[8:11], v[170:173], v[212:215], v[8:11]
	v_mfma_f32_16x16x32_bf16 v[60:63], v[162:165], v[192:195], v[60:63]
	v_mfma_f32_16x16x32_bf16 v[56:59], v[174:177], v[192:195], v[56:59]
	v_mfma_f32_16x16x32_bf16 v[44:47], v[162:165], v[200:203], v[44:47]
	v_mfma_f32_16x16x32_bf16 v[40:43], v[174:177], v[200:203], v[40:43]
	v_mfma_f32_16x16x32_bf16 v[28:31], v[162:165], v[208:211], v[28:31]
	v_mfma_f32_16x16x32_bf16 v[24:27], v[174:177], v[208:211], v[24:27]
	v_mfma_f32_16x16x32_bf16 v[12:15], v[162:165], v[216:219], v[12:15]
	v_mfma_f32_16x16x32_bf16 v[8:11], v[174:177], v[216:219], v[8:11]
	s_barrier
; #define PG8_STAGE(bufoff, gbase, voff) do { _Pragma("unroll") for (int _i = 0; _i < 2; ++_i) \
;         __builtin_amdgcn_global_load_lds((const unsigned*)((const char*)(gbase) + (voff)[_i]), (PG8_LAS unsigned*)(lds + (bufoff) + ldsw + _i * 8192), 16, 0, 0); } while (0)
; #define PG8_LDA(dst, b, h) do { _Pragma("unroll") for (int m = 0; m < 4; ++m) _Pragma("unroll") for (int k = 0; k < 2; ++k) dst[m][k] = *(const PG8_LAS bf16x8*)(lds + PG8_SA(b, h) + aoff + m * 2048 + k * 1024); } while (0)
; #define PG8_LDB(dst, b, h) do { _Pragma("unroll") for (int n = 0; n < 2; ++n) _Pragma("unroll") for (int k = 0; k < 2; ++k) dst[n][k] = *(const PG8_LAS bf16x8*)(lds + PG8_SB(b, h) + boff + n * 2048 + k * 1024); } while (0)
; #define PG8_MMA(ai, bj, At, Bt) do { __builtin_amdgcn_s_setprio(1); _Pragma("unroll") for (int m = 0; m < 4; ++m) _Pragma("unroll") for (int n = 0; n < 2; ++n) _Pragma("unroll") for (int k = 0; k < 2; ++k) \
;         acc[ai][bj][m][n] = __builtin_amdgcn_mfma_f32_16x16x32_bf16(Bt[n][k], At[m][k], acc[ai][bj][m][n], 0, 0, 0); __builtin_amdgcn_s_setprio(0); } while (0)
; #define PG8_WAIT_V(n) asm volatile("s_waitcnt vmcnt(" #n ")" ::: "memory")
; #define PG8_WAIT_L(n) asm volatile("s_waitcnt lgkmcnt(" #n ")" ::: "memory")
; #define PG8_BAR __builtin_amdgcn_s_barrier()
; #define PG8_SCHED __builtin_amdgcn_sched_barrier(0)
; template <class Epi, class Sched, bool STAMP = false>
; __device__ __forceinline__ void gemm_phase(PG8_LAS unsigned char* lds, const Gemm g, const Sched& S, const Epi& E, unsigned long long* stamps) {
;     ...
;             PG8_WAIT_V(6); PG8_BAR; PG8_MMA(1, 1, At, B1); PG8_BAR;
;             PG8_LDB(B0, 1, 0); PG8_SCHED; PG8_LDA(At, 1, 0); PG8_STAGE(PG8_SA(0, 1), a2 + hstep, voffA);
;             PG8_WAIT_L(8); PG8_BAR; PG8_WAIT_L(0); PG8_MMA(0, 0, At, B0); PG8_BAR; PG8_SCHED;
;             PG8_LDB(B1, 1, 1); PG8_STAGE(PG8_SB(1, 0), b3, voffB);
;             PG8_BAR; PG8_WAIT_L(0); PG8_MMA(0, 1, At, B1); PG8_BAR;
;             PG8_LDA(At, 1, 1); PG8_STAGE(PG8_SA(1, 0), a3, voffA);
;             PG8_BAR; PG8_WAIT_L(0); PG8_MMA(1, 0, At, B0); PG8_BAR; PG8_SCHED;
	s_add_u32 s14, s26, 0x40000
	s_addc_u32 s15, s27, 0
	s_add_i32 s16, s17, s43
	v_lshl_add_u64 v[158:159], s[14:15], 0, v[128:129]
	s_mov_b32 m0, s16
	s_nop 0
	global_load_lds_dwordx4 v[158:159], off
	v_lshl_add_u64 v[158:159], s[14:15], 0, v[148:149]
	s_add_i32 m0, s16, 0x2000
	s_nop 0
	global_load_lds_dwordx4 v[158:159], off
	s_waitcnt vmcnt(6)
	s_barrier
	v_mfma_f32_16x16x32_bf16 v[52:55], v[220:223], v[178:181], v[52:55]
	v_mfma_f32_16x16x32_bf16 v[48:51], v[228:231], v[178:181], v[48:51]
	v_mfma_f32_16x16x32_bf16 v[36:39], v[220:223], v[196:199], v[36:39]
	v_mfma_f32_16x16x32_bf16 v[32:35], v[228:231], v[196:199], v[32:35]
	v_mfma_f32_16x16x32_bf16 v[20:23], v[220:223], v[204:207], v[20:23]
	v_mfma_f32_16x16x32_bf16 v[16:19], v[228:231], v[204:207], v[16:19]
	v_mfma_f32_16x16x32_bf16 v[4:7], v[220:223], v[212:215], v[4:7]
	v_mfma_f32_16x16x32_bf16 v[0:3], v[228:231], v[212:215], v[0:3]
	v_mfma_f32_16x16x32_bf16 v[52:55], v[224:227], v[192:195], v[52:55]
	v_mfma_f32_16x16x32_bf16 v[48:51], v[232:235], v[192:195], v[48:51]
	v_mfma_f32_16x16x32_bf16 v[36:39], v[224:227], v[200:203], v[36:39]
	v_mfma_f32_16x16x32_bf16 v[32:35], v[232:235], v[200:203], v[32:35]
	v_mfma_f32_16x16x32_bf16 v[20:23], v[224:227], v[208:211], v[20:23]
	v_mfma_f32_16x16x32_bf16 v[16:19], v[232:235], v[208:211], v[16:19]
	v_mfma_f32_16x16x32_bf16 v[4:7], v[224:227], v[216:219], v[4:7]
	v_mfma_f32_16x16x32_bf16 v[0:3], v[232:235], v[216:219], v[0:3]
	s_add_i32 s16, 0, 0x18000
	v_add_u32_e32 v169, s16, v166
	s_barrier
	ds_read_b128 v[158:161], v169
	ds_read_b128 v[162:165], v169 offset:1024
	ds_read_b128 v[170:173], v169 offset:2048
	ds_read_b128 v[174:177], v169 offset:3072
	s_add_u32 s14, s30, 0x40000
	s_addc_u32 s15, s31, 0
	s_mov_b32 m0, s46
	v_lshl_add_u64 v[220:221], s[14:15], 0, v[152:153]
	ds_read_b128 v[178:181], v168 offset:32768
	ds_read_b128 v[192:195], v168 offset:33792
	ds_read_b128 v[196:199], v168 offset:34816
	ds_read_b128 v[200:203], v168 offset:35840
	ds_read_b128 v[204:207], v168 offset:36864
	ds_read_b128 v[208:211], v168 offset:37888
	ds_read_b128 v[212:215], v168 offset:38912
	ds_read_b128 v[216:219], v168 offset:39936
	global_load_lds_dwordx4 v[220:221], off
	v_lshl_add_u64 v[220:221], s[14:15], 0, v[150:151]
	s_mov_b32 m0, s47
	s_nop 0
	global_load_lds_dwordx4 v[220:221], off
	s_waitcnt lgkmcnt(8)
	s_barrier
	s_waitcnt lgkmcnt(0)
	s_waitcnt lgkmcnt(0)
	v_mfma_f32_16x16x32_bf16 v[124:127], v[158:161], v[178:181], v[124:127]
	v_mfma_f32_16x16x32_bf16 v[120:123], v[170:173], v[178:181], v[120:123]
	v_mfma_f32_16x16x32_bf16 v[108:111], v[158:161], v[196:199], v[108:111]
	v_mfma_f32_16x16x32_bf16 v[104:107], v[170:173], v[196:199], v[104:107]
	v_mfma_f32_16x16x32_bf16 v[92:95], v[158:161], v[204:207], v[92:95]
	v_mfma_f32_16x16x32_bf16 v[88:91], v[170:173], v[204:207], v[88:91]
	v_mfma_f32_16x16x32_bf16 v[76:79], v[158:161], v[212:215], v[76:79]
	v_mfma_f32_16x16x32_bf16 v[72:75], v[170:173], v[212:215], v[72:75]
	v_mfma_f32_16x16x32_bf16 v[124:127], v[162:165], v[192:195], v[124:127]
	v_mfma_f32_16x16x32_bf16 v[120:123], v[174:177], v[192:195], v[120:123]
	v_mfma_f32_16x16x32_bf16 v[108:111], v[162:165], v[200:203], v[108:111]
	v_mfma_f32_16x16x32_bf16 v[104:107], v[174:177], v[200:203], v[104:107]
	v_mfma_f32_16x16x32_bf16 v[92:95], v[162:165], v[208:211], v[92:95]
	v_mfma_f32_16x16x32_bf16 v[88:91], v[174:177], v[208:211], v[88:91]
	v_mfma_f32_16x16x32_bf16 v[76:79], v[162:165], v[216:219], v[76:79]
	v_mfma_f32_16x16x32_bf16 v[72:75], v[174:177], v[216:219], v[72:75]
	s_barrier
	s_add_i32 s17, 0, 0x1c000
	s_add_i32 s14, s16, s43
	v_add_u32_e32 v169, s17, v166
	v_lshl_add_u64 v[182:183], v[182:183], 0, s[18:19]
	s_mov_b32 m0, s14
	ds_read_b128 v[220:223], v169
	ds_read_b128 v[224:227], v169 offset:1024
	ds_read_b128 v[228:231], v169 offset:2048
	ds_read_b128 v[232:235], v169 offset:3072
	global_load_lds_dwordx4 v[182:183], off
	v_lshl_add_u64 v[182:183], v[236:237], 0, s[18:19]
	s_add_i32 m0, s14, 0x2000
	s_nop 0
	global_load_lds_dwordx4 v[182:183], off
	s_barrier
	s_waitcnt lgkmcnt(0)
	s_waitcnt lgkmcnt(0)
	v_mfma_f32_16x16x32_bf16 v[116:119], v[220:223], v[178:181], v[116:119]
	v_mfma_f32_16x16x32_bf16 v[112:115], v[228:231], v[178:181], v[112:115]
	v_mfma_f32_16x16x32_bf16 v[100:103], v[220:223], v[196:199], v[100:103]
	v_mfma_f32_16x16x32_bf16 v[96:99], v[228:231], v[196:199], v[96:99]
	v_mfma_f32_16x16x32_bf16 v[84:87], v[220:223], v[204:207], v[84:87]
	v_mfma_f32_16x16x32_bf16 v[80:83], v[228:231], v[204:207], v[80:83]
	v_mfma_f32_16x16x32_bf16 v[68:71], v[220:223], v[212:215], v[68:71]
	v_mfma_f32_16x16x32_bf16 v[64:67], v[228:231], v[212:215], v[64:67]
	v_mfma_f32_16x16x32_bf16 v[116:119], v[224:227], v[192:195], v[116:119]
	v_mfma_f32_16x16x32_bf16 v[112:115], v[232:235], v[192:195], v[112:115]
	v_mfma_f32_16x16x32_bf16 v[100:103], v[224:227], v[200:203], v[100:103]
	v_mfma_f32_16x16x32_bf16 v[96:99], v[232:235], v[200:203], v[96:99]
	v_mfma_f32_16x16x32_bf16 v[84:87], v[224:227], v[208:211], v[84:87]
	v_mfma_f32_16x16x32_bf16 v[80:83], v[232:235], v[208:211], v[80:83]
	v_mfma_f32_16x16x32_bf16 v[68:71], v[224:227], v[216:219], v[68:71]
	v_mfma_f32_16x16x32_bf16 v[64:67], v[232:235], v[216:219], v[64:67]
	s_mov_b32 m0, s49
	v_lshl_add_u64 v[182:183], v[238:239], 0, s[18:19]
	s_barrier
	ds_read_b128 v[178:181], v168 offset:49152
	ds_read_b128 v[192:195], v168 offset:50176
	ds_read_b128 v[196:199], v168 offset:51200
	ds_read_b128 v[200:203], v168 offset:52224
	ds_read_b128 v[204:207], v168 offset:53248
	ds_read_b128 v[208:211], v168 offset:54272
	ds_read_b128 v[212:215], v168 offset:55296
	ds_read_b128 v[216:219], v168 offset:56320
	global_load_lds_dwordx4 v[182:183], off
	v_lshl_add_u64 v[182:183], v[240:241], 0, s[18:19]
	s_mov_b32 m0, s53
	s_nop 0
	global_load_lds_dwordx4 v[182:183], off
	s_barrier
; #define PG8_STAGE(bufoff, gbase, voff) do { _Pragma("unroll") for (int _i = 0; _i < 2; ++_i) \
;         __builtin_amdgcn_global_load_lds((const unsigned*)((const char*)(gbase) + (voff)[_i]), (PG8_LAS unsigned*)(lds + (bufoff) + ldsw + _i * 8192), 16, 0, 0); } while (0)
; #define PG8_MMA(ai, bj, At, Bt) do { __builtin_amdgcn_s_setprio(1); _Pragma("unroll") for (int m = 0; m < 4; ++m) _Pragma("unroll") for (int n = 0; n < 2; ++n) _Pragma("unroll") for (int k = 0; k < 2; ++k) \
;         acc[ai][bj][m][n] = __builtin_amdgcn_mfma_f32_16x16x32_bf16(Bt[n][k], At[m][k], acc[ai][bj][m][n], 0, 0, 0); __builtin_amdgcn_s_setprio(0); } while (0)
; #define PG8_WAIT_V(n) asm volatile("s_waitcnt vmcnt(" #n ")" ::: "memory")
; #define PG8_WAIT_L(n) asm volatile("s_waitcnt lgkmcnt(" #n ")" ::: "memory")
; #define PG8_BAR __builtin_amdgcn_s_barrier()
; #define PG8_SCHED __builtin_amdgcn_sched_barrier(0)
; __device__ __forceinline__ float rstd_of(const float* rowss, int row) { return rsqrtf(rowss[row] * (1.0f / 1024.0f) + 1e-6f); }
; template <class Epi, class Sched, bool STAMP = false>
; __device__ __forceinline__ void gemm_phase(PG8_LAS unsigned char* lds, const Gemm g, const Sched& S, const Epi& E, unsigned long long* stamps) {
;     ...
;             PG8_BAR; PG8_WAIT_L(0); PG8_MMA(1, 0, At, B0); PG8_BAR; PG8_SCHED;
;             PG8_STAGE(PG8_SB(1, 1), b3 + hstep, voffB);
;             PG8_WAIT_V(6); PG8_BAR; PG8_MMA(1, 1, At, B1); PG8_BAR;
;     __device__ __forceinline__ void operator()(const f32x4 (&acc)[2][2][4][2], const pg8::Unit& u, int wr, int wc, int fr, int fq) const {
;         const int row0 = u.pm * 256 + wr * 64 + fr, col0 = u.pn * 256 + wc * 32 + 8 * fq;
; #pragma unroll
;         for (int ai = 0; ai < 2; ++ai)
; #pragma unroll
;             for (int m = 0; m < 4; ++m) {
;                 const int row = row0 + ai * 128 + m * 16;
;                 const float s = (MODE == 2) ? 1.0f : rstd_of(rowss, row);
;                 bf16_t* rowp = O + (size_t)row * ldc + col0;
; #pragma unroll
;                 for (int bj = 0; bj < 2; ++bj) {
;                     f32x4 v0 = acc[ai][bj][m][0] * s, v1 = acc[ai][bj][m][1] * s;
;                     if (MODE == 1) {
; #pragma unroll
;                         for (int j = 0; j < 4; ++j) { const float a = fmaxf(v0[j], 0.f), b = fmaxf(v1[j], 0.f); v0[j] = a * a; v1[j] = b * b; } }
	s_waitcnt lgkmcnt(0)
	s_waitcnt lgkmcnt(0)
	v_mfma_f32_16x16x32_bf16 v[60:63], v[158:161], v[178:181], v[60:63]
	v_mfma_f32_16x16x32_bf16 v[56:59], v[170:173], v[178:181], v[56:59]
	v_mfma_f32_16x16x32_bf16 v[44:47], v[158:161], v[196:199], v[44:47]
	v_mfma_f32_16x16x32_bf16 v[40:43], v[170:173], v[196:199], v[40:43]
	v_mfma_f32_16x16x32_bf16 v[28:31], v[158:161], v[204:207], v[28:31]
	v_mfma_f32_16x16x32_bf16 v[24:27], v[170:173], v[204:207], v[24:27]
	v_mfma_f32_16x16x32_bf16 v[12:15], v[158:161], v[212:215], v[12:15]
	v_mfma_f32_16x16x32_bf16 v[8:11], v[170:173], v[212:215], v[8:11]
	v_mfma_f32_16x16x32_bf16 v[60:63], v[162:165], v[192:195], v[60:63]
	v_mfma_f32_16x16x32_bf16 v[56:59], v[174:177], v[192:195], v[56:59]
	v_mfma_f32_16x16x32_bf16 v[44:47], v[162:165], v[200:203], v[44:47]
	v_mfma_f32_16x16x32_bf16 v[40:43], v[174:177], v[200:203], v[40:43]
	v_mfma_f32_16x16x32_bf16 v[28:31], v[162:165], v[208:211], v[28:31]
	v_mfma_f32_16x16x32_bf16 v[24:27], v[174:177], v[208:211], v[24:27]
	v_mfma_f32_16x16x32_bf16 v[12:15], v[162:165], v[216:219], v[12:15]
	v_mfma_f32_16x16x32_bf16 v[8:11], v[174:177], v[216:219], v[8:11]
	s_barrier
	s_add_u32 s14, s26, 0x40080
	s_addc_u32 s15, s27, 0
	s_add_i32 s16, s17, s43
	v_lshl_add_u64 v[158:159], s[14:15], 0, v[128:129]
	s_mov_b32 m0, s16
	s_nop 0
	global_load_lds_dwordx4 v[158:159], off
	v_lshl_add_u64 v[158:159], s[14:15], 0, v[148:149]
	s_add_i32 m0, s16, 0x2000
	s_nop 0
	global_load_lds_dwordx4 v[158:159], off
	s_waitcnt vmcnt(6)
	s_barrier
	v_mfma_f32_16x16x32_bf16 v[52:55], v[220:223], v[178:181], v[52:55]
	v_mfma_f32_16x16x32_bf16 v[48:51], v[228:231], v[178:181], v[48:51]
	v_mfma_f32_16x16x32_bf16 v[36:39], v[220:223], v[196:199], v[36:39]
	v_mfma_f32_16x16x32_bf16 v[32:35], v[228:231], v[196:199], v[32:35]
	v_mfma_f32_16x16x32_bf16 v[20:23], v[220:223], v[204:207], v[20:23]
	v_mfma_f32_16x16x32_bf16 v[16:19], v[228:231], v[204:207], v[16:19]
	v_mfma_f32_16x16x32_bf16 v[4:7], v[220:223], v[212:215], v[4:7]
	v_mfma_f32_16x16x32_bf16 v[0:3], v[228:231], v[212:215], v[0:3]
	v_mfma_f32_16x16x32_bf16 v[52:55], v[224:227], v[192:195], v[52:55]
	v_mfma_f32_16x16x32_bf16 v[48:51], v[232:235], v[192:195], v[48:51]
	v_mfma_f32_16x16x32_bf16 v[36:39], v[224:227], v[200:203], v[36:39]
	v_mfma_f32_16x16x32_bf16 v[32:35], v[232:235], v[200:203], v[32:35]
	v_mfma_f32_16x16x32_bf16 v[20:23], v[224:227], v[208:211], v[20:23]
	v_mfma_f32_16x16x32_bf16 v[16:19], v[232:235], v[208:211], v[16:19]
	v_mfma_f32_16x16x32_bf16 v[4:7], v[224:227], v[216:219], v[4:7]
	v_mfma_f32_16x16x32_bf16 v[0:3], v[232:235], v[216:219], v[0:3]
	s_add_i32 s61, s61, 2
	s_add_u32 s24, s24, 0x100
	s_addc_u32 s25, s25, 0
	s_add_u32 s59, s59, 0x100
	s_addc_u32 s60, s60, 0
	s_cmp_gt_u32 s61, 13
	s_barrier
	s_cbranch_scc0 .LBB0_44
	v_lshl_add_u32 v162, s22, 8, v139
	v_ashrrev_i32_e32 v163, 31, v162
	v_lshl_add_u64 v[158:159], v[162:163], 2, s[0:1]
	global_load_dword v164, v[158:159], off
	global_load_dword v193, v[158:159], off offset:64
	global_load_dword v194, v[158:159], off offset:128
	global_load_dword v195, v[158:159], off offset:192
	global_load_dword v196, v[158:159], off offset:512
	global_load_dword v197, v[158:159], off offset:576
	global_load_dword v198, v[158:159], off offset:640
	global_load_dword v199, v[158:159], off offset:704
	v_lshl_or_b32 v160, s56, 8, v167
	v_ashrrev_i32_e32 v161, 31, v160
	s_mov_b32 s5, 0x100000
	s_mov_b64 s[14:15], 0x100000
	s_mov_b32 s56, s4
	s_mov_b32 s22, s6
	s_mov_b64 s[26:27], s[20:21]
	s_mov_b64 s[24:25], s[12:13]
	s_waitcnt vmcnt(0)
	v_fmamk_f32 v164, v164, 0x3a800000, v187
	v_cmp_gt_f32_e32 vcc, s67, v164
	v_mul_f32_e32 v165, 0x4b800000, v164
	s_nop 0
	v_cndmask_b32_e32 v164, v164, v165, vcc
	v_rsq_f32_e32 v164, v164
	s_nop 0
	v_mul_f32_e32 v165, 0x45800000, v164
	v_cndmask_b32_e32 v170, v164, v165, vcc
	v_lshlrev_b64 v[164:165], 13, v[162:163]
	v_pk_mul_f32 v[120:121], v[120:121], v[170:171] op_sel_hi:[1,0]
	v_lshl_add_u64 v[172:173], s[2:3], 0, v[164:165]
	v_lshlrev_b64 v[164:165], 1, v[160:161]
	v_pk_mul_f32 v[126:127], v[126:127], v[170:171] op_sel_hi:[1,0]
	v_pk_mul_f32 v[124:125], v[124:125], v[170:171] op_sel_hi:[1,0]
	v_pk_mul_f32 v[122:123], v[122:123], v[170:171] op_sel_hi:[1,0]
	v_max_f32_e32 v120, 0, v120
	v_max_f32_e32 v121, 0, v121
	v_lshl_add_u64 v[160:161], v[172:173], 0, v[164:165]
	v_max_f32_e32 v124, 0, v124
	v_max_f32_e32 v125, 0, v125
	v_pk_mul_f32 v[172:173], v[120:121], v[120:121]
	v_max_f32_e32 v120, 0, v126
	v_max_f32_e32 v122, 0, v122
	v_max_f32_e32 v121, 0, v127
	v_max_f32_e32 v123, 0, v123
	v_pk_mul_f32 v[124:125], v[124:125], v[124:125]
	v_pk_mul_f32 v[126:127], v[120:121], v[120:121]
	v_pk_mul_f32 v[174:175], v[122:123], v[122:123]
	v_pk_mul_f32 v[112:113], v[112:113], v[170:171] op_sel_hi:[1,0]
	v_cvt_pk_bf16_f32 v120, v124, v125
	v_cvt_pk_bf16_f32 v121, v126, v127
	v_cvt_pk_bf16_f32 v122, v172, v173
	v_cvt_pk_bf16_f32 v123, v174, v175
	v_pk_mul_f32 v[118:119], v[118:119], v[170:171] op_sel_hi:[1,0]
	v_pk_mul_f32 v[116:117], v[116:117], v[170:171] op_sel_hi:[1,0]
	v_pk_mul_f32 v[114:115], v[114:115], v[170:171] op_sel_hi:[1,0]
	v_max_f32_e32 v112, 0, v112
	v_max_f32_e32 v113, 0, v113
	global_store_dwordx4 v[160:161], v[120:123], off
	v_max_f32_e32 v116, 0, v116
	v_max_f32_e32 v117, 0, v117
	v_pk_mul_f32 v[120:121], v[112:113], v[112:113]
	v_max_f32_e32 v112, 0, v118
	v_max_f32_e32 v114, 0, v114
	v_max_f32_e32 v113, 0, v119
	v_max_f32_e32 v115, 0, v115
	v_pk_mul_f32 v[116:117], v[116:117], v[116:117]
	v_pk_mul_f32 v[118:119], v[112:113], v[112:113]
	v_pk_mul_f32 v[122:123], v[114:115], v[114:115]
	v_cvt_pk_bf16_f32 v112, v116, v117
	v_cvt_pk_bf16_f32 v113, v118, v119
; __device__ __forceinline__ unsigned cvt_pk_bf16(float lo, float hi) { const f32x2_cv v = {lo, hi}; const bf16x2_cv b = __builtin_convertvector(v, bf16x2_cv); return __builtin_bit_cast(unsigned, b); }
; __device__ __forceinline__ float rstd_of(const float* rowss, int row) { return rsqrtf(rowss[row] * (1.0f / 1024.0f) + 1e-6f); }
;     __device__ __forceinline__ void operator()(const f32x4 (&acc)[2][2][4][2], const pg8::Unit& u, int wr, int wc, int fr, int fq) const {
;     ...
;             for (int m = 0; m < 4; ++m) {
;                 const int row = row0 + ai * 128 + m * 16;
;                 const float s = (MODE == 2) ? 1.0f : rstd_of(rowss, row);
;                 bf16_t* rowp = O + (size_t)row * ldc + col0;
; #pragma unroll
;                 for (int bj = 0; bj < 2; ++bj) {
;                     f32x4 v0 = acc[ai][bj][m][0] * s, v1 = acc[ai][bj][m][1] * s;
;                     if (MODE == 1) {
; #pragma unroll
;                         for (int j = 0; j < 4; ++j) { const float a = fmaxf(v0[j], 0.f), b = fmaxf(v1[j], 0.f); v0[j] = a * a; v1[j] = b * b; } }
;                     u32x4 w; w.x = cvt_pk_bf16(v0[0], v0[1]); w.y = cvt_pk_bf16(v0[2], v0[3]); w.z = cvt_pk_bf16(v1[0], v1[1]); w.w = cvt_pk_bf16(v1[2], v1[3]);
;                     *(u32x4*)(rowp + bj * 128) = w; } }
	v_cvt_pk_bf16_f32 v114, v120, v121
	v_cvt_pk_bf16_f32 v115, v122, v123
	global_store_dwordx4 v[160:161], v[112:115], off offset:256
	s_nop 1
	v_mov_b32_e32 v114, v193
	s_nop 0
	v_or_b32_e32 v112, 16, v162
	v_ashrrev_i32_e32 v113, 31, v112
	v_lshlrev_b64 v[112:113], 13, v[112:113]
	v_lshl_add_u64 v[112:113], s[2:3], 0, v[112:113]
	v_lshl_add_u64 v[112:113], v[112:113], 0, v[164:165]
	v_fmamk_f32 v114, v114, 0x3a800000, v187
	v_cmp_gt_f32_e32 vcc, s67, v114
	v_mul_f32_e32 v115, 0x4b800000, v114
	s_nop 0
	v_cndmask_b32_e32 v114, v114, v115, vcc
	v_rsq_f32_e32 v114, v114
	s_nop 0
	v_mul_f32_e32 v115, 0x45800000, v114
	v_cndmask_b32_e32 v114, v114, v115, vcc
	v_pk_mul_f32 v[104:105], v[104:105], v[114:115] op_sel_hi:[1,0]
	v_pk_mul_f32 v[110:111], v[110:111], v[114:115] op_sel_hi:[1,0]
	v_pk_mul_f32 v[108:109], v[108:109], v[114:115] op_sel_hi:[1,0]
	v_pk_mul_f32 v[106:107], v[106:107], v[114:115] op_sel_hi:[1,0]
	v_max_f32_e32 v104, 0, v104
	v_max_f32_e32 v105, 0, v105
	v_max_f32_e32 v108, 0, v108
	v_max_f32_e32 v109, 0, v109
	v_pk_mul_f32 v[116:117], v[104:105], v[104:105]
	v_max_f32_e32 v104, 0, v110
	v_max_f32_e32 v106, 0, v106
	v_max_f32_e32 v105, 0, v111
	v_max_f32_e32 v107, 0, v107
	v_pk_mul_f32 v[108:109], v[108:109], v[108:109]
	v_pk_mul_f32 v[110:111], v[104:105], v[104:105]
	v_pk_mul_f32 v[118:119], v[106:107], v[106:107]
	v_pk_mul_f32 v[96:97], v[96:97], v[114:115] op_sel_hi:[1,0]
	v_cvt_pk_bf16_f32 v104, v108, v109
	v_cvt_pk_bf16_f32 v105, v110, v111
	v_cvt_pk_bf16_f32 v106, v116, v117
	v_cvt_pk_bf16_f32 v107, v118, v119
	v_pk_mul_f32 v[102:103], v[102:103], v[114:115] op_sel_hi:[1,0]
	v_pk_mul_f32 v[100:101], v[100:101], v[114:115] op_sel_hi:[1,0]
	v_pk_mul_f32 v[98:99], v[98:99], v[114:115] op_sel_hi:[1,0]
	v_max_f32_e32 v96, 0, v96
	v_max_f32_e32 v97, 0, v97
	global_store_dwordx4 v[112:113], v[104:107], off
	v_max_f32_e32 v100, 0, v100
	v_max_f32_e32 v101, 0, v101
	v_pk_mul_f32 v[104:105], v[96:97], v[96:97]
	v_max_f32_e32 v96, 0, v102
	v_max_f32_e32 v98, 0, v98
	v_max_f32_e32 v97, 0, v103
	v_max_f32_e32 v99, 0, v99
	v_pk_mul_f32 v[100:101], v[100:101], v[100:101]
	v_pk_mul_f32 v[102:103], v[96:97], v[96:97]
	v_pk_mul_f32 v[106:107], v[98:99], v[98:99]
	v_cvt_pk_bf16_f32 v96, v100, v101
	v_cvt_pk_bf16_f32 v97, v102, v103
	v_cvt_pk_bf16_f32 v98, v104, v105
	v_cvt_pk_bf16_f32 v99, v106, v107
	global_store_dwordx4 v[112:113], v[96:99], off offset:256
	s_nop 1
	v_mov_b32_e32 v98, v194
	s_nop 0
	v_or_b32_e32 v96, 32, v162
	v_ashrrev_i32_e32 v97, 31, v96
	v_lshlrev_b64 v[96:97], 13, v[96:97]
	v_lshl_add_u64 v[96:97], s[2:3], 0, v[96:97]
	v_lshl_add_u64 v[96:97], v[96:97], 0, v[164:165]
	v_fmamk_f32 v98, v98, 0x3a800000, v187
	v_cmp_gt_f32_e32 vcc, s67, v98
	v_mul_f32_e32 v99, 0x4b800000, v98
	s_nop 0
	v_cndmask_b32_e32 v98, v98, v99, vcc
	v_rsq_f32_e32 v98, v98
	s_nop 0
	v_mul_f32_e32 v99, 0x45800000, v98
	v_cndmask_b32_e32 v98, v98, v99, vcc
	v_pk_mul_f32 v[88:89], v[88:89], v[98:99] op_sel_hi:[1,0]
	v_pk_mul_f32 v[94:95], v[94:95], v[98:99] op_sel_hi:[1,0]
	v_pk_mul_f32 v[92:93], v[92:93], v[98:99] op_sel_hi:[1,0]
	v_pk_mul_f32 v[90:91], v[90:91], v[98:99] op_sel_hi:[1,0]
	v_max_f32_e32 v88, 0, v88
	v_max_f32_e32 v89, 0, v89
	v_max_f32_e32 v92, 0, v92
	v_max_f32_e32 v93, 0, v93
	v_pk_mul_f32 v[100:101], v[88:89], v[88:89]
	v_max_f32_e32 v88, 0, v94
	v_max_f32_e32 v90, 0, v90
	v_max_f32_e32 v89, 0, v95
	v_max_f32_e32 v91, 0, v91
	v_pk_mul_f32 v[92:93], v[92:93], v[92:93]
	v_pk_mul_f32 v[94:95], v[88:89], v[88:89]
	v_pk_mul_f32 v[102:103], v[90:91], v[90:91]
	v_pk_mul_f32 v[80:81], v[80:81], v[98:99] op_sel_hi:[1,0]
	v_cvt_pk_bf16_f32 v88, v92, v93
	v_cvt_pk_bf16_f32 v89, v94, v95
	v_cvt_pk_bf16_f32 v90, v100, v101
	v_cvt_pk_bf16_f32 v91, v102, v103
	v_pk_mul_f32 v[86:87], v[86:87], v[98:99] op_sel_hi:[1,0]
	v_pk_mul_f32 v[84:85], v[84:85], v[98:99] op_sel_hi:[1,0]
	v_pk_mul_f32 v[82:83], v[82:83], v[98:99] op_sel_hi:[1,0]
	v_max_f32_e32 v80, 0, v80
	v_max_f32_e32 v81, 0, v81
	global_store_dwordx4 v[96:97], v[88:91], off
	v_max_f32_e32 v84, 0, v84
	v_max_f32_e32 v85, 0, v85
	v_pk_mul_f32 v[88:89], v[80:81], v[80:81]
	v_max_f32_e32 v80, 0, v86
	v_max_f32_e32 v82, 0, v82
	v_max_f32_e32 v81, 0, v87
	v_max_f32_e32 v83, 0, v83
	v_pk_mul_f32 v[84:85], v[84:85], v[84:85]
	v_pk_mul_f32 v[86:87], v[80:81], v[80:81]
	v_pk_mul_f32 v[90:91], v[82:83], v[82:83]
	v_cvt_pk_bf16_f32 v80, v84, v85
	v_cvt_pk_bf16_f32 v81, v86, v87
	v_cvt_pk_bf16_f32 v82, v88, v89
	v_cvt_pk_bf16_f32 v83, v90, v91
	global_store_dwordx4 v[96:97], v[80:83], off offset:256
	s_nop 1
	v_mov_b32_e32 v82, v195
	s_nop 0
	v_or_b32_e32 v80, 48, v162
	v_ashrrev_i32_e32 v81, 31, v80
	v_lshlrev_b64 v[80:81], 13, v[80:81]
	v_lshl_add_u64 v[80:81], s[2:3], 0, v[80:81]
	v_lshl_add_u64 v[80:81], v[80:81], 0, v[164:165]
	v_fmamk_f32 v82, v82, 0x3a800000, v187
	v_cmp_gt_f32_e32 vcc, s67, v82
	v_mul_f32_e32 v83, 0x4b800000, v82
	s_nop 0
	v_cndmask_b32_e32 v82, v82, v83, vcc
	v_rsq_f32_e32 v82, v82
	s_nop 0
	v_mul_f32_e32 v83, 0x45800000, v82
	v_cndmask_b32_e32 v82, v82, v83, vcc
	v_pk_mul_f32 v[72:73], v[72:73], v[82:83] op_sel_hi:[1,0]
	v_pk_mul_f32 v[78:79], v[78:79], v[82:83] op_sel_hi:[1,0]
	v_pk_mul_f32 v[76:77], v[76:77], v[82:83] op_sel_hi:[1,0]
	v_pk_mul_f32 v[74:75], v[74:75], v[82:83] op_sel_hi:[1,0]
	v_max_f32_e32 v72, 0, v72
	v_max_f32_e32 v73, 0, v73
	v_max_f32_e32 v76, 0, v76
	v_max_f32_e32 v77, 0, v77
	v_pk_mul_f32 v[84:85], v[72:73], v[72:73]
	v_max_f32_e32 v72, 0, v78
	v_max_f32_e32 v74, 0, v74
	v_max_f32_e32 v73, 0, v79
	v_max_f32_e32 v75, 0, v75
	v_pk_mul_f32 v[76:77], v[76:77], v[76:77]
	v_pk_mul_f32 v[78:79], v[72:73], v[72:73]
	v_pk_mul_f32 v[86:87], v[74:75], v[74:75]
; __device__ __forceinline__ unsigned cvt_pk_bf16(float lo, float hi) { const f32x2_cv v = {lo, hi}; const bf16x2_cv b = __builtin_convertvector(v, bf16x2_cv); return __builtin_bit_cast(unsigned, b); }
; __device__ __forceinline__ float rstd_of(const float* rowss, int row) { return rsqrtf(rowss[row] * (1.0f / 1024.0f) + 1e-6f); }
;     __device__ __forceinline__ void operator()(const f32x4 (&acc)[2][2][4][2], const pg8::Unit& u, int wr, int wc, int fr, int fq) const {
;         const int row0 = u.pm * 256 + wr * 64 + fr, col0 = u.pn * 256 + wc * 32 + 8 * fq;
; #pragma unroll
;         for (int ai = 0; ai < 2; ++ai)
; #pragma unroll
;             for (int m = 0; m < 4; ++m) {
;                 const int row = row0 + ai * 128 + m * 16;
;                 const float s = (MODE == 2) ? 1.0f : rstd_of(rowss, row);
;                 bf16_t* rowp = O + (size_t)row * ldc + col0;
; #pragma unroll
;                 for (int bj = 0; bj < 2; ++bj) {
;                     f32x4 v0 = acc[ai][bj][m][0] * s, v1 = acc[ai][bj][m][1] * s;
;                     if (MODE == 1) {
; #pragma unroll
;                         for (int j = 0; j < 4; ++j) { const float a = fmaxf(v0[j], 0.f), b = fmaxf(v1[j], 0.f); v0[j] = a * a; v1[j] = b * b; } }
;                     u32x4 w; w.x = cvt_pk_bf16(v0[0], v0[1]); w.y = cvt_pk_bf16(v0[2], v0[3]); w.z = cvt_pk_bf16(v1[0], v1[1]); w.w = cvt_pk_bf16(v1[2], v1[3]);
;                     *(u32x4*)(rowp + bj * 128) = w; } }
	v_pk_mul_f32 v[64:65], v[64:65], v[82:83] op_sel_hi:[1,0]
	v_cvt_pk_bf16_f32 v72, v76, v77
	v_cvt_pk_bf16_f32 v73, v78, v79
	v_cvt_pk_bf16_f32 v74, v84, v85
	v_cvt_pk_bf16_f32 v75, v86, v87
	v_pk_mul_f32 v[70:71], v[70:71], v[82:83] op_sel_hi:[1,0]
	v_pk_mul_f32 v[68:69], v[68:69], v[82:83] op_sel_hi:[1,0]
	v_pk_mul_f32 v[66:67], v[66:67], v[82:83] op_sel_hi:[1,0]
	v_max_f32_e32 v64, 0, v64
	v_max_f32_e32 v65, 0, v65
	global_store_dwordx4 v[80:81], v[72:75], off
	v_max_f32_e32 v68, 0, v68
	v_max_f32_e32 v69, 0, v69
	v_pk_mul_f32 v[72:73], v[64:65], v[64:65]
	v_max_f32_e32 v64, 0, v70
	v_max_f32_e32 v66, 0, v66
	v_max_f32_e32 v65, 0, v71
	v_max_f32_e32 v67, 0, v67
	v_pk_mul_f32 v[68:69], v[68:69], v[68:69]
	v_pk_mul_f32 v[70:71], v[64:65], v[64:65]
	v_pk_mul_f32 v[74:75], v[66:67], v[66:67]
	v_cvt_pk_bf16_f32 v64, v68, v69
	v_cvt_pk_bf16_f32 v65, v70, v71
	v_cvt_pk_bf16_f32 v66, v72, v73
	v_cvt_pk_bf16_f32 v67, v74, v75
	global_store_dwordx4 v[80:81], v[64:67], off offset:256
	s_nop 1
	v_mov_b32_e32 v64, v196
	v_fmamk_f32 v64, v64, 0x3a800000, v187
	v_cmp_gt_f32_e32 vcc, s67, v64
	v_mul_f32_e32 v65, 0x4b800000, v64
	s_nop 0
	v_cndmask_b32_e32 v64, v64, v65, vcc
	v_rsq_f32_e32 v64, v64
	s_nop 0
	v_mul_f32_e32 v65, 0x45800000, v64
	v_cndmask_b32_e32 v66, v64, v65, vcc
	v_pk_mul_f32 v[60:61], v[60:61], v[66:67] op_sel_hi:[1,0]
	v_pk_mul_f32 v[56:57], v[56:57], v[66:67] op_sel_hi:[1,0]
	v_pk_mul_f32 v[62:63], v[62:63], v[66:67] op_sel_hi:[1,0]
	v_pk_mul_f32 v[58:59], v[58:59], v[66:67] op_sel_hi:[1,0]
	v_max_f32_e32 v60, 0, v60
	v_max_f32_e32 v56, 0, v56
	v_max_f32_e32 v61, 0, v61
	v_max_f32_e32 v57, 0, v57
	v_pk_mul_f32 v[60:61], v[60:61], v[60:61]
	v_pk_mul_f32 v[68:69], v[56:57], v[56:57]
	v_max_f32_e32 v56, 0, v62
	v_max_f32_e32 v58, 0, v58
	v_max_f32_e32 v57, 0, v63
	v_max_f32_e32 v59, 0, v59
	v_pk_mul_f32 v[62:63], v[56:57], v[56:57]
	v_pk_mul_f32 v[70:71], v[58:59], v[58:59]
	v_cvt_pk_bf16_f32 v56, v60, v61
	v_add_co_u32_e32 v60, vcc, s5, v160
	v_pk_mul_f32 v[48:49], v[48:49], v[66:67] op_sel_hi:[1,0]
	v_cvt_pk_bf16_f32 v57, v62, v63
	v_cvt_pk_bf16_f32 v58, v68, v69
	v_cvt_pk_bf16_f32 v59, v70, v71
	v_addc_co_u32_e32 v61, vcc, 0, v161, vcc
	v_pk_mul_f32 v[54:55], v[54:55], v[66:67] op_sel_hi:[1,0]
	v_pk_mul_f32 v[52:53], v[52:53], v[66:67] op_sel_hi:[1,0]
	v_pk_mul_f32 v[50:51], v[50:51], v[66:67] op_sel_hi:[1,0]
	v_max_f32_e32 v48, 0, v48
	v_max_f32_e32 v49, 0, v49
	global_store_dwordx4 v[60:61], v[56:59], off
	v_max_f32_e32 v52, 0, v52
	v_max_f32_e32 v53, 0, v53
	v_pk_mul_f32 v[56:57], v[48:49], v[48:49]
	v_max_f32_e32 v48, 0, v54
	v_max_f32_e32 v50, 0, v50
	v_max_f32_e32 v49, 0, v55
	v_max_f32_e32 v51, 0, v51
	v_pk_mul_f32 v[52:53], v[52:53], v[52:53]
	v_pk_mul_f32 v[54:55], v[48:49], v[48:49]
	v_pk_mul_f32 v[58:59], v[50:51], v[50:51]
	v_lshl_add_u64 v[64:65], v[160:161], 0, s[14:15]
	v_cvt_pk_bf16_f32 v48, v52, v53
	v_cvt_pk_bf16_f32 v49, v54, v55
	v_cvt_pk_bf16_f32 v50, v56, v57
	v_cvt_pk_bf16_f32 v51, v58, v59
	global_store_dwordx4 v[64:65], v[48:51], off offset:256
	s_nop 1
	v_mov_b32_e32 v48, v197
	s_mov_b32 s5, 0x120000
	s_mov_b64 s[14:15], 0x120000
	v_fmamk_f32 v48, v48, 0x3a800000, v187
	v_cmp_gt_f32_e32 vcc, s67, v48
	v_mul_f32_e32 v49, 0x4b800000, v48
	s_nop 0
	v_cndmask_b32_e32 v48, v48, v49, vcc
	v_rsq_f32_e32 v48, v48
	s_nop 0
	v_mul_f32_e32 v49, 0x45800000, v48
	v_cndmask_b32_e32 v50, v48, v49, vcc
	v_pk_mul_f32 v[44:45], v[44:45], v[50:51] op_sel_hi:[1,0]
	v_pk_mul_f32 v[40:41], v[40:41], v[50:51] op_sel_hi:[1,0]
	v_pk_mul_f32 v[46:47], v[46:47], v[50:51] op_sel_hi:[1,0]
	v_pk_mul_f32 v[42:43], v[42:43], v[50:51] op_sel_hi:[1,0]
	v_max_f32_e32 v44, 0, v44
	v_max_f32_e32 v40, 0, v40
	v_max_f32_e32 v45, 0, v45
	v_max_f32_e32 v41, 0, v41
	v_pk_mul_f32 v[44:45], v[44:45], v[44:45]
	v_pk_mul_f32 v[52:53], v[40:41], v[40:41]
	v_max_f32_e32 v40, 0, v46
	v_max_f32_e32 v42, 0, v42
	v_max_f32_e32 v41, 0, v47
	v_max_f32_e32 v43, 0, v43
	v_pk_mul_f32 v[46:47], v[40:41], v[40:41]
	v_pk_mul_f32 v[54:55], v[42:43], v[42:43]
	v_cvt_pk_bf16_f32 v40, v44, v45
	v_add_co_u32_e32 v44, vcc, s5, v160
	v_pk_mul_f32 v[32:33], v[32:33], v[50:51] op_sel_hi:[1,0]
	v_cvt_pk_bf16_f32 v41, v46, v47
	v_cvt_pk_bf16_f32 v42, v52, v53
	v_cvt_pk_bf16_f32 v43, v54, v55
	v_addc_co_u32_e32 v45, vcc, 0, v161, vcc
	v_pk_mul_f32 v[38:39], v[38:39], v[50:51] op_sel_hi:[1,0]
	v_pk_mul_f32 v[36:37], v[36:37], v[50:51] op_sel_hi:[1,0]
	v_pk_mul_f32 v[34:35], v[34:35], v[50:51] op_sel_hi:[1,0]
	v_max_f32_e32 v32, 0, v32
	v_max_f32_e32 v33, 0, v33
	global_store_dwordx4 v[44:45], v[40:43], off
	v_max_f32_e32 v36, 0, v36
	v_max_f32_e32 v37, 0, v37
	v_pk_mul_f32 v[40:41], v[32:33], v[32:33]
	v_max_f32_e32 v32, 0, v38
; __device__ __forceinline__ unsigned cvt_pk_bf16(float lo, float hi) { const f32x2_cv v = {lo, hi}; const bf16x2_cv b = __builtin_convertvector(v, bf16x2_cv); return __builtin_bit_cast(unsigned, b); }
; __device__ __forceinline__ float rstd_of(const float* rowss, int row) { return rsqrtf(rowss[row] * (1.0f / 1024.0f) + 1e-6f); }
; template <class Epi, class Sched, bool STAMP = false>
; __device__ __forceinline__ void gemm_phase(PG8_LAS unsigned char* lds, const Gemm g, const Sched& S, const Epi& E, unsigned long long* stamps) {
;     ...
;         if constexpr (!Epi::AFTER_DRAIN) { E(acc, cur, wr, wc, fr, fq); S.done(cur); }
;         if (!has_next) break;
;     __device__ __forceinline__ void operator()(const f32x4 (&acc)[2][2][4][2], const pg8::Unit& u, int wr, int wc, int fr, int fq) const {
;         const int row0 = u.pm * 256 + wr * 64 + fr, col0 = u.pn * 256 + wc * 32 + 8 * fq;
; #pragma unroll
;         for (int ai = 0; ai < 2; ++ai)
; #pragma unroll
;             for (int m = 0; m < 4; ++m) {
;                 const int row = row0 + ai * 128 + m * 16;
;                 const float s = (MODE == 2) ? 1.0f : rstd_of(rowss, row);
;                 bf16_t* rowp = O + (size_t)row * ldc + col0;
; #pragma unroll
;                 for (int bj = 0; bj < 2; ++bj) {
;                     f32x4 v0 = acc[ai][bj][m][0] * s, v1 = acc[ai][bj][m][1] * s;
;                     if (MODE == 1) {
; #pragma unroll
;                         for (int j = 0; j < 4; ++j) { const float a = fmaxf(v0[j], 0.f), b = fmaxf(v1[j], 0.f); v0[j] = a * a; v1[j] = b * b; } }
;                     u32x4 w; w.x = cvt_pk_bf16(v0[0], v0[1]); w.y = cvt_pk_bf16(v0[2], v0[3]); w.z = cvt_pk_bf16(v1[0], v1[1]); w.w = cvt_pk_bf16(v1[2], v1[3]);
;                     *(u32x4*)(rowp + bj * 128) = w; } }
	v_max_f32_e32 v34, 0, v34
	v_max_f32_e32 v33, 0, v39
	v_max_f32_e32 v35, 0, v35
	v_pk_mul_f32 v[36:37], v[36:37], v[36:37]
	v_pk_mul_f32 v[38:39], v[32:33], v[32:33]
	v_pk_mul_f32 v[42:43], v[34:35], v[34:35]
	v_lshl_add_u64 v[48:49], v[160:161], 0, s[14:15]
	v_cvt_pk_bf16_f32 v32, v36, v37
	v_cvt_pk_bf16_f32 v33, v38, v39
	v_cvt_pk_bf16_f32 v34, v40, v41
	v_cvt_pk_bf16_f32 v35, v42, v43
	global_store_dwordx4 v[48:49], v[32:35], off offset:256
	s_nop 1
	v_mov_b32_e32 v32, v198
	s_mov_b32 s5, 0x140000
	s_mov_b64 s[14:15], 0x140000
	v_fmamk_f32 v32, v32, 0x3a800000, v187
	v_cmp_gt_f32_e32 vcc, s67, v32
	v_mul_f32_e32 v33, 0x4b800000, v32
	s_nop 0
	v_cndmask_b32_e32 v32, v32, v33, vcc
	v_rsq_f32_e32 v32, v32
	s_nop 0
	v_mul_f32_e32 v33, 0x45800000, v32
	v_cndmask_b32_e32 v34, v32, v33, vcc
	v_pk_mul_f32 v[28:29], v[28:29], v[34:35] op_sel_hi:[1,0]
	v_pk_mul_f32 v[24:25], v[24:25], v[34:35] op_sel_hi:[1,0]
	v_pk_mul_f32 v[30:31], v[30:31], v[34:35] op_sel_hi:[1,0]
	v_pk_mul_f32 v[26:27], v[26:27], v[34:35] op_sel_hi:[1,0]
	v_max_f32_e32 v28, 0, v28
	v_max_f32_e32 v24, 0, v24
	v_max_f32_e32 v29, 0, v29
	v_max_f32_e32 v25, 0, v25
	v_pk_mul_f32 v[28:29], v[28:29], v[28:29]
	v_pk_mul_f32 v[36:37], v[24:25], v[24:25]
	v_max_f32_e32 v24, 0, v30
	v_max_f32_e32 v26, 0, v26
	v_max_f32_e32 v25, 0, v31
	v_max_f32_e32 v27, 0, v27
	v_pk_mul_f32 v[30:31], v[24:25], v[24:25]
	v_pk_mul_f32 v[38:39], v[26:27], v[26:27]
	v_cvt_pk_bf16_f32 v24, v28, v29
	v_add_co_u32_e32 v28, vcc, s5, v160
	v_pk_mul_f32 v[16:17], v[16:17], v[34:35] op_sel_hi:[1,0]
	v_cvt_pk_bf16_f32 v25, v30, v31
	v_cvt_pk_bf16_f32 v26, v36, v37
	v_cvt_pk_bf16_f32 v27, v38, v39
	v_addc_co_u32_e32 v29, vcc, 0, v161, vcc
	v_pk_mul_f32 v[22:23], v[22:23], v[34:35] op_sel_hi:[1,0]
	v_pk_mul_f32 v[20:21], v[20:21], v[34:35] op_sel_hi:[1,0]
	v_pk_mul_f32 v[18:19], v[18:19], v[34:35] op_sel_hi:[1,0]
	v_max_f32_e32 v16, 0, v16
	v_max_f32_e32 v17, 0, v17
	global_store_dwordx4 v[28:29], v[24:27], off
	v_max_f32_e32 v20, 0, v20
	v_max_f32_e32 v21, 0, v21
	v_pk_mul_f32 v[24:25], v[16:17], v[16:17]
	v_max_f32_e32 v16, 0, v22
	v_max_f32_e32 v18, 0, v18
	v_max_f32_e32 v17, 0, v23
	v_max_f32_e32 v19, 0, v19
	v_pk_mul_f32 v[20:21], v[20:21], v[20:21]
	v_pk_mul_f32 v[22:23], v[16:17], v[16:17]
	v_pk_mul_f32 v[26:27], v[18:19], v[18:19]
	v_lshl_add_u64 v[32:33], v[160:161], 0, s[14:15]
	v_cvt_pk_bf16_f32 v16, v20, v21
	v_cvt_pk_bf16_f32 v17, v22, v23
	v_cvt_pk_bf16_f32 v18, v24, v25
	v_cvt_pk_bf16_f32 v19, v26, v27
	global_store_dwordx4 v[32:33], v[16:19], off offset:256
	s_nop 1
	v_mov_b32_e32 v16, v199
	s_mov_b32 s5, 0x160000
	s_mov_b64 s[14:15], 0x160000
	v_lshl_add_u64 v[18:19], v[160:161], 0, s[14:15]
	v_fmamk_f32 v16, v16, 0x3a800000, v187
	v_cmp_gt_f32_e32 vcc, s67, v16
	v_mul_f32_e32 v17, 0x4b800000, v16
	s_nop 0
	v_cndmask_b32_e32 v16, v16, v17, vcc
	v_rsq_f32_e32 v16, v16
	s_nop 0
	v_mul_f32_e32 v17, 0x45800000, v16
	v_cndmask_b32_e32 v16, v16, v17, vcc
	v_pk_mul_f32 v[12:13], v[12:13], v[16:17] op_sel_hi:[1,0]
	v_pk_mul_f32 v[8:9], v[8:9], v[16:17] op_sel_hi:[1,0]
	v_pk_mul_f32 v[14:15], v[14:15], v[16:17] op_sel_hi:[1,0]
	v_pk_mul_f32 v[10:11], v[10:11], v[16:17] op_sel_hi:[1,0]
	v_max_f32_e32 v12, 0, v12
	v_max_f32_e32 v8, 0, v8
	v_max_f32_e32 v13, 0, v13
	v_max_f32_e32 v9, 0, v9
	v_pk_mul_f32 v[12:13], v[12:13], v[12:13]
	v_pk_mul_f32 v[20:21], v[8:9], v[8:9]
	v_max_f32_e32 v8, 0, v14
	v_max_f32_e32 v10, 0, v10
	v_max_f32_e32 v9, 0, v15
	v_max_f32_e32 v11, 0, v11
	v_pk_mul_f32 v[14:15], v[8:9], v[8:9]
	v_pk_mul_f32 v[22:23], v[10:11], v[10:11]
	v_cvt_pk_bf16_f32 v8, v12, v13
	v_add_co_u32_e32 v12, vcc, s5, v160
	v_pk_mul_f32 v[0:1], v[0:1], v[16:17] op_sel_hi:[1,0]
	v_cvt_pk_bf16_f32 v9, v14, v15
	v_cvt_pk_bf16_f32 v10, v20, v21
	v_cvt_pk_bf16_f32 v11, v22, v23
	v_addc_co_u32_e32 v13, vcc, 0, v161, vcc
	v_pk_mul_f32 v[6:7], v[6:7], v[16:17] op_sel_hi:[1,0]
	v_pk_mul_f32 v[4:5], v[4:5], v[16:17] op_sel_hi:[1,0]
	v_pk_mul_f32 v[2:3], v[2:3], v[16:17] op_sel_hi:[1,0]
	v_max_f32_e32 v0, 0, v0
	v_max_f32_e32 v1, 0, v1
	global_store_dwordx4 v[12:13], v[8:11], off
	v_max_f32_e32 v4, 0, v4
	v_max_f32_e32 v5, 0, v5
	v_pk_mul_f32 v[8:9], v[0:1], v[0:1]
	v_max_f32_e32 v0, 0, v6
	v_max_f32_e32 v2, 0, v2
	v_max_f32_e32 v1, 0, v7
	v_max_f32_e32 v3, 0, v3
	v_pk_mul_f32 v[4:5], v[4:5], v[4:5]
	v_pk_mul_f32 v[6:7], v[0:1], v[0:1]
	v_pk_mul_f32 v[10:11], v[2:3], v[2:3]
	v_cvt_pk_bf16_f32 v0, v4, v5
	v_cvt_pk_bf16_f32 v1, v6, v7
	v_cvt_pk_bf16_f32 v2, v8, v9
	v_cvt_pk_bf16_f32 v3, v10, v11
	s_and_b64 vcc, exec, s[38:39]
	global_store_dwordx4 v[18:19], v[0:3], off offset:256
	s_cbranch_vccz .LBB0_41
	s_cmpk_gt_u32 s36, 0xff
	s_cbranch_scc1 .LBB0_48
	s_barrier

; #define PG8_STAGE(bufoff, gbase, voff) do { _Pragma("unroll") for (int _i = 0; _i < 2; ++_i) \
;         __builtin_amdgcn_global_load_lds((const unsigned*)((const char*)(gbase) + (voff)[_i]), (PG8_LAS unsigned*)(lds + (bufoff) + ldsw + _i * 8192), 16, 0, 0); } while (0)
; #define PG8_LDA(dst, b, h) do { _Pragma("unroll") for (int m = 0; m < 4; ++m) _Pragma("unroll") for (int k = 0; k < 2; ++k) dst[m][k] = *(const PG8_LAS bf16x8*)(lds + PG8_SA(b, h) + aoff + m * 2048 + k * 1024); } while (0)
; #define PG8_LDB(dst, b, h) do { _Pragma("unroll") for (int n = 0; n < 2; ++n) _Pragma("unroll") for (int k = 0; k < 2; ++k) dst[n][k] = *(const PG8_LAS bf16x8*)(lds + PG8_SB(b, h) + boff + n * 2048 + k * 1024); } while (0)
; #define PG8_MMA(ai, bj, At, Bt) do { __builtin_amdgcn_s_setprio(1); _Pragma("unroll") for (int m = 0; m < 4; ++m) _Pragma("unroll") for (int n = 0; n < 2; ++n) _Pragma("unroll") for (int k = 0; k < 2; ++k) \
;         acc[ai][bj][m][n] = __builtin_amdgcn_mfma_f32_16x16x32_bf16(Bt[n][k], At[m][k], acc[ai][bj][m][n], 0, 0, 0); __builtin_amdgcn_s_setprio(0); } while (0)
; #define PG8_WAIT_L(n) asm volatile("s_waitcnt lgkmcnt(" #n ")" ::: "memory")
; #define PG8_BAR __builtin_amdgcn_s_barrier()
; #define PG8_SCHED __builtin_amdgcn_sched_barrier(0)
; template <class Epi, class Sched, bool STAMP = false>
; __device__ __forceinline__ void gemm_phase(PG8_LAS unsigned char* lds, const Gemm g, const Sched& S, const Epi& E, unsigned long long* stamps) {
;     ...
;             PG8_LDB(B0, 0, 0); PG8_SCHED; PG8_LDA(At, 0, 0); PG8_STAGE(PG8_SA(1, 1), a1 + hstep, voffA);
;             PG8_WAIT_L(8); PG8_BAR; PG8_WAIT_L(0); PG8_MMA(0, 0, At, B0); PG8_BAR; PG8_SCHED;
;             PG8_LDB(B1, 0, 1); PG8_STAGE(PG8_SB(0, 0), b2, voffB);
;             PG8_BAR; PG8_WAIT_L(0); PG8_MMA(0, 1, At, B1); PG8_BAR;
;             PG8_LDA(At, 0, 1); PG8_STAGE(PG8_SA(0, 0), a2, voffA);
;             PG8_BAR; PG8_WAIT_L(0); PG8_MMA(1, 0, At, B0); PG8_BAR; PG8_SCHED;
.LBB0_141:
	s_add_u32 s48, s44, 0x100
	s_addc_u32 s49, s45, 0
	s_add_i32 s14, 0, 0x10000
	v_add_u32_e32 v128, s14, v166
	ds_read_b128 v[156:159], v128
	ds_read_b128 v[160:163], v128 offset:1024
	ds_read_b128 v[170:173], v128 offset:2048
	ds_read_b128 v[174:177], v128 offset:3072
	s_cmp_eq_u32 s39, 12
	s_cselect_b32 s59, s23, s49
	s_cselect_b32 s58, s31, s48
	s_cselect_b32 s57, s21, s38
	s_cselect_b32 s56, vcc_lo, vcc_hi
	v_lshl_add_u64 v[164:165], s[44:45], 0, v[152:153]
	s_add_i32 m0, s37, 0xc000
	ds_read_b128 v[178:181], v168
	ds_read_b128 v[192:195], v168 offset:1024
	ds_read_b128 v[196:199], v168 offset:2048
	ds_read_b128 v[200:203], v168 offset:3072
	ds_read_b128 v[204:207], v168 offset:4096
	ds_read_b128 v[208:211], v168 offset:5120
	ds_read_b128 v[212:215], v168 offset:6144
	ds_read_b128 v[216:219], v168 offset:7168
	global_load_lds_dwordx4 v[164:165], off
	v_lshl_add_u64 v[164:165], s[44:45], 0, v[154:155]
	s_add_i32 m0, s37, 0xe000
	s_nop 0
	global_load_lds_dwordx4 v[164:165], off
	s_waitcnt lgkmcnt(8)
	s_barrier
	s_waitcnt lgkmcnt(0)
	s_waitcnt lgkmcnt(0)
	v_mfma_f32_16x16x32_bf16 v[124:127], v[156:159], v[178:181], v[124:127]
	v_mfma_f32_16x16x32_bf16 v[120:123], v[170:173], v[178:181], v[120:123]
	v_mfma_f32_16x16x32_bf16 v[108:111], v[156:159], v[196:199], v[108:111]
	v_mfma_f32_16x16x32_bf16 v[104:107], v[170:173], v[196:199], v[104:107]
	v_mfma_f32_16x16x32_bf16 v[92:95], v[156:159], v[204:207], v[92:95]
	v_mfma_f32_16x16x32_bf16 v[88:91], v[170:173], v[204:207], v[88:91]
	v_mfma_f32_16x16x32_bf16 v[76:79], v[156:159], v[212:215], v[76:79]
	v_mfma_f32_16x16x32_bf16 v[72:75], v[170:173], v[212:215], v[72:75]
	v_mfma_f32_16x16x32_bf16 v[124:127], v[160:163], v[192:195], v[124:127]
	v_mfma_f32_16x16x32_bf16 v[120:123], v[174:177], v[192:195], v[120:123]
	v_mfma_f32_16x16x32_bf16 v[108:111], v[160:163], v[200:203], v[108:111]
	v_mfma_f32_16x16x32_bf16 v[104:107], v[174:177], v[200:203], v[104:107]
	v_mfma_f32_16x16x32_bf16 v[92:95], v[160:163], v[208:211], v[92:95]
	v_mfma_f32_16x16x32_bf16 v[88:91], v[174:177], v[208:211], v[88:91]
	v_mfma_f32_16x16x32_bf16 v[76:79], v[160:163], v[216:219], v[76:79]
	v_mfma_f32_16x16x32_bf16 v[72:75], v[174:177], v[216:219], v[72:75]
	s_barrier
	s_add_i32 s16, 0, 0x14000
	s_add_i32 s14, s14, s64
	v_add_u32_e32 v128, s16, v166
	v_lshl_add_u64 v[164:165], s[56:57], 0, v[148:149]
	s_mov_b32 m0, s14
	ds_read_b128 v[220:223], v128
	ds_read_b128 v[224:227], v128 offset:1024
	ds_read_b128 v[228:231], v128 offset:2048
	ds_read_b128 v[232:235], v128 offset:3072
	global_load_lds_dwordx4 v[164:165], off
	v_lshl_add_u64 v[182:183], s[56:57], 0, v[150:151]
	s_add_i32 m0, s14, 0x2000
	s_nop 0
	global_load_lds_dwordx4 v[182:183], off
	s_barrier
	s_waitcnt lgkmcnt(0)
	s_waitcnt lgkmcnt(0)
	v_mfma_f32_16x16x32_bf16 v[116:119], v[220:223], v[178:181], v[116:119]
	v_mfma_f32_16x16x32_bf16 v[112:115], v[228:231], v[178:181], v[112:115]
	v_mfma_f32_16x16x32_bf16 v[100:103], v[220:223], v[196:199], v[100:103]
	v_mfma_f32_16x16x32_bf16 v[96:99], v[228:231], v[196:199], v[96:99]
	v_mfma_f32_16x16x32_bf16 v[84:87], v[220:223], v[204:207], v[84:87]
	v_mfma_f32_16x16x32_bf16 v[80:83], v[228:231], v[204:207], v[80:83]
	v_mfma_f32_16x16x32_bf16 v[68:71], v[220:223], v[212:215], v[68:71]
	v_mfma_f32_16x16x32_bf16 v[64:67], v[228:231], v[212:215], v[64:67]
	v_mfma_f32_16x16x32_bf16 v[116:119], v[224:227], v[192:195], v[116:119]
	v_mfma_f32_16x16x32_bf16 v[112:115], v[232:235], v[192:195], v[112:115]
	v_mfma_f32_16x16x32_bf16 v[100:103], v[224:227], v[200:203], v[100:103]
	v_mfma_f32_16x16x32_bf16 v[96:99], v[232:235], v[200:203], v[96:99]
	v_mfma_f32_16x16x32_bf16 v[84:87], v[224:227], v[208:211], v[84:87]
	v_mfma_f32_16x16x32_bf16 v[80:83], v[232:235], v[208:211], v[80:83]
	v_mfma_f32_16x16x32_bf16 v[68:71], v[224:227], v[216:219], v[68:71]
	v_mfma_f32_16x16x32_bf16 v[64:67], v[232:235], v[216:219], v[64:67]
	s_mov_b32 m0, s37
	v_lshl_add_u64 v[236:237], s[58:59], 0, v[148:149]
	s_barrier
	ds_read_b128 v[178:181], v168 offset:16384
	ds_read_b128 v[192:195], v168 offset:17408
	ds_read_b128 v[196:199], v168 offset:18432
	ds_read_b128 v[200:203], v168 offset:19456
	ds_read_b128 v[204:207], v168 offset:20480
	ds_read_b128 v[208:211], v168 offset:21504
	ds_read_b128 v[212:215], v168 offset:22528
	ds_read_b128 v[216:219], v168 offset:23552
	global_load_lds_dwordx4 v[236:237], off
	v_lshl_add_u64 v[238:239], s[58:59], 0, v[150:151]
	s_mov_b32 m0, s65
	s_nop 0
	global_load_lds_dwordx4 v[238:239], off
	s_barrier
	s_waitcnt lgkmcnt(0)
	s_waitcnt lgkmcnt(0)
	v_mfma_f32_16x16x32_bf16 v[60:63], v[156:159], v[178:181], v[60:63]
	v_mfma_f32_16x16x32_bf16 v[56:59], v[170:173], v[178:181], v[56:59]
	v_mfma_f32_16x16x32_bf16 v[44:47], v[156:159], v[196:199], v[44:47]
	v_mfma_f32_16x16x32_bf16 v[40:43], v[170:173], v[196:199], v[40:43]
	v_mfma_f32_16x16x32_bf16 v[28:31], v[156:159], v[204:207], v[28:31]
	v_mfma_f32_16x16x32_bf16 v[24:27], v[170:173], v[204:207], v[24:27]
	v_mfma_f32_16x16x32_bf16 v[12:15], v[156:159], v[212:215], v[12:15]
	v_mfma_f32_16x16x32_bf16 v[8:11], v[170:173], v[212:215], v[8:11]
	v_mfma_f32_16x16x32_bf16 v[60:63], v[160:163], v[192:195], v[60:63]
	v_mfma_f32_16x16x32_bf16 v[56:59], v[174:177], v[192:195], v[56:59]
	v_mfma_f32_16x16x32_bf16 v[44:47], v[160:163], v[200:203], v[44:47]
	v_mfma_f32_16x16x32_bf16 v[40:43], v[174:177], v[200:203], v[40:43]
	v_mfma_f32_16x16x32_bf16 v[28:31], v[160:163], v[208:211], v[28:31]
	v_mfma_f32_16x16x32_bf16 v[24:27], v[174:177], v[208:211], v[24:27]
	v_mfma_f32_16x16x32_bf16 v[12:15], v[160:163], v[216:219], v[12:15]
	v_mfma_f32_16x16x32_bf16 v[8:11], v[174:177], v[216:219], v[8:11]
	s_barrier
; #define PG8_STAGE(bufoff, gbase, voff) do { _Pragma("unroll") for (int _i = 0; _i < 2; ++_i) \
;         __builtin_amdgcn_global_load_lds((const unsigned*)((const char*)(gbase) + (voff)[_i]), (PG8_LAS unsigned*)(lds + (bufoff) + ldsw + _i * 8192), 16, 0, 0); } while (0)
; #define PG8_LDA(dst, b, h) do { _Pragma("unroll") for (int m = 0; m < 4; ++m) _Pragma("unroll") for (int k = 0; k < 2; ++k) dst[m][k] = *(const PG8_LAS bf16x8*)(lds + PG8_SA(b, h) + aoff + m * 2048 + k * 1024); } while (0)
; #define PG8_LDB(dst, b, h) do { _Pragma("unroll") for (int n = 0; n < 2; ++n) _Pragma("unroll") for (int k = 0; k < 2; ++k) dst[n][k] = *(const PG8_LAS bf16x8*)(lds + PG8_SB(b, h) + boff + n * 2048 + k * 1024); } while (0)
; #define PG8_MMA(ai, bj, At, Bt) do { __builtin_amdgcn_s_setprio(1); _Pragma("unroll") for (int m = 0; m < 4; ++m) _Pragma("unroll") for (int n = 0; n < 2; ++n) _Pragma("unroll") for (int k = 0; k < 2; ++k) \
;         acc[ai][bj][m][n] = __builtin_amdgcn_mfma_f32_16x16x32_bf16(Bt[n][k], At[m][k], acc[ai][bj][m][n], 0, 0, 0); __builtin_amdgcn_s_setprio(0); } while (0)
; #define PG8_WAIT_V(n) asm volatile("s_waitcnt vmcnt(" #n ")" ::: "memory")
; #define PG8_WAIT_L(n) asm volatile("s_waitcnt lgkmcnt(" #n ")" ::: "memory")
; #define PG8_BAR __builtin_amdgcn_s_barrier()
; #define PG8_SCHED __builtin_amdgcn_sched_barrier(0)
; template <class Epi, class Sched, bool STAMP = false>
; __device__ __forceinline__ void gemm_phase(PG8_LAS unsigned char* lds, const Gemm g, const Sched& S, const Epi& E, unsigned long long* stamps) {
;     ...
;             PG8_STAGE(PG8_SB(0, 1), b2 + hstep, voffB);
;             PG8_WAIT_V(6); PG8_BAR; PG8_MMA(1, 1, At, B1); PG8_BAR;
;             PG8_LDB(B0, 1, 0); PG8_SCHED; PG8_LDA(At, 1, 0); PG8_STAGE(PG8_SA(0, 1), a2 + hstep, voffA);
;             PG8_WAIT_L(8); PG8_BAR; PG8_WAIT_L(0); PG8_MMA(0, 0, At, B0); PG8_BAR; PG8_SCHED;
;             PG8_LDB(B1, 1, 1); PG8_STAGE(PG8_SB(1, 0), b3, voffB);
;             PG8_BAR; PG8_WAIT_L(0); PG8_MMA(0, 1, At, B1); PG8_BAR;
	s_add_u32 s14, s56, 0x40000
	s_addc_u32 s15, s57, 0
	s_add_i32 s16, s16, s64
	v_lshl_add_u64 v[156:157], s[14:15], 0, v[148:149]
	s_mov_b32 m0, s16
	s_nop 0
	global_load_lds_dwordx4 v[156:157], off
	v_lshl_add_u64 v[156:157], s[14:15], 0, v[150:151]
	s_add_i32 m0, s16, 0x2000
	s_nop 0
	global_load_lds_dwordx4 v[156:157], off
	s_waitcnt vmcnt(6)
	s_barrier
	v_mfma_f32_16x16x32_bf16 v[52:55], v[220:223], v[178:181], v[52:55]
	v_mfma_f32_16x16x32_bf16 v[48:51], v[228:231], v[178:181], v[48:51]
	v_mfma_f32_16x16x32_bf16 v[36:39], v[220:223], v[196:199], v[36:39]
	v_mfma_f32_16x16x32_bf16 v[32:35], v[228:231], v[196:199], v[32:35]
	v_mfma_f32_16x16x32_bf16 v[20:23], v[220:223], v[204:207], v[20:23]
	v_mfma_f32_16x16x32_bf16 v[16:19], v[228:231], v[204:207], v[16:19]
	v_mfma_f32_16x16x32_bf16 v[4:7], v[220:223], v[212:215], v[4:7]
	v_mfma_f32_16x16x32_bf16 v[0:3], v[228:231], v[212:215], v[0:3]
	v_mfma_f32_16x16x32_bf16 v[52:55], v[224:227], v[192:195], v[52:55]
	v_mfma_f32_16x16x32_bf16 v[48:51], v[232:235], v[192:195], v[48:51]
	v_mfma_f32_16x16x32_bf16 v[36:39], v[224:227], v[200:203], v[36:39]
	v_mfma_f32_16x16x32_bf16 v[32:35], v[232:235], v[200:203], v[32:35]
	v_mfma_f32_16x16x32_bf16 v[20:23], v[224:227], v[208:211], v[20:23]
	v_mfma_f32_16x16x32_bf16 v[16:19], v[232:235], v[208:211], v[16:19]
	v_mfma_f32_16x16x32_bf16 v[4:7], v[224:227], v[216:219], v[4:7]
	v_mfma_f32_16x16x32_bf16 v[0:3], v[232:235], v[216:219], v[0:3]
	s_add_i32 s16, 0, 0x18000
	v_add_u32_e32 v128, s16, v166
	s_barrier
	ds_read_b128 v[156:159], v128
	ds_read_b128 v[160:163], v128 offset:1024
	ds_read_b128 v[170:173], v128 offset:2048
	ds_read_b128 v[174:177], v128 offset:3072
	s_add_u32 s14, s58, 0x40000
	s_addc_u32 s15, s59, 0
	s_mov_b32 m0, s76
	v_lshl_add_u64 v[220:221], s[14:15], 0, v[148:149]
	ds_read_b128 v[178:181], v168 offset:32768
	ds_read_b128 v[192:195], v168 offset:33792
	ds_read_b128 v[196:199], v168 offset:34816
	ds_read_b128 v[200:203], v168 offset:35840
	ds_read_b128 v[204:207], v168 offset:36864
	ds_read_b128 v[208:211], v168 offset:37888
	ds_read_b128 v[212:215], v168 offset:38912
	ds_read_b128 v[216:219], v168 offset:39936
	global_load_lds_dwordx4 v[220:221], off
	v_lshl_add_u64 v[220:221], s[14:15], 0, v[150:151]
	s_mov_b32 m0, s77
	s_nop 0
	global_load_lds_dwordx4 v[220:221], off
	s_waitcnt lgkmcnt(8)
	s_barrier
	s_waitcnt lgkmcnt(0)
	s_waitcnt lgkmcnt(0)
	v_mfma_f32_16x16x32_bf16 v[124:127], v[156:159], v[178:181], v[124:127]
	v_mfma_f32_16x16x32_bf16 v[120:123], v[170:173], v[178:181], v[120:123]
	v_mfma_f32_16x16x32_bf16 v[108:111], v[156:159], v[196:199], v[108:111]
	v_mfma_f32_16x16x32_bf16 v[104:107], v[170:173], v[196:199], v[104:107]
	v_mfma_f32_16x16x32_bf16 v[92:95], v[156:159], v[204:207], v[92:95]
	v_mfma_f32_16x16x32_bf16 v[88:91], v[170:173], v[204:207], v[88:91]
	v_mfma_f32_16x16x32_bf16 v[76:79], v[156:159], v[212:215], v[76:79]
	v_mfma_f32_16x16x32_bf16 v[72:75], v[170:173], v[212:215], v[72:75]
	v_mfma_f32_16x16x32_bf16 v[124:127], v[160:163], v[192:195], v[124:127]
	v_mfma_f32_16x16x32_bf16 v[120:123], v[174:177], v[192:195], v[120:123]
	v_mfma_f32_16x16x32_bf16 v[108:111], v[160:163], v[200:203], v[108:111]
	v_mfma_f32_16x16x32_bf16 v[104:107], v[174:177], v[200:203], v[104:107]
	v_mfma_f32_16x16x32_bf16 v[92:95], v[160:163], v[208:211], v[92:95]
	v_mfma_f32_16x16x32_bf16 v[88:91], v[174:177], v[208:211], v[88:91]
	v_mfma_f32_16x16x32_bf16 v[76:79], v[160:163], v[216:219], v[76:79]
	v_mfma_f32_16x16x32_bf16 v[72:75], v[174:177], v[216:219], v[72:75]
	s_barrier
	s_add_i32 s17, 0, 0x1c000
	s_add_i32 s14, s16, s64
	v_add_u32_e32 v128, s17, v166
	v_lshl_add_u64 v[164:165], v[164:165], 0, s[18:19]
	s_mov_b32 m0, s14
	ds_read_b128 v[220:223], v128
	ds_read_b128 v[224:227], v128 offset:1024
	ds_read_b128 v[228:231], v128 offset:2048
	ds_read_b128 v[232:235], v128 offset:3072
	global_load_lds_dwordx4 v[164:165], off
	v_lshl_add_u64 v[164:165], v[182:183], 0, s[18:19]
	s_add_i32 m0, s14, 0x2000
	s_nop 0
	global_load_lds_dwordx4 v[164:165], off
	s_barrier
	s_waitcnt lgkmcnt(0)
	s_waitcnt lgkmcnt(0)
	v_mfma_f32_16x16x32_bf16 v[116:119], v[220:223], v[178:181], v[116:119]
	v_mfma_f32_16x16x32_bf16 v[112:115], v[228:231], v[178:181], v[112:115]
	v_mfma_f32_16x16x32_bf16 v[100:103], v[220:223], v[196:199], v[100:103]
	v_mfma_f32_16x16x32_bf16 v[96:99], v[228:231], v[196:199], v[96:99]
	v_mfma_f32_16x16x32_bf16 v[84:87], v[220:223], v[204:207], v[84:87]
	v_mfma_f32_16x16x32_bf16 v[80:83], v[228:231], v[204:207], v[80:83]
	v_mfma_f32_16x16x32_bf16 v[68:71], v[220:223], v[212:215], v[68:71]
	v_mfma_f32_16x16x32_bf16 v[64:67], v[228:231], v[212:215], v[64:67]
	v_mfma_f32_16x16x32_bf16 v[116:119], v[224:227], v[192:195], v[116:119]
	v_mfma_f32_16x16x32_bf16 v[112:115], v[232:235], v[192:195], v[112:115]
	v_mfma_f32_16x16x32_bf16 v[100:103], v[224:227], v[200:203], v[100:103]
	v_mfma_f32_16x16x32_bf16 v[96:99], v[232:235], v[200:203], v[96:99]
	v_mfma_f32_16x16x32_bf16 v[84:87], v[224:227], v[208:211], v[84:87]
	v_mfma_f32_16x16x32_bf16 v[80:83], v[232:235], v[208:211], v[80:83]
	v_mfma_f32_16x16x32_bf16 v[68:71], v[224:227], v[216:219], v[68:71]
	v_mfma_f32_16x16x32_bf16 v[64:67], v[232:235], v[216:219], v[64:67]
	s_mov_b32 m0, s88
	v_lshl_add_u64 v[164:165], v[236:237], 0, s[18:19]
	s_barrier
; #define PG8_STAGE(bufoff, gbase, voff) do { _Pragma("unroll") for (int _i = 0; _i < 2; ++_i) \
;         __builtin_amdgcn_global_load_lds((const unsigned*)((const char*)(gbase) + (voff)[_i]), (PG8_LAS unsigned*)(lds + (bufoff) + ldsw + _i * 8192), 16, 0, 0); } while (0)
; #define PG8_LDA(dst, b, h) do { _Pragma("unroll") for (int m = 0; m < 4; ++m) _Pragma("unroll") for (int k = 0; k < 2; ++k) dst[m][k] = *(const PG8_LAS bf16x8*)(lds + PG8_SA(b, h) + aoff + m * 2048 + k * 1024); } while (0)
; #define PG8_MMA(ai, bj, At, Bt) do { __builtin_amdgcn_s_setprio(1); _Pragma("unroll") for (int m = 0; m < 4; ++m) _Pragma("unroll") for (int n = 0; n < 2; ++n) _Pragma("unroll") for (int k = 0; k < 2; ++k) \
;         acc[ai][bj][m][n] = __builtin_amdgcn_mfma_f32_16x16x32_bf16(Bt[n][k], At[m][k], acc[ai][bj][m][n], 0, 0, 0); __builtin_amdgcn_s_setprio(0); } while (0)
; #define PG8_WAIT_V(n) asm volatile("s_waitcnt vmcnt(" #n ")" ::: "memory")
; #define PG8_WAIT_L(n) asm volatile("s_waitcnt lgkmcnt(" #n ")" ::: "memory")
; #define PG8_BAR __builtin_amdgcn_s_barrier()
; #define PG8_SCHED __builtin_amdgcn_sched_barrier(0)
; template <class Epi, class Sched, bool STAMP = false>
; __device__ __forceinline__ void gemm_phase(PG8_LAS unsigned char* lds, const Gemm g, const Sched& S, const Epi& E, unsigned long long* stamps) {
;     ...
;             PG8_LDA(At, 1, 1); PG8_STAGE(PG8_SA(1, 0), a3, voffA);
;             PG8_BAR; PG8_WAIT_L(0); PG8_MMA(1, 0, At, B0); PG8_BAR; PG8_SCHED;
;             PG8_STAGE(PG8_SB(1, 1), b3 + hstep, voffB);
;             PG8_WAIT_V(6); PG8_BAR; PG8_MMA(1, 1, At, B1); PG8_BAR;
;         }
;     __device__ __forceinline__ void operator()(const f32x4 (&acc)[2][2][4][2], const pg8::Unit& u, int wr, int wc, int fr, int fq) const {
;         const int row0 = u.pm * 256 + wr * 64 + fr, col0 = u.pn * 256 + wc * 32 + 4 * fq;
; #pragma unroll
;         for (int ai = 0; ai < 2; ++ai)
; #pragma unroll
;             for (int m = 0; m < 4; ++m) {
;                 const int row = row0 + ai * 128 + m * 16;
;                 float* xp = X + (size_t)row * 1024 + col0; bf16_t* bp = XB + (size_t)row * 1024 + col0;
;                 const float* xi = Xp0 ? (row < T_P ? Xp0 + (size_t)row * 1024 + col0 : Xs0 + (size_t)(row - T_P) * 1024 + col0) : xp;
	ds_read_b128 v[178:181], v168 offset:49152
	ds_read_b128 v[192:195], v168 offset:50176
	ds_read_b128 v[196:199], v168 offset:51200
	ds_read_b128 v[200:203], v168 offset:52224
	ds_read_b128 v[204:207], v168 offset:53248
	ds_read_b128 v[208:211], v168 offset:54272
	ds_read_b128 v[212:215], v168 offset:55296
	ds_read_b128 v[216:219], v168 offset:56320
	global_load_lds_dwordx4 v[164:165], off
	v_lshl_add_u64 v[164:165], v[238:239], 0, s[18:19]
	s_mov_b32 m0, s89
	s_nop 0
	global_load_lds_dwordx4 v[164:165], off
	s_barrier
	s_waitcnt lgkmcnt(0)
	s_waitcnt lgkmcnt(0)
	v_mfma_f32_16x16x32_bf16 v[60:63], v[156:159], v[178:181], v[60:63]
	v_mfma_f32_16x16x32_bf16 v[56:59], v[170:173], v[178:181], v[56:59]
	v_mfma_f32_16x16x32_bf16 v[44:47], v[156:159], v[196:199], v[44:47]
	v_mfma_f32_16x16x32_bf16 v[40:43], v[170:173], v[196:199], v[40:43]
	v_mfma_f32_16x16x32_bf16 v[28:31], v[156:159], v[204:207], v[28:31]
	v_mfma_f32_16x16x32_bf16 v[24:27], v[170:173], v[204:207], v[24:27]
	v_mfma_f32_16x16x32_bf16 v[12:15], v[156:159], v[212:215], v[12:15]
	v_mfma_f32_16x16x32_bf16 v[8:11], v[170:173], v[212:215], v[8:11]
	v_mfma_f32_16x16x32_bf16 v[60:63], v[160:163], v[192:195], v[60:63]
	v_mfma_f32_16x16x32_bf16 v[56:59], v[174:177], v[192:195], v[56:59]
	v_mfma_f32_16x16x32_bf16 v[44:47], v[160:163], v[200:203], v[44:47]
	v_mfma_f32_16x16x32_bf16 v[40:43], v[174:177], v[200:203], v[40:43]
	v_mfma_f32_16x16x32_bf16 v[28:31], v[160:163], v[208:211], v[28:31]
	v_mfma_f32_16x16x32_bf16 v[24:27], v[174:177], v[208:211], v[24:27]
	v_mfma_f32_16x16x32_bf16 v[12:15], v[160:163], v[216:219], v[12:15]
	v_mfma_f32_16x16x32_bf16 v[8:11], v[174:177], v[216:219], v[8:11]
	s_barrier
	s_add_u32 s14, s56, 0x40080
	s_addc_u32 s15, s57, 0
	s_add_i32 s16, s17, s64
	v_lshl_add_u64 v[156:157], s[14:15], 0, v[148:149]
	s_mov_b32 m0, s16
	s_nop 0
	global_load_lds_dwordx4 v[156:157], off
	v_lshl_add_u64 v[156:157], s[14:15], 0, v[150:151]
	s_add_i32 m0, s16, 0x2000
	s_nop 0
	global_load_lds_dwordx4 v[156:157], off
	s_waitcnt vmcnt(6)
	s_barrier
	v_mfma_f32_16x16x32_bf16 v[52:55], v[220:223], v[178:181], v[52:55]
	v_mfma_f32_16x16x32_bf16 v[48:51], v[228:231], v[178:181], v[48:51]
	v_mfma_f32_16x16x32_bf16 v[36:39], v[220:223], v[196:199], v[36:39]
	v_mfma_f32_16x16x32_bf16 v[32:35], v[228:231], v[196:199], v[32:35]
	v_mfma_f32_16x16x32_bf16 v[20:23], v[220:223], v[204:207], v[20:23]
	v_mfma_f32_16x16x32_bf16 v[16:19], v[228:231], v[204:207], v[16:19]
	v_mfma_f32_16x16x32_bf16 v[4:7], v[220:223], v[212:215], v[4:7]
	v_mfma_f32_16x16x32_bf16 v[0:3], v[228:231], v[212:215], v[0:3]
	v_mfma_f32_16x16x32_bf16 v[52:55], v[224:227], v[192:195], v[52:55]
	v_mfma_f32_16x16x32_bf16 v[48:51], v[232:235], v[192:195], v[48:51]
	v_mfma_f32_16x16x32_bf16 v[36:39], v[224:227], v[200:203], v[36:39]
	v_mfma_f32_16x16x32_bf16 v[32:35], v[232:235], v[200:203], v[32:35]
	v_mfma_f32_16x16x32_bf16 v[20:23], v[224:227], v[208:211], v[20:23]
	v_mfma_f32_16x16x32_bf16 v[16:19], v[232:235], v[208:211], v[16:19]
	v_mfma_f32_16x16x32_bf16 v[4:7], v[224:227], v[216:219], v[4:7]
	v_mfma_f32_16x16x32_bf16 v[0:3], v[232:235], v[216:219], v[0:3]
	s_add_i32 s39, s39, 2
	s_add_u32 vcc_hi, vcc_hi, 0x100
	s_addc_u32 s38, s38, 0
	s_cmp_gt_u32 s39, 13
	s_mov_b64 s[44:45], s[48:49]
	s_barrier
	s_cbranch_scc0 .LBB0_141
	v_lshl_add_u32 v158, s30, 8, v139
	v_ashrrev_i32_e32 v159, 31, v158
	v_lshl_or_b32 v156, s36, 8, v167
	v_lshlrev_b64 v[160:161], 12, v[158:159]
	v_ashrrev_i32_e32 v157, 31, v156
	v_lshl_add_u64 v[160:161], s[84:85], 0, v[160:161]
	v_lshl_add_u64 v[160:161], v[156:157], 2, v[160:161]
	v_cndmask_b32_e64 v128, 0, 1, s[12:13]
	v_lshlrev_b64 v[164:165], 10, v[158:159]
	v_cmp_ne_u32_e64 s[44:45], 1, v128
	s_andn2_b64 vcc, exec, s[12:13]
	v_mov_b64_e32 v[162:163], v[160:161]
	v_readlane_b32 s39, v242, 28
	s_movk_i32 s21, 0x3fff
	s_mov_b32 s38, 0x1ffff
	s_cbranch_vccnz .LBB0_148
	v_cmp_lt_i32_e32 vcc, s21, v158
	s_and_saveexec_b64 s[14:15], vcc
	s_xor_b64 s[30:31], exec, s[14:15]
	v_add_u32_e32 v128, 0xffffc000, v158
	v_lshlrev_b64 v[162:163], 12, v[128:129]
	v_lshl_add_u64 v[162:163], s[4:5], 0, v[162:163]
	v_lshl_add_u64 v[162:163], v[156:157], 2, v[162:163]
	s_andn2_saveexec_b64 s[30:31], s[30:31]
	v_lshl_add_u64 v[162:163], v[164:165], 2, s[0:1]
	v_lshl_add_u64 v[162:163], v[156:157], 2, v[162:163]
	s_or_b64 exec, exec, s[30:31]

; #define PG8_STAGE(bufoff, gbase, voff) do { _Pragma("unroll") for (int _i = 0; _i < 2; ++_i) \
;         __builtin_amdgcn_global_load_lds((const unsigned*)((const char*)(gbase) + (voff)[_i]), (PG8_LAS unsigned*)(lds + (bufoff) + ldsw + _i * 8192), 16, 0, 0); } while (0)
; #define PG8_LDA(dst, b, h) do { _Pragma("unroll") for (int m = 0; m < 4; ++m) _Pragma("unroll") for (int k = 0; k < 2; ++k) dst[m][k] = *(const PG8_LAS bf16x8*)(lds + PG8_SA(b, h) + aoff + m * 2048 + k * 1024); } while (0)
; #define PG8_LDB(dst, b, h) do { _Pragma("unroll") for (int n = 0; n < 2; ++n) _Pragma("unroll") for (int k = 0; k < 2; ++k) dst[n][k] = *(const PG8_LAS bf16x8*)(lds + PG8_SB(b, h) + boff + n * 2048 + k * 1024); } while (0)
; #define PG8_MMA(ai, bj, At, Bt) do { __builtin_amdgcn_s_setprio(1); _Pragma("unroll") for (int m = 0; m < 4; ++m) _Pragma("unroll") for (int n = 0; n < 2; ++n) _Pragma("unroll") for (int k = 0; k < 2; ++k) \
;         acc[ai][bj][m][n] = __builtin_amdgcn_mfma_f32_16x16x32_bf16(Bt[n][k], At[m][k], acc[ai][bj][m][n], 0, 0, 0); __builtin_amdgcn_s_setprio(0); } while (0)
; #define PG8_WAIT_L(n) asm volatile("s_waitcnt lgkmcnt(" #n ")" ::: "memory")
; #define PG8_BAR __builtin_amdgcn_s_barrier()
; #define PG8_SCHED __builtin_amdgcn_sched_barrier(0)
; template <class Epi, class Sched, bool STAMP = false>
; __device__ __forceinline__ void gemm_phase(PG8_LAS unsigned char* lds, const Gemm g, const Sched& S, const Epi& E, unsigned long long* stamps) {
;     ...
;         for (int t = 0; t < nt; t += 2) {
;             const bool last = (t == nt - 2);
;             const char* a1 = cA + (size_t)(t + 1) * kstep;
;             const char* a2 = last ? nA : cA + (size_t)(t + 2) * kstep; const char* b2 = last ? nB : cB + (size_t)(t + 2) * kstep;
;             const char* a3 = a2 + kstep; const char* b3 = b2 + kstep;
;             if (last && has_next) S.a_ready(nxt);
;             PG8_LDB(B0, 0, 0); PG8_SCHED; PG8_LDA(At, 0, 0); PG8_STAGE(PG8_SA(1, 1), a1 + hstep, voffA);
;             PG8_WAIT_L(8); PG8_BAR; PG8_WAIT_L(0); PG8_MMA(0, 0, At, B0); PG8_BAR; PG8_SCHED;
;             PG8_LDB(B1, 0, 1); PG8_STAGE(PG8_SB(0, 0), b2, voffB);
;             PG8_BAR; PG8_WAIT_L(0); PG8_MMA(0, 1, At, B1); PG8_BAR;
;             PG8_LDA(At, 0, 1); PG8_STAGE(PG8_SA(0, 0), a2, voffA);
;             PG8_BAR; PG8_WAIT_L(0); PG8_MMA(1, 0, At, B0); PG8_BAR; PG8_SCHED;
.LBB0_213:
	s_add_i32 s15, s14, 0x100
	s_and_b64 s[16:17], s[20:21], exec
	s_cselect_b32 s15, 0, s15
	s_cselect_b32 s16, 0, 0
	s_add_u32 s26, s4, s15
	s_addc_u32 s27, s5, s16
	s_add_i32 s21, 0, 0x10000
	s_add_u32 s30, s0, s15
	s_addc_u32 s31, s1, s16
	s_add_u32 s36, s6, s14
	s_addc_u32 s37, s7, 0
	s_add_i32 s61, s21, s44
	s_add_i32 m0, s45, 0xc000
	s_add_i32 s62, s45, 0xe000
	s_add_i32 s60, 0, 0x14000
	s_add_i32 s59, s61, 0x2000
	s_add_u32 s24, s30, 0x40000
	v_add_u32_e32 v153, s21, v151
	s_addc_u32 s25, s31, 0
	s_add_i32 s38, s60, s44
	ds_read_b128 v[154:157], v153
	ds_read_b128 v[158:161], v153 offset:1024
	ds_read_b128 v[162:165], v153 offset:2048
	ds_read_b128 v[166:169], v153 offset:3072
	s_add_i32 s29, s38, 0x2000
	s_add_i32 s17, 0, 0x18000
	s_add_u32 s22, s26, 0x40000
	s_addc_u32 s23, s27, 0
	s_add_i32 s16, s17, s44
	s_add_i32 s15, 0, 0x1c000
	s_add_i32 s14, s16, 0x2000
	s_add_u32 s20, s30, 0x40080
	s_addc_u32 s21, s31, 0
	s_add_i32 s52, s15, s44
	s_add_i32 s39, s52, 0x2000
	v_lshl_add_u64 v[182:183], s[36:37], 0, v[128:129]
	v_lshl_add_u64 v[182:183], v[182:183], 0, s[18:19]
	ds_read_b128 v[170:173], v152
	ds_read_b128 v[174:177], v152 offset:1024
	ds_read_b128 v[178:181], v152 offset:2048
	ds_read_b128 v[192:195], v152 offset:3072
	ds_read_b128 v[196:199], v152 offset:4096
	ds_read_b128 v[200:203], v152 offset:5120
	ds_read_b128 v[204:207], v152 offset:6144
	ds_read_b128 v[208:211], v152 offset:7168
	global_load_lds_dwordx4 v[182:183], off
	v_lshl_add_u64 v[182:183], s[36:37], 0, v[148:149]
	v_lshl_add_u64 v[182:183], v[182:183], 0, s[18:19]
	s_mov_b32 m0, s62
	s_nop 0
	global_load_lds_dwordx4 v[182:183], off
	s_waitcnt lgkmcnt(8)
	s_barrier
	s_waitcnt lgkmcnt(0)
	s_waitcnt lgkmcnt(0)
	v_mfma_f32_16x16x32_bf16 v[124:127], v[154:157], v[170:173], v[124:127]
	v_mfma_f32_16x16x32_bf16 v[120:123], v[162:165], v[170:173], v[120:123]
	v_mfma_f32_16x16x32_bf16 v[116:119], v[154:157], v[178:181], v[116:119]
	v_mfma_f32_16x16x32_bf16 v[112:115], v[162:165], v[178:181], v[112:115]
	v_mfma_f32_16x16x32_bf16 v[104:107], v[154:157], v[196:199], v[104:107]
	v_mfma_f32_16x16x32_bf16 v[96:99], v[162:165], v[196:199], v[96:99]
	v_mfma_f32_16x16x32_bf16 v[88:91], v[154:157], v[204:207], v[88:91]
	v_mfma_f32_16x16x32_bf16 v[80:83], v[162:165], v[204:207], v[80:83]
	v_mfma_f32_16x16x32_bf16 v[124:127], v[158:161], v[174:177], v[124:127]
	v_mfma_f32_16x16x32_bf16 v[120:123], v[166:169], v[174:177], v[120:123]
	v_mfma_f32_16x16x32_bf16 v[116:119], v[158:161], v[192:195], v[116:119]
	v_mfma_f32_16x16x32_bf16 v[112:115], v[166:169], v[192:195], v[112:115]
	v_mfma_f32_16x16x32_bf16 v[104:107], v[158:161], v[200:203], v[104:107]
	v_mfma_f32_16x16x32_bf16 v[96:99], v[166:169], v[200:203], v[96:99]
	v_mfma_f32_16x16x32_bf16 v[88:91], v[158:161], v[208:211], v[88:91]
	v_mfma_f32_16x16x32_bf16 v[80:83], v[166:169], v[208:211], v[80:83]
	s_barrier
	s_mov_b32 m0, s61
	v_add_u32_e32 v153, s60, v151
	v_lshl_add_u64 v[182:183], s[30:31], 0, v[128:129]
	ds_read_b128 v[212:215], v153
	ds_read_b128 v[216:219], v153 offset:1024
	ds_read_b128 v[220:223], v153 offset:2048
	ds_read_b128 v[224:227], v153 offset:3072
	global_load_lds_dwordx4 v[182:183], off
	v_lshl_add_u64 v[228:229], s[30:31], 0, v[148:149]
	s_mov_b32 m0, s59
	s_nop 0
	global_load_lds_dwordx4 v[228:229], off
	s_barrier
	s_waitcnt lgkmcnt(0)
	s_waitcnt lgkmcnt(0)
	v_mfma_f32_16x16x32_bf16 v[108:111], v[212:215], v[170:173], v[108:111]
	v_mfma_f32_16x16x32_bf16 v[100:103], v[220:223], v[170:173], v[100:103]
	v_mfma_f32_16x16x32_bf16 v[92:95], v[212:215], v[178:181], v[92:95]
	v_mfma_f32_16x16x32_bf16 v[84:87], v[220:223], v[178:181], v[84:87]
	v_mfma_f32_16x16x32_bf16 v[76:79], v[212:215], v[196:199], v[76:79]
	v_mfma_f32_16x16x32_bf16 v[72:75], v[220:223], v[196:199], v[72:75]
	v_mfma_f32_16x16x32_bf16 v[68:71], v[212:215], v[204:207], v[68:71]
	v_mfma_f32_16x16x32_bf16 v[64:67], v[220:223], v[204:207], v[64:67]
	v_mfma_f32_16x16x32_bf16 v[108:111], v[216:219], v[174:177], v[108:111]
	v_mfma_f32_16x16x32_bf16 v[100:103], v[224:227], v[174:177], v[100:103]
	v_mfma_f32_16x16x32_bf16 v[92:95], v[216:219], v[192:195], v[92:95]
	v_mfma_f32_16x16x32_bf16 v[84:87], v[224:227], v[192:195], v[84:87]
	v_mfma_f32_16x16x32_bf16 v[76:79], v[216:219], v[200:203], v[76:79]
	v_mfma_f32_16x16x32_bf16 v[72:75], v[224:227], v[200:203], v[72:75]
	v_mfma_f32_16x16x32_bf16 v[68:71], v[216:219], v[208:211], v[68:71]
	v_mfma_f32_16x16x32_bf16 v[64:67], v[224:227], v[208:211], v[64:67]
	s_mov_b32 m0, s45
	v_lshl_add_u64 v[230:231], s[26:27], 0, v[128:129]
	s_barrier
	ds_read_b128 v[170:173], v152 offset:16384
	ds_read_b128 v[174:177], v152 offset:17408
	ds_read_b128 v[178:181], v152 offset:18432
	ds_read_b128 v[192:195], v152 offset:19456
	ds_read_b128 v[196:199], v152 offset:20480
	ds_read_b128 v[200:203], v152 offset:21504
	ds_read_b128 v[204:207], v152 offset:22528
	ds_read_b128 v[208:211], v152 offset:23552
	global_load_lds_dwordx4 v[230:231], off
	v_lshl_add_u64 v[232:233], s[26:27], 0, v[148:149]
	s_mov_b32 m0, s47
	s_nop 0
	global_load_lds_dwordx4 v[232:233], off
	s_barrier
; #define PG8_STAGE(bufoff, gbase, voff) do { _Pragma("unroll") for (int _i = 0; _i < 2; ++_i) \
;         __builtin_amdgcn_global_load_lds((const unsigned*)((const char*)(gbase) + (voff)[_i]), (PG8_LAS unsigned*)(lds + (bufoff) + ldsw + _i * 8192), 16, 0, 0); } while (0)
; #define PG8_LDA(dst, b, h) do { _Pragma("unroll") for (int m = 0; m < 4; ++m) _Pragma("unroll") for (int k = 0; k < 2; ++k) dst[m][k] = *(const PG8_LAS bf16x8*)(lds + PG8_SA(b, h) + aoff + m * 2048 + k * 1024); } while (0)
; #define PG8_LDB(dst, b, h) do { _Pragma("unroll") for (int n = 0; n < 2; ++n) _Pragma("unroll") for (int k = 0; k < 2; ++k) dst[n][k] = *(const PG8_LAS bf16x8*)(lds + PG8_SB(b, h) + boff + n * 2048 + k * 1024); } while (0)
; #define PG8_MMA(ai, bj, At, Bt) do { __builtin_amdgcn_s_setprio(1); _Pragma("unroll") for (int m = 0; m < 4; ++m) _Pragma("unroll") for (int n = 0; n < 2; ++n) _Pragma("unroll") for (int k = 0; k < 2; ++k) \
;         acc[ai][bj][m][n] = __builtin_amdgcn_mfma_f32_16x16x32_bf16(Bt[n][k], At[m][k], acc[ai][bj][m][n], 0, 0, 0); __builtin_amdgcn_s_setprio(0); } while (0)
; #define PG8_WAIT_V(n) asm volatile("s_waitcnt vmcnt(" #n ")" ::: "memory")
; #define PG8_WAIT_L(n) asm volatile("s_waitcnt lgkmcnt(" #n ")" ::: "memory")
; #define PG8_BAR __builtin_amdgcn_s_barrier()
; #define PG8_SCHED __builtin_amdgcn_sched_barrier(0)
; template <class Epi, class Sched, bool STAMP = false>
; __device__ __forceinline__ void gemm_phase(PG8_LAS unsigned char* lds, const Gemm g, const Sched& S, const Epi& E, unsigned long long* stamps) {
;     ...
;             PG8_BAR; PG8_WAIT_L(0); PG8_MMA(1, 0, At, B0); PG8_BAR; PG8_SCHED;
;             PG8_STAGE(PG8_SB(0, 1), b2 + hstep, voffB);
;             PG8_WAIT_V(6); PG8_BAR; PG8_MMA(1, 1, At, B1); PG8_BAR;
;             PG8_LDB(B0, 1, 0); PG8_SCHED; PG8_LDA(At, 1, 0); PG8_STAGE(PG8_SA(0, 1), a2 + hstep, voffA);
;             PG8_WAIT_L(8); PG8_BAR; PG8_WAIT_L(0); PG8_MMA(0, 0, At, B0); PG8_BAR; PG8_SCHED;
;             PG8_LDB(B1, 1, 1); PG8_STAGE(PG8_SB(1, 0), b3, voffB);
;             PG8_BAR; PG8_WAIT_L(0); PG8_MMA(0, 1, At, B1); PG8_BAR;
;             PG8_LDA(At, 1, 1); PG8_STAGE(PG8_SA(1, 0), a3, voffA);
;             PG8_BAR; PG8_WAIT_L(0); PG8_MMA(1, 0, At, B0); PG8_BAR; PG8_SCHED;
	s_waitcnt lgkmcnt(0)
	s_waitcnt lgkmcnt(0)
	v_mfma_f32_16x16x32_bf16 v[60:63], v[154:157], v[170:173], v[60:63]
	v_mfma_f32_16x16x32_bf16 v[56:59], v[162:165], v[170:173], v[56:59]
	v_mfma_f32_16x16x32_bf16 v[52:55], v[154:157], v[178:181], v[52:55]
	v_mfma_f32_16x16x32_bf16 v[48:51], v[162:165], v[178:181], v[48:51]
	v_mfma_f32_16x16x32_bf16 v[36:39], v[154:157], v[196:199], v[36:39]
	v_mfma_f32_16x16x32_bf16 v[32:35], v[162:165], v[196:199], v[32:35]
	v_mfma_f32_16x16x32_bf16 v[20:23], v[154:157], v[204:207], v[20:23]
	v_mfma_f32_16x16x32_bf16 v[16:19], v[162:165], v[204:207], v[16:19]
	v_mfma_f32_16x16x32_bf16 v[60:63], v[158:161], v[174:177], v[60:63]
	v_mfma_f32_16x16x32_bf16 v[56:59], v[166:169], v[174:177], v[56:59]
	v_mfma_f32_16x16x32_bf16 v[52:55], v[158:161], v[192:195], v[52:55]
	v_mfma_f32_16x16x32_bf16 v[48:51], v[166:169], v[192:195], v[48:51]
	v_mfma_f32_16x16x32_bf16 v[36:39], v[158:161], v[200:203], v[36:39]
	v_mfma_f32_16x16x32_bf16 v[32:35], v[166:169], v[200:203], v[32:35]
	v_mfma_f32_16x16x32_bf16 v[20:23], v[158:161], v[208:211], v[20:23]
	v_mfma_f32_16x16x32_bf16 v[16:19], v[166:169], v[208:211], v[16:19]
	s_barrier
	s_mov_b32 m0, s38
	v_lshl_add_u64 v[154:155], s[24:25], 0, v[128:129]
	global_load_lds_dwordx4 v[154:155], off
	v_lshl_add_u64 v[154:155], s[24:25], 0, v[148:149]
	s_mov_b32 m0, s29
	s_nop 0
	global_load_lds_dwordx4 v[154:155], off
	s_waitcnt vmcnt(6)
	s_barrier
	v_mfma_f32_16x16x32_bf16 v[44:47], v[212:215], v[170:173], v[44:47]
	v_mfma_f32_16x16x32_bf16 v[40:43], v[220:223], v[170:173], v[40:43]
	v_mfma_f32_16x16x32_bf16 v[28:31], v[212:215], v[178:181], v[28:31]
	v_mfma_f32_16x16x32_bf16 v[24:27], v[220:223], v[178:181], v[24:27]
	v_mfma_f32_16x16x32_bf16 v[12:15], v[212:215], v[196:199], v[12:15]
	v_mfma_f32_16x16x32_bf16 v[8:11], v[220:223], v[196:199], v[8:11]
	v_mfma_f32_16x16x32_bf16 v[4:7], v[212:215], v[204:207], v[4:7]
	v_mfma_f32_16x16x32_bf16 v[0:3], v[220:223], v[204:207], v[0:3]
	v_mfma_f32_16x16x32_bf16 v[44:47], v[216:219], v[174:177], v[44:47]
	v_mfma_f32_16x16x32_bf16 v[40:43], v[224:227], v[174:177], v[40:43]
	v_mfma_f32_16x16x32_bf16 v[28:31], v[216:219], v[192:195], v[28:31]
	v_mfma_f32_16x16x32_bf16 v[24:27], v[224:227], v[192:195], v[24:27]
	v_mfma_f32_16x16x32_bf16 v[12:15], v[216:219], v[200:203], v[12:15]
	v_mfma_f32_16x16x32_bf16 v[8:11], v[224:227], v[200:203], v[8:11]
	v_mfma_f32_16x16x32_bf16 v[4:7], v[216:219], v[208:211], v[4:7]
	v_mfma_f32_16x16x32_bf16 v[0:3], v[224:227], v[208:211], v[0:3]
	v_add_u32_e32 v153, s17, v151
	s_barrier
	ds_read_b128 v[154:157], v153
	ds_read_b128 v[158:161], v153 offset:1024
	ds_read_b128 v[162:165], v153 offset:2048
	ds_read_b128 v[166:169], v153 offset:3072
	s_mov_b32 m0, s48
	v_lshl_add_u64 v[212:213], s[22:23], 0, v[128:129]
	ds_read_b128 v[170:173], v152 offset:32768
	ds_read_b128 v[174:177], v152 offset:33792
	ds_read_b128 v[178:181], v152 offset:34816
	ds_read_b128 v[192:195], v152 offset:35840
	ds_read_b128 v[196:199], v152 offset:36864
	ds_read_b128 v[200:203], v152 offset:37888
	ds_read_b128 v[204:207], v152 offset:38912
	ds_read_b128 v[208:211], v152 offset:39936
	global_load_lds_dwordx4 v[212:213], off
	v_lshl_add_u64 v[212:213], s[22:23], 0, v[148:149]
	s_mov_b32 m0, s49
	s_nop 0
	global_load_lds_dwordx4 v[212:213], off
	s_waitcnt lgkmcnt(8)
	s_barrier
	s_waitcnt lgkmcnt(0)
	s_waitcnt lgkmcnt(0)
	v_mfma_f32_16x16x32_bf16 v[124:127], v[154:157], v[170:173], v[124:127]
	v_mfma_f32_16x16x32_bf16 v[120:123], v[162:165], v[170:173], v[120:123]
	v_mfma_f32_16x16x32_bf16 v[116:119], v[154:157], v[178:181], v[116:119]
	v_mfma_f32_16x16x32_bf16 v[112:115], v[162:165], v[178:181], v[112:115]
	v_mfma_f32_16x16x32_bf16 v[104:107], v[154:157], v[196:199], v[104:107]
	v_mfma_f32_16x16x32_bf16 v[96:99], v[162:165], v[196:199], v[96:99]
	v_mfma_f32_16x16x32_bf16 v[88:91], v[154:157], v[204:207], v[88:91]
	v_mfma_f32_16x16x32_bf16 v[80:83], v[162:165], v[204:207], v[80:83]
	v_mfma_f32_16x16x32_bf16 v[124:127], v[158:161], v[174:177], v[124:127]
	v_mfma_f32_16x16x32_bf16 v[120:123], v[166:169], v[174:177], v[120:123]
	v_mfma_f32_16x16x32_bf16 v[116:119], v[158:161], v[192:195], v[116:119]
	v_mfma_f32_16x16x32_bf16 v[112:115], v[166:169], v[192:195], v[112:115]
	v_mfma_f32_16x16x32_bf16 v[104:107], v[158:161], v[200:203], v[104:107]
	v_mfma_f32_16x16x32_bf16 v[96:99], v[166:169], v[200:203], v[96:99]
	v_mfma_f32_16x16x32_bf16 v[88:91], v[158:161], v[208:211], v[88:91]
	v_mfma_f32_16x16x32_bf16 v[80:83], v[166:169], v[208:211], v[80:83]
	s_barrier
	s_mov_b32 m0, s16
	v_add_u32_e32 v153, s15, v151
	v_lshl_add_u64 v[182:183], v[182:183], 0, s[18:19]
	ds_read_b128 v[212:215], v153
	ds_read_b128 v[216:219], v153 offset:1024
	ds_read_b128 v[220:223], v153 offset:2048
	ds_read_b128 v[224:227], v153 offset:3072
	global_load_lds_dwordx4 v[182:183], off
	v_lshl_add_u64 v[182:183], v[228:229], 0, s[18:19]
	s_mov_b32 m0, s14
	s_nop 0
	global_load_lds_dwordx4 v[182:183], off
	s_barrier
	s_waitcnt lgkmcnt(0)
	s_waitcnt lgkmcnt(0)
	v_mfma_f32_16x16x32_bf16 v[108:111], v[212:215], v[170:173], v[108:111]
	v_mfma_f32_16x16x32_bf16 v[100:103], v[220:223], v[170:173], v[100:103]
	v_mfma_f32_16x16x32_bf16 v[92:95], v[212:215], v[178:181], v[92:95]
	v_mfma_f32_16x16x32_bf16 v[84:87], v[220:223], v[178:181], v[84:87]
	v_mfma_f32_16x16x32_bf16 v[76:79], v[212:215], v[196:199], v[76:79]
	v_mfma_f32_16x16x32_bf16 v[72:75], v[220:223], v[196:199], v[72:75]
	v_mfma_f32_16x16x32_bf16 v[68:71], v[212:215], v[204:207], v[68:71]
	v_mfma_f32_16x16x32_bf16 v[64:67], v[220:223], v[204:207], v[64:67]
	v_mfma_f32_16x16x32_bf16 v[108:111], v[216:219], v[174:177], v[108:111]
	v_mfma_f32_16x16x32_bf16 v[100:103], v[224:227], v[174:177], v[100:103]
	v_mfma_f32_16x16x32_bf16 v[92:95], v[216:219], v[192:195], v[92:95]
	v_mfma_f32_16x16x32_bf16 v[84:87], v[224:227], v[192:195], v[84:87]
	v_mfma_f32_16x16x32_bf16 v[76:79], v[216:219], v[200:203], v[76:79]
	v_mfma_f32_16x16x32_bf16 v[72:75], v[224:227], v[200:203], v[72:75]
	v_mfma_f32_16x16x32_bf16 v[68:71], v[216:219], v[208:211], v[68:71]
	v_mfma_f32_16x16x32_bf16 v[64:67], v[224:227], v[208:211], v[64:67]
	s_mov_b32 m0, s57
	v_lshl_add_u64 v[182:183], v[230:231], 0, s[18:19]
	s_barrier
; #define PG8_STAGE(bufoff, gbase, voff) do { _Pragma("unroll") for (int _i = 0; _i < 2; ++_i) \
;         __builtin_amdgcn_global_load_lds((const unsigned*)((const char*)(gbase) + (voff)[_i]), (PG8_LAS unsigned*)(lds + (bufoff) + ldsw + _i * 8192), 16, 0, 0); } while (0)
; #define PG8_MMA(ai, bj, At, Bt) do { __builtin_amdgcn_s_setprio(1); _Pragma("unroll") for (int m = 0; m < 4; ++m) _Pragma("unroll") for (int n = 0; n < 2; ++n) _Pragma("unroll") for (int k = 0; k < 2; ++k) \
;         acc[ai][bj][m][n] = __builtin_amdgcn_mfma_f32_16x16x32_bf16(Bt[n][k], At[m][k], acc[ai][bj][m][n], 0, 0, 0); __builtin_amdgcn_s_setprio(0); } while (0)
; #define PG8_WAIT_V(n) asm volatile("s_waitcnt vmcnt(" #n ")" ::: "memory")
; #define PG8_WAIT_L(n) asm volatile("s_waitcnt lgkmcnt(" #n ")" ::: "memory")
; #define PG8_BAR __builtin_amdgcn_s_barrier()
; #define PG8_SCHED __builtin_amdgcn_sched_barrier(0)
; template <class Epi, class Sched, bool STAMP = false>
; __device__ __forceinline__ void gemm_phase(PG8_LAS unsigned char* lds, const Gemm g, const Sched& S, const Epi& E, unsigned long long* stamps) {
;     ...
;             PG8_BAR; PG8_WAIT_L(0); PG8_MMA(1, 0, At, B0); PG8_BAR; PG8_SCHED;
;             PG8_STAGE(PG8_SB(1, 1), b3 + hstep, voffB);
;             PG8_WAIT_V(6); PG8_BAR; PG8_MMA(1, 1, At, B1); PG8_BAR;
;     __device__ __forceinline__ void operator()(const f32x4 (&acc)[2][2][4][2], const pg8::Unit& u, int wr, int wc, int fr, int fq) const {
;         const int row0 = (u.pm - 64) * 256 + wr * 64 + fr, col0 = u.pn * 256 + wc * 32 + 4 * fq;
; #pragma unroll
;         for (int ai = 0; ai < 2; ++ai)
; #pragma unroll
;             for (int m = 0; m < 4; ++m) { float* xp = PART + (size_t)(row0 + ai * 128 + m * 16) * ldp + col0;
; #pragma unroll
;                 for (int bj = 0; bj < 2; ++bj)
; #pragma unroll
;                     for (int n = 0; n < 2; ++n) *(f32x4*)(xp + bj * 128 + n * 16) = acc[ai][bj][m][n]; }
	ds_read_b128 v[170:173], v152 offset:49152
	ds_read_b128 v[174:177], v152 offset:50176
	ds_read_b128 v[178:181], v152 offset:51200
	ds_read_b128 v[192:195], v152 offset:52224
	ds_read_b128 v[196:199], v152 offset:53248
	ds_read_b128 v[200:203], v152 offset:54272
	ds_read_b128 v[204:207], v152 offset:55296
	ds_read_b128 v[208:211], v152 offset:56320
	global_load_lds_dwordx4 v[182:183], off
	v_lshl_add_u64 v[182:183], v[232:233], 0, s[18:19]
	s_mov_b32 m0, s58
	s_nop 0
	global_load_lds_dwordx4 v[182:183], off
	s_barrier
	s_waitcnt lgkmcnt(0)
	s_waitcnt lgkmcnt(0)
	v_mfma_f32_16x16x32_bf16 v[60:63], v[154:157], v[170:173], v[60:63]
	v_mfma_f32_16x16x32_bf16 v[56:59], v[162:165], v[170:173], v[56:59]
	v_mfma_f32_16x16x32_bf16 v[52:55], v[154:157], v[178:181], v[52:55]
	v_mfma_f32_16x16x32_bf16 v[48:51], v[162:165], v[178:181], v[48:51]
	v_mfma_f32_16x16x32_bf16 v[36:39], v[154:157], v[196:199], v[36:39]
	v_mfma_f32_16x16x32_bf16 v[32:35], v[162:165], v[196:199], v[32:35]
	v_mfma_f32_16x16x32_bf16 v[20:23], v[154:157], v[204:207], v[20:23]
	v_mfma_f32_16x16x32_bf16 v[16:19], v[162:165], v[204:207], v[16:19]
	v_mfma_f32_16x16x32_bf16 v[60:63], v[158:161], v[174:177], v[60:63]
	v_mfma_f32_16x16x32_bf16 v[56:59], v[166:169], v[174:177], v[56:59]
	v_mfma_f32_16x16x32_bf16 v[52:55], v[158:161], v[192:195], v[52:55]
	v_mfma_f32_16x16x32_bf16 v[48:51], v[166:169], v[192:195], v[48:51]
	v_mfma_f32_16x16x32_bf16 v[36:39], v[158:161], v[200:203], v[36:39]
	v_mfma_f32_16x16x32_bf16 v[32:35], v[166:169], v[200:203], v[32:35]
	v_mfma_f32_16x16x32_bf16 v[20:23], v[158:161], v[208:211], v[20:23]
	v_mfma_f32_16x16x32_bf16 v[16:19], v[166:169], v[208:211], v[16:19]
	s_barrier
	s_mov_b32 m0, s52
	v_lshl_add_u64 v[154:155], s[20:21], 0, v[128:129]
	global_load_lds_dwordx4 v[154:155], off
	v_lshl_add_u64 v[154:155], s[20:21], 0, v[148:149]
	s_mov_b32 m0, s39
	s_nop 0
	global_load_lds_dwordx4 v[154:155], off
	s_waitcnt vmcnt(6)
	s_barrier
	v_mfma_f32_16x16x32_bf16 v[44:47], v[212:215], v[170:173], v[44:47]
	v_mfma_f32_16x16x32_bf16 v[40:43], v[220:223], v[170:173], v[40:43]
	v_mfma_f32_16x16x32_bf16 v[28:31], v[212:215], v[178:181], v[28:31]
	v_mfma_f32_16x16x32_bf16 v[24:27], v[220:223], v[178:181], v[24:27]
	v_mfma_f32_16x16x32_bf16 v[12:15], v[212:215], v[196:199], v[12:15]
	v_mfma_f32_16x16x32_bf16 v[8:11], v[220:223], v[196:199], v[8:11]
	v_mfma_f32_16x16x32_bf16 v[4:7], v[212:215], v[204:207], v[4:7]
	v_mfma_f32_16x16x32_bf16 v[0:3], v[220:223], v[204:207], v[0:3]
	v_mfma_f32_16x16x32_bf16 v[44:47], v[216:219], v[174:177], v[44:47]
	v_mfma_f32_16x16x32_bf16 v[40:43], v[224:227], v[174:177], v[40:43]
	v_mfma_f32_16x16x32_bf16 v[28:31], v[216:219], v[192:195], v[28:31]
	v_mfma_f32_16x16x32_bf16 v[24:27], v[224:227], v[192:195], v[24:27]
	v_mfma_f32_16x16x32_bf16 v[12:15], v[216:219], v[200:203], v[12:15]
	v_mfma_f32_16x16x32_bf16 v[8:11], v[224:227], v[200:203], v[8:11]
	v_mfma_f32_16x16x32_bf16 v[4:7], v[216:219], v[208:211], v[4:7]
	v_mfma_f32_16x16x32_bf16 v[0:3], v[224:227], v[208:211], v[0:3]
	s_andn2_b64 vcc, exec, s[12:13]
	s_mov_b64 s[20:21], -1
	s_mov_b64 s[12:13], 0
	s_movk_i32 s14, 0x100
	s_barrier
	s_cbranch_vccz .LBB0_213
	s_lshl_b32 s0, s43, 22
	s_add_u32 s0, s10, s0
	s_addc_u32 s1, s46, 0
	s_add_u32 s0, s0, 0xbb00000
	s_addc_u32 s1, s1, 0
	s_lshl_b32 s4, s42, 8
	s_add_i32 s4, s4, s53
	v_add_u32_e32 v150, s4, v150
	v_add_u32_e32 v148, 0xffffc000, v150
	s_lshl_b32 s4, s41, 8
	v_lshl_or_b32 v128, v139, 2, s4
	v_ashrrev_i32_e32 v149, 31, v148
	v_or_b32_e32 v128, s56, v128
	v_lshlrev_b64 v[148:149], 12, v[148:149]
	v_lshl_add_u64 v[148:149], s[0:1], 0, v[148:149]
	v_lshlrev_b32_e32 v128, 2, v128
	v_lshl_add_u64 v[148:149], v[148:149], 0, v[128:129]
	global_store_dwordx4 v[148:149], v[124:127], off
	global_store_dwordx4 v[148:149], v[120:123], off offset:64
	global_store_dwordx4 v[148:149], v[108:111], off offset:512
	global_store_dwordx4 v[148:149], v[100:103], off offset:576
	s_cmpk_lt_u32 s40, 0x100
	s_movk_i32 s58, 0xff60
	v_add_u32_e32 v100, 0xffffc010, v150
	v_ashrrev_i32_e32 v101, 31, v100
	v_lshlrev_b64 v[100:101], 12, v[100:101]
	v_lshl_add_u64 v[100:101], s[0:1], 0, v[100:101]
	v_lshl_add_u64 v[100:101], v[100:101], 0, v[128:129]
	global_store_dwordx4 v[100:101], v[116:119], off
	global_store_dwordx4 v[100:101], v[112:115], off offset:64
	global_store_dwordx4 v[100:101], v[92:95], off offset:512
	global_store_dwordx4 v[100:101], v[84:87], off offset:576
	s_nop 1
	v_add_u32_e32 v84, 0xffffc020, v150
	v_ashrrev_i32_e32 v85, 31, v84
	v_lshlrev_b64 v[84:85], 12, v[84:85]
	v_lshl_add_u64 v[84:85], s[0:1], 0, v[84:85]
	v_lshl_add_u64 v[84:85], v[84:85], 0, v[128:129]
	global_store_dwordx4 v[84:85], v[104:107], off
	global_store_dwordx4 v[84:85], v[96:99], off offset:64
	global_store_dwordx4 v[84:85], v[76:79], off offset:512
	global_store_dwordx4 v[84:85], v[72:75], off offset:576
	s_nop 1
	v_add_u32_e32 v72, 0xffffc030, v150
	v_ashrrev_i32_e32 v73, 31, v72
	v_lshlrev_b64 v[72:73], 12, v[72:73]
	v_lshl_add_u64 v[72:73], s[0:1], 0, v[72:73]
	v_lshl_add_u64 v[72:73], v[72:73], 0, v[128:129]
	s_mov_b64 s[0:1], 0x80000
	global_store_dwordx4 v[72:73], v[88:91], off
	global_store_dwordx4 v[72:73], v[80:83], off offset:64
	global_store_dwordx4 v[72:73], v[68:71], off offset:512
	global_store_dwordx4 v[72:73], v[64:67], off offset:576
	s_nop 1
	v_lshl_add_u64 v[64:65], v[148:149], 0, s[0:1]
	s_mov_b32 s0, 0x80000
	v_add_co_u32_e32 v66, vcc, s0, v148
	s_mov_b64 s[0:1], 0x90000
	s_nop 0
	v_addc_co_u32_e32 v67, vcc, 0, v149, vcc
	global_store_dwordx4 v[66:67], v[60:63], off
	global_store_dwordx4 v[64:65], v[56:59], off offset:64
	global_store_dwordx4 v[64:65], v[44:47], off offset:512
	global_store_dwordx4 v[64:65], v[40:43], off offset:576
	s_nop 1
	v_lshl_add_u64 v[40:41], v[148:149], 0, s[0:1]
	s_mov_b32 s0, 0x90000
	v_add_co_u32_e32 v42, vcc, s0, v148
	s_mov_b64 s[0:1], 0xa0000
	s_nop 0
	v_addc_co_u32_e32 v43, vcc, 0, v149, vcc
	global_store_dwordx4 v[42:43], v[52:55], off
	global_store_dwordx4 v[40:41], v[48:51], off offset:64
	global_store_dwordx4 v[40:41], v[28:31], off offset:512
	global_store_dwordx4 v[40:41], v[24:27], off offset:576
	s_nop 1
	v_lshl_add_u64 v[24:25], v[148:149], 0, s[0:1]
	s_mov_b32 s0, 0xa0000
	v_add_co_u32_e32 v26, vcc, s0, v148
	s_mov_b64 s[0:1], 0xb0000
	s_nop 0
	v_addc_co_u32_e32 v27, vcc, 0, v149, vcc
	global_store_dwordx4 v[26:27], v[36:39], off
	global_store_dwordx4 v[24:25], v[32:35], off offset:64
	global_store_dwordx4 v[24:25], v[12:15], off offset:512
	global_store_dwordx4 v[24:25], v[8:11], off offset:576
	s_nop 1
	v_add_co_u32_e32 v10, vcc, 0xb0000, v148
	v_lshl_add_u64 v[8:9], v[148:149], 0, s[0:1]
	s_nop 0
	v_addc_co_u32_e32 v11, vcc, 0, v149, vcc
	global_store_dwordx4 v[10:11], v[20:23], off
	global_store_dwordx4 v[8:9], v[16:19], off offset:64
	global_store_dwordx4 v[8:9], v[4:7], off offset:512
	global_store_dwordx4 v[8:9], v[0:3], off offset:576
	s_waitcnt vmcnt(0)
	s_cbranch_scc0 .LBB0_216
	s_barrier

; #define PG8_STAGE(bufoff, gbase, voff) do { _Pragma("unroll") for (int _i = 0; _i < 2; ++_i) \
;         __builtin_amdgcn_global_load_lds((const unsigned*)((const char*)(gbase) + (voff)[_i]), (PG8_LAS unsigned*)(lds + (bufoff) + ldsw + _i * 8192), 16, 0, 0); } while (0)
; #define PG8_LDA(dst, b, h) do { _Pragma("unroll") for (int m = 0; m < 4; ++m) _Pragma("unroll") for (int k = 0; k < 2; ++k) dst[m][k] = *(const PG8_LAS bf16x8*)(lds + PG8_SA(b, h) + aoff + m * 2048 + k * 1024); } while (0)
; #define PG8_LDB(dst, b, h) do { _Pragma("unroll") for (int n = 0; n < 2; ++n) _Pragma("unroll") for (int k = 0; k < 2; ++k) dst[n][k] = *(const PG8_LAS bf16x8*)(lds + PG8_SB(b, h) + boff + n * 2048 + k * 1024); } while (0)
; #define PG8_MMA(ai, bj, At, Bt) do { __builtin_amdgcn_s_setprio(1); _Pragma("unroll") for (int m = 0; m < 4; ++m) _Pragma("unroll") for (int n = 0; n < 2; ++n) _Pragma("unroll") for (int k = 0; k < 2; ++k) \
;         acc[ai][bj][m][n] = __builtin_amdgcn_mfma_f32_16x16x32_bf16(Bt[n][k], At[m][k], acc[ai][bj][m][n], 0, 0, 0); __builtin_amdgcn_s_setprio(0); } while (0)
; #define PG8_WAIT_L(n) asm volatile("s_waitcnt lgkmcnt(" #n ")" ::: "memory")
; #define PG8_BAR __builtin_amdgcn_s_barrier()
; #define PG8_SCHED __builtin_amdgcn_sched_barrier(0)
; template <class Epi, class Sched, bool STAMP = false>
; __device__ __forceinline__ void gemm_phase(PG8_LAS unsigned char* lds, const Gemm g, const Sched& S, const Epi& E, unsigned long long* stamps) {
;     ...
;             PG8_LDB(B0, 0, 0); PG8_SCHED; PG8_LDA(At, 0, 0); PG8_STAGE(PG8_SA(1, 1), a1 + hstep, voffA);
;             PG8_WAIT_L(8); PG8_BAR; PG8_WAIT_L(0); PG8_MMA(0, 0, At, B0); PG8_BAR; PG8_SCHED;
;             PG8_LDB(B1, 0, 1); PG8_STAGE(PG8_SB(0, 0), b2, voffB);
;             PG8_BAR; PG8_WAIT_L(0); PG8_MMA(0, 1, At, B1); PG8_BAR;
;             PG8_LDA(At, 0, 1); PG8_STAGE(PG8_SA(0, 0), a2, voffA);
;             PG8_BAR; PG8_WAIT_L(0); PG8_MMA(1, 0, At, B0); PG8_BAR; PG8_SCHED;
.LBB0_293:
	s_add_u32 s14, s24, 0xfffe0080
	s_addc_u32 s15, s25, -1
	s_add_i32 s16, 0, 0x10000
	v_add_u32_e32 v161, s16, v158
	ds_read_b128 v[162:165], v161
	ds_read_b128 v[166:169], v161 offset:1024
	ds_read_b128 v[170:173], v161 offset:2048
	ds_read_b128 v[174:177], v161 offset:3072
	s_cmp_eq_u32 s59, 4
	s_cselect_b32 s31, s7, s15
	s_cselect_b32 s30, s53, s14
	s_cselect_b32 s27, s5, s58
	s_cselect_b32 s26, s56, s57
	v_lshl_add_u64 v[182:183], s[24:25], 0, v[154:155]
	s_add_i32 m0, s3, 0xc000
	ds_read_b128 v[178:181], v160
	ds_read_b128 v[192:195], v160 offset:1024
	ds_read_b128 v[196:199], v160 offset:2048
	ds_read_b128 v[200:203], v160 offset:3072
	ds_read_b128 v[204:207], v160 offset:4096
	ds_read_b128 v[208:211], v160 offset:5120
	ds_read_b128 v[212:215], v160 offset:6144
	ds_read_b128 v[216:219], v160 offset:7168
	global_load_lds_dwordx4 v[182:183], off
	v_lshl_add_u64 v[182:183], s[24:25], 0, v[156:157]
	s_add_i32 m0, s3, 0xe000
	s_nop 0
	global_load_lds_dwordx4 v[182:183], off
	s_waitcnt lgkmcnt(8)
	s_barrier
	s_waitcnt lgkmcnt(0)
	s_waitcnt lgkmcnt(0)
	v_mfma_f32_16x16x32_bf16 v[124:127], v[162:165], v[178:181], v[124:127]
	v_mfma_f32_16x16x32_bf16 v[120:123], v[170:173], v[178:181], v[120:123]
	v_mfma_f32_16x16x32_bf16 v[116:119], v[162:165], v[196:199], v[116:119]
	v_mfma_f32_16x16x32_bf16 v[112:115], v[170:173], v[196:199], v[112:115]
	v_mfma_f32_16x16x32_bf16 v[100:103], v[162:165], v[204:207], v[100:103]
	v_mfma_f32_16x16x32_bf16 v[96:99], v[170:173], v[204:207], v[96:99]
	v_mfma_f32_16x16x32_bf16 v[84:87], v[162:165], v[212:215], v[84:87]
	v_mfma_f32_16x16x32_bf16 v[80:83], v[170:173], v[212:215], v[80:83]
	v_mfma_f32_16x16x32_bf16 v[124:127], v[166:169], v[192:195], v[124:127]
	v_mfma_f32_16x16x32_bf16 v[120:123], v[174:177], v[192:195], v[120:123]
	v_mfma_f32_16x16x32_bf16 v[116:119], v[166:169], v[200:203], v[116:119]
	v_mfma_f32_16x16x32_bf16 v[112:115], v[174:177], v[200:203], v[112:115]
	v_mfma_f32_16x16x32_bf16 v[100:103], v[166:169], v[208:211], v[100:103]
	v_mfma_f32_16x16x32_bf16 v[96:99], v[174:177], v[208:211], v[96:99]
	v_mfma_f32_16x16x32_bf16 v[84:87], v[166:169], v[216:219], v[84:87]
	v_mfma_f32_16x16x32_bf16 v[80:83], v[174:177], v[216:219], v[80:83]
	s_barrier
	s_add_i32 s17, 0, 0x14000
	s_add_i32 s14, s16, s40
	v_add_u32_e32 v161, s17, v158
	v_lshl_add_u64 v[182:183], s[26:27], 0, v[128:129]
	s_mov_b32 m0, s14
	ds_read_b128 v[220:223], v161
	ds_read_b128 v[224:227], v161 offset:1024
	ds_read_b128 v[228:231], v161 offset:2048
	ds_read_b128 v[232:235], v161 offset:3072
	global_load_lds_dwordx4 v[182:183], off
	v_lshl_add_u64 v[236:237], s[26:27], 0, v[152:153]
	s_add_i32 m0, s14, 0x2000
	s_nop 0
	global_load_lds_dwordx4 v[236:237], off
	s_barrier
	s_waitcnt lgkmcnt(0)
	s_waitcnt lgkmcnt(0)
	v_mfma_f32_16x16x32_bf16 v[108:111], v[220:223], v[178:181], v[108:111]
	v_mfma_f32_16x16x32_bf16 v[104:107], v[228:231], v[178:181], v[104:107]
	v_mfma_f32_16x16x32_bf16 v[92:95], v[220:223], v[196:199], v[92:95]
	v_mfma_f32_16x16x32_bf16 v[88:91], v[228:231], v[196:199], v[88:91]
	v_mfma_f32_16x16x32_bf16 v[76:79], v[220:223], v[204:207], v[76:79]
	v_mfma_f32_16x16x32_bf16 v[72:75], v[228:231], v[204:207], v[72:75]
	v_mfma_f32_16x16x32_bf16 v[68:71], v[220:223], v[212:215], v[68:71]
	v_mfma_f32_16x16x32_bf16 v[64:67], v[228:231], v[212:215], v[64:67]
	v_mfma_f32_16x16x32_bf16 v[108:111], v[224:227], v[192:195], v[108:111]
	v_mfma_f32_16x16x32_bf16 v[104:107], v[232:235], v[192:195], v[104:107]
	v_mfma_f32_16x16x32_bf16 v[92:95], v[224:227], v[200:203], v[92:95]
	v_mfma_f32_16x16x32_bf16 v[88:91], v[232:235], v[200:203], v[88:91]
	v_mfma_f32_16x16x32_bf16 v[76:79], v[224:227], v[208:211], v[76:79]
	v_mfma_f32_16x16x32_bf16 v[72:75], v[232:235], v[208:211], v[72:75]
	v_mfma_f32_16x16x32_bf16 v[68:71], v[224:227], v[216:219], v[68:71]
	v_mfma_f32_16x16x32_bf16 v[64:67], v[232:235], v[216:219], v[64:67]
	s_mov_b32 m0, s3
	v_lshl_add_u64 v[238:239], s[30:31], 0, v[148:149]
	s_barrier
	ds_read_b128 v[178:181], v160 offset:16384
	ds_read_b128 v[192:195], v160 offset:17408
	ds_read_b128 v[196:199], v160 offset:18432
	ds_read_b128 v[200:203], v160 offset:19456
	ds_read_b128 v[204:207], v160 offset:20480
	ds_read_b128 v[208:211], v160 offset:21504
	ds_read_b128 v[212:215], v160 offset:22528
	ds_read_b128 v[216:219], v160 offset:23552
	global_load_lds_dwordx4 v[238:239], off
	v_lshl_add_u64 v[240:241], s[30:31], 0, v[150:151]
	s_mov_b32 m0, s41
	s_nop 0
	global_load_lds_dwordx4 v[240:241], off
	s_barrier
	s_waitcnt lgkmcnt(0)
	s_waitcnt lgkmcnt(0)
	v_mfma_f32_16x16x32_bf16 v[60:63], v[162:165], v[178:181], v[60:63]
	v_mfma_f32_16x16x32_bf16 v[56:59], v[170:173], v[178:181], v[56:59]
	v_mfma_f32_16x16x32_bf16 v[52:55], v[162:165], v[196:199], v[52:55]
	v_mfma_f32_16x16x32_bf16 v[48:51], v[170:173], v[196:199], v[48:51]
	v_mfma_f32_16x16x32_bf16 v[36:39], v[162:165], v[204:207], v[36:39]
	v_mfma_f32_16x16x32_bf16 v[32:35], v[170:173], v[204:207], v[32:35]
	v_mfma_f32_16x16x32_bf16 v[20:23], v[162:165], v[212:215], v[20:23]
	v_mfma_f32_16x16x32_bf16 v[16:19], v[170:173], v[212:215], v[16:19]
	v_mfma_f32_16x16x32_bf16 v[60:63], v[166:169], v[192:195], v[60:63]
	v_mfma_f32_16x16x32_bf16 v[56:59], v[174:177], v[192:195], v[56:59]
	v_mfma_f32_16x16x32_bf16 v[52:55], v[166:169], v[200:203], v[52:55]
	v_mfma_f32_16x16x32_bf16 v[48:51], v[174:177], v[200:203], v[48:51]
	v_mfma_f32_16x16x32_bf16 v[36:39], v[166:169], v[208:211], v[36:39]
	v_mfma_f32_16x16x32_bf16 v[32:35], v[174:177], v[208:211], v[32:35]
	v_mfma_f32_16x16x32_bf16 v[20:23], v[166:169], v[216:219], v[20:23]
	v_mfma_f32_16x16x32_bf16 v[16:19], v[174:177], v[216:219], v[16:19]
	s_barrier
; #define PG8_STAGE(bufoff, gbase, voff) do { _Pragma("unroll") for (int _i = 0; _i < 2; ++_i) \
;         __builtin_amdgcn_global_load_lds((const unsigned*)((const char*)(gbase) + (voff)[_i]), (PG8_LAS unsigned*)(lds + (bufoff) + ldsw + _i * 8192), 16, 0, 0); } while (0)
; #define PG8_LDA(dst, b, h) do { _Pragma("unroll") for (int m = 0; m < 4; ++m) _Pragma("unroll") for (int k = 0; k < 2; ++k) dst[m][k] = *(const PG8_LAS bf16x8*)(lds + PG8_SA(b, h) + aoff + m * 2048 + k * 1024); } while (0)
; #define PG8_LDB(dst, b, h) do { _Pragma("unroll") for (int n = 0; n < 2; ++n) _Pragma("unroll") for (int k = 0; k < 2; ++k) dst[n][k] = *(const PG8_LAS bf16x8*)(lds + PG8_SB(b, h) + boff + n * 2048 + k * 1024); } while (0)
; #define PG8_MMA(ai, bj, At, Bt) do { __builtin_amdgcn_s_setprio(1); _Pragma("unroll") for (int m = 0; m < 4; ++m) _Pragma("unroll") for (int n = 0; n < 2; ++n) _Pragma("unroll") for (int k = 0; k < 2; ++k) \
;         acc[ai][bj][m][n] = __builtin_amdgcn_mfma_f32_16x16x32_bf16(Bt[n][k], At[m][k], acc[ai][bj][m][n], 0, 0, 0); __builtin_amdgcn_s_setprio(0); } while (0)
; #define PG8_WAIT_V(n) asm volatile("s_waitcnt vmcnt(" #n ")" ::: "memory")
; #define PG8_WAIT_L(n) asm volatile("s_waitcnt lgkmcnt(" #n ")" ::: "memory")
; #define PG8_BAR __builtin_amdgcn_s_barrier()
; #define PG8_SCHED __builtin_amdgcn_sched_barrier(0)
; template <class Epi, class Sched, bool STAMP = false>
; __device__ __forceinline__ void gemm_phase(PG8_LAS unsigned char* lds, const Gemm g, const Sched& S, const Epi& E, unsigned long long* stamps) {
;     ...
;             PG8_STAGE(PG8_SB(0, 1), b2 + hstep, voffB);
;             PG8_WAIT_V(6); PG8_BAR; PG8_MMA(1, 1, At, B1); PG8_BAR;
;             PG8_LDB(B0, 1, 0); PG8_SCHED; PG8_LDA(At, 1, 0); PG8_STAGE(PG8_SA(0, 1), a2 + hstep, voffA);
;             PG8_WAIT_L(8); PG8_BAR; PG8_WAIT_L(0); PG8_MMA(0, 0, At, B0); PG8_BAR; PG8_SCHED;
;             PG8_LDB(B1, 1, 1); PG8_STAGE(PG8_SB(1, 0), b3, voffB);
;             PG8_BAR; PG8_WAIT_L(0); PG8_MMA(0, 1, At, B1); PG8_BAR;
;             PG8_LDA(At, 1, 1); PG8_STAGE(PG8_SA(1, 0), a3, voffA);
;             PG8_BAR; PG8_WAIT_L(0); PG8_MMA(1, 0, At, B0); PG8_BAR; PG8_SCHED;
	s_add_u32 s14, s26, 0x20000
	s_addc_u32 s15, s27, 0
	s_add_i32 s16, s17, s40
	v_lshl_add_u64 v[162:163], s[14:15], 0, v[128:129]
	s_mov_b32 m0, s16
	s_nop 0
	global_load_lds_dwordx4 v[162:163], off
	v_lshl_add_u64 v[162:163], s[14:15], 0, v[152:153]
	s_add_i32 m0, s16, 0x2000
	s_nop 0
	global_load_lds_dwordx4 v[162:163], off
	s_waitcnt vmcnt(6)
	s_barrier
	v_mfma_f32_16x16x32_bf16 v[44:47], v[220:223], v[178:181], v[44:47]
	v_mfma_f32_16x16x32_bf16 v[40:43], v[228:231], v[178:181], v[40:43]
	v_mfma_f32_16x16x32_bf16 v[28:31], v[220:223], v[196:199], v[28:31]
	v_mfma_f32_16x16x32_bf16 v[24:27], v[228:231], v[196:199], v[24:27]
	v_mfma_f32_16x16x32_bf16 v[12:15], v[220:223], v[204:207], v[12:15]
	v_mfma_f32_16x16x32_bf16 v[8:11], v[228:231], v[204:207], v[8:11]
	v_mfma_f32_16x16x32_bf16 v[4:7], v[220:223], v[212:215], v[4:7]
	v_mfma_f32_16x16x32_bf16 v[0:3], v[228:231], v[212:215], v[0:3]
	v_mfma_f32_16x16x32_bf16 v[44:47], v[224:227], v[192:195], v[44:47]
	v_mfma_f32_16x16x32_bf16 v[40:43], v[232:235], v[192:195], v[40:43]
	v_mfma_f32_16x16x32_bf16 v[28:31], v[224:227], v[200:203], v[28:31]
	v_mfma_f32_16x16x32_bf16 v[24:27], v[232:235], v[200:203], v[24:27]
	v_mfma_f32_16x16x32_bf16 v[12:15], v[224:227], v[208:211], v[12:15]
	v_mfma_f32_16x16x32_bf16 v[8:11], v[232:235], v[208:211], v[8:11]
	v_mfma_f32_16x16x32_bf16 v[4:7], v[224:227], v[216:219], v[4:7]
	v_mfma_f32_16x16x32_bf16 v[0:3], v[232:235], v[216:219], v[0:3]
	s_add_i32 s16, 0, 0x18000
	v_add_u32_e32 v161, s16, v158
	s_barrier
	ds_read_b128 v[162:165], v161
	ds_read_b128 v[166:169], v161 offset:1024
	ds_read_b128 v[170:173], v161 offset:2048
	ds_read_b128 v[174:177], v161 offset:3072
	s_add_u32 s14, s30, 0x20000
	s_addc_u32 s15, s31, 0
	s_mov_b32 m0, s42
	v_lshl_add_u64 v[220:221], s[14:15], 0, v[148:149]
	ds_read_b128 v[178:181], v160 offset:32768
	ds_read_b128 v[192:195], v160 offset:33792
	ds_read_b128 v[196:199], v160 offset:34816
	ds_read_b128 v[200:203], v160 offset:35840
	ds_read_b128 v[204:207], v160 offset:36864
	ds_read_b128 v[208:211], v160 offset:37888
	ds_read_b128 v[212:215], v160 offset:38912
	ds_read_b128 v[216:219], v160 offset:39936
	global_load_lds_dwordx4 v[220:221], off
	v_lshl_add_u64 v[220:221], s[14:15], 0, v[150:151]
	s_mov_b32 m0, s43
	s_nop 0
	global_load_lds_dwordx4 v[220:221], off
	s_waitcnt lgkmcnt(8)
	s_barrier
	s_waitcnt lgkmcnt(0)
	s_waitcnt lgkmcnt(0)
	v_mfma_f32_16x16x32_bf16 v[124:127], v[162:165], v[178:181], v[124:127]
	v_mfma_f32_16x16x32_bf16 v[120:123], v[170:173], v[178:181], v[120:123]
	v_mfma_f32_16x16x32_bf16 v[116:119], v[162:165], v[196:199], v[116:119]
	v_mfma_f32_16x16x32_bf16 v[112:115], v[170:173], v[196:199], v[112:115]
	v_mfma_f32_16x16x32_bf16 v[100:103], v[162:165], v[204:207], v[100:103]
	v_mfma_f32_16x16x32_bf16 v[96:99], v[170:173], v[204:207], v[96:99]
	v_mfma_f32_16x16x32_bf16 v[84:87], v[162:165], v[212:215], v[84:87]
	v_mfma_f32_16x16x32_bf16 v[80:83], v[170:173], v[212:215], v[80:83]
	v_mfma_f32_16x16x32_bf16 v[124:127], v[166:169], v[192:195], v[124:127]
	v_mfma_f32_16x16x32_bf16 v[120:123], v[174:177], v[192:195], v[120:123]
	v_mfma_f32_16x16x32_bf16 v[116:119], v[166:169], v[200:203], v[116:119]
	v_mfma_f32_16x16x32_bf16 v[112:115], v[174:177], v[200:203], v[112:115]
	v_mfma_f32_16x16x32_bf16 v[100:103], v[166:169], v[208:211], v[100:103]
	v_mfma_f32_16x16x32_bf16 v[96:99], v[174:177], v[208:211], v[96:99]
	v_mfma_f32_16x16x32_bf16 v[84:87], v[166:169], v[216:219], v[84:87]
	v_mfma_f32_16x16x32_bf16 v[80:83], v[174:177], v[216:219], v[80:83]
	s_barrier
	s_add_i32 s17, 0, 0x1c000
	s_add_i32 s14, s16, s40
	v_add_u32_e32 v161, s17, v158
	v_lshl_add_u64 v[182:183], v[182:183], 0, s[18:19]
	s_mov_b32 m0, s14
	ds_read_b128 v[220:223], v161
	ds_read_b128 v[224:227], v161 offset:1024
	ds_read_b128 v[228:231], v161 offset:2048
	ds_read_b128 v[232:235], v161 offset:3072
	global_load_lds_dwordx4 v[182:183], off
	v_lshl_add_u64 v[182:183], v[236:237], 0, s[18:19]
	s_add_i32 m0, s14, 0x2000
	s_nop 0
	global_load_lds_dwordx4 v[182:183], off
	s_barrier
	s_waitcnt lgkmcnt(0)
	s_waitcnt lgkmcnt(0)
	v_mfma_f32_16x16x32_bf16 v[108:111], v[220:223], v[178:181], v[108:111]
	v_mfma_f32_16x16x32_bf16 v[104:107], v[228:231], v[178:181], v[104:107]
	v_mfma_f32_16x16x32_bf16 v[92:95], v[220:223], v[196:199], v[92:95]
	v_mfma_f32_16x16x32_bf16 v[88:91], v[228:231], v[196:199], v[88:91]
	v_mfma_f32_16x16x32_bf16 v[76:79], v[220:223], v[204:207], v[76:79]
	v_mfma_f32_16x16x32_bf16 v[72:75], v[228:231], v[204:207], v[72:75]
	v_mfma_f32_16x16x32_bf16 v[68:71], v[220:223], v[212:215], v[68:71]
	v_mfma_f32_16x16x32_bf16 v[64:67], v[228:231], v[212:215], v[64:67]
	v_mfma_f32_16x16x32_bf16 v[108:111], v[224:227], v[192:195], v[108:111]
	v_mfma_f32_16x16x32_bf16 v[104:107], v[232:235], v[192:195], v[104:107]
	v_mfma_f32_16x16x32_bf16 v[92:95], v[224:227], v[200:203], v[92:95]
	v_mfma_f32_16x16x32_bf16 v[88:91], v[232:235], v[200:203], v[88:91]
	v_mfma_f32_16x16x32_bf16 v[76:79], v[224:227], v[208:211], v[76:79]
	v_mfma_f32_16x16x32_bf16 v[72:75], v[232:235], v[208:211], v[72:75]
	v_mfma_f32_16x16x32_bf16 v[68:71], v[224:227], v[216:219], v[68:71]
	v_mfma_f32_16x16x32_bf16 v[64:67], v[232:235], v[216:219], v[64:67]
	s_mov_b32 m0, s46
	v_lshl_add_u64 v[182:183], v[238:239], 0, s[18:19]
	s_barrier
	ds_read_b128 v[178:181], v160 offset:49152
	ds_read_b128 v[192:195], v160 offset:50176
	ds_read_b128 v[196:199], v160 offset:51200
	ds_read_b128 v[200:203], v160 offset:52224
	ds_read_b128 v[204:207], v160 offset:53248
	ds_read_b128 v[208:211], v160 offset:54272
	ds_read_b128 v[212:215], v160 offset:55296
	ds_read_b128 v[216:219], v160 offset:56320
	global_load_lds_dwordx4 v[182:183], off
	v_lshl_add_u64 v[182:183], v[240:241], 0, s[18:19]
	s_mov_b32 m0, s47
	s_nop 0
	global_load_lds_dwordx4 v[182:183], off
	s_barrier
; #define PG8_STAGE(bufoff, gbase, voff) do { _Pragma("unroll") for (int _i = 0; _i < 2; ++_i) \
;         __builtin_amdgcn_global_load_lds((const unsigned*)((const char*)(gbase) + (voff)[_i]), (PG8_LAS unsigned*)(lds + (bufoff) + ldsw + _i * 8192), 16, 0, 0); } while (0)
; #define PG8_MMA(ai, bj, At, Bt) do { __builtin_amdgcn_s_setprio(1); _Pragma("unroll") for (int m = 0; m < 4; ++m) _Pragma("unroll") for (int n = 0; n < 2; ++n) _Pragma("unroll") for (int k = 0; k < 2; ++k) \
;         acc[ai][bj][m][n] = __builtin_amdgcn_mfma_f32_16x16x32_bf16(Bt[n][k], At[m][k], acc[ai][bj][m][n], 0, 0, 0); __builtin_amdgcn_s_setprio(0); } while (0)
; #define PG8_WAIT_V(n) asm volatile("s_waitcnt vmcnt(" #n ")" ::: "memory")
; #define PG8_WAIT_L(n) asm volatile("s_waitcnt lgkmcnt(" #n ")" ::: "memory")
; #define PG8_BAR __builtin_amdgcn_s_barrier()
; #define PG8_SCHED __builtin_amdgcn_sched_barrier(0)
; template <class Epi, class Sched, bool STAMP = false>
; __device__ __forceinline__ void gemm_phase(PG8_LAS unsigned char* lds, const Gemm g, const Sched& S, const Epi& E, unsigned long long* stamps) {
;     ...
;             PG8_BAR; PG8_WAIT_L(0); PG8_MMA(1, 0, At, B0); PG8_BAR; PG8_SCHED;
;             PG8_STAGE(PG8_SB(1, 1), b3 + hstep, voffB);
;             PG8_WAIT_V(6); PG8_BAR; PG8_MMA(1, 1, At, B1); PG8_BAR;
	s_waitcnt lgkmcnt(0)
	s_waitcnt lgkmcnt(0)
	v_mfma_f32_16x16x32_bf16 v[60:63], v[162:165], v[178:181], v[60:63]
	v_mfma_f32_16x16x32_bf16 v[56:59], v[170:173], v[178:181], v[56:59]
	v_mfma_f32_16x16x32_bf16 v[52:55], v[162:165], v[196:199], v[52:55]
	v_mfma_f32_16x16x32_bf16 v[48:51], v[170:173], v[196:199], v[48:51]
	v_mfma_f32_16x16x32_bf16 v[36:39], v[162:165], v[204:207], v[36:39]
	v_mfma_f32_16x16x32_bf16 v[32:35], v[170:173], v[204:207], v[32:35]
	v_mfma_f32_16x16x32_bf16 v[20:23], v[162:165], v[212:215], v[20:23]
	v_mfma_f32_16x16x32_bf16 v[16:19], v[170:173], v[212:215], v[16:19]
	v_mfma_f32_16x16x32_bf16 v[60:63], v[166:169], v[192:195], v[60:63]
	v_mfma_f32_16x16x32_bf16 v[56:59], v[174:177], v[192:195], v[56:59]
	v_mfma_f32_16x16x32_bf16 v[52:55], v[166:169], v[200:203], v[52:55]
	v_mfma_f32_16x16x32_bf16 v[48:51], v[174:177], v[200:203], v[48:51]
	v_mfma_f32_16x16x32_bf16 v[36:39], v[166:169], v[208:211], v[36:39]
	v_mfma_f32_16x16x32_bf16 v[32:35], v[174:177], v[208:211], v[32:35]
	v_mfma_f32_16x16x32_bf16 v[20:23], v[166:169], v[216:219], v[20:23]
	v_mfma_f32_16x16x32_bf16 v[16:19], v[174:177], v[216:219], v[16:19]
	s_barrier
	s_add_u32 s14, s26, 0x20080
	s_addc_u32 s15, s27, 0
	s_add_i32 s16, s17, s40
	v_lshl_add_u64 v[162:163], s[14:15], 0, v[128:129]
	s_mov_b32 m0, s16
	s_nop 0
	global_load_lds_dwordx4 v[162:163], off
	v_lshl_add_u64 v[162:163], s[14:15], 0, v[152:153]
	s_add_i32 m0, s16, 0x2000
	s_nop 0
	global_load_lds_dwordx4 v[162:163], off
	s_waitcnt vmcnt(6)
	s_barrier
	v_mfma_f32_16x16x32_bf16 v[44:47], v[220:223], v[178:181], v[44:47]
	v_mfma_f32_16x16x32_bf16 v[40:43], v[228:231], v[178:181], v[40:43]
	v_mfma_f32_16x16x32_bf16 v[28:31], v[220:223], v[196:199], v[28:31]
	v_mfma_f32_16x16x32_bf16 v[24:27], v[228:231], v[196:199], v[24:27]
	v_mfma_f32_16x16x32_bf16 v[12:15], v[220:223], v[204:207], v[12:15]
	v_mfma_f32_16x16x32_bf16 v[8:11], v[228:231], v[204:207], v[8:11]
	v_mfma_f32_16x16x32_bf16 v[4:7], v[220:223], v[212:215], v[4:7]
	v_mfma_f32_16x16x32_bf16 v[0:3], v[228:231], v[212:215], v[0:3]
	v_mfma_f32_16x16x32_bf16 v[44:47], v[224:227], v[192:195], v[44:47]
	v_mfma_f32_16x16x32_bf16 v[40:43], v[232:235], v[192:195], v[40:43]
	v_mfma_f32_16x16x32_bf16 v[28:31], v[224:227], v[200:203], v[28:31]
	v_mfma_f32_16x16x32_bf16 v[24:27], v[232:235], v[200:203], v[24:27]
	v_mfma_f32_16x16x32_bf16 v[12:15], v[224:227], v[208:211], v[12:15]
	v_mfma_f32_16x16x32_bf16 v[8:11], v[232:235], v[208:211], v[8:11]
	v_mfma_f32_16x16x32_bf16 v[4:7], v[224:227], v[216:219], v[4:7]
	v_mfma_f32_16x16x32_bf16 v[0:3], v[232:235], v[216:219], v[0:3]
	s_add_i32 s59, s59, 2
	s_add_u32 s24, s24, 0x100
	s_addc_u32 s25, s25, 0
	s_add_u32 s57, s57, 0x100
	s_addc_u32 s58, s58, 0
	s_cmp_gt_u32 s59, 5
	s_barrier
	s_cbranch_scc0 .LBB0_293
; __device__ __forceinline__ unsigned cvt_pk_bf16(float lo, float hi) { const f32x2_cv v = {lo, hi}; const bf16x2_cv b = __builtin_convertvector(v, bf16x2_cv); return __builtin_bit_cast(unsigned, b); }
; __device__ __forceinline__ float rstd_of(const float* rowss, int row) { return rsqrtf(rowss[row] * (1.0f / 1024.0f) + 1e-6f); }
;     __device__ __forceinline__ void operator()(const f32x4 (&acc)[2][2][4][2], const pg8::Unit& u, int wr, int wc, int fr, int fq) const {
;         const int row0 = u.pm * 256 + wr * 64 + fr, col0 = u.pn * 256 + wc * 32 + 8 * fq;
; #pragma unroll
;         for (int ai = 0; ai < 2; ++ai)
; #pragma unroll
;             for (int m = 0; m < 4; ++m) {
;                 const int row = row0 + ai * 128 + m * 16;
;                 const float s = (MODE == 2) ? 1.0f : rstd_of(rowss, row);
;                 bf16_t* rowp = O + (size_t)row * ldc + col0;
; #pragma unroll
;                 for (int bj = 0; bj < 2; ++bj) {
;                     f32x4 v0 = acc[ai][bj][m][0] * s, v1 = acc[ai][bj][m][1] * s;
;                     if (MODE == 1) {
; #pragma unroll
;                         for (int j = 0; j < 4; ++j) { const float a = fmaxf(v0[j], 0.f), b = fmaxf(v1[j], 0.f); v0[j] = a * a; v1[j] = b * b; } }
;                     u32x4 w; w.x = cvt_pk_bf16(v0[0], v0[1]); w.y = cvt_pk_bf16(v0[2], v0[3]); w.z = cvt_pk_bf16(v1[0], v1[1]); w.w = cvt_pk_bf16(v1[2], v1[3]);
;                     *(u32x4*)(rowp + bj * 128) = w; } }
	v_lshl_add_u32 v162, s2, 8, v139
	v_lshl_or_b32 v164, s49, 8, v159
	v_ashrrev_i32_e32 v163, 31, v162
	v_ashrrev_i32_e32 v165, 31, v164
	v_lshlrev_b64 v[166:167], 11, v[162:163]
	v_lshl_add_u64 v[166:167], s[0:1], 0, v[166:167]
	v_lshlrev_b64 v[164:165], 1, v[164:165]
	v_lshl_add_u64 v[166:167], v[166:167], 0, v[164:165]
	s_mov_b32 s2, 0x40000
	s_mov_b64 s[14:15], 0x40000
	v_cvt_pk_bf16_f32 v60, v60, v61
	v_cvt_pk_bf16_f32 v61, v62, v63
	v_cvt_pk_bf16_f32 v62, v56, v57
	v_add_co_u32_e32 v56, vcc, s2, v166
	v_cvt_pk_bf16_f32 v68, v68, v69
	v_cvt_pk_bf16_f32 v69, v70, v71
	v_cvt_pk_bf16_f32 v70, v64, v65
	v_lshl_add_u64 v[64:65], v[166:167], 0, s[14:15]
	v_addc_co_u32_e32 v57, vcc, 0, v167, vcc
	v_cvt_pk_bf16_f32 v44, v44, v45
	v_cvt_pk_bf16_f32 v45, v46, v47
	v_cvt_pk_bf16_f32 v46, v40, v41
	v_cvt_pk_bf16_f32 v47, v42, v43
	s_mov_b32 s2, 0x48000
	v_cvt_pk_bf16_f32 v108, v108, v109
	v_cvt_pk_bf16_f32 v109, v110, v111
	v_cvt_pk_bf16_f32 v110, v104, v105
	v_or_b32_e32 v104, 16, v162
	global_store_dwordx4 v[64:65], v[44:47], off offset:256
	s_mov_b64 s[14:15], 0x48000
	v_ashrrev_i32_e32 v105, 31, v104
	v_add_co_u32_e32 v46, vcc, s2, v166
	v_cvt_pk_bf16_f32 v92, v92, v93
	v_cvt_pk_bf16_f32 v93, v94, v95
	v_cvt_pk_bf16_f32 v94, v88, v89
	v_or_b32_e32 v88, 32, v162
	v_lshl_add_u64 v[44:45], v[166:167], 0, s[14:15]
	v_addc_co_u32_e32 v47, vcc, 0, v167, vcc
	v_cvt_pk_bf16_f32 v28, v28, v29
	v_cvt_pk_bf16_f32 v29, v30, v31
	v_cvt_pk_bf16_f32 v30, v24, v25
	v_cvt_pk_bf16_f32 v31, v26, v27
	s_mov_b32 s2, 0x50000
	v_lshlrev_b64 v[104:105], 11, v[104:105]
	v_ashrrev_i32_e32 v89, 31, v88
	v_cvt_pk_bf16_f32 v76, v76, v77
	v_cvt_pk_bf16_f32 v77, v78, v79
	v_cvt_pk_bf16_f32 v78, v72, v73
	v_or_b32_e32 v72, 48, v162
	global_store_dwordx4 v[44:45], v[28:31], off offset:256
	s_mov_b64 s[14:15], 0x50000
	v_cvt_pk_bf16_f32 v111, v106, v107
	v_add_co_u32_e32 v30, vcc, s2, v166
	v_lshl_add_u64 v[104:105], s[0:1], 0, v[104:105]
	v_lshlrev_b64 v[88:89], 11, v[88:89]
	v_ashrrev_i32_e32 v73, 31, v72
	v_lshl_add_u64 v[28:29], v[166:167], 0, s[14:15]
	v_addc_co_u32_e32 v31, vcc, 0, v167, vcc
	v_cvt_pk_bf16_f32 v12, v12, v13
	v_cvt_pk_bf16_f32 v13, v14, v15
	v_cvt_pk_bf16_f32 v14, v8, v9
	v_cvt_pk_bf16_f32 v15, v10, v11
	s_mov_b32 s2, 0x58000
	global_store_dwordx4 v[166:167], v[108:111], off offset:256
	v_cvt_pk_bf16_f32 v95, v90, v91
	v_lshl_add_u64 v[88:89], s[0:1], 0, v[88:89]
	v_lshl_add_u64 v[108:109], v[104:105], 0, v[164:165]
	v_lshlrev_b64 v[72:73], 11, v[72:73]
	global_store_dwordx4 v[28:29], v[12:15], off offset:256
	global_store_dwordx4 v[108:109], v[92:95], off offset:256
	v_cvt_pk_bf16_f32 v79, v74, v75
	v_add_co_u32_e32 v14, vcc, s2, v166
	v_lshl_add_u64 v[92:93], v[88:89], 0, v[164:165]
	v_lshl_add_u64 v[72:73], s[0:1], 0, v[72:73]
	s_mov_b64 s[14:15], 0x58000
	v_addc_co_u32_e32 v15, vcc, 0, v167, vcc
	v_cvt_pk_bf16_f32 v124, v124, v125
	v_cvt_pk_bf16_f32 v125, v126, v127
	v_cvt_pk_bf16_f32 v126, v120, v121
	v_cvt_pk_bf16_f32 v127, v122, v123
	v_cvt_pk_bf16_f32 v104, v116, v117
	v_cvt_pk_bf16_f32 v105, v118, v119
	v_cvt_pk_bf16_f32 v106, v112, v113
	v_cvt_pk_bf16_f32 v107, v114, v115
	v_cvt_pk_bf16_f32 v88, v100, v101
	v_cvt_pk_bf16_f32 v89, v102, v103
	v_cvt_pk_bf16_f32 v90, v96, v97
	v_cvt_pk_bf16_f32 v91, v98, v99
	global_store_dwordx4 v[92:93], v[76:79], off offset:256
	v_cvt_pk_bf16_f32 v74, v80, v81
	v_cvt_pk_bf16_f32 v75, v82, v83
	v_lshl_add_u64 v[76:77], v[72:73], 0, v[164:165]
	v_cvt_pk_bf16_f32 v72, v84, v85
	v_cvt_pk_bf16_f32 v73, v86, v87
	v_cvt_pk_bf16_f32 v71, v66, v67
	v_cvt_pk_bf16_f32 v63, v58, v59
	v_cvt_pk_bf16_f32 v40, v52, v53
	v_cvt_pk_bf16_f32 v41, v54, v55
	v_cvt_pk_bf16_f32 v42, v48, v49
	v_cvt_pk_bf16_f32 v43, v50, v51
	v_cvt_pk_bf16_f32 v24, v36, v37
	v_cvt_pk_bf16_f32 v25, v38, v39
	v_cvt_pk_bf16_f32 v26, v32, v33
	v_cvt_pk_bf16_f32 v27, v34, v35
	v_lshl_add_u64 v[12:13], v[166:167], 0, s[14:15]
	v_cvt_pk_bf16_f32 v8, v20, v21
	v_cvt_pk_bf16_f32 v9, v22, v23
	v_cvt_pk_bf16_f32 v10, v16, v17
	v_cvt_pk_bf16_f32 v11, v18, v19
	v_cvt_pk_bf16_f32 v4, v4, v5
	v_cvt_pk_bf16_f32 v5, v6, v7
	v_cvt_pk_bf16_f32 v6, v0, v1
	v_cvt_pk_bf16_f32 v7, v2, v3
	s_and_b64 vcc, exec, s[38:39]
	s_mov_b32 s49, s4
	s_mov_b32 s2, s6
	s_mov_b64 s[26:27], s[22:23]
	s_mov_b64 s[24:25], s[12:13]
	s_movk_i32 s58, 0xff60
	global_store_dwordx4 v[166:167], v[124:127], off
	global_store_dwordx4 v[108:109], v[104:107], off
	global_store_dwordx4 v[92:93], v[88:91], off
	global_store_dwordx4 v[76:77], v[72:75], off
	global_store_dwordx4 v[76:77], v[68:71], off offset:256
	global_store_dwordx4 v[56:57], v[60:63], off
	global_store_dwordx4 v[46:47], v[40:43], off
	global_store_dwordx4 v[30:31], v[24:27], off
	global_store_dwordx4 v[14:15], v[8:11], off
	global_store_dwordx4 v[12:13], v[4:7], off offset:256
	s_cbranch_vccz .LBB0_286
	s_cmpk_gt_u32 s36, 0xff
	s_cbranch_scc1 .LBB0_297
	s_barrier

; #define PG8_STAGE(bufoff, gbase, voff) do { _Pragma("unroll") for (int _i = 0; _i < 2; ++_i) \
;         __builtin_amdgcn_global_load_lds((const unsigned*)((const char*)(gbase) + (voff)[_i]), (PG8_LAS unsigned*)(lds + (bufoff) + ldsw + _i * 8192), 16, 0, 0); } while (0)
; #define PG8_LDA(dst, b, h) do { _Pragma("unroll") for (int m = 0; m < 4; ++m) _Pragma("unroll") for (int k = 0; k < 2; ++k) dst[m][k] = *(const PG8_LAS bf16x8*)(lds + PG8_SA(b, h) + aoff + m * 2048 + k * 1024); } while (0)
; #define PG8_LDB(dst, b, h) do { _Pragma("unroll") for (int n = 0; n < 2; ++n) _Pragma("unroll") for (int k = 0; k < 2; ++k) dst[n][k] = *(const PG8_LAS bf16x8*)(lds + PG8_SB(b, h) + boff + n * 2048 + k * 1024); } while (0)
; #define PG8_MMA(ai, bj, At, Bt) do { __builtin_amdgcn_s_setprio(1); _Pragma("unroll") for (int m = 0; m < 4; ++m) _Pragma("unroll") for (int n = 0; n < 2; ++n) _Pragma("unroll") for (int k = 0; k < 2; ++k) \
;         acc[ai][bj][m][n] = __builtin_amdgcn_mfma_f32_16x16x32_bf16(Bt[n][k], At[m][k], acc[ai][bj][m][n], 0, 0, 0); __builtin_amdgcn_s_setprio(0); } while (0)
; #define PG8_WAIT_L(n) asm volatile("s_waitcnt lgkmcnt(" #n ")" ::: "memory")
; #define PG8_BAR __builtin_amdgcn_s_barrier()
; #define PG8_SCHED __builtin_amdgcn_sched_barrier(0)
; template <class Epi, class Sched, bool STAMP = false>
; __device__ __forceinline__ void gemm_phase(PG8_LAS unsigned char* lds, const Gemm g, const Sched& S, const Epi& E, unsigned long long* stamps) {
;     ...
;             PG8_LDB(B0, 0, 0); PG8_SCHED; PG8_LDA(At, 0, 0); PG8_STAGE(PG8_SA(1, 1), a1 + hstep, voffA);
;             PG8_WAIT_L(8); PG8_BAR; PG8_WAIT_L(0); PG8_MMA(0, 0, At, B0); PG8_BAR; PG8_SCHED;
;             PG8_LDB(B1, 0, 1); PG8_STAGE(PG8_SB(0, 0), b2, voffB);
;             PG8_BAR; PG8_WAIT_L(0); PG8_MMA(0, 1, At, B1); PG8_BAR;
;             PG8_LDA(At, 0, 1); PG8_STAGE(PG8_SA(0, 0), a2, voffA);
;             PG8_BAR; PG8_WAIT_L(0); PG8_MMA(1, 0, At, B0); PG8_BAR; PG8_SCHED;
.LBB0_313:
	s_add_u32 s12, s4, 0xfffc0080
	s_addc_u32 s13, s5, -1
	s_add_i32 s14, 0, 0x10000
	v_add_u32_e32 v166, s14, v167
	ds_read_b128 v[158:161], v166
	ds_read_b128 v[162:165], v166 offset:1024
	ds_read_b128 v[170:173], v166 offset:2048
	ds_read_b128 v[174:177], v166 offset:3072
	s_cmp_eq_u32 s65, 12
	s_cselect_b32 s27, s31, s13
	s_cselect_b32 s26, s47, s12
	s_cselect_b32 s13, s7, s63
	s_cselect_b32 s12, s53, s62
	v_lshl_add_u64 v[182:183], s[4:5], 0, v[154:155]
	s_add_i32 m0, s3, 0xc000
	ds_read_b128 v[178:181], v169
	ds_read_b128 v[192:195], v169 offset:1024
	ds_read_b128 v[196:199], v169 offset:2048
	ds_read_b128 v[200:203], v169 offset:3072
	ds_read_b128 v[204:207], v169 offset:4096
	ds_read_b128 v[208:211], v169 offset:5120
	ds_read_b128 v[212:215], v169 offset:6144
	ds_read_b128 v[216:219], v169 offset:7168
	global_load_lds_dwordx4 v[182:183], off
	v_lshl_add_u64 v[182:183], s[4:5], 0, v[156:157]
	s_add_i32 m0, s3, 0xe000
	s_nop 0
	global_load_lds_dwordx4 v[182:183], off
	s_waitcnt lgkmcnt(8)
	s_barrier
	s_waitcnt lgkmcnt(0)
	s_waitcnt lgkmcnt(0)
	v_mfma_f32_16x16x32_bf16 v[124:127], v[158:161], v[178:181], v[124:127]
	v_mfma_f32_16x16x32_bf16 v[120:123], v[170:173], v[178:181], v[120:123]
	v_mfma_f32_16x16x32_bf16 v[108:111], v[158:161], v[196:199], v[108:111]
	v_mfma_f32_16x16x32_bf16 v[104:107], v[170:173], v[196:199], v[104:107]
	v_mfma_f32_16x16x32_bf16 v[92:95], v[158:161], v[204:207], v[92:95]
	v_mfma_f32_16x16x32_bf16 v[88:91], v[170:173], v[204:207], v[88:91]
	v_mfma_f32_16x16x32_bf16 v[76:79], v[158:161], v[212:215], v[76:79]
	v_mfma_f32_16x16x32_bf16 v[72:75], v[170:173], v[212:215], v[72:75]
	v_mfma_f32_16x16x32_bf16 v[124:127], v[162:165], v[192:195], v[124:127]
	v_mfma_f32_16x16x32_bf16 v[120:123], v[174:177], v[192:195], v[120:123]
	v_mfma_f32_16x16x32_bf16 v[108:111], v[162:165], v[200:203], v[108:111]
	v_mfma_f32_16x16x32_bf16 v[104:107], v[174:177], v[200:203], v[104:107]
	v_mfma_f32_16x16x32_bf16 v[92:95], v[162:165], v[208:211], v[92:95]
	v_mfma_f32_16x16x32_bf16 v[88:91], v[174:177], v[208:211], v[88:91]
	v_mfma_f32_16x16x32_bf16 v[76:79], v[162:165], v[216:219], v[76:79]
	v_mfma_f32_16x16x32_bf16 v[72:75], v[174:177], v[216:219], v[72:75]
	s_barrier
	s_add_i32 s16, 0, 0x14000
	s_add_i32 s14, s14, s56
	v_add_u32_e32 v166, s16, v167
	v_lshl_add_u64 v[182:183], s[12:13], 0, v[128:129]
	s_mov_b32 m0, s14
	ds_read_b128 v[220:223], v166
	ds_read_b128 v[224:227], v166 offset:1024
	ds_read_b128 v[228:231], v166 offset:2048
	ds_read_b128 v[232:235], v166 offset:3072
	global_load_lds_dwordx4 v[182:183], off
	v_lshl_add_u64 v[236:237], s[12:13], 0, v[152:153]
	s_add_i32 m0, s14, 0x2000
	s_nop 0
	global_load_lds_dwordx4 v[236:237], off
	s_barrier
	s_waitcnt lgkmcnt(0)
	s_waitcnt lgkmcnt(0)
	v_mfma_f32_16x16x32_bf16 v[116:119], v[220:223], v[178:181], v[116:119]
	v_mfma_f32_16x16x32_bf16 v[112:115], v[228:231], v[178:181], v[112:115]
	v_mfma_f32_16x16x32_bf16 v[100:103], v[220:223], v[196:199], v[100:103]
	v_mfma_f32_16x16x32_bf16 v[96:99], v[228:231], v[196:199], v[96:99]
	v_mfma_f32_16x16x32_bf16 v[84:87], v[220:223], v[204:207], v[84:87]
	v_mfma_f32_16x16x32_bf16 v[80:83], v[228:231], v[204:207], v[80:83]
	v_mfma_f32_16x16x32_bf16 v[68:71], v[220:223], v[212:215], v[68:71]
	v_mfma_f32_16x16x32_bf16 v[64:67], v[228:231], v[212:215], v[64:67]
	v_mfma_f32_16x16x32_bf16 v[116:119], v[224:227], v[192:195], v[116:119]
	v_mfma_f32_16x16x32_bf16 v[112:115], v[232:235], v[192:195], v[112:115]
	v_mfma_f32_16x16x32_bf16 v[100:103], v[224:227], v[200:203], v[100:103]
	v_mfma_f32_16x16x32_bf16 v[96:99], v[232:235], v[200:203], v[96:99]
	v_mfma_f32_16x16x32_bf16 v[84:87], v[224:227], v[208:211], v[84:87]
	v_mfma_f32_16x16x32_bf16 v[80:83], v[232:235], v[208:211], v[80:83]
	v_mfma_f32_16x16x32_bf16 v[68:71], v[224:227], v[216:219], v[68:71]
	v_mfma_f32_16x16x32_bf16 v[64:67], v[232:235], v[216:219], v[64:67]
	s_mov_b32 m0, s3
	v_lshl_add_u64 v[238:239], s[26:27], 0, v[148:149]
	s_barrier
	ds_read_b128 v[178:181], v169 offset:16384
	ds_read_b128 v[192:195], v169 offset:17408
	ds_read_b128 v[196:199], v169 offset:18432
	ds_read_b128 v[200:203], v169 offset:19456
	ds_read_b128 v[204:207], v169 offset:20480
	ds_read_b128 v[208:211], v169 offset:21504
	ds_read_b128 v[212:215], v169 offset:22528
	ds_read_b128 v[216:219], v169 offset:23552
	global_load_lds_dwordx4 v[238:239], off
	v_lshl_add_u64 v[240:241], s[26:27], 0, v[150:151]
	s_mov_b32 m0, s57
	s_nop 0
	global_load_lds_dwordx4 v[240:241], off
	s_barrier
	s_waitcnt lgkmcnt(0)
	s_waitcnt lgkmcnt(0)
	v_mfma_f32_16x16x32_bf16 v[60:63], v[158:161], v[178:181], v[60:63]
	v_mfma_f32_16x16x32_bf16 v[56:59], v[170:173], v[178:181], v[56:59]
	v_mfma_f32_16x16x32_bf16 v[44:47], v[158:161], v[196:199], v[44:47]
	v_mfma_f32_16x16x32_bf16 v[40:43], v[170:173], v[196:199], v[40:43]
	v_mfma_f32_16x16x32_bf16 v[28:31], v[158:161], v[204:207], v[28:31]
	v_mfma_f32_16x16x32_bf16 v[24:27], v[170:173], v[204:207], v[24:27]
	v_mfma_f32_16x16x32_bf16 v[12:15], v[158:161], v[212:215], v[12:15]
	v_mfma_f32_16x16x32_bf16 v[8:11], v[170:173], v[212:215], v[8:11]
	v_mfma_f32_16x16x32_bf16 v[60:63], v[162:165], v[192:195], v[60:63]
	v_mfma_f32_16x16x32_bf16 v[56:59], v[174:177], v[192:195], v[56:59]
	v_mfma_f32_16x16x32_bf16 v[44:47], v[162:165], v[200:203], v[44:47]
	v_mfma_f32_16x16x32_bf16 v[40:43], v[174:177], v[200:203], v[40:43]
	v_mfma_f32_16x16x32_bf16 v[28:31], v[162:165], v[208:211], v[28:31]
	v_mfma_f32_16x16x32_bf16 v[24:27], v[174:177], v[208:211], v[24:27]
	v_mfma_f32_16x16x32_bf16 v[12:15], v[162:165], v[216:219], v[12:15]
	v_mfma_f32_16x16x32_bf16 v[8:11], v[174:177], v[216:219], v[8:11]
	s_barrier
; #define PG8_STAGE(bufoff, gbase, voff) do { _Pragma("unroll") for (int _i = 0; _i < 2; ++_i) \
;         __builtin_amdgcn_global_load_lds((const unsigned*)((const char*)(gbase) + (voff)[_i]), (PG8_LAS unsigned*)(lds + (bufoff) + ldsw + _i * 8192), 16, 0, 0); } while (0)
; #define PG8_LDA(dst, b, h) do { _Pragma("unroll") for (int m = 0; m < 4; ++m) _Pragma("unroll") for (int k = 0; k < 2; ++k) dst[m][k] = *(const PG8_LAS bf16x8*)(lds + PG8_SA(b, h) + aoff + m * 2048 + k * 1024); } while (0)
; #define PG8_LDB(dst, b, h) do { _Pragma("unroll") for (int n = 0; n < 2; ++n) _Pragma("unroll") for (int k = 0; k < 2; ++k) dst[n][k] = *(const PG8_LAS bf16x8*)(lds + PG8_SB(b, h) + boff + n * 2048 + k * 1024); } while (0)
; #define PG8_MMA(ai, bj, At, Bt) do { __builtin_amdgcn_s_setprio(1); _Pragma("unroll") for (int m = 0; m < 4; ++m) _Pragma("unroll") for (int n = 0; n < 2; ++n) _Pragma("unroll") for (int k = 0; k < 2; ++k) \
;         acc[ai][bj][m][n] = __builtin_amdgcn_mfma_f32_16x16x32_bf16(Bt[n][k], At[m][k], acc[ai][bj][m][n], 0, 0, 0); __builtin_amdgcn_s_setprio(0); } while (0)
; #define PG8_WAIT_V(n) asm volatile("s_waitcnt vmcnt(" #n ")" ::: "memory")
; #define PG8_WAIT_L(n) asm volatile("s_waitcnt lgkmcnt(" #n ")" ::: "memory")
; #define PG8_BAR __builtin_amdgcn_s_barrier()
; #define PG8_SCHED __builtin_amdgcn_sched_barrier(0)
; template <class Epi, class Sched, bool STAMP = false>
; __device__ __forceinline__ void gemm_phase(PG8_LAS unsigned char* lds, const Gemm g, const Sched& S, const Epi& E, unsigned long long* stamps) {
;     ...
;             PG8_STAGE(PG8_SB(0, 1), b2 + hstep, voffB);
;             PG8_WAIT_V(6); PG8_BAR; PG8_MMA(1, 1, At, B1); PG8_BAR;
;             PG8_LDB(B0, 1, 0); PG8_SCHED; PG8_LDA(At, 1, 0); PG8_STAGE(PG8_SA(0, 1), a2 + hstep, voffA);
;             PG8_WAIT_L(8); PG8_BAR; PG8_WAIT_L(0); PG8_MMA(0, 0, At, B0); PG8_BAR; PG8_SCHED;
;             PG8_LDB(B1, 1, 1); PG8_STAGE(PG8_SB(1, 0), b3, voffB);
;             PG8_BAR; PG8_WAIT_L(0); PG8_MMA(0, 1, At, B1); PG8_BAR;
;             PG8_LDA(At, 1, 1); PG8_STAGE(PG8_SA(1, 0), a3, voffA);
;             PG8_BAR; PG8_WAIT_L(0); PG8_MMA(1, 0, At, B0); PG8_BAR; PG8_SCHED;
	s_add_u32 s14, s12, 0x40000
	s_addc_u32 s15, s13, 0
	s_add_i32 s16, s16, s56
	v_lshl_add_u64 v[158:159], s[14:15], 0, v[128:129]
	s_mov_b32 m0, s16
	s_nop 0
	global_load_lds_dwordx4 v[158:159], off
	v_lshl_add_u64 v[158:159], s[14:15], 0, v[152:153]
	s_add_i32 m0, s16, 0x2000
	s_nop 0
	global_load_lds_dwordx4 v[158:159], off
	s_waitcnt vmcnt(6)
	s_barrier
	v_mfma_f32_16x16x32_bf16 v[52:55], v[220:223], v[178:181], v[52:55]
	v_mfma_f32_16x16x32_bf16 v[48:51], v[228:231], v[178:181], v[48:51]
	v_mfma_f32_16x16x32_bf16 v[36:39], v[220:223], v[196:199], v[36:39]
	v_mfma_f32_16x16x32_bf16 v[32:35], v[228:231], v[196:199], v[32:35]
	v_mfma_f32_16x16x32_bf16 v[20:23], v[220:223], v[204:207], v[20:23]
	v_mfma_f32_16x16x32_bf16 v[16:19], v[228:231], v[204:207], v[16:19]
	v_mfma_f32_16x16x32_bf16 v[4:7], v[220:223], v[212:215], v[4:7]
	v_mfma_f32_16x16x32_bf16 v[0:3], v[228:231], v[212:215], v[0:3]
	v_mfma_f32_16x16x32_bf16 v[52:55], v[224:227], v[192:195], v[52:55]
	v_mfma_f32_16x16x32_bf16 v[48:51], v[232:235], v[192:195], v[48:51]
	v_mfma_f32_16x16x32_bf16 v[36:39], v[224:227], v[200:203], v[36:39]
	v_mfma_f32_16x16x32_bf16 v[32:35], v[232:235], v[200:203], v[32:35]
	v_mfma_f32_16x16x32_bf16 v[20:23], v[224:227], v[208:211], v[20:23]
	v_mfma_f32_16x16x32_bf16 v[16:19], v[232:235], v[208:211], v[16:19]
	v_mfma_f32_16x16x32_bf16 v[4:7], v[224:227], v[216:219], v[4:7]
	v_mfma_f32_16x16x32_bf16 v[0:3], v[232:235], v[216:219], v[0:3]
	s_add_i32 s16, 0, 0x18000
	v_add_u32_e32 v166, s16, v167
	s_barrier
	ds_read_b128 v[158:161], v166
	ds_read_b128 v[162:165], v166 offset:1024
	ds_read_b128 v[170:173], v166 offset:2048
	ds_read_b128 v[174:177], v166 offset:3072
	s_add_u32 s14, s26, 0x40000
	s_addc_u32 s15, s27, 0
	s_mov_b32 m0, s58
	v_lshl_add_u64 v[220:221], s[14:15], 0, v[148:149]
	ds_read_b128 v[178:181], v169 offset:32768
	ds_read_b128 v[192:195], v169 offset:33792
	ds_read_b128 v[196:199], v169 offset:34816
	ds_read_b128 v[200:203], v169 offset:35840
	ds_read_b128 v[204:207], v169 offset:36864
	ds_read_b128 v[208:211], v169 offset:37888
	ds_read_b128 v[212:215], v169 offset:38912
	ds_read_b128 v[216:219], v169 offset:39936
	global_load_lds_dwordx4 v[220:221], off
	v_lshl_add_u64 v[220:221], s[14:15], 0, v[150:151]
	s_mov_b32 m0, s59
	s_nop 0
	global_load_lds_dwordx4 v[220:221], off
	s_waitcnt lgkmcnt(8)
	s_barrier
	s_waitcnt lgkmcnt(0)
	s_waitcnt lgkmcnt(0)
	v_mfma_f32_16x16x32_bf16 v[124:127], v[158:161], v[178:181], v[124:127]
	v_mfma_f32_16x16x32_bf16 v[120:123], v[170:173], v[178:181], v[120:123]
	v_mfma_f32_16x16x32_bf16 v[108:111], v[158:161], v[196:199], v[108:111]
	v_mfma_f32_16x16x32_bf16 v[104:107], v[170:173], v[196:199], v[104:107]
	v_mfma_f32_16x16x32_bf16 v[92:95], v[158:161], v[204:207], v[92:95]
	v_mfma_f32_16x16x32_bf16 v[88:91], v[170:173], v[204:207], v[88:91]
	v_mfma_f32_16x16x32_bf16 v[76:79], v[158:161], v[212:215], v[76:79]
	v_mfma_f32_16x16x32_bf16 v[72:75], v[170:173], v[212:215], v[72:75]
	v_mfma_f32_16x16x32_bf16 v[124:127], v[162:165], v[192:195], v[124:127]
	v_mfma_f32_16x16x32_bf16 v[120:123], v[174:177], v[192:195], v[120:123]
	v_mfma_f32_16x16x32_bf16 v[108:111], v[162:165], v[200:203], v[108:111]
	v_mfma_f32_16x16x32_bf16 v[104:107], v[174:177], v[200:203], v[104:107]
	v_mfma_f32_16x16x32_bf16 v[92:95], v[162:165], v[208:211], v[92:95]
	v_mfma_f32_16x16x32_bf16 v[88:91], v[174:177], v[208:211], v[88:91]
	v_mfma_f32_16x16x32_bf16 v[76:79], v[162:165], v[216:219], v[76:79]
	v_mfma_f32_16x16x32_bf16 v[72:75], v[174:177], v[216:219], v[72:75]
	s_barrier
	s_add_i32 s14, 0, 0x1c000
	s_add_i32 s15, s16, s56
	v_add_u32_e32 v166, s14, v167
	v_lshl_add_u64 v[182:183], v[182:183], 0, s[18:19]
	s_mov_b32 m0, s15
	ds_read_b128 v[220:223], v166
	ds_read_b128 v[224:227], v166 offset:1024
	ds_read_b128 v[228:231], v166 offset:2048
	ds_read_b128 v[232:235], v166 offset:3072
	global_load_lds_dwordx4 v[182:183], off
	v_lshl_add_u64 v[182:183], v[236:237], 0, s[18:19]
	s_add_i32 m0, s15, 0x2000
	s_nop 0
	global_load_lds_dwordx4 v[182:183], off
	s_barrier
	s_waitcnt lgkmcnt(0)
	s_waitcnt lgkmcnt(0)
	v_mfma_f32_16x16x32_bf16 v[116:119], v[220:223], v[178:181], v[116:119]
	v_mfma_f32_16x16x32_bf16 v[112:115], v[228:231], v[178:181], v[112:115]
	v_mfma_f32_16x16x32_bf16 v[100:103], v[220:223], v[196:199], v[100:103]
	v_mfma_f32_16x16x32_bf16 v[96:99], v[228:231], v[196:199], v[96:99]
	v_mfma_f32_16x16x32_bf16 v[84:87], v[220:223], v[204:207], v[84:87]
	v_mfma_f32_16x16x32_bf16 v[80:83], v[228:231], v[204:207], v[80:83]
	v_mfma_f32_16x16x32_bf16 v[68:71], v[220:223], v[212:215], v[68:71]
	v_mfma_f32_16x16x32_bf16 v[64:67], v[228:231], v[212:215], v[64:67]
	v_mfma_f32_16x16x32_bf16 v[116:119], v[224:227], v[192:195], v[116:119]
	v_mfma_f32_16x16x32_bf16 v[112:115], v[232:235], v[192:195], v[112:115]
	v_mfma_f32_16x16x32_bf16 v[100:103], v[224:227], v[200:203], v[100:103]
	v_mfma_f32_16x16x32_bf16 v[96:99], v[232:235], v[200:203], v[96:99]
	v_mfma_f32_16x16x32_bf16 v[84:87], v[224:227], v[208:211], v[84:87]
	v_mfma_f32_16x16x32_bf16 v[80:83], v[232:235], v[208:211], v[80:83]
	v_mfma_f32_16x16x32_bf16 v[68:71], v[224:227], v[216:219], v[68:71]
	v_mfma_f32_16x16x32_bf16 v[64:67], v[232:235], v[216:219], v[64:67]
	s_mov_b32 m0, s60
	v_lshl_add_u64 v[182:183], v[238:239], 0, s[18:19]
	s_barrier
	ds_read_b128 v[178:181], v169 offset:49152
	ds_read_b128 v[192:195], v169 offset:50176
	ds_read_b128 v[196:199], v169 offset:51200
	ds_read_b128 v[200:203], v169 offset:52224
	ds_read_b128 v[204:207], v169 offset:53248
	ds_read_b128 v[208:211], v169 offset:54272
	ds_read_b128 v[212:215], v169 offset:55296
	ds_read_b128 v[216:219], v169 offset:56320
	global_load_lds_dwordx4 v[182:183], off
	v_lshl_add_u64 v[182:183], v[240:241], 0, s[18:19]
	s_mov_b32 m0, s61
	s_nop 0
	global_load_lds_dwordx4 v[182:183], off
	s_barrier
; #define PG8_STAGE(bufoff, gbase, voff) do { _Pragma("unroll") for (int _i = 0; _i < 2; ++_i) \
;         __builtin_amdgcn_global_load_lds((const unsigned*)((const char*)(gbase) + (voff)[_i]), (PG8_LAS unsigned*)(lds + (bufoff) + ldsw + _i * 8192), 16, 0, 0); } while (0)
; #define PG8_MMA(ai, bj, At, Bt) do { __builtin_amdgcn_s_setprio(1); _Pragma("unroll") for (int m = 0; m < 4; ++m) _Pragma("unroll") for (int n = 0; n < 2; ++n) _Pragma("unroll") for (int k = 0; k < 2; ++k) \
;         acc[ai][bj][m][n] = __builtin_amdgcn_mfma_f32_16x16x32_bf16(Bt[n][k], At[m][k], acc[ai][bj][m][n], 0, 0, 0); __builtin_amdgcn_s_setprio(0); } while (0)
; #define PG8_WAIT_V(n) asm volatile("s_waitcnt vmcnt(" #n ")" ::: "memory")
; #define PG8_WAIT_L(n) asm volatile("s_waitcnt lgkmcnt(" #n ")" ::: "memory")
; #define PG8_BAR __builtin_amdgcn_s_barrier()
; #define PG8_SCHED __builtin_amdgcn_sched_barrier(0)
; __device__ __forceinline__ float rstd_of(const float* rowss, int row) { return rsqrtf(rowss[row] * (1.0f / 1024.0f) + 1e-6f); }
; template <class Epi, class Sched, bool STAMP = false>
; __device__ __forceinline__ void gemm_phase(PG8_LAS unsigned char* lds, const Gemm g, const Sched& S, const Epi& E, unsigned long long* stamps) {
;     ...
;             PG8_BAR; PG8_WAIT_L(0); PG8_MMA(1, 0, At, B0); PG8_BAR; PG8_SCHED;
;             PG8_STAGE(PG8_SB(1, 1), b3 + hstep, voffB);
;             PG8_WAIT_V(6); PG8_BAR; PG8_MMA(1, 1, At, B1); PG8_BAR;
;     __device__ __forceinline__ void operator()(const f32x4 (&acc)[2][2][4][2], const pg8::Unit& u, int wr, int wc, int fr, int fq) const {
;         const int row0 = u.pm * 256 + wr * 64 + fr, col0 = u.pn * 256 + wc * 32 + 8 * fq;
; #pragma unroll
;         for (int ai = 0; ai < 2; ++ai)
; #pragma unroll
;             for (int m = 0; m < 4; ++m) {
;                 const int row = row0 + ai * 128 + m * 16;
;                 const float s = rstd_of(rowss, row);
; #pragma unroll
;                 for (int bj = 0; bj < 2; ++bj) {
;                     const size_t off = (size_t)row * 1024 + col0 + bj * 128;
;                     const u32x4 tv = *(const u32x4*)(Tm + off);
;                     u32x4 pv = (u32x4){0u, 0u, 0u, 0u};
;                     if (ACC) pv = *(const u32x4*)(M + off);
	s_waitcnt lgkmcnt(0)
	s_waitcnt lgkmcnt(0)
	v_mfma_f32_16x16x32_bf16 v[60:63], v[158:161], v[178:181], v[60:63]
	v_mfma_f32_16x16x32_bf16 v[56:59], v[170:173], v[178:181], v[56:59]
	v_mfma_f32_16x16x32_bf16 v[44:47], v[158:161], v[196:199], v[44:47]
	v_mfma_f32_16x16x32_bf16 v[40:43], v[170:173], v[196:199], v[40:43]
	v_mfma_f32_16x16x32_bf16 v[28:31], v[158:161], v[204:207], v[28:31]
	v_mfma_f32_16x16x32_bf16 v[24:27], v[170:173], v[204:207], v[24:27]
	v_mfma_f32_16x16x32_bf16 v[12:15], v[158:161], v[212:215], v[12:15]
	v_mfma_f32_16x16x32_bf16 v[8:11], v[170:173], v[212:215], v[8:11]
	v_mfma_f32_16x16x32_bf16 v[60:63], v[162:165], v[192:195], v[60:63]
	v_mfma_f32_16x16x32_bf16 v[56:59], v[174:177], v[192:195], v[56:59]
	v_mfma_f32_16x16x32_bf16 v[44:47], v[162:165], v[200:203], v[44:47]
	v_mfma_f32_16x16x32_bf16 v[40:43], v[174:177], v[200:203], v[40:43]
	v_mfma_f32_16x16x32_bf16 v[28:31], v[162:165], v[208:211], v[28:31]
	v_mfma_f32_16x16x32_bf16 v[24:27], v[174:177], v[208:211], v[24:27]
	v_mfma_f32_16x16x32_bf16 v[12:15], v[162:165], v[216:219], v[12:15]
	v_mfma_f32_16x16x32_bf16 v[8:11], v[174:177], v[216:219], v[8:11]
	s_barrier
	s_add_u32 s12, s12, 0x40080
	s_addc_u32 s13, s13, 0
	s_add_i32 s14, s14, s56
	v_lshl_add_u64 v[158:159], s[12:13], 0, v[128:129]
	s_mov_b32 m0, s14
	s_nop 0
	global_load_lds_dwordx4 v[158:159], off
	v_lshl_add_u64 v[158:159], s[12:13], 0, v[152:153]
	s_add_i32 m0, s14, 0x2000
	s_nop 0
	global_load_lds_dwordx4 v[158:159], off
	s_waitcnt vmcnt(6)
	s_barrier
	v_mfma_f32_16x16x32_bf16 v[52:55], v[220:223], v[178:181], v[52:55]
	v_mfma_f32_16x16x32_bf16 v[48:51], v[228:231], v[178:181], v[48:51]
	v_mfma_f32_16x16x32_bf16 v[36:39], v[220:223], v[196:199], v[36:39]
	v_mfma_f32_16x16x32_bf16 v[32:35], v[228:231], v[196:199], v[32:35]
	v_mfma_f32_16x16x32_bf16 v[20:23], v[220:223], v[204:207], v[20:23]
	v_mfma_f32_16x16x32_bf16 v[16:19], v[228:231], v[204:207], v[16:19]
	v_mfma_f32_16x16x32_bf16 v[4:7], v[220:223], v[212:215], v[4:7]
	v_mfma_f32_16x16x32_bf16 v[0:3], v[228:231], v[212:215], v[0:3]
	v_mfma_f32_16x16x32_bf16 v[52:55], v[224:227], v[192:195], v[52:55]
	v_mfma_f32_16x16x32_bf16 v[48:51], v[232:235], v[192:195], v[48:51]
	v_mfma_f32_16x16x32_bf16 v[36:39], v[224:227], v[200:203], v[36:39]
	v_mfma_f32_16x16x32_bf16 v[32:35], v[232:235], v[200:203], v[32:35]
	v_mfma_f32_16x16x32_bf16 v[20:23], v[224:227], v[208:211], v[20:23]
	v_mfma_f32_16x16x32_bf16 v[16:19], v[232:235], v[208:211], v[16:19]
	v_mfma_f32_16x16x32_bf16 v[4:7], v[224:227], v[216:219], v[4:7]
	v_mfma_f32_16x16x32_bf16 v[0:3], v[232:235], v[216:219], v[0:3]
	s_add_i32 s65, s65, 2
	s_add_u32 s4, s4, 0x100
	s_addc_u32 s5, s5, 0
	s_add_u32 s62, s62, 0x100
	s_addc_u32 s63, s63, 0
	s_cmp_gt_u32 s65, 13
	s_barrier
	s_cbranch_scc0 .LBB0_313
	v_lshl_add_u32 v162, s2, 8, v139
	v_ashrrev_i32_e32 v163, 31, v162
	v_lshl_add_u64 v[160:161], v[162:163], 2, s[40:41]
	global_load_dword v164, v[160:161], off
	v_lshl_or_b32 v158, s46, 8, v168
	v_ashrrev_i32_e32 v159, 31, v158
	s_mov_b32 s2, 0x40000
	s_mov_b64 s[4:5], 0x40000
	s_mov_b32 s46, s6
	s_mov_b64 s[12:13], s[24:25]
	s_mov_b32 s62, 0x1800000
	s_waitcnt vmcnt(0)
	v_fmamk_f32 v164, v164, 0x3a800000, v187
	v_cmp_gt_f32_e32 vcc, s67, v164
	v_mul_f32_e32 v165, 0x4b800000, v164
	s_nop 0
	v_cndmask_b32_e32 v164, v164, v165, vcc
	v_rsq_f32_e32 v164, v164
	s_nop 0
	v_mul_f32_e32 v165, 0x45800000, v164
	v_cndmask_b32_e32 v166, v164, v165, vcc
	v_lshlrev_b64 v[164:165], 11, v[162:163]
	v_lshl_add_u64 v[170:171], s[0:1], 0, v[164:165]
	v_lshlrev_b64 v[164:165], 1, v[158:159]
	v_lshl_add_u64 v[158:159], v[170:171], 0, v[164:165]
	v_mov_b32_e32 v170, v158
	v_mov_b32_e32 v171, v159
	global_load_dwordx4 v[192:195], v[170:171], off
	global_load_dwordx4 v[196:199], v[170:171], off offset:256
	v_add_co_u32_e32 v170, vcc, 0x8000, v170
	s_nop 1
	v_addc_co_u32_e32 v171, vcc, 0, v171, vcc
	global_load_dwordx4 v[200:203], v[170:171], off
	global_load_dwordx4 v[204:207], v[170:171], off offset:256
	v_add_co_u32_e32 v170, vcc, 0x8000, v170
	s_nop 1
	v_addc_co_u32_e32 v171, vcc, 0, v171, vcc
	global_load_dwordx4 v[208:211], v[170:171], off
	global_load_dwordx4 v[212:215], v[170:171], off offset:256
	v_add_co_u32_e32 v170, vcc, 0x8000, v170
	s_nop 1
	v_addc_co_u32_e32 v171, vcc, 0, v171, vcc
	global_load_dwordx4 v[216:219], v[170:171], off
	global_load_dwordx4 v[220:223], v[170:171], off offset:256
	v_lshl_add_u64 v[170:171], v[158:159], 0, s[4:5]
	global_load_dwordx4 v[224:227], v[170:171], off
	global_load_dwordx4 v[228:231], v[170:171], off offset:256
	v_add_co_u32_e32 v170, vcc, 0x8000, v170
	s_nop 1
	v_addc_co_u32_e32 v171, vcc, 0, v171, vcc
	global_load_dwordx4 v[232:235], v[170:171], off
	global_load_dwordx4 v[236:239], v[170:171], off offset:256
	v_add_co_u32_e32 v170, vcc, 0x8000, v170
	s_nop 1
	v_addc_co_u32_e32 v171, vcc, 0, v171, vcc
	global_load_dwordx4 v[244:247], v[170:171], off
	global_load_dwordx4 v[248:251], v[170:171], off offset:256
	v_add_co_u32_e32 v170, vcc, 0x8000, v170
	s_nop 1
	v_addc_co_u32_e32 v171, vcc, 0, v171, vcc
	global_load_dwordx4 v[176:179], v[170:171], off
	global_load_dwordx4 v[252:255], v[170:171], off offset:256
	global_load_dword v180, v[160:161], off offset:64
	global_load_dword v181, v[160:161], off offset:128
	global_load_dword v182, v[160:161], off offset:192
	global_load_dword v183, v[160:161], off offset:512
	global_load_dword v240, v[160:161], off offset:576
	global_load_dword v241, v[160:161], off offset:640
	global_load_dword v169, v[160:161], off offset:704
	v_pk_mul_f32 v[126:127], v[126:127], v[166:167] op_sel_hi:[1,0]
	v_pk_mul_f32 v[120:121], v[120:121], v[166:167] op_sel_hi:[1,0]
; __device__ __forceinline__ unsigned cvt_pk_bf16(float lo, float hi) { const f32x2_cv v = {lo, hi}; const bf16x2_cv b = __builtin_convertvector(v, bf16x2_cv); return __builtin_bit_cast(unsigned, b); }
; __device__ __forceinline__ float sigm(float x) { return __builtin_amdgcn_rcpf(1.0f + __expf(-x)); }
; __device__ __forceinline__ float lo16(unsigned w) { return __uint_as_float(w << 16); }
; __device__ __forceinline__ float hi16(unsigned w) { return __uint_as_float(w & 0xffff0000u); }
; __device__ __forceinline__ float rstd_of(const float* rowss, int row) { return rsqrtf(rowss[row] * (1.0f / 1024.0f) + 1e-6f); }
;     __device__ __forceinline__ void operator()(const f32x4 (&acc)[2][2][4][2], const pg8::Unit& u, int wr, int wc, int fr, int fq) const {
;     ...
;                 const int row = row0 + ai * 128 + m * 16;
;                 const float s = rstd_of(rowss, row);
; #pragma unroll
;                 for (int bj = 0; bj < 2; ++bj) {
;                     const size_t off = (size_t)row * 1024 + col0 + bj * 128;
;                     const u32x4 tv = *(const u32x4*)(Tm + off);
;                     u32x4 pv = (u32x4){0u, 0u, 0u, 0u};
;                     if (ACC) pv = *(const u32x4*)(M + off);
;                     const f32x4 a0 = acc[ai][bj][m][0] * s, a1 = acc[ai][bj][m][1] * s;
;                     float o[8];
;                     o[0] = sigm(a0[0]) * lo16(tv.x); o[1] = sigm(a0[1]) * hi16(tv.x); o[2] = sigm(a0[2]) * lo16(tv.y); o[3] = sigm(a0[3]) * hi16(tv.y);
;                     o[4] = sigm(a1[0]) * lo16(tv.z); o[5] = sigm(a1[1]) * hi16(tv.z); o[6] = sigm(a1[2]) * lo16(tv.w); o[7] = sigm(a1[3]) * hi16(tv.w);
;                     if (ACC) { o[0] += lo16(pv.x); o[1] += hi16(pv.x); o[2] += lo16(pv.y); o[3] += hi16(pv.y); o[4] += lo16(pv.z); o[5] += hi16(pv.z); o[6] += lo16(pv.w); o[7] += hi16(pv.w); }
;                     u32x4 w; w.x = cvt_pk_bf16(o[0], o[1]); w.y = cvt_pk_bf16(o[2], o[3]); w.z = cvt_pk_bf16(o[4], o[5]); w.w = cvt_pk_bf16(o[6], o[7]);
;                     *(u32x4*)(M + off) = w; } }
	v_mul_f32_e32 v126, 0xbfb8aa3b, v126
	v_mul_f32_e32 v127, 0xbfb8aa3b, v127
	v_exp_f32_e32 v126, v126
	v_exp_f32_e32 v127, v127
	v_mul_f32_e32 v120, 0xbfb8aa3b, v120
	v_mul_f32_e32 v121, 0xbfb8aa3b, v121
	v_exp_f32_e32 v120, v120
	v_exp_f32_e32 v121, v121
	v_add_f32_e32 v126, 1.0, v126
	v_add_f32_e32 v127, 1.0, v127
	v_rcp_f32_e32 v126, v126
	v_rcp_f32_e32 v127, v127
	v_add_f32_e32 v120, 1.0, v120
	v_add_f32_e32 v121, 1.0, v121
	v_rcp_f32_e32 v120, v120
	v_rcp_f32_e32 v121, v121
	v_pk_mul_f32 v[124:125], v[124:125], v[166:167] op_sel_hi:[1,0]
	v_pk_mul_f32 v[122:123], v[122:123], v[166:167] op_sel_hi:[1,0]
	v_mul_f32_e32 v124, 0xbfb8aa3b, v124
	v_mul_f32_e32 v125, 0xbfb8aa3b, v125
	v_exp_f32_e32 v124, v124
	v_exp_f32_e32 v125, v125
	v_pk_mul_f32 v[118:119], v[118:119], v[166:167] op_sel_hi:[1,0]
	v_pk_mul_f32 v[112:113], v[112:113], v[166:167] op_sel_hi:[1,0]
	v_add_f32_e32 v124, 1.0, v124
	v_add_f32_e32 v125, 1.0, v125
	v_rcp_f32_e32 v124, v124
	v_rcp_f32_e32 v125, v125
	v_mul_f32_e32 v118, 0xbfb8aa3b, v118
	v_mul_f32_e32 v119, 0xbfb8aa3b, v119
	v_exp_f32_e32 v118, v118
	v_exp_f32_e32 v119, v119
	v_mul_f32_e32 v112, 0xbfb8aa3b, v112
	v_mul_f32_e32 v113, 0xbfb8aa3b, v113
	v_exp_f32_e32 v112, v112
	v_exp_f32_e32 v113, v113
	v_add_f32_e32 v118, 1.0, v118
	v_add_f32_e32 v119, 1.0, v119
	v_rcp_f32_e32 v118, v118
	v_rcp_f32_e32 v119, v119
	v_add_f32_e32 v112, 1.0, v112
	v_add_f32_e32 v113, 1.0, v113
	v_rcp_f32_e32 v112, v112
	v_rcp_f32_e32 v113, v113
	v_pk_mul_f32 v[116:117], v[116:117], v[166:167] op_sel_hi:[1,0]
	v_pk_mul_f32 v[114:115], v[114:115], v[166:167] op_sel_hi:[1,0]
	v_mul_f32_e32 v116, 0xbfb8aa3b, v116
	v_mul_f32_e32 v117, 0xbfb8aa3b, v117
	v_exp_f32_e32 v116, v116
	v_exp_f32_e32 v117, v117
	v_add_f32_e32 v116, 1.0, v116
	v_add_f32_e32 v117, 1.0, v117
	v_rcp_f32_e32 v116, v116
	v_rcp_f32_e32 v117, v117
	s_waitcnt vmcnt(0)
	v_mov_b32_e32 v170, v192
	v_mov_b32_e32 v171, v193
	v_mov_b32_e32 v172, v194
	v_mov_b32_e32 v173, v195
	v_lshlrev_b32_e32 v174, 16, v170
	v_and_b32_e32 v175, 0xffff0000, v170
	v_lshlrev_b32_e32 v170, 16, v171
	v_and_b32_e32 v171, 0xffff0000, v171
	v_pk_mul_f32 v[126:127], v[126:127], v[170:171]
	v_lshlrev_b32_e32 v170, 16, v172
	v_and_b32_e32 v171, 0xffff0000, v172
	v_pk_mul_f32 v[170:171], v[120:121], v[170:171]
	v_mul_f32_e32 v120, 0xbfb8aa3b, v122
	v_mul_f32_e32 v121, 0xbfb8aa3b, v123
	v_exp_f32_e32 v120, v120
	v_exp_f32_e32 v121, v121
	v_lshlrev_b32_e32 v122, 16, v173
	v_and_b32_e32 v123, 0xffff0000, v173
	v_add_f32_e32 v120, 1.0, v120
	v_add_f32_e32 v121, 1.0, v121
	v_rcp_f32_e32 v120, v120
	v_rcp_f32_e32 v121, v121
	v_pk_mul_f32 v[124:125], v[124:125], v[174:175]
	v_pk_mul_f32 v[172:173], v[120:121], v[122:123]
	v_cvt_pk_bf16_f32 v120, v124, v125
	v_cvt_pk_bf16_f32 v121, v126, v127
	v_cvt_pk_bf16_f32 v122, v170, v171
	v_cvt_pk_bf16_f32 v123, v172, v173
	global_store_dwordx4 v[158:159], v[120:123], off
	s_nop 1
	v_mov_b32_e32 v120, v196
	v_mov_b32_e32 v121, v197
	v_mov_b32_e32 v122, v198
	v_mov_b32_e32 v123, v199
	v_lshlrev_b32_e32 v124, 16, v120
	v_and_b32_e32 v125, 0xffff0000, v120
	v_lshlrev_b32_e32 v120, 16, v121
	v_and_b32_e32 v121, 0xffff0000, v121
	v_pk_mul_f32 v[118:119], v[118:119], v[120:121]
	v_lshlrev_b32_e32 v120, 16, v122
	v_and_b32_e32 v121, 0xffff0000, v122
	v_pk_mul_f32 v[120:121], v[112:113], v[120:121]
	v_mul_f32_e32 v112, 0xbfb8aa3b, v114
	v_mul_f32_e32 v113, 0xbfb8aa3b, v115
	v_exp_f32_e32 v112, v112
	v_exp_f32_e32 v113, v113
	v_lshlrev_b32_e32 v114, 16, v123
	v_and_b32_e32 v115, 0xffff0000, v123
	v_add_f32_e32 v112, 1.0, v112
	v_add_f32_e32 v113, 1.0, v113
	v_rcp_f32_e32 v112, v112
	v_rcp_f32_e32 v113, v113
	v_pk_mul_f32 v[116:117], v[116:117], v[124:125]
	v_pk_mul_f32 v[122:123], v[112:113], v[114:115]
	v_cvt_pk_bf16_f32 v112, v116, v117
	v_cvt_pk_bf16_f32 v113, v118, v119
	v_cvt_pk_bf16_f32 v114, v120, v121
	v_cvt_pk_bf16_f32 v115, v122, v123
	global_store_dwordx4 v[158:159], v[112:115], off offset:256
	s_nop 1
	v_mov_b32_e32 v114, v180
	s_nop 0
	v_or_b32_e32 v112, 16, v162
	v_ashrrev_i32_e32 v113, 31, v112
	v_lshlrev_b64 v[112:113], 11, v[112:113]
	v_lshl_add_u64 v[112:113], s[0:1], 0, v[112:113]
	v_lshl_add_u64 v[112:113], v[112:113], 0, v[164:165]
	s_nop 1
	v_mov_b32_e32 v116, v200
	v_mov_b32_e32 v117, v201
	v_mov_b32_e32 v118, v202
	v_mov_b32_e32 v119, v203
	v_fmamk_f32 v114, v114, 0x3a800000, v187
	v_cmp_gt_f32_e32 vcc, s67, v114
	v_mul_f32_e32 v115, 0x4b800000, v114
	v_lshlrev_b32_e32 v120, 16, v116
	v_cndmask_b32_e32 v114, v114, v115, vcc
	v_rsq_f32_e32 v114, v114
	v_and_b32_e32 v121, 0xffff0000, v116
	v_lshlrev_b32_e32 v116, 16, v117
	v_and_b32_e32 v117, 0xffff0000, v117
	v_mul_f32_e32 v115, 0x45800000, v114
	v_cndmask_b32_e32 v114, v114, v115, vcc
	v_pk_mul_f32 v[110:111], v[110:111], v[114:115] op_sel_hi:[1,0]
	v_pk_mul_f32 v[104:105], v[104:105], v[114:115] op_sel_hi:[1,0]
	v_mul_f32_e32 v110, 0xbfb8aa3b, v110
	v_mul_f32_e32 v111, 0xbfb8aa3b, v111
	v_exp_f32_e32 v110, v110
	v_exp_f32_e32 v111, v111
	v_mul_f32_e32 v104, 0xbfb8aa3b, v104
	v_mul_f32_e32 v105, 0xbfb8aa3b, v105
	v_exp_f32_e32 v104, v104
	v_exp_f32_e32 v105, v105
	v_add_f32_e32 v110, 1.0, v110
	v_add_f32_e32 v111, 1.0, v111
	v_rcp_f32_e32 v110, v110
	v_rcp_f32_e32 v111, v111
	v_add_f32_e32 v104, 1.0, v104
	v_add_f32_e32 v105, 1.0, v105
	v_rcp_f32_e32 v104, v104
	v_rcp_f32_e32 v105, v105
	v_pk_mul_f32 v[108:109], v[108:109], v[114:115] op_sel_hi:[1,0]
	v_pk_mul_f32 v[106:107], v[106:107], v[114:115] op_sel_hi:[1,0]
	v_pk_mul_f32 v[110:111], v[110:111], v[116:117]
	v_lshlrev_b32_e32 v116, 16, v118
	v_and_b32_e32 v117, 0xffff0000, v118
	v_mul_f32_e32 v108, 0xbfb8aa3b, v108
	v_mul_f32_e32 v109, 0xbfb8aa3b, v109
; __device__ __forceinline__ unsigned cvt_pk_bf16(float lo, float hi) { const f32x2_cv v = {lo, hi}; const bf16x2_cv b = __builtin_convertvector(v, bf16x2_cv); return __builtin_bit_cast(unsigned, b); }
; __device__ __forceinline__ float sigm(float x) { return __builtin_amdgcn_rcpf(1.0f + __expf(-x)); }
; __device__ __forceinline__ float lo16(unsigned w) { return __uint_as_float(w << 16); }
; __device__ __forceinline__ float hi16(unsigned w) { return __uint_as_float(w & 0xffff0000u); }
; __device__ __forceinline__ float rstd_of(const float* rowss, int row) { return rsqrtf(rowss[row] * (1.0f / 1024.0f) + 1e-6f); }
;     __device__ __forceinline__ void operator()(const f32x4 (&acc)[2][2][4][2], const pg8::Unit& u, int wr, int wc, int fr, int fq) const {
;     ...
;                 const int row = row0 + ai * 128 + m * 16;
;                 const float s = rstd_of(rowss, row);
; #pragma unroll
;                 for (int bj = 0; bj < 2; ++bj) {
;                     const size_t off = (size_t)row * 1024 + col0 + bj * 128;
;                     const u32x4 tv = *(const u32x4*)(Tm + off);
;                     u32x4 pv = (u32x4){0u, 0u, 0u, 0u};
;                     if (ACC) pv = *(const u32x4*)(M + off);
;                     const f32x4 a0 = acc[ai][bj][m][0] * s, a1 = acc[ai][bj][m][1] * s;
;                     float o[8];
;                     o[0] = sigm(a0[0]) * lo16(tv.x); o[1] = sigm(a0[1]) * hi16(tv.x); o[2] = sigm(a0[2]) * lo16(tv.y); o[3] = sigm(a0[3]) * hi16(tv.y);
;                     o[4] = sigm(a1[0]) * lo16(tv.z); o[5] = sigm(a1[1]) * hi16(tv.z); o[6] = sigm(a1[2]) * lo16(tv.w); o[7] = sigm(a1[3]) * hi16(tv.w);
;                     if (ACC) { o[0] += lo16(pv.x); o[1] += hi16(pv.x); o[2] += lo16(pv.y); o[3] += hi16(pv.y); o[4] += lo16(pv.z); o[5] += hi16(pv.z); o[6] += lo16(pv.w); o[7] += hi16(pv.w); }
;                     u32x4 w; w.x = cvt_pk_bf16(o[0], o[1]); w.y = cvt_pk_bf16(o[2], o[3]); w.z = cvt_pk_bf16(o[4], o[5]); w.w = cvt_pk_bf16(o[6], o[7]);
;                     *(u32x4*)(M + off) = w; } }
	v_pk_mul_f32 v[116:117], v[104:105], v[116:117]
	v_mul_f32_e32 v104, 0xbfb8aa3b, v106
	v_mul_f32_e32 v105, 0xbfb8aa3b, v107
	v_exp_f32_e32 v108, v108
	v_exp_f32_e32 v109, v109
	v_exp_f32_e32 v104, v104
	v_exp_f32_e32 v105, v105
	v_add_f32_e32 v108, 1.0, v108
	v_add_f32_e32 v109, 1.0, v109
	v_add_f32_e32 v104, 1.0, v104
	v_add_f32_e32 v105, 1.0, v105
	v_rcp_f32_e32 v108, v108
	v_rcp_f32_e32 v109, v109
	v_rcp_f32_e32 v104, v104
	v_rcp_f32_e32 v105, v105
	v_lshlrev_b32_e32 v106, 16, v119
	v_and_b32_e32 v107, 0xffff0000, v119
	v_pk_mul_f32 v[108:109], v[108:109], v[120:121]
	v_pk_mul_f32 v[118:119], v[104:105], v[106:107]
	v_cvt_pk_bf16_f32 v104, v108, v109
	v_cvt_pk_bf16_f32 v105, v110, v111
	v_cvt_pk_bf16_f32 v106, v116, v117
	v_cvt_pk_bf16_f32 v107, v118, v119
	global_store_dwordx4 v[112:113], v[104:107], off
	s_nop 1
	v_mov_b32_e32 v104, v204
	v_mov_b32_e32 v105, v205
	v_mov_b32_e32 v106, v206
	v_mov_b32_e32 v107, v207
	v_pk_mul_f32 v[102:103], v[102:103], v[114:115] op_sel_hi:[1,0]
	v_pk_mul_f32 v[96:97], v[96:97], v[114:115] op_sel_hi:[1,0]
	v_mul_f32_e32 v102, 0xbfb8aa3b, v102
	v_mul_f32_e32 v103, 0xbfb8aa3b, v103
	v_exp_f32_e32 v102, v102
	v_exp_f32_e32 v103, v103
	v_mul_f32_e32 v96, 0xbfb8aa3b, v96
	v_mul_f32_e32 v97, 0xbfb8aa3b, v97
	v_exp_f32_e32 v96, v96
	v_exp_f32_e32 v97, v97
	v_add_f32_e32 v102, 1.0, v102
	v_add_f32_e32 v103, 1.0, v103
	v_rcp_f32_e32 v102, v102
	v_rcp_f32_e32 v103, v103
	v_add_f32_e32 v96, 1.0, v96
	v_add_f32_e32 v97, 1.0, v97
	v_rcp_f32_e32 v96, v96
	v_rcp_f32_e32 v97, v97
	v_pk_mul_f32 v[100:101], v[100:101], v[114:115] op_sel_hi:[1,0]
	v_pk_mul_f32 v[98:99], v[98:99], v[114:115] op_sel_hi:[1,0]
	v_mul_f32_e32 v100, 0xbfb8aa3b, v100
	v_mul_f32_e32 v101, 0xbfb8aa3b, v101
	v_exp_f32_e32 v100, v100
	v_exp_f32_e32 v101, v101
	v_add_f32_e32 v100, 1.0, v100
	v_add_f32_e32 v101, 1.0, v101
	v_rcp_f32_e32 v100, v100
	v_rcp_f32_e32 v101, v101
	v_lshlrev_b32_e32 v108, 16, v104
	v_and_b32_e32 v109, 0xffff0000, v104
	v_lshlrev_b32_e32 v104, 16, v105
	v_and_b32_e32 v105, 0xffff0000, v105
	v_pk_mul_f32 v[102:103], v[102:103], v[104:105]
	v_lshlrev_b32_e32 v104, 16, v106
	v_and_b32_e32 v105, 0xffff0000, v106
	v_pk_mul_f32 v[104:105], v[96:97], v[104:105]
	v_mul_f32_e32 v96, 0xbfb8aa3b, v98
	v_mul_f32_e32 v97, 0xbfb8aa3b, v99
	v_exp_f32_e32 v96, v96
	v_exp_f32_e32 v97, v97
	v_lshlrev_b32_e32 v98, 16, v107
	v_and_b32_e32 v99, 0xffff0000, v107
	v_add_f32_e32 v96, 1.0, v96
	v_add_f32_e32 v97, 1.0, v97
	v_rcp_f32_e32 v96, v96
	v_rcp_f32_e32 v97, v97
	v_pk_mul_f32 v[100:101], v[100:101], v[108:109]
	v_pk_mul_f32 v[106:107], v[96:97], v[98:99]
	v_cvt_pk_bf16_f32 v96, v100, v101
	v_cvt_pk_bf16_f32 v97, v102, v103
	v_cvt_pk_bf16_f32 v98, v104, v105
	v_cvt_pk_bf16_f32 v99, v106, v107
	global_store_dwordx4 v[112:113], v[96:99], off offset:256
	s_nop 1
	v_mov_b32_e32 v98, v181
	s_nop 0
	v_or_b32_e32 v96, 32, v162
	v_ashrrev_i32_e32 v97, 31, v96
	v_lshlrev_b64 v[96:97], 11, v[96:97]
	v_lshl_add_u64 v[96:97], s[0:1], 0, v[96:97]
	v_lshl_add_u64 v[96:97], v[96:97], 0, v[164:165]
	s_nop 1
	v_mov_b32_e32 v100, v208
	v_mov_b32_e32 v101, v209
	v_mov_b32_e32 v102, v210
	v_mov_b32_e32 v103, v211
	v_fmamk_f32 v98, v98, 0x3a800000, v187
	v_cmp_gt_f32_e32 vcc, s67, v98
	v_mul_f32_e32 v99, 0x4b800000, v98
	v_lshlrev_b32_e32 v104, 16, v100
	v_cndmask_b32_e32 v98, v98, v99, vcc
	v_rsq_f32_e32 v98, v98
	v_and_b32_e32 v105, 0xffff0000, v100
	v_lshlrev_b32_e32 v100, 16, v101
	v_and_b32_e32 v101, 0xffff0000, v101
	v_mul_f32_e32 v99, 0x45800000, v98
	v_cndmask_b32_e32 v98, v98, v99, vcc
	v_pk_mul_f32 v[94:95], v[94:95], v[98:99] op_sel_hi:[1,0]
	v_pk_mul_f32 v[88:89], v[88:89], v[98:99] op_sel_hi:[1,0]
	v_mul_f32_e32 v94, 0xbfb8aa3b, v94
	v_mul_f32_e32 v95, 0xbfb8aa3b, v95
	v_exp_f32_e32 v94, v94
	v_exp_f32_e32 v95, v95
	v_mul_f32_e32 v88, 0xbfb8aa3b, v88
	v_mul_f32_e32 v89, 0xbfb8aa3b, v89
	v_exp_f32_e32 v88, v88
	v_exp_f32_e32 v89, v89
	v_add_f32_e32 v94, 1.0, v94
	v_add_f32_e32 v95, 1.0, v95
	v_rcp_f32_e32 v94, v94
	v_rcp_f32_e32 v95, v95
	v_add_f32_e32 v88, 1.0, v88
	v_add_f32_e32 v89, 1.0, v89
	v_rcp_f32_e32 v88, v88
	v_rcp_f32_e32 v89, v89
	v_pk_mul_f32 v[92:93], v[92:93], v[98:99] op_sel_hi:[1,0]
	v_pk_mul_f32 v[90:91], v[90:91], v[98:99] op_sel_hi:[1,0]
	v_pk_mul_f32 v[94:95], v[94:95], v[100:101]
	v_lshlrev_b32_e32 v100, 16, v102
	v_and_b32_e32 v101, 0xffff0000, v102
	v_mul_f32_e32 v92, 0xbfb8aa3b, v92
	v_mul_f32_e32 v93, 0xbfb8aa3b, v93
	v_pk_mul_f32 v[100:101], v[88:89], v[100:101]
	v_mul_f32_e32 v88, 0xbfb8aa3b, v90
	v_mul_f32_e32 v89, 0xbfb8aa3b, v91
	v_exp_f32_e32 v92, v92
	v_exp_f32_e32 v93, v93
	v_exp_f32_e32 v88, v88
	v_exp_f32_e32 v89, v89
	v_add_f32_e32 v92, 1.0, v92
	v_add_f32_e32 v93, 1.0, v93
	v_add_f32_e32 v88, 1.0, v88
	v_add_f32_e32 v89, 1.0, v89
	v_rcp_f32_e32 v92, v92
	v_rcp_f32_e32 v93, v93
	v_rcp_f32_e32 v88, v88
	v_rcp_f32_e32 v89, v89
	v_lshlrev_b32_e32 v90, 16, v103
	v_and_b32_e32 v91, 0xffff0000, v103
	v_pk_mul_f32 v[92:93], v[92:93], v[104:105]
	v_pk_mul_f32 v[102:103], v[88:89], v[90:91]
	v_cvt_pk_bf16_f32 v88, v92, v93
	v_cvt_pk_bf16_f32 v89, v94, v95
	v_cvt_pk_bf16_f32 v90, v100, v101
	v_cvt_pk_bf16_f32 v91, v102, v103
	global_store_dwordx4 v[96:97], v[88:91], off
	s_nop 1
	v_mov_b32_e32 v88, v212
	v_mov_b32_e32 v89, v213
	v_mov_b32_e32 v90, v214
	v_mov_b32_e32 v91, v215
	v_pk_mul_f32 v[86:87], v[86:87], v[98:99] op_sel_hi:[1,0]
	v_pk_mul_f32 v[80:81], v[80:81], v[98:99] op_sel_hi:[1,0]
	v_mul_f32_e32 v86, 0xbfb8aa3b, v86
	v_mul_f32_e32 v87, 0xbfb8aa3b, v87
	v_exp_f32_e32 v86, v86
	v_exp_f32_e32 v87, v87
	v_mul_f32_e32 v80, 0xbfb8aa3b, v80
	v_mul_f32_e32 v81, 0xbfb8aa3b, v81
	v_exp_f32_e32 v80, v80
	v_exp_f32_e32 v81, v81
; __device__ __forceinline__ unsigned cvt_pk_bf16(float lo, float hi) { const f32x2_cv v = {lo, hi}; const bf16x2_cv b = __builtin_convertvector(v, bf16x2_cv); return __builtin_bit_cast(unsigned, b); }
; __device__ __forceinline__ float sigm(float x) { return __builtin_amdgcn_rcpf(1.0f + __expf(-x)); }
; __device__ __forceinline__ float lo16(unsigned w) { return __uint_as_float(w << 16); }
; __device__ __forceinline__ float hi16(unsigned w) { return __uint_as_float(w & 0xffff0000u); }
; __device__ __forceinline__ float rstd_of(const float* rowss, int row) { return rsqrtf(rowss[row] * (1.0f / 1024.0f) + 1e-6f); }
;     __device__ __forceinline__ void operator()(const f32x4 (&acc)[2][2][4][2], const pg8::Unit& u, int wr, int wc, int fr, int fq) const {
;     ...
;                 const int row = row0 + ai * 128 + m * 16;
;                 const float s = rstd_of(rowss, row);
; #pragma unroll
;                 for (int bj = 0; bj < 2; ++bj) {
;                     const size_t off = (size_t)row * 1024 + col0 + bj * 128;
;                     const u32x4 tv = *(const u32x4*)(Tm + off);
;                     u32x4 pv = (u32x4){0u, 0u, 0u, 0u};
;                     if (ACC) pv = *(const u32x4*)(M + off);
;                     const f32x4 a0 = acc[ai][bj][m][0] * s, a1 = acc[ai][bj][m][1] * s;
;                     float o[8];
;                     o[0] = sigm(a0[0]) * lo16(tv.x); o[1] = sigm(a0[1]) * hi16(tv.x); o[2] = sigm(a0[2]) * lo16(tv.y); o[3] = sigm(a0[3]) * hi16(tv.y);
;                     o[4] = sigm(a1[0]) * lo16(tv.z); o[5] = sigm(a1[1]) * hi16(tv.z); o[6] = sigm(a1[2]) * lo16(tv.w); o[7] = sigm(a1[3]) * hi16(tv.w);
;                     if (ACC) { o[0] += lo16(pv.x); o[1] += hi16(pv.x); o[2] += lo16(pv.y); o[3] += hi16(pv.y); o[4] += lo16(pv.z); o[5] += hi16(pv.z); o[6] += lo16(pv.w); o[7] += hi16(pv.w); }
;                     u32x4 w; w.x = cvt_pk_bf16(o[0], o[1]); w.y = cvt_pk_bf16(o[2], o[3]); w.z = cvt_pk_bf16(o[4], o[5]); w.w = cvt_pk_bf16(o[6], o[7]);
;                     *(u32x4*)(M + off) = w; } }
	v_add_f32_e32 v86, 1.0, v86
	v_add_f32_e32 v87, 1.0, v87
	v_rcp_f32_e32 v86, v86
	v_rcp_f32_e32 v87, v87
	v_add_f32_e32 v80, 1.0, v80
	v_add_f32_e32 v81, 1.0, v81
	v_rcp_f32_e32 v80, v80
	v_rcp_f32_e32 v81, v81
	v_pk_mul_f32 v[84:85], v[84:85], v[98:99] op_sel_hi:[1,0]
	v_pk_mul_f32 v[82:83], v[82:83], v[98:99] op_sel_hi:[1,0]
	v_mul_f32_e32 v84, 0xbfb8aa3b, v84
	v_mul_f32_e32 v85, 0xbfb8aa3b, v85
	v_exp_f32_e32 v84, v84
	v_exp_f32_e32 v85, v85
	v_add_f32_e32 v84, 1.0, v84
	v_add_f32_e32 v85, 1.0, v85
	v_rcp_f32_e32 v84, v84
	v_rcp_f32_e32 v85, v85
	v_lshlrev_b32_e32 v92, 16, v88
	v_and_b32_e32 v93, 0xffff0000, v88
	v_lshlrev_b32_e32 v88, 16, v89
	v_and_b32_e32 v89, 0xffff0000, v89
	v_pk_mul_f32 v[86:87], v[86:87], v[88:89]
	v_lshlrev_b32_e32 v88, 16, v90
	v_and_b32_e32 v89, 0xffff0000, v90
	v_pk_mul_f32 v[88:89], v[80:81], v[88:89]
	v_mul_f32_e32 v80, 0xbfb8aa3b, v82
	v_mul_f32_e32 v81, 0xbfb8aa3b, v83
	v_exp_f32_e32 v80, v80
	v_exp_f32_e32 v81, v81
	v_lshlrev_b32_e32 v82, 16, v91
	v_and_b32_e32 v83, 0xffff0000, v91
	v_add_f32_e32 v80, 1.0, v80
	v_add_f32_e32 v81, 1.0, v81
	v_rcp_f32_e32 v80, v80
	v_rcp_f32_e32 v81, v81
	v_pk_mul_f32 v[84:85], v[84:85], v[92:93]
	v_pk_mul_f32 v[90:91], v[80:81], v[82:83]
	v_cvt_pk_bf16_f32 v80, v84, v85
	v_cvt_pk_bf16_f32 v81, v86, v87
	v_cvt_pk_bf16_f32 v82, v88, v89
	v_cvt_pk_bf16_f32 v83, v90, v91
	global_store_dwordx4 v[96:97], v[80:83], off offset:256
	s_nop 1
	v_mov_b32_e32 v82, v182
	s_nop 0
	v_or_b32_e32 v80, 48, v162
	v_ashrrev_i32_e32 v81, 31, v80
	v_lshlrev_b64 v[80:81], 11, v[80:81]
	v_lshl_add_u64 v[80:81], s[0:1], 0, v[80:81]
	v_lshl_add_u64 v[80:81], v[80:81], 0, v[164:165]
	s_nop 1
	v_mov_b32_e32 v84, v216
	v_mov_b32_e32 v85, v217
	v_mov_b32_e32 v86, v218
	v_mov_b32_e32 v87, v219
	v_fmamk_f32 v82, v82, 0x3a800000, v187
	v_cmp_gt_f32_e32 vcc, s67, v82
	v_mul_f32_e32 v83, 0x4b800000, v82
	v_lshlrev_b32_e32 v88, 16, v84
	v_cndmask_b32_e32 v82, v82, v83, vcc
	v_rsq_f32_e32 v82, v82
	v_and_b32_e32 v89, 0xffff0000, v84
	v_lshlrev_b32_e32 v84, 16, v85
	v_and_b32_e32 v85, 0xffff0000, v85
	v_mul_f32_e32 v83, 0x45800000, v82
	v_cndmask_b32_e32 v82, v82, v83, vcc
	v_pk_mul_f32 v[78:79], v[78:79], v[82:83] op_sel_hi:[1,0]
	v_pk_mul_f32 v[72:73], v[72:73], v[82:83] op_sel_hi:[1,0]
	v_mul_f32_e32 v78, 0xbfb8aa3b, v78
	v_mul_f32_e32 v79, 0xbfb8aa3b, v79
	v_exp_f32_e32 v78, v78
	v_exp_f32_e32 v79, v79
	v_mul_f32_e32 v72, 0xbfb8aa3b, v72
	v_mul_f32_e32 v73, 0xbfb8aa3b, v73
	v_exp_f32_e32 v72, v72
	v_exp_f32_e32 v73, v73
	v_add_f32_e32 v78, 1.0, v78
	v_add_f32_e32 v79, 1.0, v79
	v_rcp_f32_e32 v78, v78
	v_rcp_f32_e32 v79, v79
	v_add_f32_e32 v72, 1.0, v72
	v_add_f32_e32 v73, 1.0, v73
	v_rcp_f32_e32 v72, v72
	v_rcp_f32_e32 v73, v73
	v_pk_mul_f32 v[76:77], v[76:77], v[82:83] op_sel_hi:[1,0]
	v_pk_mul_f32 v[74:75], v[74:75], v[82:83] op_sel_hi:[1,0]
	v_pk_mul_f32 v[78:79], v[78:79], v[84:85]
	v_lshlrev_b32_e32 v84, 16, v86
	v_and_b32_e32 v85, 0xffff0000, v86
	v_mul_f32_e32 v76, 0xbfb8aa3b, v76
	v_mul_f32_e32 v77, 0xbfb8aa3b, v77
	v_pk_mul_f32 v[84:85], v[72:73], v[84:85]
	v_mul_f32_e32 v72, 0xbfb8aa3b, v74
	v_mul_f32_e32 v73, 0xbfb8aa3b, v75
	v_exp_f32_e32 v76, v76
	v_exp_f32_e32 v77, v77
	v_exp_f32_e32 v72, v72
	v_exp_f32_e32 v73, v73
	v_add_f32_e32 v76, 1.0, v76
	v_add_f32_e32 v77, 1.0, v77
	v_add_f32_e32 v72, 1.0, v72
	v_add_f32_e32 v73, 1.0, v73
	v_rcp_f32_e32 v76, v76
	v_rcp_f32_e32 v77, v77
	v_rcp_f32_e32 v72, v72
	v_rcp_f32_e32 v73, v73
	v_lshlrev_b32_e32 v74, 16, v87
	v_and_b32_e32 v75, 0xffff0000, v87
	v_pk_mul_f32 v[76:77], v[76:77], v[88:89]
	v_pk_mul_f32 v[86:87], v[72:73], v[74:75]
	v_cvt_pk_bf16_f32 v72, v76, v77
	v_cvt_pk_bf16_f32 v73, v78, v79
	v_cvt_pk_bf16_f32 v74, v84, v85
	v_cvt_pk_bf16_f32 v75, v86, v87
	global_store_dwordx4 v[80:81], v[72:75], off
	s_nop 1
	v_mov_b32_e32 v72, v220
	v_mov_b32_e32 v73, v221
	v_mov_b32_e32 v74, v222
	v_mov_b32_e32 v75, v223
	v_pk_mul_f32 v[70:71], v[70:71], v[82:83] op_sel_hi:[1,0]
	v_pk_mul_f32 v[64:65], v[64:65], v[82:83] op_sel_hi:[1,0]
	v_mul_f32_e32 v70, 0xbfb8aa3b, v70
	v_mul_f32_e32 v71, 0xbfb8aa3b, v71
	v_exp_f32_e32 v70, v70
	v_exp_f32_e32 v71, v71
	v_mul_f32_e32 v64, 0xbfb8aa3b, v64
	v_mul_f32_e32 v65, 0xbfb8aa3b, v65
	v_exp_f32_e32 v64, v64
	v_exp_f32_e32 v65, v65
	v_add_f32_e32 v70, 1.0, v70
	v_add_f32_e32 v71, 1.0, v71
	v_rcp_f32_e32 v70, v70
	v_rcp_f32_e32 v71, v71
	v_add_f32_e32 v64, 1.0, v64
	v_add_f32_e32 v65, 1.0, v65
	v_rcp_f32_e32 v64, v64
	v_rcp_f32_e32 v65, v65
	v_pk_mul_f32 v[68:69], v[68:69], v[82:83] op_sel_hi:[1,0]
	v_pk_mul_f32 v[66:67], v[66:67], v[82:83] op_sel_hi:[1,0]
	v_mul_f32_e32 v68, 0xbfb8aa3b, v68
	v_mul_f32_e32 v69, 0xbfb8aa3b, v69
	v_exp_f32_e32 v68, v68
	v_exp_f32_e32 v69, v69
	v_add_f32_e32 v68, 1.0, v68
	v_add_f32_e32 v69, 1.0, v69
	v_rcp_f32_e32 v68, v68
	v_rcp_f32_e32 v69, v69
	v_lshlrev_b32_e32 v76, 16, v72
	v_and_b32_e32 v77, 0xffff0000, v72
	v_lshlrev_b32_e32 v72, 16, v73
	v_and_b32_e32 v73, 0xffff0000, v73
	v_pk_mul_f32 v[70:71], v[70:71], v[72:73]
	v_lshlrev_b32_e32 v72, 16, v74
	v_and_b32_e32 v73, 0xffff0000, v74
	v_pk_mul_f32 v[72:73], v[64:65], v[72:73]
	v_mul_f32_e32 v64, 0xbfb8aa3b, v66
	v_mul_f32_e32 v65, 0xbfb8aa3b, v67
	v_exp_f32_e32 v64, v64
	v_exp_f32_e32 v65, v65
	v_lshlrev_b32_e32 v66, 16, v75
	v_and_b32_e32 v67, 0xffff0000, v75
	v_add_f32_e32 v64, 1.0, v64
	v_add_f32_e32 v65, 1.0, v65
	v_rcp_f32_e32 v64, v64
	v_rcp_f32_e32 v65, v65
	v_pk_mul_f32 v[68:69], v[68:69], v[76:77]
	v_pk_mul_f32 v[74:75], v[64:65], v[66:67]
	v_cvt_pk_bf16_f32 v64, v68, v69
	v_cvt_pk_bf16_f32 v65, v70, v71
	v_cvt_pk_bf16_f32 v66, v72, v73
	v_cvt_pk_bf16_f32 v67, v74, v75
	global_store_dwordx4 v[80:81], v[64:67], off offset:256
; __device__ __forceinline__ unsigned cvt_pk_bf16(float lo, float hi) { const f32x2_cv v = {lo, hi}; const bf16x2_cv b = __builtin_convertvector(v, bf16x2_cv); return __builtin_bit_cast(unsigned, b); }
; __device__ __forceinline__ float sigm(float x) { return __builtin_amdgcn_rcpf(1.0f + __expf(-x)); }
; __device__ __forceinline__ float lo16(unsigned w) { return __uint_as_float(w << 16); }
; __device__ __forceinline__ float hi16(unsigned w) { return __uint_as_float(w & 0xffff0000u); }
; __device__ __forceinline__ float rstd_of(const float* rowss, int row) { return rsqrtf(rowss[row] * (1.0f / 1024.0f) + 1e-6f); }
;     __device__ __forceinline__ void operator()(const f32x4 (&acc)[2][2][4][2], const pg8::Unit& u, int wr, int wc, int fr, int fq) const {
;     ...
;                 const int row = row0 + ai * 128 + m * 16;
;                 const float s = rstd_of(rowss, row);
; #pragma unroll
;                 for (int bj = 0; bj < 2; ++bj) {
;                     const size_t off = (size_t)row * 1024 + col0 + bj * 128;
;                     const u32x4 tv = *(const u32x4*)(Tm + off);
;                     u32x4 pv = (u32x4){0u, 0u, 0u, 0u};
;                     if (ACC) pv = *(const u32x4*)(M + off);
;                     const f32x4 a0 = acc[ai][bj][m][0] * s, a1 = acc[ai][bj][m][1] * s;
;                     float o[8];
;                     o[0] = sigm(a0[0]) * lo16(tv.x); o[1] = sigm(a0[1]) * hi16(tv.x); o[2] = sigm(a0[2]) * lo16(tv.y); o[3] = sigm(a0[3]) * hi16(tv.y);
;                     o[4] = sigm(a1[0]) * lo16(tv.z); o[5] = sigm(a1[1]) * hi16(tv.z); o[6] = sigm(a1[2]) * lo16(tv.w); o[7] = sigm(a1[3]) * hi16(tv.w);
;                     if (ACC) { o[0] += lo16(pv.x); o[1] += hi16(pv.x); o[2] += lo16(pv.y); o[3] += hi16(pv.y); o[4] += lo16(pv.z); o[5] += hi16(pv.z); o[6] += lo16(pv.w); o[7] += hi16(pv.w); }
;                     u32x4 w; w.x = cvt_pk_bf16(o[0], o[1]); w.y = cvt_pk_bf16(o[2], o[3]); w.z = cvt_pk_bf16(o[4], o[5]); w.w = cvt_pk_bf16(o[6], o[7]);
;                     *(u32x4*)(M + off) = w; } }
	s_nop 1
	v_mov_b32_e32 v64, v183
	v_fmamk_f32 v64, v64, 0x3a800000, v187
	v_cmp_gt_f32_e32 vcc, s67, v64
	v_mul_f32_e32 v65, 0x4b800000, v64
	s_nop 0
	v_cndmask_b32_e32 v64, v64, v65, vcc
	v_rsq_f32_e32 v64, v64
	s_nop 0
	v_mul_f32_e32 v65, 0x45800000, v64
	v_cndmask_b32_e32 v66, v64, v65, vcc
	v_add_co_u32_e32 v72, vcc, s2, v158
	v_pk_mul_f32 v[62:63], v[62:63], v[66:67] op_sel_hi:[1,0]
	s_nop 0
	v_addc_co_u32_e32 v73, vcc, 0, v159, vcc
	s_nop 1
	v_mov_b32_e32 v68, v224
	v_mov_b32_e32 v69, v225
	v_mov_b32_e32 v70, v226
	v_mov_b32_e32 v71, v227
	v_pk_mul_f32 v[56:57], v[56:57], v[66:67] op_sel_hi:[1,0]
	v_mul_f32_e32 v62, 0xbfb8aa3b, v62
	v_mul_f32_e32 v63, 0xbfb8aa3b, v63
	v_exp_f32_e32 v62, v62
	v_exp_f32_e32 v63, v63
	v_mul_f32_e32 v56, 0xbfb8aa3b, v56
	v_mul_f32_e32 v57, 0xbfb8aa3b, v57
	v_exp_f32_e32 v56, v56
	v_exp_f32_e32 v57, v57
	v_add_f32_e32 v62, 1.0, v62
	v_add_f32_e32 v63, 1.0, v63
	v_rcp_f32_e32 v62, v62
	v_rcp_f32_e32 v63, v63
	v_add_f32_e32 v56, 1.0, v56
	v_add_f32_e32 v57, 1.0, v57
	v_rcp_f32_e32 v56, v56
	v_rcp_f32_e32 v57, v57
	v_pk_mul_f32 v[60:61], v[60:61], v[66:67] op_sel_hi:[1,0]
	v_pk_mul_f32 v[58:59], v[58:59], v[66:67] op_sel_hi:[1,0]
	v_mul_f32_e32 v60, 0xbfb8aa3b, v60
	v_mul_f32_e32 v61, 0xbfb8aa3b, v61
	v_exp_f32_e32 v60, v60
	v_exp_f32_e32 v61, v61
	v_lshl_add_u64 v[64:65], v[158:159], 0, s[4:5]
	v_pk_mul_f32 v[54:55], v[54:55], v[66:67] op_sel_hi:[1,0]
	v_add_f32_e32 v60, 1.0, v60
	v_add_f32_e32 v61, 1.0, v61
	v_rcp_f32_e32 v60, v60
	v_rcp_f32_e32 v61, v61
	v_pk_mul_f32 v[48:49], v[48:49], v[66:67] op_sel_hi:[1,0]
	v_mul_f32_e32 v54, 0xbfb8aa3b, v54
	v_mul_f32_e32 v55, 0xbfb8aa3b, v55
	v_exp_f32_e32 v54, v54
	v_exp_f32_e32 v55, v55
	v_mul_f32_e32 v48, 0xbfb8aa3b, v48
	v_mul_f32_e32 v49, 0xbfb8aa3b, v49
	v_exp_f32_e32 v48, v48
	v_exp_f32_e32 v49, v49
	v_add_f32_e32 v54, 1.0, v54
	v_add_f32_e32 v55, 1.0, v55
	v_rcp_f32_e32 v54, v54
	v_rcp_f32_e32 v55, v55
	v_add_f32_e32 v48, 1.0, v48
	v_add_f32_e32 v49, 1.0, v49
	v_rcp_f32_e32 v48, v48
	v_rcp_f32_e32 v49, v49
	v_pk_mul_f32 v[52:53], v[52:53], v[66:67] op_sel_hi:[1,0]
	v_pk_mul_f32 v[50:51], v[50:51], v[66:67] op_sel_hi:[1,0]
	v_mul_f32_e32 v52, 0xbfb8aa3b, v52
	v_mul_f32_e32 v53, 0xbfb8aa3b, v53
	v_exp_f32_e32 v52, v52
	v_exp_f32_e32 v53, v53
	s_mov_b32 s2, 0x48000
	s_mov_b64 s[4:5], 0x48000
	v_add_f32_e32 v52, 1.0, v52
	v_add_f32_e32 v53, 1.0, v53
	v_rcp_f32_e32 v52, v52
	v_rcp_f32_e32 v53, v53
	v_lshlrev_b32_e32 v74, 16, v68
	v_and_b32_e32 v75, 0xffff0000, v68
	v_lshlrev_b32_e32 v68, 16, v69
	v_and_b32_e32 v69, 0xffff0000, v69
	v_pk_mul_f32 v[62:63], v[62:63], v[68:69]
	v_lshlrev_b32_e32 v68, 16, v70
	v_and_b32_e32 v69, 0xffff0000, v70
	v_pk_mul_f32 v[68:69], v[56:57], v[68:69]
	v_mul_f32_e32 v56, 0xbfb8aa3b, v58
	v_mul_f32_e32 v57, 0xbfb8aa3b, v59
	v_exp_f32_e32 v56, v56
	v_exp_f32_e32 v57, v57
	v_lshlrev_b32_e32 v58, 16, v71
	v_and_b32_e32 v59, 0xffff0000, v71
	v_add_f32_e32 v56, 1.0, v56
	v_add_f32_e32 v57, 1.0, v57
	v_rcp_f32_e32 v56, v56
	v_rcp_f32_e32 v57, v57
	v_pk_mul_f32 v[60:61], v[60:61], v[74:75]
	v_pk_mul_f32 v[70:71], v[56:57], v[58:59]
	v_cvt_pk_bf16_f32 v56, v60, v61
	v_cvt_pk_bf16_f32 v57, v62, v63
	v_cvt_pk_bf16_f32 v58, v68, v69
	v_cvt_pk_bf16_f32 v59, v70, v71
	global_store_dwordx4 v[72:73], v[56:59], off
	s_nop 1
	v_mov_b32_e32 v56, v228
	v_mov_b32_e32 v57, v229
	v_mov_b32_e32 v58, v230
	v_mov_b32_e32 v59, v231
	v_lshlrev_b32_e32 v60, 16, v56
	v_and_b32_e32 v61, 0xffff0000, v56
	v_lshlrev_b32_e32 v56, 16, v57
	v_and_b32_e32 v57, 0xffff0000, v57
	v_pk_mul_f32 v[54:55], v[54:55], v[56:57]
	v_lshlrev_b32_e32 v56, 16, v58
	v_and_b32_e32 v57, 0xffff0000, v58
	v_pk_mul_f32 v[56:57], v[48:49], v[56:57]
	v_mul_f32_e32 v48, 0xbfb8aa3b, v50
	v_mul_f32_e32 v49, 0xbfb8aa3b, v51
	v_exp_f32_e32 v48, v48
	v_exp_f32_e32 v49, v49
	v_lshlrev_b32_e32 v50, 16, v59
	v_and_b32_e32 v51, 0xffff0000, v59
	v_add_f32_e32 v48, 1.0, v48
	v_add_f32_e32 v49, 1.0, v49
	v_rcp_f32_e32 v48, v48
	v_rcp_f32_e32 v49, v49
	v_pk_mul_f32 v[52:53], v[52:53], v[60:61]
	v_pk_mul_f32 v[58:59], v[48:49], v[50:51]
	v_cvt_pk_bf16_f32 v48, v52, v53
	v_cvt_pk_bf16_f32 v49, v54, v55
	v_cvt_pk_bf16_f32 v50, v56, v57
	v_cvt_pk_bf16_f32 v51, v58, v59
	global_store_dwordx4 v[64:65], v[48:51], off offset:256
	s_nop 1
	v_mov_b32_e32 v48, v240
	v_fmamk_f32 v48, v48, 0x3a800000, v187
	v_cmp_gt_f32_e32 vcc, s67, v48
	v_mul_f32_e32 v49, 0x4b800000, v48
	s_nop 0
	v_cndmask_b32_e32 v48, v48, v49, vcc
	v_rsq_f32_e32 v48, v48
	s_nop 0
	v_mul_f32_e32 v49, 0x45800000, v48
	v_cndmask_b32_e32 v50, v48, v49, vcc
	v_add_co_u32_e32 v56, vcc, s2, v158
	v_pk_mul_f32 v[46:47], v[46:47], v[50:51] op_sel_hi:[1,0]
	s_nop 0
	v_addc_co_u32_e32 v57, vcc, 0, v159, vcc
	s_nop 1
	v_mov_b32_e32 v52, v232
	v_mov_b32_e32 v53, v233
	v_mov_b32_e32 v54, v234
	v_mov_b32_e32 v55, v235
	v_pk_mul_f32 v[40:41], v[40:41], v[50:51] op_sel_hi:[1,0]
	v_mul_f32_e32 v46, 0xbfb8aa3b, v46
	v_mul_f32_e32 v47, 0xbfb8aa3b, v47
	v_exp_f32_e32 v46, v46
	v_exp_f32_e32 v47, v47
	v_mul_f32_e32 v40, 0xbfb8aa3b, v40
	v_mul_f32_e32 v41, 0xbfb8aa3b, v41
	v_exp_f32_e32 v40, v40
	v_exp_f32_e32 v41, v41
	v_add_f32_e32 v46, 1.0, v46
	v_add_f32_e32 v47, 1.0, v47
	v_rcp_f32_e32 v46, v46
	v_rcp_f32_e32 v47, v47
	v_add_f32_e32 v40, 1.0, v40
	v_add_f32_e32 v41, 1.0, v41
	v_rcp_f32_e32 v40, v40
	v_rcp_f32_e32 v41, v41
	v_pk_mul_f32 v[44:45], v[44:45], v[50:51] op_sel_hi:[1,0]
	v_pk_mul_f32 v[42:43], v[42:43], v[50:51] op_sel_hi:[1,0]
	v_mul_f32_e32 v44, 0xbfb8aa3b, v44
	v_mul_f32_e32 v45, 0xbfb8aa3b, v45
	v_exp_f32_e32 v44, v44
	v_exp_f32_e32 v45, v45
	v_lshl_add_u64 v[48:49], v[158:159], 0, s[4:5]
	v_pk_mul_f32 v[38:39], v[38:39], v[50:51] op_sel_hi:[1,0]
; __device__ __forceinline__ unsigned cvt_pk_bf16(float lo, float hi) { const f32x2_cv v = {lo, hi}; const bf16x2_cv b = __builtin_convertvector(v, bf16x2_cv); return __builtin_bit_cast(unsigned, b); }
; __device__ __forceinline__ float sigm(float x) { return __builtin_amdgcn_rcpf(1.0f + __expf(-x)); }
; __device__ __forceinline__ float lo16(unsigned w) { return __uint_as_float(w << 16); }
; __device__ __forceinline__ float hi16(unsigned w) { return __uint_as_float(w & 0xffff0000u); }
; __device__ __forceinline__ float rstd_of(const float* rowss, int row) { return rsqrtf(rowss[row] * (1.0f / 1024.0f) + 1e-6f); }
;     __device__ __forceinline__ void operator()(const f32x4 (&acc)[2][2][4][2], const pg8::Unit& u, int wr, int wc, int fr, int fq) const {
;     ...
;                 const int row = row0 + ai * 128 + m * 16;
;                 const float s = rstd_of(rowss, row);
; #pragma unroll
;                 for (int bj = 0; bj < 2; ++bj) {
;                     const size_t off = (size_t)row * 1024 + col0 + bj * 128;
;                     const u32x4 tv = *(const u32x4*)(Tm + off);
;                     u32x4 pv = (u32x4){0u, 0u, 0u, 0u};
;                     if (ACC) pv = *(const u32x4*)(M + off);
;                     const f32x4 a0 = acc[ai][bj][m][0] * s, a1 = acc[ai][bj][m][1] * s;
;                     float o[8];
;                     o[0] = sigm(a0[0]) * lo16(tv.x); o[1] = sigm(a0[1]) * hi16(tv.x); o[2] = sigm(a0[2]) * lo16(tv.y); o[3] = sigm(a0[3]) * hi16(tv.y);
;                     o[4] = sigm(a1[0]) * lo16(tv.z); o[5] = sigm(a1[1]) * hi16(tv.z); o[6] = sigm(a1[2]) * lo16(tv.w); o[7] = sigm(a1[3]) * hi16(tv.w);
;                     if (ACC) { o[0] += lo16(pv.x); o[1] += hi16(pv.x); o[2] += lo16(pv.y); o[3] += hi16(pv.y); o[4] += lo16(pv.z); o[5] += hi16(pv.z); o[6] += lo16(pv.w); o[7] += hi16(pv.w); }
;                     u32x4 w; w.x = cvt_pk_bf16(o[0], o[1]); w.y = cvt_pk_bf16(o[2], o[3]); w.z = cvt_pk_bf16(o[4], o[5]); w.w = cvt_pk_bf16(o[6], o[7]);
;                     *(u32x4*)(M + off) = w; } }
	v_add_f32_e32 v44, 1.0, v44
	v_add_f32_e32 v45, 1.0, v45
	v_rcp_f32_e32 v44, v44
	v_rcp_f32_e32 v45, v45
	v_pk_mul_f32 v[32:33], v[32:33], v[50:51] op_sel_hi:[1,0]
	v_mul_f32_e32 v38, 0xbfb8aa3b, v38
	v_mul_f32_e32 v39, 0xbfb8aa3b, v39
	v_exp_f32_e32 v38, v38
	v_exp_f32_e32 v39, v39
	v_mul_f32_e32 v32, 0xbfb8aa3b, v32
	v_mul_f32_e32 v33, 0xbfb8aa3b, v33
	v_exp_f32_e32 v32, v32
	v_exp_f32_e32 v33, v33
	v_add_f32_e32 v38, 1.0, v38
	v_add_f32_e32 v39, 1.0, v39
	v_rcp_f32_e32 v38, v38
	v_rcp_f32_e32 v39, v39
	v_add_f32_e32 v32, 1.0, v32
	v_add_f32_e32 v33, 1.0, v33
	v_rcp_f32_e32 v32, v32
	v_rcp_f32_e32 v33, v33
	v_pk_mul_f32 v[36:37], v[36:37], v[50:51] op_sel_hi:[1,0]
	v_pk_mul_f32 v[34:35], v[34:35], v[50:51] op_sel_hi:[1,0]
	v_mul_f32_e32 v36, 0xbfb8aa3b, v36
	v_mul_f32_e32 v37, 0xbfb8aa3b, v37
	v_exp_f32_e32 v36, v36
	v_exp_f32_e32 v37, v37
	s_mov_b32 s2, 0x50000
	s_mov_b64 s[4:5], 0x50000
	v_add_f32_e32 v36, 1.0, v36
	v_add_f32_e32 v37, 1.0, v37
	v_rcp_f32_e32 v36, v36
	v_rcp_f32_e32 v37, v37
	v_lshlrev_b32_e32 v58, 16, v52
	v_and_b32_e32 v59, 0xffff0000, v52
	v_lshlrev_b32_e32 v52, 16, v53
	v_and_b32_e32 v53, 0xffff0000, v53
	v_pk_mul_f32 v[46:47], v[46:47], v[52:53]
	v_lshlrev_b32_e32 v52, 16, v54
	v_and_b32_e32 v53, 0xffff0000, v54
	v_pk_mul_f32 v[52:53], v[40:41], v[52:53]
	v_mul_f32_e32 v40, 0xbfb8aa3b, v42
	v_mul_f32_e32 v41, 0xbfb8aa3b, v43
	v_exp_f32_e32 v40, v40
	v_exp_f32_e32 v41, v41
	v_lshlrev_b32_e32 v42, 16, v55
	v_and_b32_e32 v43, 0xffff0000, v55
	v_add_f32_e32 v40, 1.0, v40
	v_add_f32_e32 v41, 1.0, v41
	v_rcp_f32_e32 v40, v40
	v_rcp_f32_e32 v41, v41
	v_pk_mul_f32 v[44:45], v[44:45], v[58:59]
	v_pk_mul_f32 v[54:55], v[40:41], v[42:43]
	v_cvt_pk_bf16_f32 v40, v44, v45
	v_cvt_pk_bf16_f32 v41, v46, v47
	v_cvt_pk_bf16_f32 v42, v52, v53
	v_cvt_pk_bf16_f32 v43, v54, v55
	global_store_dwordx4 v[56:57], v[40:43], off
	s_nop 1
	v_mov_b32_e32 v40, v236
	v_mov_b32_e32 v41, v237
	v_mov_b32_e32 v42, v238
	v_mov_b32_e32 v43, v239
	v_lshlrev_b32_e32 v44, 16, v40
	v_and_b32_e32 v45, 0xffff0000, v40
	v_lshlrev_b32_e32 v40, 16, v41
	v_and_b32_e32 v41, 0xffff0000, v41
	v_pk_mul_f32 v[38:39], v[38:39], v[40:41]
	v_lshlrev_b32_e32 v40, 16, v42
	v_and_b32_e32 v41, 0xffff0000, v42
	v_pk_mul_f32 v[40:41], v[32:33], v[40:41]
	v_mul_f32_e32 v32, 0xbfb8aa3b, v34
	v_mul_f32_e32 v33, 0xbfb8aa3b, v35
	v_exp_f32_e32 v32, v32
	v_exp_f32_e32 v33, v33
	v_lshlrev_b32_e32 v34, 16, v43
	v_and_b32_e32 v35, 0xffff0000, v43
	v_add_f32_e32 v32, 1.0, v32
	v_add_f32_e32 v33, 1.0, v33
	v_rcp_f32_e32 v32, v32
	v_rcp_f32_e32 v33, v33
	v_pk_mul_f32 v[36:37], v[36:37], v[44:45]
	v_pk_mul_f32 v[42:43], v[32:33], v[34:35]
	v_cvt_pk_bf16_f32 v32, v36, v37
	v_cvt_pk_bf16_f32 v33, v38, v39
	v_cvt_pk_bf16_f32 v34, v40, v41
	v_cvt_pk_bf16_f32 v35, v42, v43
	global_store_dwordx4 v[48:49], v[32:35], off offset:256
	s_nop 1
	v_mov_b32_e32 v32, v241
	v_fmamk_f32 v32, v32, 0x3a800000, v187
	v_cmp_gt_f32_e32 vcc, s67, v32
	v_mul_f32_e32 v33, 0x4b800000, v32
	s_nop 0
	v_cndmask_b32_e32 v32, v32, v33, vcc
	v_rsq_f32_e32 v32, v32
	s_nop 0
	v_mul_f32_e32 v33, 0x45800000, v32
	v_cndmask_b32_e32 v34, v32, v33, vcc
	v_add_co_u32_e32 v40, vcc, s2, v158
	v_pk_mul_f32 v[30:31], v[30:31], v[34:35] op_sel_hi:[1,0]
	s_nop 0
	v_addc_co_u32_e32 v41, vcc, 0, v159, vcc
	s_nop 1
	v_mov_b32_e32 v36, v244
	v_mov_b32_e32 v37, v245
	v_mov_b32_e32 v38, v246
	v_mov_b32_e32 v39, v247
	v_pk_mul_f32 v[24:25], v[24:25], v[34:35] op_sel_hi:[1,0]
	v_mul_f32_e32 v30, 0xbfb8aa3b, v30
	v_mul_f32_e32 v31, 0xbfb8aa3b, v31
	v_exp_f32_e32 v30, v30
	v_exp_f32_e32 v31, v31
	v_mul_f32_e32 v24, 0xbfb8aa3b, v24
	v_mul_f32_e32 v25, 0xbfb8aa3b, v25
	v_exp_f32_e32 v24, v24
	v_exp_f32_e32 v25, v25
	v_add_f32_e32 v30, 1.0, v30
	v_add_f32_e32 v31, 1.0, v31
	v_rcp_f32_e32 v30, v30
	v_rcp_f32_e32 v31, v31
	v_add_f32_e32 v24, 1.0, v24
	v_add_f32_e32 v25, 1.0, v25
	v_rcp_f32_e32 v24, v24
	v_rcp_f32_e32 v25, v25
	v_pk_mul_f32 v[28:29], v[28:29], v[34:35] op_sel_hi:[1,0]
	v_pk_mul_f32 v[26:27], v[26:27], v[34:35] op_sel_hi:[1,0]
	v_mul_f32_e32 v28, 0xbfb8aa3b, v28
	v_mul_f32_e32 v29, 0xbfb8aa3b, v29
	v_exp_f32_e32 v28, v28
	v_exp_f32_e32 v29, v29
	v_lshl_add_u64 v[32:33], v[158:159], 0, s[4:5]
	v_pk_mul_f32 v[22:23], v[22:23], v[34:35] op_sel_hi:[1,0]
	v_add_f32_e32 v28, 1.0, v28
	v_add_f32_e32 v29, 1.0, v29
	v_rcp_f32_e32 v28, v28
	v_rcp_f32_e32 v29, v29
	v_pk_mul_f32 v[16:17], v[16:17], v[34:35] op_sel_hi:[1,0]
	v_mul_f32_e32 v22, 0xbfb8aa3b, v22
	v_mul_f32_e32 v23, 0xbfb8aa3b, v23
	v_exp_f32_e32 v22, v22
	v_exp_f32_e32 v23, v23
	v_mul_f32_e32 v16, 0xbfb8aa3b, v16
	v_mul_f32_e32 v17, 0xbfb8aa3b, v17
	v_exp_f32_e32 v16, v16
	v_exp_f32_e32 v17, v17
	v_add_f32_e32 v22, 1.0, v22
	v_add_f32_e32 v23, 1.0, v23
	v_rcp_f32_e32 v22, v22
	v_rcp_f32_e32 v23, v23
	v_add_f32_e32 v16, 1.0, v16
	v_add_f32_e32 v17, 1.0, v17
	v_rcp_f32_e32 v16, v16
	v_rcp_f32_e32 v17, v17
	v_pk_mul_f32 v[20:21], v[20:21], v[34:35] op_sel_hi:[1,0]
	v_pk_mul_f32 v[18:19], v[18:19], v[34:35] op_sel_hi:[1,0]
	v_mul_f32_e32 v20, 0xbfb8aa3b, v20
	v_mul_f32_e32 v21, 0xbfb8aa3b, v21
	v_exp_f32_e32 v20, v20
	v_exp_f32_e32 v21, v21
	s_mov_b32 s2, 0x58000
	s_mov_b64 s[4:5], 0x58000
	v_add_f32_e32 v20, 1.0, v20
	v_add_f32_e32 v21, 1.0, v21
	v_rcp_f32_e32 v20, v20
	v_rcp_f32_e32 v21, v21
	v_lshlrev_b32_e32 v42, 16, v36
	v_and_b32_e32 v43, 0xffff0000, v36
	v_lshlrev_b32_e32 v36, 16, v37
	v_and_b32_e32 v37, 0xffff0000, v37
	v_pk_mul_f32 v[30:31], v[30:31], v[36:37]
	v_lshlrev_b32_e32 v36, 16, v38
	v_and_b32_e32 v37, 0xffff0000, v38
	v_pk_mul_f32 v[36:37], v[24:25], v[36:37]
	v_mul_f32_e32 v24, 0xbfb8aa3b, v26
	v_mul_f32_e32 v25, 0xbfb8aa3b, v27
	v_exp_f32_e32 v24, v24
; __device__ __forceinline__ unsigned cvt_pk_bf16(float lo, float hi) { const f32x2_cv v = {lo, hi}; const bf16x2_cv b = __builtin_convertvector(v, bf16x2_cv); return __builtin_bit_cast(unsigned, b); }
; __device__ __forceinline__ float sigm(float x) { return __builtin_amdgcn_rcpf(1.0f + __expf(-x)); }
; __device__ __forceinline__ float lo16(unsigned w) { return __uint_as_float(w << 16); }
; __device__ __forceinline__ float hi16(unsigned w) { return __uint_as_float(w & 0xffff0000u); }
; __device__ __forceinline__ float rstd_of(const float* rowss, int row) { return rsqrtf(rowss[row] * (1.0f / 1024.0f) + 1e-6f); }
; template <class Epi, class Sched, bool STAMP = false>
; __device__ __forceinline__ void gemm_phase(PG8_LAS unsigned char* lds, const Gemm g, const Sched& S, const Epi& E, unsigned long long* stamps) {
;     ...
;         if (!has_next) break;
;     __device__ __forceinline__ void operator()(const f32x4 (&acc)[2][2][4][2], const pg8::Unit& u, int wr, int wc, int fr, int fq) const {
;     ...
;                 const int row = row0 + ai * 128 + m * 16;
;                 const float s = rstd_of(rowss, row);
; #pragma unroll
;                 for (int bj = 0; bj < 2; ++bj) {
;                     const size_t off = (size_t)row * 1024 + col0 + bj * 128;
;                     const u32x4 tv = *(const u32x4*)(Tm + off);
;                     u32x4 pv = (u32x4){0u, 0u, 0u, 0u};
;                     if (ACC) pv = *(const u32x4*)(M + off);
;                     const f32x4 a0 = acc[ai][bj][m][0] * s, a1 = acc[ai][bj][m][1] * s;
;                     float o[8];
;                     o[0] = sigm(a0[0]) * lo16(tv.x); o[1] = sigm(a0[1]) * hi16(tv.x); o[2] = sigm(a0[2]) * lo16(tv.y); o[3] = sigm(a0[3]) * hi16(tv.y);
;                     o[4] = sigm(a1[0]) * lo16(tv.z); o[5] = sigm(a1[1]) * hi16(tv.z); o[6] = sigm(a1[2]) * lo16(tv.w); o[7] = sigm(a1[3]) * hi16(tv.w);
;                     if (ACC) { o[0] += lo16(pv.x); o[1] += hi16(pv.x); o[2] += lo16(pv.y); o[3] += hi16(pv.y); o[4] += lo16(pv.z); o[5] += hi16(pv.z); o[6] += lo16(pv.w); o[7] += hi16(pv.w); }
;                     u32x4 w; w.x = cvt_pk_bf16(o[0], o[1]); w.y = cvt_pk_bf16(o[2], o[3]); w.z = cvt_pk_bf16(o[4], o[5]); w.w = cvt_pk_bf16(o[6], o[7]);
;                     *(u32x4*)(M + off) = w; } }
	v_exp_f32_e32 v25, v25
	v_lshlrev_b32_e32 v26, 16, v39
	v_and_b32_e32 v27, 0xffff0000, v39
	v_add_f32_e32 v24, 1.0, v24
	v_add_f32_e32 v25, 1.0, v25
	v_rcp_f32_e32 v24, v24
	v_rcp_f32_e32 v25, v25
	v_pk_mul_f32 v[28:29], v[28:29], v[42:43]
	v_pk_mul_f32 v[38:39], v[24:25], v[26:27]
	v_cvt_pk_bf16_f32 v24, v28, v29
	v_cvt_pk_bf16_f32 v25, v30, v31
	v_cvt_pk_bf16_f32 v26, v36, v37
	v_cvt_pk_bf16_f32 v27, v38, v39
	global_store_dwordx4 v[40:41], v[24:27], off
	s_nop 1
	v_mov_b32_e32 v24, v248
	v_mov_b32_e32 v25, v249
	v_mov_b32_e32 v26, v250
	v_mov_b32_e32 v27, v251
	v_lshlrev_b32_e32 v28, 16, v24
	v_and_b32_e32 v29, 0xffff0000, v24
	v_lshlrev_b32_e32 v24, 16, v25
	v_and_b32_e32 v25, 0xffff0000, v25
	v_pk_mul_f32 v[22:23], v[22:23], v[24:25]
	v_lshlrev_b32_e32 v24, 16, v26
	v_and_b32_e32 v25, 0xffff0000, v26
	v_pk_mul_f32 v[24:25], v[16:17], v[24:25]
	v_mul_f32_e32 v16, 0xbfb8aa3b, v18
	v_mul_f32_e32 v17, 0xbfb8aa3b, v19
	v_exp_f32_e32 v16, v16
	v_exp_f32_e32 v17, v17
	v_lshlrev_b32_e32 v18, 16, v27
	v_and_b32_e32 v19, 0xffff0000, v27
	v_add_f32_e32 v16, 1.0, v16
	v_add_f32_e32 v17, 1.0, v17
	v_rcp_f32_e32 v16, v16
	v_rcp_f32_e32 v17, v17
	v_pk_mul_f32 v[20:21], v[20:21], v[28:29]
	v_pk_mul_f32 v[26:27], v[16:17], v[18:19]
	v_cvt_pk_bf16_f32 v16, v20, v21
	v_cvt_pk_bf16_f32 v17, v22, v23
	v_cvt_pk_bf16_f32 v18, v24, v25
	v_cvt_pk_bf16_f32 v19, v26, v27
	global_store_dwordx4 v[32:33], v[16:19], off offset:256
	s_nop 1
	v_mov_b32_e32 v16, v169
	v_fmamk_f32 v16, v16, 0x3a800000, v187
	v_cmp_gt_f32_e32 vcc, s67, v16
	v_mul_f32_e32 v17, 0x4b800000, v16
	s_nop 0
	v_cndmask_b32_e32 v16, v16, v17, vcc
	v_rsq_f32_e32 v16, v16
	s_nop 0
	v_mul_f32_e32 v17, 0x45800000, v16
	v_cndmask_b32_e32 v18, v16, v17, vcc
	v_add_co_u32_e32 v24, vcc, s2, v158
	v_pk_mul_f32 v[14:15], v[14:15], v[18:19] op_sel_hi:[1,0]
	s_nop 0
	v_addc_co_u32_e32 v25, vcc, 0, v159, vcc
	s_nop 1
	v_mov_b32_e32 v20, v176
	v_mov_b32_e32 v21, v177
	v_mov_b32_e32 v22, v178
	v_mov_b32_e32 v23, v179
	v_pk_mul_f32 v[8:9], v[8:9], v[18:19] op_sel_hi:[1,0]
	v_mul_f32_e32 v14, 0xbfb8aa3b, v14
	v_mul_f32_e32 v15, 0xbfb8aa3b, v15
	v_exp_f32_e32 v14, v14
	v_exp_f32_e32 v15, v15
	v_mul_f32_e32 v8, 0xbfb8aa3b, v8
	v_mul_f32_e32 v9, 0xbfb8aa3b, v9
	v_exp_f32_e32 v8, v8
	v_exp_f32_e32 v9, v9
	v_add_f32_e32 v14, 1.0, v14
	v_add_f32_e32 v15, 1.0, v15
	v_rcp_f32_e32 v14, v14
	v_rcp_f32_e32 v15, v15
	v_add_f32_e32 v8, 1.0, v8
	v_add_f32_e32 v9, 1.0, v9
	v_rcp_f32_e32 v8, v8
	v_rcp_f32_e32 v9, v9
	v_pk_mul_f32 v[12:13], v[12:13], v[18:19] op_sel_hi:[1,0]
	v_pk_mul_f32 v[10:11], v[10:11], v[18:19] op_sel_hi:[1,0]
	v_mul_f32_e32 v12, 0xbfb8aa3b, v12
	v_mul_f32_e32 v13, 0xbfb8aa3b, v13
	v_exp_f32_e32 v12, v12
	v_exp_f32_e32 v13, v13
	v_lshl_add_u64 v[16:17], v[158:159], 0, s[4:5]
	v_pk_mul_f32 v[6:7], v[6:7], v[18:19] op_sel_hi:[1,0]
	v_add_f32_e32 v12, 1.0, v12
	v_add_f32_e32 v13, 1.0, v13
	v_rcp_f32_e32 v12, v12
	v_rcp_f32_e32 v13, v13
	v_pk_mul_f32 v[0:1], v[0:1], v[18:19] op_sel_hi:[1,0]
	v_mul_f32_e32 v6, 0xbfb8aa3b, v6
	v_mul_f32_e32 v7, 0xbfb8aa3b, v7
	v_exp_f32_e32 v6, v6
	v_exp_f32_e32 v7, v7
	v_mul_f32_e32 v0, 0xbfb8aa3b, v0
	v_mul_f32_e32 v1, 0xbfb8aa3b, v1
	v_exp_f32_e32 v0, v0
	v_exp_f32_e32 v1, v1
	v_add_f32_e32 v6, 1.0, v6
	v_add_f32_e32 v7, 1.0, v7
	v_rcp_f32_e32 v6, v6
	v_rcp_f32_e32 v7, v7
	v_add_f32_e32 v0, 1.0, v0
	v_add_f32_e32 v1, 1.0, v1
	v_rcp_f32_e32 v0, v0
	v_rcp_f32_e32 v1, v1
	v_pk_mul_f32 v[4:5], v[4:5], v[18:19] op_sel_hi:[1,0]
	v_pk_mul_f32 v[2:3], v[2:3], v[18:19] op_sel_hi:[1,0]
	v_mul_f32_e32 v4, 0xbfb8aa3b, v4
	v_mul_f32_e32 v5, 0xbfb8aa3b, v5
	v_exp_f32_e32 v4, v4
	v_exp_f32_e32 v5, v5
	s_and_b64 vcc, exec, s[38:39]
	s_mov_b32 s2, s30
	v_add_f32_e32 v4, 1.0, v4
	v_add_f32_e32 v5, 1.0, v5
	v_rcp_f32_e32 v4, v4
	v_rcp_f32_e32 v5, v5
	s_mov_b64 s[4:5], s[48:49]
	v_lshlrev_b32_e32 v26, 16, v20
	v_and_b32_e32 v27, 0xffff0000, v20
	v_lshlrev_b32_e32 v20, 16, v21
	v_and_b32_e32 v21, 0xffff0000, v21
	v_pk_mul_f32 v[14:15], v[14:15], v[20:21]
	v_lshlrev_b32_e32 v20, 16, v22
	v_and_b32_e32 v21, 0xffff0000, v22
	v_pk_mul_f32 v[20:21], v[8:9], v[20:21]
	v_mul_f32_e32 v8, 0xbfb8aa3b, v10
	v_mul_f32_e32 v9, 0xbfb8aa3b, v11
	v_exp_f32_e32 v8, v8
	v_exp_f32_e32 v9, v9
	v_lshlrev_b32_e32 v10, 16, v23
	v_and_b32_e32 v11, 0xffff0000, v23
	v_add_f32_e32 v8, 1.0, v8
	v_add_f32_e32 v9, 1.0, v9
	v_rcp_f32_e32 v8, v8
	v_rcp_f32_e32 v9, v9
	v_pk_mul_f32 v[12:13], v[12:13], v[26:27]
	v_pk_mul_f32 v[22:23], v[8:9], v[10:11]
	v_cvt_pk_bf16_f32 v8, v12, v13
	v_cvt_pk_bf16_f32 v9, v14, v15
	v_cvt_pk_bf16_f32 v10, v20, v21
	v_cvt_pk_bf16_f32 v11, v22, v23
	global_store_dwordx4 v[24:25], v[8:11], off
	s_nop 1
	v_mov_b32_e32 v8, v252
	v_mov_b32_e32 v9, v253
	v_mov_b32_e32 v10, v254
	v_mov_b32_e32 v11, v255
	v_lshlrev_b32_e32 v12, 16, v8
	v_and_b32_e32 v13, 0xffff0000, v8
	v_lshlrev_b32_e32 v8, 16, v9
	v_and_b32_e32 v9, 0xffff0000, v9
	v_pk_mul_f32 v[6:7], v[6:7], v[8:9]
	v_lshlrev_b32_e32 v8, 16, v10
	v_and_b32_e32 v9, 0xffff0000, v10
	v_pk_mul_f32 v[8:9], v[0:1], v[8:9]
	v_mul_f32_e32 v0, 0xbfb8aa3b, v2
	v_mul_f32_e32 v1, 0xbfb8aa3b, v3
	v_exp_f32_e32 v0, v0
	v_exp_f32_e32 v1, v1
	v_lshlrev_b32_e32 v2, 16, v11
	v_and_b32_e32 v3, 0xffff0000, v11
	v_add_f32_e32 v0, 1.0, v0
	v_add_f32_e32 v1, 1.0, v1
	v_rcp_f32_e32 v0, v0
	v_rcp_f32_e32 v1, v1
	v_pk_mul_f32 v[4:5], v[4:5], v[12:13]
	v_pk_mul_f32 v[10:11], v[0:1], v[2:3]
	v_cvt_pk_bf16_f32 v0, v4, v5
	v_cvt_pk_bf16_f32 v1, v6, v7
	v_cvt_pk_bf16_f32 v2, v8, v9
	v_cvt_pk_bf16_f32 v3, v10, v11
	global_store_dwordx4 v[16:17], v[0:3], off offset:256
	s_cbranch_vccz .LBB0_306
	s_cmpk_gt_u32 s36, 0xff
	s_cbranch_scc1 .LBB0_317
	s_barrier

; #define PG8_STAGE(bufoff, gbase, voff) do { _Pragma("unroll") for (int _i = 0; _i < 2; ++_i) \
;         __builtin_amdgcn_global_load_lds((const unsigned*)((const char*)(gbase) + (voff)[_i]), (PG8_LAS unsigned*)(lds + (bufoff) + ldsw + _i * 8192), 16, 0, 0); } while (0)
; #define PG8_LDA(dst, b, h) do { _Pragma("unroll") for (int m = 0; m < 4; ++m) _Pragma("unroll") for (int k = 0; k < 2; ++k) dst[m][k] = *(const PG8_LAS bf16x8*)(lds + PG8_SA(b, h) + aoff + m * 2048 + k * 1024); } while (0)
; #define PG8_LDB(dst, b, h) do { _Pragma("unroll") for (int n = 0; n < 2; ++n) _Pragma("unroll") for (int k = 0; k < 2; ++k) dst[n][k] = *(const PG8_LAS bf16x8*)(lds + PG8_SB(b, h) + boff + n * 2048 + k * 1024); } while (0)
; #define PG8_MMA(ai, bj, At, Bt) do { __builtin_amdgcn_s_setprio(1); _Pragma("unroll") for (int m = 0; m < 4; ++m) _Pragma("unroll") for (int n = 0; n < 2; ++n) _Pragma("unroll") for (int k = 0; k < 2; ++k) \
;         acc[ai][bj][m][n] = __builtin_amdgcn_mfma_f32_16x16x32_bf16(Bt[n][k], At[m][k], acc[ai][bj][m][n], 0, 0, 0); __builtin_amdgcn_s_setprio(0); } while (0)
; #define PG8_WAIT_L(n) asm volatile("s_waitcnt lgkmcnt(" #n ")" ::: "memory")
; #define PG8_BAR __builtin_amdgcn_s_barrier()
; #define PG8_SCHED __builtin_amdgcn_sched_barrier(0)
; template <class Epi, class Sched, bool STAMP = false>
; __device__ __forceinline__ void gemm_phase(PG8_LAS unsigned char* lds, const Gemm g, const Sched& S, const Epi& E, unsigned long long* stamps) {
;     ...
;             PG8_LDB(B0, 0, 0); PG8_SCHED; PG8_LDA(At, 0, 0); PG8_STAGE(PG8_SA(1, 1), a1 + hstep, voffA);
;             PG8_WAIT_L(8); PG8_BAR; PG8_WAIT_L(0); PG8_MMA(0, 0, At, B0); PG8_BAR; PG8_SCHED;
;             PG8_LDB(B1, 0, 1); PG8_STAGE(PG8_SB(0, 0), b2, voffB);
;             PG8_BAR; PG8_WAIT_L(0); PG8_MMA(0, 1, At, B1); PG8_BAR;
;             PG8_LDA(At, 0, 1); PG8_STAGE(PG8_SA(0, 0), a2, voffA);
;             PG8_BAR; PG8_WAIT_L(0); PG8_MMA(1, 0, At, B0); PG8_BAR; PG8_SCHED;
.LBB0_333:
	s_add_u32 s14, s36, 0xfffe0080
	s_addc_u32 s15, s37, -1
	s_add_i32 s16, 0, 0x10000
	v_add_u32_e32 v161, s16, v158
	ds_read_b128 v[162:165], v161
	ds_read_b128 v[166:169], v161 offset:1024
	ds_read_b128 v[170:173], v161 offset:2048
	ds_read_b128 v[174:177], v161 offset:3072
	s_cmp_eq_u32 s97, 4
	s_cselect_b32 s59, s13, s15
	s_cselect_b32 s58, s77, s14
	s_cselect_b32 s57, s5, s96
	s_cselect_b32 s56, s88, s89
	v_lshl_add_u64 v[182:183], s[36:37], 0, v[154:155]
	s_add_i32 m0, s3, 0xc000
	ds_read_b128 v[178:181], v160
	ds_read_b128 v[192:195], v160 offset:1024
	ds_read_b128 v[196:199], v160 offset:2048
	ds_read_b128 v[200:203], v160 offset:3072
	ds_read_b128 v[204:207], v160 offset:4096
	ds_read_b128 v[208:211], v160 offset:5120
	ds_read_b128 v[212:215], v160 offset:6144
	ds_read_b128 v[216:219], v160 offset:7168
	global_load_lds_dwordx4 v[182:183], off
	v_lshl_add_u64 v[182:183], s[36:37], 0, v[156:157]
	s_add_i32 m0, s3, 0xe000
	s_nop 0
	global_load_lds_dwordx4 v[182:183], off
	s_waitcnt lgkmcnt(8)
	s_barrier
	s_waitcnt lgkmcnt(0)
	s_waitcnt lgkmcnt(0)
	v_mfma_f32_16x16x32_bf16 v[124:127], v[162:165], v[178:181], v[124:127]
	v_mfma_f32_16x16x32_bf16 v[120:123], v[170:173], v[178:181], v[120:123]
	v_mfma_f32_16x16x32_bf16 v[116:119], v[162:165], v[196:199], v[116:119]
	v_mfma_f32_16x16x32_bf16 v[112:115], v[170:173], v[196:199], v[112:115]
	v_mfma_f32_16x16x32_bf16 v[100:103], v[162:165], v[204:207], v[100:103]
	v_mfma_f32_16x16x32_bf16 v[96:99], v[170:173], v[204:207], v[96:99]
	v_mfma_f32_16x16x32_bf16 v[84:87], v[162:165], v[212:215], v[84:87]
	v_mfma_f32_16x16x32_bf16 v[80:83], v[170:173], v[212:215], v[80:83]
	v_mfma_f32_16x16x32_bf16 v[124:127], v[166:169], v[192:195], v[124:127]
	v_mfma_f32_16x16x32_bf16 v[120:123], v[174:177], v[192:195], v[120:123]
	v_mfma_f32_16x16x32_bf16 v[116:119], v[166:169], v[200:203], v[116:119]
	v_mfma_f32_16x16x32_bf16 v[112:115], v[174:177], v[200:203], v[112:115]
	v_mfma_f32_16x16x32_bf16 v[100:103], v[166:169], v[208:211], v[100:103]
	v_mfma_f32_16x16x32_bf16 v[96:99], v[174:177], v[208:211], v[96:99]
	v_mfma_f32_16x16x32_bf16 v[84:87], v[166:169], v[216:219], v[84:87]
	v_mfma_f32_16x16x32_bf16 v[80:83], v[174:177], v[216:219], v[80:83]
	s_barrier
	s_add_i32 s17, 0, 0x14000
	s_add_i32 s14, s16, s53
	v_add_u32_e32 v161, s17, v158
	v_lshl_add_u64 v[182:183], s[56:57], 0, v[128:129]
	s_mov_b32 m0, s14
	ds_read_b128 v[220:223], v161
	ds_read_b128 v[224:227], v161 offset:1024
	ds_read_b128 v[228:231], v161 offset:2048
	ds_read_b128 v[232:235], v161 offset:3072
	global_load_lds_dwordx4 v[182:183], off
	v_lshl_add_u64 v[236:237], s[56:57], 0, v[152:153]
	s_add_i32 m0, s14, 0x2000
	s_nop 0
	global_load_lds_dwordx4 v[236:237], off
	s_barrier
	s_waitcnt lgkmcnt(0)
	s_waitcnt lgkmcnt(0)
	v_mfma_f32_16x16x32_bf16 v[108:111], v[220:223], v[178:181], v[108:111]
	v_mfma_f32_16x16x32_bf16 v[104:107], v[228:231], v[178:181], v[104:107]
	v_mfma_f32_16x16x32_bf16 v[92:95], v[220:223], v[196:199], v[92:95]
	v_mfma_f32_16x16x32_bf16 v[88:91], v[228:231], v[196:199], v[88:91]
	v_mfma_f32_16x16x32_bf16 v[76:79], v[220:223], v[204:207], v[76:79]
	v_mfma_f32_16x16x32_bf16 v[72:75], v[228:231], v[204:207], v[72:75]
	v_mfma_f32_16x16x32_bf16 v[68:71], v[220:223], v[212:215], v[68:71]
	v_mfma_f32_16x16x32_bf16 v[64:67], v[228:231], v[212:215], v[64:67]
	v_mfma_f32_16x16x32_bf16 v[108:111], v[224:227], v[192:195], v[108:111]
	v_mfma_f32_16x16x32_bf16 v[104:107], v[232:235], v[192:195], v[104:107]
	v_mfma_f32_16x16x32_bf16 v[92:95], v[224:227], v[200:203], v[92:95]
	v_mfma_f32_16x16x32_bf16 v[88:91], v[232:235], v[200:203], v[88:91]
	v_mfma_f32_16x16x32_bf16 v[76:79], v[224:227], v[208:211], v[76:79]
	v_mfma_f32_16x16x32_bf16 v[72:75], v[232:235], v[208:211], v[72:75]
	v_mfma_f32_16x16x32_bf16 v[68:71], v[224:227], v[216:219], v[68:71]
	v_mfma_f32_16x16x32_bf16 v[64:67], v[232:235], v[216:219], v[64:67]
	s_mov_b32 m0, s3
	v_lshl_add_u64 v[238:239], s[58:59], 0, v[148:149]
	s_barrier
	ds_read_b128 v[178:181], v160 offset:16384
	ds_read_b128 v[192:195], v160 offset:17408
	ds_read_b128 v[196:199], v160 offset:18432
	ds_read_b128 v[200:203], v160 offset:19456
	ds_read_b128 v[204:207], v160 offset:20480
	ds_read_b128 v[208:211], v160 offset:21504
	ds_read_b128 v[212:215], v160 offset:22528
	ds_read_b128 v[216:219], v160 offset:23552
	global_load_lds_dwordx4 v[238:239], off
	v_lshl_add_u64 v[240:241], s[58:59], 0, v[150:151]
	s_mov_b32 m0, s60
	s_nop 0
	global_load_lds_dwordx4 v[240:241], off
	s_barrier
	s_waitcnt lgkmcnt(0)
	s_waitcnt lgkmcnt(0)
	v_mfma_f32_16x16x32_bf16 v[60:63], v[162:165], v[178:181], v[60:63]
	v_mfma_f32_16x16x32_bf16 v[56:59], v[170:173], v[178:181], v[56:59]
	v_mfma_f32_16x16x32_bf16 v[52:55], v[162:165], v[196:199], v[52:55]
	v_mfma_f32_16x16x32_bf16 v[48:51], v[170:173], v[196:199], v[48:51]
	v_mfma_f32_16x16x32_bf16 v[36:39], v[162:165], v[204:207], v[36:39]
	v_mfma_f32_16x16x32_bf16 v[32:35], v[170:173], v[204:207], v[32:35]
	v_mfma_f32_16x16x32_bf16 v[20:23], v[162:165], v[212:215], v[20:23]
	v_mfma_f32_16x16x32_bf16 v[16:19], v[170:173], v[212:215], v[16:19]
	v_mfma_f32_16x16x32_bf16 v[60:63], v[166:169], v[192:195], v[60:63]
	v_mfma_f32_16x16x32_bf16 v[56:59], v[174:177], v[192:195], v[56:59]
	v_mfma_f32_16x16x32_bf16 v[52:55], v[166:169], v[200:203], v[52:55]
	v_mfma_f32_16x16x32_bf16 v[48:51], v[174:177], v[200:203], v[48:51]
	v_mfma_f32_16x16x32_bf16 v[36:39], v[166:169], v[208:211], v[36:39]
	v_mfma_f32_16x16x32_bf16 v[32:35], v[174:177], v[208:211], v[32:35]
	v_mfma_f32_16x16x32_bf16 v[20:23], v[166:169], v[216:219], v[20:23]
	v_mfma_f32_16x16x32_bf16 v[16:19], v[174:177], v[216:219], v[16:19]
	s_barrier
; #define PG8_STAGE(bufoff, gbase, voff) do { _Pragma("unroll") for (int _i = 0; _i < 2; ++_i) \
;         __builtin_amdgcn_global_load_lds((const unsigned*)((const char*)(gbase) + (voff)[_i]), (PG8_LAS unsigned*)(lds + (bufoff) + ldsw + _i * 8192), 16, 0, 0); } while (0)
; #define PG8_LDA(dst, b, h) do { _Pragma("unroll") for (int m = 0; m < 4; ++m) _Pragma("unroll") for (int k = 0; k < 2; ++k) dst[m][k] = *(const PG8_LAS bf16x8*)(lds + PG8_SA(b, h) + aoff + m * 2048 + k * 1024); } while (0)
; #define PG8_LDB(dst, b, h) do { _Pragma("unroll") for (int n = 0; n < 2; ++n) _Pragma("unroll") for (int k = 0; k < 2; ++k) dst[n][k] = *(const PG8_LAS bf16x8*)(lds + PG8_SB(b, h) + boff + n * 2048 + k * 1024); } while (0)
; #define PG8_MMA(ai, bj, At, Bt) do { __builtin_amdgcn_s_setprio(1); _Pragma("unroll") for (int m = 0; m < 4; ++m) _Pragma("unroll") for (int n = 0; n < 2; ++n) _Pragma("unroll") for (int k = 0; k < 2; ++k) \
;         acc[ai][bj][m][n] = __builtin_amdgcn_mfma_f32_16x16x32_bf16(Bt[n][k], At[m][k], acc[ai][bj][m][n], 0, 0, 0); __builtin_amdgcn_s_setprio(0); } while (0)
; #define PG8_WAIT_V(n) asm volatile("s_waitcnt vmcnt(" #n ")" ::: "memory")
; #define PG8_WAIT_L(n) asm volatile("s_waitcnt lgkmcnt(" #n ")" ::: "memory")
; #define PG8_BAR __builtin_amdgcn_s_barrier()
; #define PG8_SCHED __builtin_amdgcn_sched_barrier(0)
; template <class Epi, class Sched, bool STAMP = false>
; __device__ __forceinline__ void gemm_phase(PG8_LAS unsigned char* lds, const Gemm g, const Sched& S, const Epi& E, unsigned long long* stamps) {
;     ...
;             PG8_STAGE(PG8_SB(0, 1), b2 + hstep, voffB);
;             PG8_WAIT_V(6); PG8_BAR; PG8_MMA(1, 1, At, B1); PG8_BAR;
;             PG8_LDB(B0, 1, 0); PG8_SCHED; PG8_LDA(At, 1, 0); PG8_STAGE(PG8_SA(0, 1), a2 + hstep, voffA);
;             PG8_WAIT_L(8); PG8_BAR; PG8_WAIT_L(0); PG8_MMA(0, 0, At, B0); PG8_BAR; PG8_SCHED;
;             PG8_LDB(B1, 1, 1); PG8_STAGE(PG8_SB(1, 0), b3, voffB);
;             PG8_BAR; PG8_WAIT_L(0); PG8_MMA(0, 1, At, B1); PG8_BAR;
;             PG8_LDA(At, 1, 1); PG8_STAGE(PG8_SA(1, 0), a3, voffA);
	s_add_u32 s14, s56, 0x20000
	s_addc_u32 s15, s57, 0
	s_add_i32 s16, s17, s53
	v_lshl_add_u64 v[162:163], s[14:15], 0, v[128:129]
	s_mov_b32 m0, s16
	s_nop 0
	global_load_lds_dwordx4 v[162:163], off
	v_lshl_add_u64 v[162:163], s[14:15], 0, v[152:153]
	s_add_i32 m0, s16, 0x2000
	s_nop 0
	global_load_lds_dwordx4 v[162:163], off
	s_waitcnt vmcnt(6)
	s_barrier
	v_mfma_f32_16x16x32_bf16 v[44:47], v[220:223], v[178:181], v[44:47]
	v_mfma_f32_16x16x32_bf16 v[40:43], v[228:231], v[178:181], v[40:43]
	v_mfma_f32_16x16x32_bf16 v[28:31], v[220:223], v[196:199], v[28:31]
	v_mfma_f32_16x16x32_bf16 v[24:27], v[228:231], v[196:199], v[24:27]
	v_mfma_f32_16x16x32_bf16 v[12:15], v[220:223], v[204:207], v[12:15]
	v_mfma_f32_16x16x32_bf16 v[8:11], v[228:231], v[204:207], v[8:11]
	v_mfma_f32_16x16x32_bf16 v[4:7], v[220:223], v[212:215], v[4:7]
	v_mfma_f32_16x16x32_bf16 v[0:3], v[228:231], v[212:215], v[0:3]
	v_mfma_f32_16x16x32_bf16 v[44:47], v[224:227], v[192:195], v[44:47]
	v_mfma_f32_16x16x32_bf16 v[40:43], v[232:235], v[192:195], v[40:43]
	v_mfma_f32_16x16x32_bf16 v[28:31], v[224:227], v[200:203], v[28:31]
	v_mfma_f32_16x16x32_bf16 v[24:27], v[232:235], v[200:203], v[24:27]
	v_mfma_f32_16x16x32_bf16 v[12:15], v[224:227], v[208:211], v[12:15]
	v_mfma_f32_16x16x32_bf16 v[8:11], v[232:235], v[208:211], v[8:11]
	v_mfma_f32_16x16x32_bf16 v[4:7], v[224:227], v[216:219], v[4:7]
	v_mfma_f32_16x16x32_bf16 v[0:3], v[232:235], v[216:219], v[0:3]
	s_add_i32 s16, 0, 0x18000
	v_add_u32_e32 v161, s16, v158
	s_barrier
	ds_read_b128 v[162:165], v161
	ds_read_b128 v[166:169], v161 offset:1024
	ds_read_b128 v[170:173], v161 offset:2048
	ds_read_b128 v[174:177], v161 offset:3072
	s_add_u32 s14, s58, 0x20000
	s_addc_u32 s15, s59, 0
	s_mov_b32 m0, s61
	v_lshl_add_u64 v[220:221], s[14:15], 0, v[148:149]
	ds_read_b128 v[178:181], v160 offset:32768
	ds_read_b128 v[192:195], v160 offset:33792
	ds_read_b128 v[196:199], v160 offset:34816
	ds_read_b128 v[200:203], v160 offset:35840
	ds_read_b128 v[204:207], v160 offset:36864
	ds_read_b128 v[208:211], v160 offset:37888
	ds_read_b128 v[212:215], v160 offset:38912
	ds_read_b128 v[216:219], v160 offset:39936
	global_load_lds_dwordx4 v[220:221], off
	v_lshl_add_u64 v[220:221], s[14:15], 0, v[150:151]
	s_mov_b32 m0, s62
	s_nop 0
	global_load_lds_dwordx4 v[220:221], off
	s_waitcnt lgkmcnt(8)
	s_barrier
	s_waitcnt lgkmcnt(0)
	s_waitcnt lgkmcnt(0)
	v_mfma_f32_16x16x32_bf16 v[124:127], v[162:165], v[178:181], v[124:127]
	v_mfma_f32_16x16x32_bf16 v[120:123], v[170:173], v[178:181], v[120:123]
	v_mfma_f32_16x16x32_bf16 v[116:119], v[162:165], v[196:199], v[116:119]
	v_mfma_f32_16x16x32_bf16 v[112:115], v[170:173], v[196:199], v[112:115]
	v_mfma_f32_16x16x32_bf16 v[100:103], v[162:165], v[204:207], v[100:103]
	v_mfma_f32_16x16x32_bf16 v[96:99], v[170:173], v[204:207], v[96:99]
	v_mfma_f32_16x16x32_bf16 v[84:87], v[162:165], v[212:215], v[84:87]
	v_mfma_f32_16x16x32_bf16 v[80:83], v[170:173], v[212:215], v[80:83]
	v_mfma_f32_16x16x32_bf16 v[124:127], v[166:169], v[192:195], v[124:127]
	v_mfma_f32_16x16x32_bf16 v[120:123], v[174:177], v[192:195], v[120:123]
	v_mfma_f32_16x16x32_bf16 v[116:119], v[166:169], v[200:203], v[116:119]
	v_mfma_f32_16x16x32_bf16 v[112:115], v[174:177], v[200:203], v[112:115]
	v_mfma_f32_16x16x32_bf16 v[100:103], v[166:169], v[208:211], v[100:103]
	v_mfma_f32_16x16x32_bf16 v[96:99], v[174:177], v[208:211], v[96:99]
	v_mfma_f32_16x16x32_bf16 v[84:87], v[166:169], v[216:219], v[84:87]
	v_mfma_f32_16x16x32_bf16 v[80:83], v[174:177], v[216:219], v[80:83]
	s_barrier
	s_add_i32 s17, 0, 0x1c000
	s_add_i32 s14, s16, s53
	v_add_u32_e32 v161, s17, v158
	v_lshl_add_u64 v[182:183], v[182:183], 0, s[18:19]
	s_mov_b32 m0, s14
	ds_read_b128 v[220:223], v161
	ds_read_b128 v[224:227], v161 offset:1024
	ds_read_b128 v[228:231], v161 offset:2048
	ds_read_b128 v[232:235], v161 offset:3072
	global_load_lds_dwordx4 v[182:183], off
	v_lshl_add_u64 v[182:183], v[236:237], 0, s[18:19]
	s_add_i32 m0, s14, 0x2000
	s_nop 0
	global_load_lds_dwordx4 v[182:183], off
	s_barrier
	s_waitcnt lgkmcnt(0)
	s_waitcnt lgkmcnt(0)
	v_mfma_f32_16x16x32_bf16 v[108:111], v[220:223], v[178:181], v[108:111]
	v_mfma_f32_16x16x32_bf16 v[104:107], v[228:231], v[178:181], v[104:107]
	v_mfma_f32_16x16x32_bf16 v[92:95], v[220:223], v[196:199], v[92:95]
	v_mfma_f32_16x16x32_bf16 v[88:91], v[228:231], v[196:199], v[88:91]
	v_mfma_f32_16x16x32_bf16 v[76:79], v[220:223], v[204:207], v[76:79]
	v_mfma_f32_16x16x32_bf16 v[72:75], v[228:231], v[204:207], v[72:75]
	v_mfma_f32_16x16x32_bf16 v[68:71], v[220:223], v[212:215], v[68:71]
	v_mfma_f32_16x16x32_bf16 v[64:67], v[228:231], v[212:215], v[64:67]
	v_mfma_f32_16x16x32_bf16 v[108:111], v[224:227], v[192:195], v[108:111]
	v_mfma_f32_16x16x32_bf16 v[104:107], v[232:235], v[192:195], v[104:107]
	v_mfma_f32_16x16x32_bf16 v[92:95], v[224:227], v[200:203], v[92:95]
	v_mfma_f32_16x16x32_bf16 v[88:91], v[232:235], v[200:203], v[88:91]
	v_mfma_f32_16x16x32_bf16 v[76:79], v[224:227], v[208:211], v[76:79]
	v_mfma_f32_16x16x32_bf16 v[72:75], v[232:235], v[208:211], v[72:75]
	v_mfma_f32_16x16x32_bf16 v[68:71], v[224:227], v[216:219], v[68:71]
	v_mfma_f32_16x16x32_bf16 v[64:67], v[232:235], v[216:219], v[64:67]
	s_mov_b32 m0, s63
	v_lshl_add_u64 v[182:183], v[238:239], 0, s[18:19]
	s_barrier
	ds_read_b128 v[178:181], v160 offset:49152
	ds_read_b128 v[192:195], v160 offset:50176
	ds_read_b128 v[196:199], v160 offset:51200
	ds_read_b128 v[200:203], v160 offset:52224
	ds_read_b128 v[204:207], v160 offset:53248
	ds_read_b128 v[208:211], v160 offset:54272
	ds_read_b128 v[212:215], v160 offset:55296
	ds_read_b128 v[216:219], v160 offset:56320
	global_load_lds_dwordx4 v[182:183], off
	v_lshl_add_u64 v[182:183], v[240:241], 0, s[18:19]
	s_mov_b32 m0, s64
	s_nop 0
	global_load_lds_dwordx4 v[182:183], off
	s_barrier
; #define PG8_STAGE(bufoff, gbase, voff) do { _Pragma("unroll") for (int _i = 0; _i < 2; ++_i) \
;         __builtin_amdgcn_global_load_lds((const unsigned*)((const char*)(gbase) + (voff)[_i]), (PG8_LAS unsigned*)(lds + (bufoff) + ldsw + _i * 8192), 16, 0, 0); } while (0)
; #define PG8_MMA(ai, bj, At, Bt) do { __builtin_amdgcn_s_setprio(1); _Pragma("unroll") for (int m = 0; m < 4; ++m) _Pragma("unroll") for (int n = 0; n < 2; ++n) _Pragma("unroll") for (int k = 0; k < 2; ++k) \
;         acc[ai][bj][m][n] = __builtin_amdgcn_mfma_f32_16x16x32_bf16(Bt[n][k], At[m][k], acc[ai][bj][m][n], 0, 0, 0); __builtin_amdgcn_s_setprio(0); } while (0)
; #define PG8_WAIT_V(n) asm volatile("s_waitcnt vmcnt(" #n ")" ::: "memory")
; #define PG8_WAIT_L(n) asm volatile("s_waitcnt lgkmcnt(" #n ")" ::: "memory")
; #define PG8_BAR __builtin_amdgcn_s_barrier()
; #define PG8_SCHED __builtin_amdgcn_sched_barrier(0)
; template <class Epi, class Sched, bool STAMP = false>
; __device__ __forceinline__ void gemm_phase(PG8_LAS unsigned char* lds, const Gemm g, const Sched& S, const Epi& E, unsigned long long* stamps) {
;     ...
;             PG8_BAR; PG8_WAIT_L(0); PG8_MMA(1, 0, At, B0); PG8_BAR; PG8_SCHED;
;             PG8_STAGE(PG8_SB(1, 1), b3 + hstep, voffB);
;             PG8_WAIT_V(6); PG8_BAR; PG8_MMA(1, 1, At, B1); PG8_BAR;
	s_waitcnt lgkmcnt(0)
	s_waitcnt lgkmcnt(0)
	v_mfma_f32_16x16x32_bf16 v[60:63], v[162:165], v[178:181], v[60:63]
	v_mfma_f32_16x16x32_bf16 v[56:59], v[170:173], v[178:181], v[56:59]
	v_mfma_f32_16x16x32_bf16 v[52:55], v[162:165], v[196:199], v[52:55]
	v_mfma_f32_16x16x32_bf16 v[48:51], v[170:173], v[196:199], v[48:51]
	v_mfma_f32_16x16x32_bf16 v[36:39], v[162:165], v[204:207], v[36:39]
	v_mfma_f32_16x16x32_bf16 v[32:35], v[170:173], v[204:207], v[32:35]
	v_mfma_f32_16x16x32_bf16 v[20:23], v[162:165], v[212:215], v[20:23]
	v_mfma_f32_16x16x32_bf16 v[16:19], v[170:173], v[212:215], v[16:19]
	v_mfma_f32_16x16x32_bf16 v[60:63], v[166:169], v[192:195], v[60:63]
	v_mfma_f32_16x16x32_bf16 v[56:59], v[174:177], v[192:195], v[56:59]
	v_mfma_f32_16x16x32_bf16 v[52:55], v[166:169], v[200:203], v[52:55]
	v_mfma_f32_16x16x32_bf16 v[48:51], v[174:177], v[200:203], v[48:51]
	v_mfma_f32_16x16x32_bf16 v[36:39], v[166:169], v[208:211], v[36:39]
	v_mfma_f32_16x16x32_bf16 v[32:35], v[174:177], v[208:211], v[32:35]
	v_mfma_f32_16x16x32_bf16 v[20:23], v[166:169], v[216:219], v[20:23]
	v_mfma_f32_16x16x32_bf16 v[16:19], v[174:177], v[216:219], v[16:19]
	s_barrier
	s_add_u32 s14, s56, 0x20080
	s_addc_u32 s15, s57, 0
	s_add_i32 s16, s17, s53
	v_lshl_add_u64 v[162:163], s[14:15], 0, v[128:129]
	s_mov_b32 m0, s16
	s_nop 0
	global_load_lds_dwordx4 v[162:163], off
	v_lshl_add_u64 v[162:163], s[14:15], 0, v[152:153]
	s_add_i32 m0, s16, 0x2000
	s_nop 0
	global_load_lds_dwordx4 v[162:163], off
	s_waitcnt vmcnt(6)
	s_barrier
	v_mfma_f32_16x16x32_bf16 v[44:47], v[220:223], v[178:181], v[44:47]
	v_mfma_f32_16x16x32_bf16 v[40:43], v[228:231], v[178:181], v[40:43]
	v_mfma_f32_16x16x32_bf16 v[28:31], v[220:223], v[196:199], v[28:31]
	v_mfma_f32_16x16x32_bf16 v[24:27], v[228:231], v[196:199], v[24:27]
	v_mfma_f32_16x16x32_bf16 v[12:15], v[220:223], v[204:207], v[12:15]
	v_mfma_f32_16x16x32_bf16 v[8:11], v[228:231], v[204:207], v[8:11]
	v_mfma_f32_16x16x32_bf16 v[4:7], v[220:223], v[212:215], v[4:7]
	v_mfma_f32_16x16x32_bf16 v[0:3], v[228:231], v[212:215], v[0:3]
	v_mfma_f32_16x16x32_bf16 v[44:47], v[224:227], v[192:195], v[44:47]
	v_mfma_f32_16x16x32_bf16 v[40:43], v[232:235], v[192:195], v[40:43]
	v_mfma_f32_16x16x32_bf16 v[28:31], v[224:227], v[200:203], v[28:31]
	v_mfma_f32_16x16x32_bf16 v[24:27], v[232:235], v[200:203], v[24:27]
	v_mfma_f32_16x16x32_bf16 v[12:15], v[224:227], v[208:211], v[12:15]
	v_mfma_f32_16x16x32_bf16 v[8:11], v[232:235], v[208:211], v[8:11]
	v_mfma_f32_16x16x32_bf16 v[4:7], v[224:227], v[216:219], v[4:7]
	v_mfma_f32_16x16x32_bf16 v[0:3], v[232:235], v[216:219], v[0:3]
	s_add_i32 s97, s97, 2
	s_add_u32 s36, s36, 0x100
	s_addc_u32 s37, s37, 0
	s_add_u32 s89, s89, 0x100
	s_addc_u32 s96, s96, 0
	s_cmp_gt_u32 s97, 5
	s_barrier
	s_cbranch_scc0 .LBB0_333
; __device__ __forceinline__ unsigned cvt_pk_bf16(float lo, float hi) { const f32x2_cv v = {lo, hi}; const bf16x2_cv b = __builtin_convertvector(v, bf16x2_cv); return __builtin_bit_cast(unsigned, b); }
; __device__ __forceinline__ float rstd_of(const float* rowss, int row) { return rsqrtf(rowss[row] * (1.0f / 1024.0f) + 1e-6f); }
;     __device__ __forceinline__ void operator()(const f32x4 (&acc)[2][2][4][2], const pg8::Unit& u, int wr, int wc, int fr, int fq) const {
;         const int row0 = u.pm * 256 + wr * 64 + fr, col0 = u.pn * 256 + wc * 32 + 8 * fq;
; #pragma unroll
;         for (int ai = 0; ai < 2; ++ai)
; #pragma unroll
;             for (int m = 0; m < 4; ++m) {
;                 const int row = row0 + ai * 128 + m * 16;
;                 const float s = (MODE == 2) ? 1.0f : rstd_of(rowss, row);
;                 bf16_t* rowp = O + (size_t)row * ldc + col0;
; #pragma unroll
;                 for (int bj = 0; bj < 2; ++bj) {
;                     f32x4 v0 = acc[ai][bj][m][0] * s, v1 = acc[ai][bj][m][1] * s;
;                     if (MODE == 1) {
; #pragma unroll
;                         for (int j = 0; j < 4; ++j) { const float a = fmaxf(v0[j], 0.f), b = fmaxf(v1[j], 0.f); v0[j] = a * a; v1[j] = b * b; } }
;                     u32x4 w; w.x = cvt_pk_bf16(v0[0], v0[1]); w.y = cvt_pk_bf16(v0[2], v0[3]); w.z = cvt_pk_bf16(v1[0], v1[1]); w.w = cvt_pk_bf16(v1[2], v1[3]);
;                     *(u32x4*)(rowp + bj * 128) = w; } }
	v_lshl_add_u32 v162, s2, 8, v139
	v_lshl_or_b32 v164, s76, 8, v159
	v_ashrrev_i32_e32 v163, 31, v162
	v_ashrrev_i32_e32 v165, 31, v164
	v_lshlrev_b64 v[166:167], 11, v[162:163]
	v_lshl_add_u64 v[166:167], s[30:31], 0, v[166:167]
	v_lshlrev_b64 v[164:165], 1, v[164:165]
	v_lshl_add_u64 v[166:167], v[166:167], 0, v[164:165]
	s_mov_b32 s2, 0x40000
	s_mov_b64 s[14:15], 0x40000
	v_cvt_pk_bf16_f32 v60, v60, v61
	v_cvt_pk_bf16_f32 v61, v62, v63
	v_cvt_pk_bf16_f32 v62, v56, v57
	v_add_co_u32_e32 v56, vcc, s2, v166
	v_cvt_pk_bf16_f32 v68, v68, v69
	v_cvt_pk_bf16_f32 v69, v70, v71
	v_cvt_pk_bf16_f32 v70, v64, v65
	v_lshl_add_u64 v[64:65], v[166:167], 0, s[14:15]
	v_addc_co_u32_e32 v57, vcc, 0, v167, vcc
	v_cvt_pk_bf16_f32 v44, v44, v45
	v_cvt_pk_bf16_f32 v45, v46, v47
	v_cvt_pk_bf16_f32 v46, v40, v41
	v_cvt_pk_bf16_f32 v47, v42, v43
	s_mov_b32 s2, 0x48000
	v_cvt_pk_bf16_f32 v108, v108, v109
	v_cvt_pk_bf16_f32 v109, v110, v111
	v_cvt_pk_bf16_f32 v110, v104, v105
	v_or_b32_e32 v104, 16, v162
	global_store_dwordx4 v[64:65], v[44:47], off offset:256
	s_mov_b64 s[14:15], 0x48000
	v_ashrrev_i32_e32 v105, 31, v104
	v_add_co_u32_e32 v46, vcc, s2, v166
	v_cvt_pk_bf16_f32 v92, v92, v93
	v_cvt_pk_bf16_f32 v93, v94, v95
	v_cvt_pk_bf16_f32 v94, v88, v89
	v_or_b32_e32 v88, 32, v162
	v_lshl_add_u64 v[44:45], v[166:167], 0, s[14:15]
	v_addc_co_u32_e32 v47, vcc, 0, v167, vcc
	v_cvt_pk_bf16_f32 v28, v28, v29
	v_cvt_pk_bf16_f32 v29, v30, v31
	v_cvt_pk_bf16_f32 v30, v24, v25
	v_cvt_pk_bf16_f32 v31, v26, v27
	s_mov_b32 s2, 0x50000
	v_lshlrev_b64 v[104:105], 11, v[104:105]
	v_ashrrev_i32_e32 v89, 31, v88
	v_cvt_pk_bf16_f32 v76, v76, v77
	v_cvt_pk_bf16_f32 v77, v78, v79
	v_cvt_pk_bf16_f32 v78, v72, v73
	v_or_b32_e32 v72, 48, v162
	global_store_dwordx4 v[44:45], v[28:31], off offset:256
	s_mov_b64 s[14:15], 0x50000
	v_cvt_pk_bf16_f32 v111, v106, v107
	v_add_co_u32_e32 v30, vcc, s2, v166
	v_lshl_add_u64 v[104:105], s[30:31], 0, v[104:105]
	v_lshlrev_b64 v[88:89], 11, v[88:89]
	v_ashrrev_i32_e32 v73, 31, v72
	v_lshl_add_u64 v[28:29], v[166:167], 0, s[14:15]
	v_addc_co_u32_e32 v31, vcc, 0, v167, vcc
	v_cvt_pk_bf16_f32 v12, v12, v13
	v_cvt_pk_bf16_f32 v13, v14, v15
	v_cvt_pk_bf16_f32 v14, v8, v9
	v_cvt_pk_bf16_f32 v15, v10, v11
	s_mov_b32 s2, 0x58000
	global_store_dwordx4 v[166:167], v[108:111], off offset:256
	v_cvt_pk_bf16_f32 v95, v90, v91
	v_lshl_add_u64 v[88:89], s[30:31], 0, v[88:89]
	v_lshl_add_u64 v[108:109], v[104:105], 0, v[164:165]
	v_lshlrev_b64 v[72:73], 11, v[72:73]
	global_store_dwordx4 v[28:29], v[12:15], off offset:256
	global_store_dwordx4 v[108:109], v[92:95], off offset:256
	v_cvt_pk_bf16_f32 v79, v74, v75
	v_add_co_u32_e32 v14, vcc, s2, v166
	v_lshl_add_u64 v[92:93], v[88:89], 0, v[164:165]
	v_lshl_add_u64 v[72:73], s[30:31], 0, v[72:73]
	s_mov_b64 s[14:15], 0x58000
	v_addc_co_u32_e32 v15, vcc, 0, v167, vcc
	v_readlane_b32 s88, v242, 39
	v_cvt_pk_bf16_f32 v124, v124, v125
	v_cvt_pk_bf16_f32 v125, v126, v127
	v_cvt_pk_bf16_f32 v126, v120, v121
	v_cvt_pk_bf16_f32 v127, v122, v123
	v_cvt_pk_bf16_f32 v104, v116, v117
	v_cvt_pk_bf16_f32 v105, v118, v119
	v_cvt_pk_bf16_f32 v106, v112, v113
	v_cvt_pk_bf16_f32 v107, v114, v115
	v_cvt_pk_bf16_f32 v88, v100, v101
	v_cvt_pk_bf16_f32 v89, v102, v103
	v_cvt_pk_bf16_f32 v90, v96, v97
	v_cvt_pk_bf16_f32 v91, v98, v99
	global_store_dwordx4 v[92:93], v[76:79], off offset:256
	v_cvt_pk_bf16_f32 v74, v80, v81
	v_cvt_pk_bf16_f32 v75, v82, v83
	v_lshl_add_u64 v[76:77], v[72:73], 0, v[164:165]
	v_cvt_pk_bf16_f32 v72, v84, v85
	v_cvt_pk_bf16_f32 v73, v86, v87
	v_cvt_pk_bf16_f32 v71, v66, v67
	v_cvt_pk_bf16_f32 v63, v58, v59
	v_cvt_pk_bf16_f32 v40, v52, v53
	v_cvt_pk_bf16_f32 v41, v54, v55
	v_cvt_pk_bf16_f32 v42, v48, v49
	v_cvt_pk_bf16_f32 v43, v50, v51
	v_cvt_pk_bf16_f32 v24, v36, v37
	v_cvt_pk_bf16_f32 v25, v38, v39
	v_cvt_pk_bf16_f32 v26, v32, v33
	v_cvt_pk_bf16_f32 v27, v34, v35
	v_lshl_add_u64 v[12:13], v[166:167], 0, s[14:15]
	v_cvt_pk_bf16_f32 v8, v20, v21
	v_cvt_pk_bf16_f32 v9, v22, v23
	v_cvt_pk_bf16_f32 v10, v16, v17
	v_cvt_pk_bf16_f32 v11, v18, v19
	v_cvt_pk_bf16_f32 v4, v4, v5
	v_cvt_pk_bf16_f32 v5, v6, v7
	v_cvt_pk_bf16_f32 v6, v0, v1
	v_cvt_pk_bf16_f32 v7, v2, v3
	s_and_b64 vcc, exec, s[38:39]
	s_mov_b32 s76, s4
	s_mov_b32 s2, s12
	s_mov_b64 s[56:57], s[26:27]
	s_mov_b64 s[36:37], s[24:25]
	s_movk_i32 s77, 0xa0
	s_movk_i32 s58, 0xff60
	v_readlane_b32 s89, v242, 40
	global_store_dwordx4 v[166:167], v[124:127], off
	global_store_dwordx4 v[108:109], v[104:107], off
	global_store_dwordx4 v[92:93], v[88:91], off
	global_store_dwordx4 v[76:77], v[72:75], off
	global_store_dwordx4 v[76:77], v[68:71], off offset:256
	global_store_dwordx4 v[56:57], v[60:63], off
	global_store_dwordx4 v[46:47], v[40:43], off
	global_store_dwordx4 v[30:31], v[24:27], off
	global_store_dwordx4 v[14:15], v[8:11], off
	global_store_dwordx4 v[12:13], v[4:7], off offset:256
	s_cbranch_vccz .LBB0_326
	s_cmpk_gt_u32 s46, 0xff
	s_cbranch_scc1 .LBB0_337
	s_barrier

; #define PG8_STAGE(bufoff, gbase, voff) do { _Pragma("unroll") for (int _i = 0; _i < 2; ++_i) \
;         __builtin_amdgcn_global_load_lds((const unsigned*)((const char*)(gbase) + (voff)[_i]), (PG8_LAS unsigned*)(lds + (bufoff) + ldsw + _i * 8192), 16, 0, 0); } while (0)
; #define PG8_LDA(dst, b, h) do { _Pragma("unroll") for (int m = 0; m < 4; ++m) _Pragma("unroll") for (int k = 0; k < 2; ++k) dst[m][k] = *(const PG8_LAS bf16x8*)(lds + PG8_SA(b, h) + aoff + m * 2048 + k * 1024); } while (0)
; #define PG8_LDB(dst, b, h) do { _Pragma("unroll") for (int n = 0; n < 2; ++n) _Pragma("unroll") for (int k = 0; k < 2; ++k) dst[n][k] = *(const PG8_LAS bf16x8*)(lds + PG8_SB(b, h) + boff + n * 2048 + k * 1024); } while (0)
; #define PG8_MMA(ai, bj, At, Bt) do { __builtin_amdgcn_s_setprio(1); _Pragma("unroll") for (int m = 0; m < 4; ++m) _Pragma("unroll") for (int n = 0; n < 2; ++n) _Pragma("unroll") for (int k = 0; k < 2; ++k) \
;         acc[ai][bj][m][n] = __builtin_amdgcn_mfma_f32_16x16x32_bf16(Bt[n][k], At[m][k], acc[ai][bj][m][n], 0, 0, 0); __builtin_amdgcn_s_setprio(0); } while (0)
; #define PG8_WAIT_L(n) asm volatile("s_waitcnt lgkmcnt(" #n ")" ::: "memory")
; #define PG8_BAR __builtin_amdgcn_s_barrier()
; #define PG8_SCHED __builtin_amdgcn_sched_barrier(0)
; template <class Epi, class Sched, bool STAMP = false>
; __device__ __forceinline__ void gemm_phase(PG8_LAS unsigned char* lds, const Gemm g, const Sched& S, const Epi& E, unsigned long long* stamps) {
;     ...
;             const bool last = (t == nt - 2);
;             const char* a1 = cA + (size_t)(t + 1) * kstep;
;             const char* a2 = last ? nA : cA + (size_t)(t + 2) * kstep; const char* b2 = last ? nB : cB + (size_t)(t + 2) * kstep;
;             const char* a3 = a2 + kstep; const char* b3 = b2 + kstep;
;             if (last && has_next) S.a_ready(nxt);
;             PG8_LDB(B0, 0, 0); PG8_SCHED; PG8_LDA(At, 0, 0); PG8_STAGE(PG8_SA(1, 1), a1 + hstep, voffA);
;             PG8_WAIT_L(8); PG8_BAR; PG8_WAIT_L(0); PG8_MMA(0, 0, At, B0); PG8_BAR; PG8_SCHED;
;             PG8_LDB(B1, 0, 1); PG8_STAGE(PG8_SB(0, 0), b2, voffB);
;             PG8_BAR; PG8_WAIT_L(0); PG8_MMA(0, 1, At, B1); PG8_BAR;
;             PG8_LDA(At, 0, 1); PG8_STAGE(PG8_SA(0, 0), a2, voffA);
;             PG8_BAR; PG8_WAIT_L(0); PG8_MMA(1, 0, At, B0); PG8_BAR; PG8_SCHED;
.LBB0_353:
	s_add_u32 s14, s56, 0xfffc0080
	s_addc_u32 s15, s57, -1
	s_add_i32 s16, 0, 0x10000
	v_add_u32_e32 v166, s16, v167
	ds_read_b128 v[158:161], v166
	ds_read_b128 v[162:165], v166 offset:1024
	ds_read_b128 v[172:175], v166 offset:2048
	ds_read_b128 v[176:179], v166 offset:3072
	s_cmp_eq_u32 vcc_lo, 12
	s_cselect_b32 s61, s13, s15
	s_cselect_b32 s60, s47, s14
	s_cselect_b32 s59, s27, s77
	s_cselect_b32 s58, s53, s76
	v_lshl_add_u64 v[168:169], s[56:57], 0, v[154:155]
	s_add_i32 m0, s89, 0xc000
	ds_read_b128 v[180:183], v171
	ds_read_b128 v[192:195], v171 offset:1024
	ds_read_b128 v[196:199], v171 offset:2048
	ds_read_b128 v[200:203], v171 offset:3072
	ds_read_b128 v[204:207], v171 offset:4096
	ds_read_b128 v[208:211], v171 offset:5120
	ds_read_b128 v[212:215], v171 offset:6144
	ds_read_b128 v[216:219], v171 offset:7168
	global_load_lds_dwordx4 v[168:169], off
	v_lshl_add_u64 v[168:169], s[56:57], 0, v[156:157]
	s_add_i32 m0, s89, 0xe000
	s_nop 0
	global_load_lds_dwordx4 v[168:169], off
	s_waitcnt lgkmcnt(8)
	s_barrier
	s_waitcnt lgkmcnt(0)
	s_waitcnt lgkmcnt(0)
	v_mfma_f32_16x16x32_bf16 v[124:127], v[158:161], v[180:183], v[124:127]
	v_mfma_f32_16x16x32_bf16 v[120:123], v[172:175], v[180:183], v[120:123]
	v_mfma_f32_16x16x32_bf16 v[108:111], v[158:161], v[196:199], v[108:111]
	v_mfma_f32_16x16x32_bf16 v[104:107], v[172:175], v[196:199], v[104:107]
	v_mfma_f32_16x16x32_bf16 v[92:95], v[158:161], v[204:207], v[92:95]
	v_mfma_f32_16x16x32_bf16 v[88:91], v[172:175], v[204:207], v[88:91]
	v_mfma_f32_16x16x32_bf16 v[76:79], v[158:161], v[212:215], v[76:79]
	v_mfma_f32_16x16x32_bf16 v[72:75], v[172:175], v[212:215], v[72:75]
	v_mfma_f32_16x16x32_bf16 v[124:127], v[162:165], v[192:195], v[124:127]
	v_mfma_f32_16x16x32_bf16 v[120:123], v[176:179], v[192:195], v[120:123]
	v_mfma_f32_16x16x32_bf16 v[108:111], v[162:165], v[200:203], v[108:111]
	v_mfma_f32_16x16x32_bf16 v[104:107], v[176:179], v[200:203], v[104:107]
	v_mfma_f32_16x16x32_bf16 v[92:95], v[162:165], v[208:211], v[92:95]
	v_mfma_f32_16x16x32_bf16 v[88:91], v[176:179], v[208:211], v[88:91]
	v_mfma_f32_16x16x32_bf16 v[76:79], v[162:165], v[216:219], v[76:79]
	v_mfma_f32_16x16x32_bf16 v[72:75], v[176:179], v[216:219], v[72:75]
	s_barrier
	s_add_i32 s17, 0, 0x14000
	s_add_i32 s14, s16, s88
	v_add_u32_e32 v166, s17, v167
	v_lshl_add_u64 v[168:169], s[58:59], 0, v[128:129]
	s_mov_b32 m0, s14
	ds_read_b128 v[220:223], v166
	ds_read_b128 v[224:227], v166 offset:1024
	ds_read_b128 v[228:231], v166 offset:2048
	ds_read_b128 v[232:235], v166 offset:3072
	global_load_lds_dwordx4 v[168:169], off
	v_lshl_add_u64 v[236:237], s[58:59], 0, v[152:153]
	s_add_i32 m0, s14, 0x2000
	s_nop 0
	global_load_lds_dwordx4 v[236:237], off
	s_barrier
	s_waitcnt lgkmcnt(0)
	s_waitcnt lgkmcnt(0)
	v_mfma_f32_16x16x32_bf16 v[116:119], v[220:223], v[180:183], v[116:119]
	v_mfma_f32_16x16x32_bf16 v[112:115], v[228:231], v[180:183], v[112:115]
	v_mfma_f32_16x16x32_bf16 v[100:103], v[220:223], v[196:199], v[100:103]
	v_mfma_f32_16x16x32_bf16 v[96:99], v[228:231], v[196:199], v[96:99]
	v_mfma_f32_16x16x32_bf16 v[84:87], v[220:223], v[204:207], v[84:87]
	v_mfma_f32_16x16x32_bf16 v[80:83], v[228:231], v[204:207], v[80:83]
	v_mfma_f32_16x16x32_bf16 v[68:71], v[220:223], v[212:215], v[68:71]
	v_mfma_f32_16x16x32_bf16 v[64:67], v[228:231], v[212:215], v[64:67]
	v_mfma_f32_16x16x32_bf16 v[116:119], v[224:227], v[192:195], v[116:119]
	v_mfma_f32_16x16x32_bf16 v[112:115], v[232:235], v[192:195], v[112:115]
	v_mfma_f32_16x16x32_bf16 v[100:103], v[224:227], v[200:203], v[100:103]
	v_mfma_f32_16x16x32_bf16 v[96:99], v[232:235], v[200:203], v[96:99]
	v_mfma_f32_16x16x32_bf16 v[84:87], v[224:227], v[208:211], v[84:87]
	v_mfma_f32_16x16x32_bf16 v[80:83], v[232:235], v[208:211], v[80:83]
	v_mfma_f32_16x16x32_bf16 v[68:71], v[224:227], v[216:219], v[68:71]
	v_mfma_f32_16x16x32_bf16 v[64:67], v[232:235], v[216:219], v[64:67]
	s_mov_b32 m0, s89
	v_lshl_add_u64 v[238:239], s[60:61], 0, v[148:149]
	s_barrier
	ds_read_b128 v[180:183], v171 offset:16384
	ds_read_b128 v[192:195], v171 offset:17408
	ds_read_b128 v[196:199], v171 offset:18432
	ds_read_b128 v[200:203], v171 offset:19456
	ds_read_b128 v[204:207], v171 offset:20480
	ds_read_b128 v[208:211], v171 offset:21504
	ds_read_b128 v[212:215], v171 offset:22528
	ds_read_b128 v[216:219], v171 offset:23552
	global_load_lds_dwordx4 v[238:239], off
	v_lshl_add_u64 v[240:241], s[60:61], 0, v[150:151]
	s_mov_b32 m0, s96
	s_nop 0
	global_load_lds_dwordx4 v[240:241], off
	s_barrier
	s_waitcnt lgkmcnt(0)
	s_waitcnt lgkmcnt(0)
	v_mfma_f32_16x16x32_bf16 v[60:63], v[158:161], v[180:183], v[60:63]
	v_mfma_f32_16x16x32_bf16 v[56:59], v[172:175], v[180:183], v[56:59]
	v_mfma_f32_16x16x32_bf16 v[44:47], v[158:161], v[196:199], v[44:47]
	v_mfma_f32_16x16x32_bf16 v[40:43], v[172:175], v[196:199], v[40:43]
	v_mfma_f32_16x16x32_bf16 v[28:31], v[158:161], v[204:207], v[28:31]
	v_mfma_f32_16x16x32_bf16 v[24:27], v[172:175], v[204:207], v[24:27]
	v_mfma_f32_16x16x32_bf16 v[12:15], v[158:161], v[212:215], v[12:15]
	v_mfma_f32_16x16x32_bf16 v[8:11], v[172:175], v[212:215], v[8:11]
	v_mfma_f32_16x16x32_bf16 v[60:63], v[162:165], v[192:195], v[60:63]
	v_mfma_f32_16x16x32_bf16 v[56:59], v[176:179], v[192:195], v[56:59]
	v_mfma_f32_16x16x32_bf16 v[44:47], v[162:165], v[200:203], v[44:47]
	v_mfma_f32_16x16x32_bf16 v[40:43], v[176:179], v[200:203], v[40:43]
	v_mfma_f32_16x16x32_bf16 v[28:31], v[162:165], v[208:211], v[28:31]
	v_mfma_f32_16x16x32_bf16 v[24:27], v[176:179], v[208:211], v[24:27]
	v_mfma_f32_16x16x32_bf16 v[12:15], v[162:165], v[216:219], v[12:15]
	v_mfma_f32_16x16x32_bf16 v[8:11], v[176:179], v[216:219], v[8:11]
	s_barrier
; #define PG8_STAGE(bufoff, gbase, voff) do { _Pragma("unroll") for (int _i = 0; _i < 2; ++_i) \
;         __builtin_amdgcn_global_load_lds((const unsigned*)((const char*)(gbase) + (voff)[_i]), (PG8_LAS unsigned*)(lds + (bufoff) + ldsw + _i * 8192), 16, 0, 0); } while (0)
; #define PG8_LDA(dst, b, h) do { _Pragma("unroll") for (int m = 0; m < 4; ++m) _Pragma("unroll") for (int k = 0; k < 2; ++k) dst[m][k] = *(const PG8_LAS bf16x8*)(lds + PG8_SA(b, h) + aoff + m * 2048 + k * 1024); } while (0)
; #define PG8_LDB(dst, b, h) do { _Pragma("unroll") for (int n = 0; n < 2; ++n) _Pragma("unroll") for (int k = 0; k < 2; ++k) dst[n][k] = *(const PG8_LAS bf16x8*)(lds + PG8_SB(b, h) + boff + n * 2048 + k * 1024); } while (0)
; #define PG8_MMA(ai, bj, At, Bt) do { __builtin_amdgcn_s_setprio(1); _Pragma("unroll") for (int m = 0; m < 4; ++m) _Pragma("unroll") for (int n = 0; n < 2; ++n) _Pragma("unroll") for (int k = 0; k < 2; ++k) \
;         acc[ai][bj][m][n] = __builtin_amdgcn_mfma_f32_16x16x32_bf16(Bt[n][k], At[m][k], acc[ai][bj][m][n], 0, 0, 0); __builtin_amdgcn_s_setprio(0); } while (0)
; #define PG8_WAIT_V(n) asm volatile("s_waitcnt vmcnt(" #n ")" ::: "memory")
; #define PG8_WAIT_L(n) asm volatile("s_waitcnt lgkmcnt(" #n ")" ::: "memory")
; #define PG8_BAR __builtin_amdgcn_s_barrier()
; #define PG8_SCHED __builtin_amdgcn_sched_barrier(0)
; template <class Epi, class Sched, bool STAMP = false>
; __device__ __forceinline__ void gemm_phase(PG8_LAS unsigned char* lds, const Gemm g, const Sched& S, const Epi& E, unsigned long long* stamps) {
;     ...
;             PG8_STAGE(PG8_SB(0, 1), b2 + hstep, voffB);
;             PG8_WAIT_V(6); PG8_BAR; PG8_MMA(1, 1, At, B1); PG8_BAR;
;             PG8_LDB(B0, 1, 0); PG8_SCHED; PG8_LDA(At, 1, 0); PG8_STAGE(PG8_SA(0, 1), a2 + hstep, voffA);
;             PG8_WAIT_L(8); PG8_BAR; PG8_WAIT_L(0); PG8_MMA(0, 0, At, B0); PG8_BAR; PG8_SCHED;
;             PG8_LDB(B1, 1, 1); PG8_STAGE(PG8_SB(1, 0), b3, voffB);
;             PG8_BAR; PG8_WAIT_L(0); PG8_MMA(0, 1, At, B1); PG8_BAR;
;             PG8_LDA(At, 1, 1); PG8_STAGE(PG8_SA(1, 0), a3, voffA);
	s_add_u32 s14, s58, 0x40000
	s_addc_u32 s15, s59, 0
	s_add_i32 s16, s17, s88
	v_lshl_add_u64 v[158:159], s[14:15], 0, v[128:129]
	s_mov_b32 m0, s16
	s_nop 0
	global_load_lds_dwordx4 v[158:159], off
	v_lshl_add_u64 v[158:159], s[14:15], 0, v[152:153]
	s_add_i32 m0, s16, 0x2000
	s_nop 0
	global_load_lds_dwordx4 v[158:159], off
	s_waitcnt vmcnt(6)
	s_barrier
	v_mfma_f32_16x16x32_bf16 v[52:55], v[220:223], v[180:183], v[52:55]
	v_mfma_f32_16x16x32_bf16 v[48:51], v[228:231], v[180:183], v[48:51]
	v_mfma_f32_16x16x32_bf16 v[36:39], v[220:223], v[196:199], v[36:39]
	v_mfma_f32_16x16x32_bf16 v[32:35], v[228:231], v[196:199], v[32:35]
	v_mfma_f32_16x16x32_bf16 v[20:23], v[220:223], v[204:207], v[20:23]
	v_mfma_f32_16x16x32_bf16 v[16:19], v[228:231], v[204:207], v[16:19]
	v_mfma_f32_16x16x32_bf16 v[4:7], v[220:223], v[212:215], v[4:7]
	v_mfma_f32_16x16x32_bf16 v[0:3], v[228:231], v[212:215], v[0:3]
	v_mfma_f32_16x16x32_bf16 v[52:55], v[224:227], v[192:195], v[52:55]
	v_mfma_f32_16x16x32_bf16 v[48:51], v[232:235], v[192:195], v[48:51]
	v_mfma_f32_16x16x32_bf16 v[36:39], v[224:227], v[200:203], v[36:39]
	v_mfma_f32_16x16x32_bf16 v[32:35], v[232:235], v[200:203], v[32:35]
	v_mfma_f32_16x16x32_bf16 v[20:23], v[224:227], v[208:211], v[20:23]
	v_mfma_f32_16x16x32_bf16 v[16:19], v[232:235], v[208:211], v[16:19]
	v_mfma_f32_16x16x32_bf16 v[4:7], v[224:227], v[216:219], v[4:7]
	v_mfma_f32_16x16x32_bf16 v[0:3], v[232:235], v[216:219], v[0:3]
	s_add_i32 s16, 0, 0x18000
	v_add_u32_e32 v166, s16, v167
	s_barrier
	ds_read_b128 v[158:161], v166
	ds_read_b128 v[162:165], v166 offset:1024
	ds_read_b128 v[172:175], v166 offset:2048
	ds_read_b128 v[176:179], v166 offset:3072
	s_add_u32 s14, s60, 0x40000
	s_addc_u32 s15, s61, 0
	s_mov_b32 m0, s97
	v_lshl_add_u64 v[220:221], s[14:15], 0, v[148:149]
	ds_read_b128 v[180:183], v171 offset:32768
	ds_read_b128 v[192:195], v171 offset:33792
	ds_read_b128 v[196:199], v171 offset:34816
	ds_read_b128 v[200:203], v171 offset:35840
	ds_read_b128 v[204:207], v171 offset:36864
	ds_read_b128 v[208:211], v171 offset:37888
	ds_read_b128 v[212:215], v171 offset:38912
	ds_read_b128 v[216:219], v171 offset:39936
	global_load_lds_dwordx4 v[220:221], off
	v_lshl_add_u64 v[220:221], s[14:15], 0, v[150:151]
	s_mov_b32 m0, s64
	s_nop 0
	global_load_lds_dwordx4 v[220:221], off
	s_waitcnt lgkmcnt(8)
	s_barrier
	s_waitcnt lgkmcnt(0)
	s_waitcnt lgkmcnt(0)
	v_mfma_f32_16x16x32_bf16 v[124:127], v[158:161], v[180:183], v[124:127]
	v_mfma_f32_16x16x32_bf16 v[120:123], v[172:175], v[180:183], v[120:123]
	v_mfma_f32_16x16x32_bf16 v[108:111], v[158:161], v[196:199], v[108:111]
	v_mfma_f32_16x16x32_bf16 v[104:107], v[172:175], v[196:199], v[104:107]
	v_mfma_f32_16x16x32_bf16 v[92:95], v[158:161], v[204:207], v[92:95]
	v_mfma_f32_16x16x32_bf16 v[88:91], v[172:175], v[204:207], v[88:91]
	v_mfma_f32_16x16x32_bf16 v[76:79], v[158:161], v[212:215], v[76:79]
	v_mfma_f32_16x16x32_bf16 v[72:75], v[172:175], v[212:215], v[72:75]
	v_mfma_f32_16x16x32_bf16 v[124:127], v[162:165], v[192:195], v[124:127]
	v_mfma_f32_16x16x32_bf16 v[120:123], v[176:179], v[192:195], v[120:123]
	v_mfma_f32_16x16x32_bf16 v[108:111], v[162:165], v[200:203], v[108:111]
	v_mfma_f32_16x16x32_bf16 v[104:107], v[176:179], v[200:203], v[104:107]
	v_mfma_f32_16x16x32_bf16 v[92:95], v[162:165], v[208:211], v[92:95]
	v_mfma_f32_16x16x32_bf16 v[88:91], v[176:179], v[208:211], v[88:91]
	v_mfma_f32_16x16x32_bf16 v[76:79], v[162:165], v[216:219], v[76:79]
	v_mfma_f32_16x16x32_bf16 v[72:75], v[176:179], v[216:219], v[72:75]
	s_barrier
	s_add_i32 s17, 0, 0x1c000
	s_add_i32 s14, s16, s88
	v_add_u32_e32 v166, s17, v167
	v_lshl_add_u64 v[168:169], v[168:169], 0, s[18:19]
	s_mov_b32 m0, s14
	ds_read_b128 v[220:223], v166
	ds_read_b128 v[224:227], v166 offset:1024
	ds_read_b128 v[228:231], v166 offset:2048
	ds_read_b128 v[232:235], v166 offset:3072
	global_load_lds_dwordx4 v[168:169], off
	v_lshl_add_u64 v[168:169], v[236:237], 0, s[18:19]
	s_add_i32 m0, s14, 0x2000
	s_nop 0
	global_load_lds_dwordx4 v[168:169], off
	s_barrier
	s_waitcnt lgkmcnt(0)
	s_waitcnt lgkmcnt(0)
	v_mfma_f32_16x16x32_bf16 v[116:119], v[220:223], v[180:183], v[116:119]
	v_mfma_f32_16x16x32_bf16 v[112:115], v[228:231], v[180:183], v[112:115]
	v_mfma_f32_16x16x32_bf16 v[100:103], v[220:223], v[196:199], v[100:103]
	v_mfma_f32_16x16x32_bf16 v[96:99], v[228:231], v[196:199], v[96:99]
	v_mfma_f32_16x16x32_bf16 v[84:87], v[220:223], v[204:207], v[84:87]
	v_mfma_f32_16x16x32_bf16 v[80:83], v[228:231], v[204:207], v[80:83]
	v_mfma_f32_16x16x32_bf16 v[68:71], v[220:223], v[212:215], v[68:71]
	v_mfma_f32_16x16x32_bf16 v[64:67], v[228:231], v[212:215], v[64:67]
	v_mfma_f32_16x16x32_bf16 v[116:119], v[224:227], v[192:195], v[116:119]
	v_mfma_f32_16x16x32_bf16 v[112:115], v[232:235], v[192:195], v[112:115]
	v_mfma_f32_16x16x32_bf16 v[100:103], v[224:227], v[200:203], v[100:103]
	v_mfma_f32_16x16x32_bf16 v[96:99], v[232:235], v[200:203], v[96:99]
	v_mfma_f32_16x16x32_bf16 v[84:87], v[224:227], v[208:211], v[84:87]
	v_mfma_f32_16x16x32_bf16 v[80:83], v[232:235], v[208:211], v[80:83]
	v_mfma_f32_16x16x32_bf16 v[68:71], v[224:227], v[216:219], v[68:71]
	v_mfma_f32_16x16x32_bf16 v[64:67], v[232:235], v[216:219], v[64:67]
	s_mov_b32 m0, s62
	v_lshl_add_u64 v[168:169], v[238:239], 0, s[18:19]
	s_barrier
	ds_read_b128 v[180:183], v171 offset:49152
	ds_read_b128 v[192:195], v171 offset:50176
	ds_read_b128 v[196:199], v171 offset:51200
	ds_read_b128 v[200:203], v171 offset:52224
	ds_read_b128 v[204:207], v171 offset:53248
	ds_read_b128 v[208:211], v171 offset:54272
	ds_read_b128 v[212:215], v171 offset:55296
	ds_read_b128 v[216:219], v171 offset:56320
	global_load_lds_dwordx4 v[168:169], off
	v_lshl_add_u64 v[168:169], v[240:241], 0, s[18:19]
	s_mov_b32 m0, s63
	s_nop 0
	global_load_lds_dwordx4 v[168:169], off
	s_barrier
; #define PG8_STAGE(bufoff, gbase, voff) do { _Pragma("unroll") for (int _i = 0; _i < 2; ++_i) \
;         __builtin_amdgcn_global_load_lds((const unsigned*)((const char*)(gbase) + (voff)[_i]), (PG8_LAS unsigned*)(lds + (bufoff) + ldsw + _i * 8192), 16, 0, 0); } while (0)
; #define PG8_MMA(ai, bj, At, Bt) do { __builtin_amdgcn_s_setprio(1); _Pragma("unroll") for (int m = 0; m < 4; ++m) _Pragma("unroll") for (int n = 0; n < 2; ++n) _Pragma("unroll") for (int k = 0; k < 2; ++k) \
;         acc[ai][bj][m][n] = __builtin_amdgcn_mfma_f32_16x16x32_bf16(Bt[n][k], At[m][k], acc[ai][bj][m][n], 0, 0, 0); __builtin_amdgcn_s_setprio(0); } while (0)
; #define PG8_WAIT_V(n) asm volatile("s_waitcnt vmcnt(" #n ")" ::: "memory")
; #define PG8_WAIT_L(n) asm volatile("s_waitcnt lgkmcnt(" #n ")" ::: "memory")
; #define PG8_BAR __builtin_amdgcn_s_barrier()
; #define PG8_SCHED __builtin_amdgcn_sched_barrier(0)
; template <class Epi, class Sched, bool STAMP = false>
; __device__ __forceinline__ void gemm_phase(PG8_LAS unsigned char* lds, const Gemm g, const Sched& S, const Epi& E, unsigned long long* stamps) {
;     ...
;             PG8_BAR; PG8_WAIT_L(0); PG8_MMA(1, 0, At, B0); PG8_BAR; PG8_SCHED;
;             PG8_STAGE(PG8_SB(1, 1), b3 + hstep, voffB);
;             PG8_WAIT_V(6); PG8_BAR; PG8_MMA(1, 1, At, B1); PG8_BAR;
;     __device__ __forceinline__ void operator()(const f32x4 (&acc)[2][2][4][2], const pg8::Unit& u, int wr, int wc, int fr, int fq) const {
;     ...
;                 const int row = row0 + ai * 128 + m * 16;
;                 const float s = rstd_of(rowss, row);
; #pragma unroll
;                 for (int bj = 0; bj < 2; ++bj) {
;                     const size_t off = (size_t)row * 1024 + col0 + bj * 128;
;                     const u32x4 tv = *(const u32x4*)(Tm + off);
;                     u32x4 pv = (u32x4){0u, 0u, 0u, 0u};
;                     if (ACC) pv = *(const u32x4*)(M + off);
;                     const f32x4 a0 = acc[ai][bj][m][0] * s, a1 = acc[ai][bj][m][1] * s;
;                     float o[8];
;                     o[0] = sigm(a0[0]) * lo16(tv.x); o[1] = sigm(a0[1]) * hi16(tv.x); o[2] = sigm(a0[2]) * lo16(tv.y); o[3] = sigm(a0[3]) * hi16(tv.y);
;                     o[4] = sigm(a1[0]) * lo16(tv.z); o[5] = sigm(a1[1]) * hi16(tv.z); o[6] = sigm(a1[2]) * lo16(tv.w); o[7] = sigm(a1[3]) * hi16(tv.w);
	s_waitcnt lgkmcnt(0)
	s_waitcnt lgkmcnt(0)
	v_mfma_f32_16x16x32_bf16 v[60:63], v[158:161], v[180:183], v[60:63]
	v_mfma_f32_16x16x32_bf16 v[56:59], v[172:175], v[180:183], v[56:59]
	v_mfma_f32_16x16x32_bf16 v[44:47], v[158:161], v[196:199], v[44:47]
	v_mfma_f32_16x16x32_bf16 v[40:43], v[172:175], v[196:199], v[40:43]
	v_mfma_f32_16x16x32_bf16 v[28:31], v[158:161], v[204:207], v[28:31]
	v_mfma_f32_16x16x32_bf16 v[24:27], v[172:175], v[204:207], v[24:27]
	v_mfma_f32_16x16x32_bf16 v[12:15], v[158:161], v[212:215], v[12:15]
	v_mfma_f32_16x16x32_bf16 v[8:11], v[172:175], v[212:215], v[8:11]
	v_mfma_f32_16x16x32_bf16 v[60:63], v[162:165], v[192:195], v[60:63]
	v_mfma_f32_16x16x32_bf16 v[56:59], v[176:179], v[192:195], v[56:59]
	v_mfma_f32_16x16x32_bf16 v[44:47], v[162:165], v[200:203], v[44:47]
	v_mfma_f32_16x16x32_bf16 v[40:43], v[176:179], v[200:203], v[40:43]
	v_mfma_f32_16x16x32_bf16 v[28:31], v[162:165], v[208:211], v[28:31]
	v_mfma_f32_16x16x32_bf16 v[24:27], v[176:179], v[208:211], v[24:27]
	v_mfma_f32_16x16x32_bf16 v[12:15], v[162:165], v[216:219], v[12:15]
	v_mfma_f32_16x16x32_bf16 v[8:11], v[176:179], v[216:219], v[8:11]
	s_barrier
	s_add_u32 s14, s58, 0x40080
	s_addc_u32 s15, s59, 0
	s_add_i32 s16, s17, s88
	v_lshl_add_u64 v[158:159], s[14:15], 0, v[128:129]
	s_mov_b32 m0, s16
	s_nop 0
	global_load_lds_dwordx4 v[158:159], off
	v_lshl_add_u64 v[158:159], s[14:15], 0, v[152:153]
	s_add_i32 m0, s16, 0x2000
	s_nop 0
	global_load_lds_dwordx4 v[158:159], off
	s_waitcnt vmcnt(6)
	s_barrier
	v_mfma_f32_16x16x32_bf16 v[52:55], v[220:223], v[180:183], v[52:55]
	v_mfma_f32_16x16x32_bf16 v[48:51], v[228:231], v[180:183], v[48:51]
	v_mfma_f32_16x16x32_bf16 v[36:39], v[220:223], v[196:199], v[36:39]
	v_mfma_f32_16x16x32_bf16 v[32:35], v[228:231], v[196:199], v[32:35]
	v_mfma_f32_16x16x32_bf16 v[20:23], v[220:223], v[204:207], v[20:23]
	v_mfma_f32_16x16x32_bf16 v[16:19], v[228:231], v[204:207], v[16:19]
	v_mfma_f32_16x16x32_bf16 v[4:7], v[220:223], v[212:215], v[4:7]
	v_mfma_f32_16x16x32_bf16 v[0:3], v[228:231], v[212:215], v[0:3]
	v_mfma_f32_16x16x32_bf16 v[52:55], v[224:227], v[192:195], v[52:55]
	v_mfma_f32_16x16x32_bf16 v[48:51], v[232:235], v[192:195], v[48:51]
	v_mfma_f32_16x16x32_bf16 v[36:39], v[224:227], v[200:203], v[36:39]
	v_mfma_f32_16x16x32_bf16 v[32:35], v[232:235], v[200:203], v[32:35]
	v_mfma_f32_16x16x32_bf16 v[20:23], v[224:227], v[208:211], v[20:23]
	v_mfma_f32_16x16x32_bf16 v[16:19], v[232:235], v[208:211], v[16:19]
	v_mfma_f32_16x16x32_bf16 v[4:7], v[224:227], v[216:219], v[4:7]
	v_mfma_f32_16x16x32_bf16 v[0:3], v[232:235], v[216:219], v[0:3]
	s_add_i32 vcc_lo, vcc_lo, 2
	s_add_u32 s56, s56, 0x100
	s_addc_u32 s57, s57, 0
	s_add_u32 s76, s76, 0x100
	s_addc_u32 s77, s77, 0
	s_cmp_gt_u32 vcc_lo, 13
	s_barrier
	s_cbranch_scc0 .LBB0_353
	v_lshl_add_u32 v164, s2, 8, v139
	v_ashrrev_i32_e32 v165, 31, v164
	v_lshl_add_u64 v[160:161], v[164:165], 2, s[40:41]
	global_load_dword v158, v[160:161], off
	v_lshl_or_b32 v162, s3, 8, v170
	v_ashrrev_i32_e32 v163, 31, v162
	s_mov_b64 s[2:3], 0x40000
	s_mov_b64 s[58:59], s[36:37]
	s_mov_b64 s[56:57], s[4:5]
	s_waitcnt vmcnt(0)
	v_fmamk_f32 v158, v158, 0x3a800000, v187
	v_cmp_gt_f32_e32 vcc, s67, v158
	v_mul_f32_e32 v159, 0x4b800000, v158
	s_nop 0
	v_cndmask_b32_e32 v158, v158, v159, vcc
	v_rsq_f32_e32 v158, v158
	s_nop 0
	v_mul_f32_e32 v159, 0x45800000, v158
	v_cndmask_b32_e32 v166, v158, v159, vcc
	v_lshlrev_b64 v[158:159], 10, v[164:165]
	v_lshl_add_u64 v[158:159], v[158:159], 0, v[162:163]
	v_lshlrev_b64 v[158:159], 1, v[158:159]
	v_lshl_add_u64 v[168:169], s[30:31], 0, v[158:159]
	v_mov_b32_e32 v249, v158
	v_mov_b32_e32 v250, v249
	global_load_dwordx4 v[192:195], v250, s[30:31]
	global_load_dwordx4 v[196:199], v250, s[0:1]
	global_load_dwordx4 v[200:203], v250, s[30:31] offset:256
	global_load_dwordx4 v[204:207], v250, s[0:1] offset:256
	v_add_u32_e32 v250, 0x8000, v249
	global_load_dwordx4 v[208:211], v250, s[30:31]
	global_load_dwordx4 v[212:215], v250, s[0:1]
	global_load_dwordx4 v[216:219], v250, s[30:31] offset:256
	global_load_dwordx4 v[220:223], v250, s[0:1] offset:256
	v_add_u32_e32 v250, 0x10000, v249
	global_load_dwordx4 v[224:227], v250, s[30:31]
	global_load_dwordx4 v[228:231], v250, s[0:1]
	global_load_dwordx4 v[232:235], v250, s[30:31] offset:256
	global_load_dwordx4 v[236:239], v250, s[0:1] offset:256
	global_load_dword v240, v[160:161], off offset:64
	global_load_dword v241, v[160:161], off offset:128
	global_load_dword v244, v[160:161], off offset:192
	global_load_dword v245, v[160:161], off offset:512
	global_load_dword v246, v[160:161], off offset:576
	global_load_dword v247, v[160:161], off offset:640
	global_load_dword v248, v[160:161], off offset:704
	v_lshl_add_u64 v[168:169], s[0:1], 0, v[158:159]
	v_pk_mul_f32 v[126:127], v[126:127], v[166:167] op_sel_hi:[1,0]
	v_pk_mul_f32 v[120:121], v[120:121], v[166:167] op_sel_hi:[1,0]
	v_mul_f32_e32 v126, 0xbfb8aa3b, v126
	v_mul_f32_e32 v127, 0xbfb8aa3b, v127
	v_pk_mul_f32 v[124:125], v[124:125], v[166:167] op_sel_hi:[1,0]
	v_pk_mul_f32 v[122:123], v[122:123], v[166:167] op_sel_hi:[1,0]
	v_exp_f32_e32 v126, v126
	v_exp_f32_e32 v127, v127
	v_mul_f32_e32 v120, 0xbfb8aa3b, v120
	v_mul_f32_e32 v121, 0xbfb8aa3b, v121
	v_mul_f32_e32 v124, 0xbfb8aa3b, v124
	v_mul_f32_e32 v125, 0xbfb8aa3b, v125
	v_exp_f32_e32 v120, v120
	v_exp_f32_e32 v121, v121
	v_mul_f32_e32 v122, 0xbfb8aa3b, v122
	v_mul_f32_e32 v123, 0xbfb8aa3b, v123
	v_exp_f32_e32 v124, v124
	v_exp_f32_e32 v125, v125
	v_exp_f32_e32 v122, v122
	v_exp_f32_e32 v123, v123
	v_add_f32_e32 v126, 1.0, v126
	v_add_f32_e32 v127, 1.0, v127
	v_rcp_f32_e32 v126, v126
	v_rcp_f32_e32 v127, v127
	v_add_f32_e32 v120, 1.0, v120
	v_add_f32_e32 v121, 1.0, v121
	v_add_f32_e32 v124, 1.0, v124
	v_add_f32_e32 v125, 1.0, v125
	v_rcp_f32_e32 v120, v120
	v_rcp_f32_e32 v121, v121
	v_add_f32_e32 v122, 1.0, v122
	v_add_f32_e32 v123, 1.0, v123
	v_rcp_f32_e32 v124, v124
	v_rcp_f32_e32 v125, v125
	v_rcp_f32_e32 v122, v122
	v_rcp_f32_e32 v123, v123
	v_pk_mul_f32 v[116:117], v[116:117], v[166:167] op_sel_hi:[1,0]
	v_pk_mul_f32 v[114:115], v[114:115], v[166:167] op_sel_hi:[1,0]
	s_waitcnt vmcnt(0)
; __device__ __forceinline__ unsigned cvt_pk_bf16(float lo, float hi) { const f32x2_cv v = {lo, hi}; const bf16x2_cv b = __builtin_convertvector(v, bf16x2_cv); return __builtin_bit_cast(unsigned, b); }
; __device__ __forceinline__ float sigm(float x) { return __builtin_amdgcn_rcpf(1.0f + __expf(-x)); }
; __device__ __forceinline__ float lo16(unsigned w) { return __uint_as_float(w << 16); }
; __device__ __forceinline__ float hi16(unsigned w) { return __uint_as_float(w & 0xffff0000u); }
; __device__ __forceinline__ float rstd_of(const float* rowss, int row) { return rsqrtf(rowss[row] * (1.0f / 1024.0f) + 1e-6f); }
;     __device__ __forceinline__ void operator()(const f32x4 (&acc)[2][2][4][2], const pg8::Unit& u, int wr, int wc, int fr, int fq) const {
;     ...
;                 const int row = row0 + ai * 128 + m * 16;
;                 const float s = rstd_of(rowss, row);
; #pragma unroll
;                 for (int bj = 0; bj < 2; ++bj) {
;                     const size_t off = (size_t)row * 1024 + col0 + bj * 128;
;                     const u32x4 tv = *(const u32x4*)(Tm + off);
;                     u32x4 pv = (u32x4){0u, 0u, 0u, 0u};
;                     if (ACC) pv = *(const u32x4*)(M + off);
;                     const f32x4 a0 = acc[ai][bj][m][0] * s, a1 = acc[ai][bj][m][1] * s;
;                     float o[8];
;                     o[0] = sigm(a0[0]) * lo16(tv.x); o[1] = sigm(a0[1]) * hi16(tv.x); o[2] = sigm(a0[2]) * lo16(tv.y); o[3] = sigm(a0[3]) * hi16(tv.y);
;                     o[4] = sigm(a1[0]) * lo16(tv.z); o[5] = sigm(a1[1]) * hi16(tv.z); o[6] = sigm(a1[2]) * lo16(tv.w); o[7] = sigm(a1[3]) * hi16(tv.w);
;                     if (ACC) { o[0] += lo16(pv.x); o[1] += hi16(pv.x); o[2] += lo16(pv.y); o[3] += hi16(pv.y); o[4] += lo16(pv.z); o[5] += hi16(pv.z); o[6] += lo16(pv.w); o[7] += hi16(pv.w); }
;                     u32x4 w; w.x = cvt_pk_bf16(o[0], o[1]); w.y = cvt_pk_bf16(o[2], o[3]); w.z = cvt_pk_bf16(o[4], o[5]); w.w = cvt_pk_bf16(o[6], o[7]);
;                     *(u32x4*)(M + off) = w; } }
	v_mov_b32_e32 v172, v192
	v_mov_b32_e32 v173, v193
	v_mov_b32_e32 v174, v194
	v_mov_b32_e32 v175, v195
	v_mov_b32_e32 v176, v196
	v_mov_b32_e32 v177, v197
	v_mov_b32_e32 v178, v198
	v_mov_b32_e32 v179, v199
	v_lshlrev_b32_e32 v180, 16, v172
	v_and_b32_e32 v181, 0xffff0000, v172
	v_lshlrev_b32_e32 v182, 16, v176
	v_and_b32_e32 v183, 0xffff0000, v176
	v_lshlrev_b32_e32 v172, 16, v173
	v_and_b32_e32 v173, 0xffff0000, v173
	v_lshlrev_b32_e32 v176, 16, v177
	v_and_b32_e32 v177, 0xffff0000, v177
	v_pk_fma_f32 v[126:127], v[126:127], v[172:173], v[176:177]
	v_lshlrev_b32_e32 v172, 16, v174
	v_and_b32_e32 v173, 0xffff0000, v174
	v_lshlrev_b32_e32 v176, 16, v178
	v_and_b32_e32 v177, 0xffff0000, v178
	v_pk_fma_f32 v[172:173], v[120:121], v[172:173], v[176:177]
	v_lshlrev_b32_e32 v120, 16, v175
	v_and_b32_e32 v121, 0xffff0000, v175
	v_lshlrev_b32_e32 v174, 16, v179
	v_and_b32_e32 v175, 0xffff0000, v179
	v_pk_fma_f32 v[124:125], v[124:125], v[180:181], v[182:183]
	v_pk_fma_f32 v[174:175], v[122:123], v[120:121], v[174:175]
	v_cvt_pk_bf16_f32 v120, v124, v125
	v_cvt_pk_bf16_f32 v121, v126, v127
	v_cvt_pk_bf16_f32 v122, v172, v173
	v_cvt_pk_bf16_f32 v123, v174, v175
	v_or_b32_e32 v124, 0x100, v158
	v_mov_b32_e32 v125, v159
	global_store_dwordx4 v[168:169], v[120:123], off
	v_lshl_add_u64 v[168:169], s[0:1], 0, v[124:125]
	v_pk_mul_f32 v[172:173], v[118:119], v[166:167] op_sel_hi:[1,0]
	v_lshl_add_u64 v[120:121], s[30:31], 0, v[124:125]
	s_nop 1
	v_mov_b32_e32 v120, v200
	v_mov_b32_e32 v121, v201
	v_mov_b32_e32 v122, v202
	v_mov_b32_e32 v123, v203
	v_pk_mul_f32 v[118:119], v[112:113], v[166:167] op_sel_hi:[1,0]
	s_nop 1
	v_mov_b32_e32 v124, v204
	v_mov_b32_e32 v125, v205
	v_mov_b32_e32 v126, v206
	v_mov_b32_e32 v127, v207
	v_add_u32_e32 v250, 0x18000, v249
	global_load_dwordx4 v[192:195], v250, s[30:31]
	global_load_dwordx4 v[196:199], v250, s[0:1]
	global_load_dwordx4 v[200:203], v250, s[30:31] offset:256
	global_load_dwordx4 v[204:207], v250, s[0:1] offset:256
	v_mul_f32_e32 v112, 0xbfb8aa3b, v116
	v_mul_f32_e32 v113, 0xbfb8aa3b, v117
	v_mul_f32_e32 v116, 0xbfb8aa3b, v172
	v_mul_f32_e32 v117, 0xbfb8aa3b, v173
	v_exp_f32_e32 v116, v116
	v_exp_f32_e32 v117, v117
	v_mul_f32_e32 v118, 0xbfb8aa3b, v118
	v_mul_f32_e32 v119, 0xbfb8aa3b, v119
	v_exp_f32_e32 v118, v118
	v_exp_f32_e32 v119, v119
	v_mul_f32_e32 v114, 0xbfb8aa3b, v114
	v_mul_f32_e32 v115, 0xbfb8aa3b, v115
	v_exp_f32_e32 v112, v112
	v_exp_f32_e32 v113, v113
	v_exp_f32_e32 v114, v114
	v_exp_f32_e32 v115, v115
	v_add_f32_e32 v116, 1.0, v116
	v_add_f32_e32 v117, 1.0, v117
	v_rcp_f32_e32 v116, v116
	v_rcp_f32_e32 v117, v117
	v_add_f32_e32 v118, 1.0, v118
	v_add_f32_e32 v119, 1.0, v119
	v_add_f32_e32 v112, 1.0, v112
	v_add_f32_e32 v113, 1.0, v113
	v_rcp_f32_e32 v118, v118
	v_rcp_f32_e32 v119, v119
	v_add_f32_e32 v114, 1.0, v114
	v_add_f32_e32 v115, 1.0, v115
	v_rcp_f32_e32 v112, v112
	v_rcp_f32_e32 v113, v113
	v_rcp_f32_e32 v114, v114
	v_rcp_f32_e32 v115, v115
	v_lshlrev_b32_e32 v172, 16, v120
	v_and_b32_e32 v173, 0xffff0000, v120
	v_lshlrev_b32_e32 v174, 16, v124
	v_and_b32_e32 v175, 0xffff0000, v124
	v_lshlrev_b32_e32 v120, 16, v121
	v_and_b32_e32 v121, 0xffff0000, v121
	v_lshlrev_b32_e32 v124, 16, v125
	v_and_b32_e32 v125, 0xffff0000, v125
	v_pk_fma_f32 v[116:117], v[116:117], v[120:121], v[124:125]
	v_lshlrev_b32_e32 v120, 16, v122
	v_and_b32_e32 v121, 0xffff0000, v122
	v_lshlrev_b32_e32 v124, 16, v126
	v_and_b32_e32 v125, 0xffff0000, v126
	v_pk_fma_f32 v[118:119], v[118:119], v[120:121], v[124:125]
	v_lshlrev_b32_e32 v120, 16, v123
	v_and_b32_e32 v121, 0xffff0000, v123
	v_lshlrev_b32_e32 v122, 16, v127
	v_and_b32_e32 v123, 0xffff0000, v127
	v_pk_fma_f32 v[112:113], v[112:113], v[172:173], v[174:175]
	v_pk_fma_f32 v[120:121], v[114:115], v[120:121], v[122:123]
	v_cvt_pk_bf16_f32 v112, v112, v113
	v_cvt_pk_bf16_f32 v113, v116, v117
	v_cvt_pk_bf16_f32 v114, v118, v119
	v_cvt_pk_bf16_f32 v115, v120, v121
	global_store_dwordx4 v[168:169], v[112:115], off
	s_nop 1
	v_mov_b32_e32 v112, v240
	s_nop 0
	v_or_b32_e32 v114, 16, v164
	v_ashrrev_i32_e32 v115, 31, v114
	v_lshlrev_b64 v[114:115], 10, v[114:115]
	v_lshl_add_u64 v[114:115], v[114:115], 0, v[162:163]
	v_lshlrev_b64 v[114:115], 1, v[114:115]
	v_lshl_add_u64 v[116:117], s[30:31], 0, v[114:115]
	v_lshl_add_u64 v[124:125], s[0:1], 0, v[114:115]
	s_nop 1
	v_mov_b32_e32 v116, v208
	v_mov_b32_e32 v117, v209
	v_mov_b32_e32 v118, v210
	v_mov_b32_e32 v119, v211
	v_or_b32_e32 v114, 0x100, v114
	s_nop 1
	v_mov_b32_e32 v120, v212
	v_mov_b32_e32 v121, v213
	v_mov_b32_e32 v122, v214
	v_mov_b32_e32 v123, v215
	v_fmamk_f32 v112, v112, 0x3a800000, v187
	v_cmp_gt_f32_e32 vcc, s67, v112
	v_mul_f32_e32 v113, 0x4b800000, v112
	v_lshlrev_b32_e32 v126, 16, v116
	v_cndmask_b32_e32 v112, v112, v113, vcc
	v_rsq_f32_e32 v112, v112
	v_and_b32_e32 v127, 0xffff0000, v116
	v_lshlrev_b32_e32 v168, 16, v120
	v_and_b32_e32 v169, 0xffff0000, v120
	v_mul_f32_e32 v113, 0x45800000, v112
	v_cndmask_b32_e32 v112, v112, v113, vcc
	v_pk_mul_f32 v[110:111], v[110:111], v[112:113] op_sel_hi:[1,0]
	v_pk_mul_f32 v[104:105], v[104:105], v[112:113] op_sel_hi:[1,0]
	v_mul_f32_e32 v110, 0xbfb8aa3b, v110
	v_mul_f32_e32 v111, 0xbfb8aa3b, v111
	v_pk_mul_f32 v[108:109], v[108:109], v[112:113] op_sel_hi:[1,0]
	v_pk_mul_f32 v[106:107], v[106:107], v[112:113] op_sel_hi:[1,0]
	v_exp_f32_e32 v110, v110
	v_exp_f32_e32 v111, v111
	v_mul_f32_e32 v104, 0xbfb8aa3b, v104
	v_mul_f32_e32 v105, 0xbfb8aa3b, v105
	v_mul_f32_e32 v108, 0xbfb8aa3b, v108
	v_mul_f32_e32 v109, 0xbfb8aa3b, v109
	v_exp_f32_e32 v104, v104
	v_exp_f32_e32 v105, v105
	v_mul_f32_e32 v106, 0xbfb8aa3b, v106
	v_mul_f32_e32 v107, 0xbfb8aa3b, v107
; __device__ __forceinline__ unsigned cvt_pk_bf16(float lo, float hi) { const f32x2_cv v = {lo, hi}; const bf16x2_cv b = __builtin_convertvector(v, bf16x2_cv); return __builtin_bit_cast(unsigned, b); }
; __device__ __forceinline__ float sigm(float x) { return __builtin_amdgcn_rcpf(1.0f + __expf(-x)); }
; __device__ __forceinline__ float lo16(unsigned w) { return __uint_as_float(w << 16); }
; __device__ __forceinline__ float hi16(unsigned w) { return __uint_as_float(w & 0xffff0000u); }
; __device__ __forceinline__ float rstd_of(const float* rowss, int row) { return rsqrtf(rowss[row] * (1.0f / 1024.0f) + 1e-6f); }
;     __device__ __forceinline__ void operator()(const f32x4 (&acc)[2][2][4][2], const pg8::Unit& u, int wr, int wc, int fr, int fq) const {
;     ...
;                 const int row = row0 + ai * 128 + m * 16;
;                 const float s = rstd_of(rowss, row);
; #pragma unroll
;                 for (int bj = 0; bj < 2; ++bj) {
;                     const size_t off = (size_t)row * 1024 + col0 + bj * 128;
;                     const u32x4 tv = *(const u32x4*)(Tm + off);
;                     u32x4 pv = (u32x4){0u, 0u, 0u, 0u};
;                     if (ACC) pv = *(const u32x4*)(M + off);
;                     const f32x4 a0 = acc[ai][bj][m][0] * s, a1 = acc[ai][bj][m][1] * s;
;                     float o[8];
;                     o[0] = sigm(a0[0]) * lo16(tv.x); o[1] = sigm(a0[1]) * hi16(tv.x); o[2] = sigm(a0[2]) * lo16(tv.y); o[3] = sigm(a0[3]) * hi16(tv.y);
;                     o[4] = sigm(a1[0]) * lo16(tv.z); o[5] = sigm(a1[1]) * hi16(tv.z); o[6] = sigm(a1[2]) * lo16(tv.w); o[7] = sigm(a1[3]) * hi16(tv.w);
;                     if (ACC) { o[0] += lo16(pv.x); o[1] += hi16(pv.x); o[2] += lo16(pv.y); o[3] += hi16(pv.y); o[4] += lo16(pv.z); o[5] += hi16(pv.z); o[6] += lo16(pv.w); o[7] += hi16(pv.w); }
;                     u32x4 w; w.x = cvt_pk_bf16(o[0], o[1]); w.y = cvt_pk_bf16(o[2], o[3]); w.z = cvt_pk_bf16(o[4], o[5]); w.w = cvt_pk_bf16(o[6], o[7]);
;                     *(u32x4*)(M + off) = w; } }
	v_exp_f32_e32 v108, v108
	v_exp_f32_e32 v109, v109
	v_exp_f32_e32 v106, v106
	v_exp_f32_e32 v107, v107
	v_add_f32_e32 v110, 1.0, v110
	v_add_f32_e32 v111, 1.0, v111
	v_rcp_f32_e32 v110, v110
	v_rcp_f32_e32 v111, v111
	v_add_f32_e32 v104, 1.0, v104
	v_add_f32_e32 v105, 1.0, v105
	v_add_f32_e32 v108, 1.0, v108
	v_add_f32_e32 v109, 1.0, v109
	v_rcp_f32_e32 v104, v104
	v_rcp_f32_e32 v105, v105
	v_add_f32_e32 v106, 1.0, v106
	v_add_f32_e32 v107, 1.0, v107
	v_rcp_f32_e32 v108, v108
	v_rcp_f32_e32 v109, v109
	v_rcp_f32_e32 v106, v106
	v_rcp_f32_e32 v107, v107
	v_lshlrev_b32_e32 v116, 16, v117
	v_and_b32_e32 v117, 0xffff0000, v117
	v_lshlrev_b32_e32 v120, 16, v121
	v_and_b32_e32 v121, 0xffff0000, v121
	v_pk_fma_f32 v[110:111], v[110:111], v[116:117], v[120:121]
	v_lshlrev_b32_e32 v116, 16, v118
	v_and_b32_e32 v117, 0xffff0000, v118
	v_lshlrev_b32_e32 v120, 16, v122
	v_and_b32_e32 v121, 0xffff0000, v122
	v_pk_fma_f32 v[116:117], v[104:105], v[116:117], v[120:121]
	v_lshlrev_b32_e32 v104, 16, v119
	v_and_b32_e32 v105, 0xffff0000, v119
	v_lshlrev_b32_e32 v118, 16, v123
	v_and_b32_e32 v119, 0xffff0000, v123
	v_pk_fma_f32 v[108:109], v[108:109], v[126:127], v[168:169]
	v_pk_fma_f32 v[118:119], v[106:107], v[104:105], v[118:119]
	v_cvt_pk_bf16_f32 v104, v108, v109
	v_cvt_pk_bf16_f32 v105, v110, v111
	v_cvt_pk_bf16_f32 v106, v116, v117
	v_cvt_pk_bf16_f32 v107, v118, v119
	global_store_dwordx4 v[124:125], v[104:107], off
	v_pk_mul_f32 v[102:103], v[102:103], v[112:113] op_sel_hi:[1,0]
	v_pk_mul_f32 v[96:97], v[96:97], v[112:113] op_sel_hi:[1,0]
	v_lshl_add_u64 v[104:105], s[30:31], 0, v[114:115]
	v_lshl_add_u64 v[114:115], s[0:1], 0, v[114:115]
	s_nop 1
	v_mov_b32_e32 v104, v216
	v_mov_b32_e32 v105, v217
	v_mov_b32_e32 v106, v218
	v_mov_b32_e32 v107, v219
	v_mul_f32_e32 v102, 0xbfb8aa3b, v102
	s_nop 1
	v_mov_b32_e32 v108, v220
	v_mov_b32_e32 v109, v221
	v_mov_b32_e32 v110, v222
	v_mov_b32_e32 v111, v223
	v_add_u32_e32 v250, 0x40000, v249
	global_load_dwordx4 v[208:211], v250, s[30:31]
	global_load_dwordx4 v[212:215], v250, s[0:1]
	global_load_dwordx4 v[216:219], v250, s[30:31] offset:256
	global_load_dwordx4 v[220:223], v250, s[0:1] offset:256
	v_mul_f32_e32 v103, 0xbfb8aa3b, v103
	v_pk_mul_f32 v[100:101], v[100:101], v[112:113] op_sel_hi:[1,0]
	v_pk_mul_f32 v[98:99], v[98:99], v[112:113] op_sel_hi:[1,0]
	v_exp_f32_e32 v102, v102
	v_exp_f32_e32 v103, v103
	v_mul_f32_e32 v96, 0xbfb8aa3b, v96
	v_mul_f32_e32 v97, 0xbfb8aa3b, v97
	v_mul_f32_e32 v100, 0xbfb8aa3b, v100
	v_mul_f32_e32 v101, 0xbfb8aa3b, v101
	v_exp_f32_e32 v96, v96
	v_exp_f32_e32 v97, v97
	v_mul_f32_e32 v98, 0xbfb8aa3b, v98
	v_mul_f32_e32 v99, 0xbfb8aa3b, v99
	v_exp_f32_e32 v100, v100
	v_exp_f32_e32 v101, v101
	v_exp_f32_e32 v98, v98
	v_exp_f32_e32 v99, v99
	v_add_f32_e32 v102, 1.0, v102
	v_add_f32_e32 v103, 1.0, v103
	v_rcp_f32_e32 v102, v102
	v_rcp_f32_e32 v103, v103
	v_add_f32_e32 v96, 1.0, v96
	v_add_f32_e32 v97, 1.0, v97
	v_add_f32_e32 v100, 1.0, v100
	v_add_f32_e32 v101, 1.0, v101
	v_rcp_f32_e32 v96, v96
	v_rcp_f32_e32 v97, v97
	v_add_f32_e32 v98, 1.0, v98
	v_add_f32_e32 v99, 1.0, v99
	v_rcp_f32_e32 v100, v100
	v_rcp_f32_e32 v101, v101
	v_rcp_f32_e32 v98, v98
	v_rcp_f32_e32 v99, v99
	v_lshlrev_b32_e32 v112, 16, v104
	v_and_b32_e32 v113, 0xffff0000, v104
	v_lshlrev_b32_e32 v116, 16, v108
	v_and_b32_e32 v117, 0xffff0000, v108
	v_lshlrev_b32_e32 v104, 16, v105
	v_and_b32_e32 v105, 0xffff0000, v105
	v_lshlrev_b32_e32 v108, 16, v109
	v_and_b32_e32 v109, 0xffff0000, v109
	v_pk_fma_f32 v[102:103], v[102:103], v[104:105], v[108:109]
	v_lshlrev_b32_e32 v104, 16, v106
	v_and_b32_e32 v105, 0xffff0000, v106
	v_lshlrev_b32_e32 v108, 16, v110
	v_and_b32_e32 v109, 0xffff0000, v110
	v_pk_fma_f32 v[104:105], v[96:97], v[104:105], v[108:109]
	v_lshlrev_b32_e32 v96, 16, v107
	v_and_b32_e32 v97, 0xffff0000, v107
	v_lshlrev_b32_e32 v106, 16, v111
	v_and_b32_e32 v107, 0xffff0000, v111
	v_pk_fma_f32 v[100:101], v[100:101], v[112:113], v[116:117]
	v_pk_fma_f32 v[106:107], v[98:99], v[96:97], v[106:107]
	v_cvt_pk_bf16_f32 v96, v100, v101
	v_cvt_pk_bf16_f32 v97, v102, v103
	v_cvt_pk_bf16_f32 v98, v104, v105
	v_cvt_pk_bf16_f32 v99, v106, v107
	global_store_dwordx4 v[114:115], v[96:99], off
	s_nop 1
	v_mov_b32_e32 v96, v241
	s_nop 0
	v_or_b32_e32 v98, 32, v164
	v_ashrrev_i32_e32 v99, 31, v98
	v_lshlrev_b64 v[98:99], 10, v[98:99]
	v_lshl_add_u64 v[98:99], v[98:99], 0, v[162:163]
	v_lshlrev_b64 v[98:99], 1, v[98:99]
	v_lshl_add_u64 v[100:101], s[30:31], 0, v[98:99]
	v_lshl_add_u64 v[108:109], s[0:1], 0, v[98:99]
	s_nop 1
	v_mov_b32_e32 v100, v224
	v_mov_b32_e32 v101, v225
	v_mov_b32_e32 v102, v226
	v_mov_b32_e32 v103, v227
	v_or_b32_e32 v98, 0x100, v98
	s_nop 1
	v_mov_b32_e32 v104, v228
	v_mov_b32_e32 v105, v229
	v_mov_b32_e32 v106, v230
	v_mov_b32_e32 v107, v231
	v_fmamk_f32 v96, v96, 0x3a800000, v187
	v_cmp_gt_f32_e32 vcc, s67, v96
	v_mul_f32_e32 v97, 0x4b800000, v96
	v_lshlrev_b32_e32 v110, 16, v100
	v_cndmask_b32_e32 v96, v96, v97, vcc
	v_rsq_f32_e32 v96, v96
	v_and_b32_e32 v111, 0xffff0000, v100
	v_lshlrev_b32_e32 v112, 16, v104
	v_and_b32_e32 v113, 0xffff0000, v104
	v_mul_f32_e32 v97, 0x45800000, v96
	v_cndmask_b32_e32 v96, v96, v97, vcc
	v_pk_mul_f32 v[94:95], v[94:95], v[96:97] op_sel_hi:[1,0]
	v_pk_mul_f32 v[88:89], v[88:89], v[96:97] op_sel_hi:[1,0]
	v_mul_f32_e32 v94, 0xbfb8aa3b, v94
	v_mul_f32_e32 v95, 0xbfb8aa3b, v95
	v_pk_mul_f32 v[92:93], v[92:93], v[96:97] op_sel_hi:[1,0]
	v_pk_mul_f32 v[90:91], v[90:91], v[96:97] op_sel_hi:[1,0]
	v_exp_f32_e32 v94, v94
	v_exp_f32_e32 v95, v95
	v_mul_f32_e32 v88, 0xbfb8aa3b, v88
	v_mul_f32_e32 v89, 0xbfb8aa3b, v89
	v_mul_f32_e32 v92, 0xbfb8aa3b, v92
; __device__ __forceinline__ unsigned cvt_pk_bf16(float lo, float hi) { const f32x2_cv v = {lo, hi}; const bf16x2_cv b = __builtin_convertvector(v, bf16x2_cv); return __builtin_bit_cast(unsigned, b); }
; __device__ __forceinline__ float sigm(float x) { return __builtin_amdgcn_rcpf(1.0f + __expf(-x)); }
; __device__ __forceinline__ float lo16(unsigned w) { return __uint_as_float(w << 16); }
; __device__ __forceinline__ float hi16(unsigned w) { return __uint_as_float(w & 0xffff0000u); }
; __device__ __forceinline__ float rstd_of(const float* rowss, int row) { return rsqrtf(rowss[row] * (1.0f / 1024.0f) + 1e-6f); }
;     __device__ __forceinline__ void operator()(const f32x4 (&acc)[2][2][4][2], const pg8::Unit& u, int wr, int wc, int fr, int fq) const {
;     ...
;                 const int row = row0 + ai * 128 + m * 16;
;                 const float s = rstd_of(rowss, row);
; #pragma unroll
;                 for (int bj = 0; bj < 2; ++bj) {
;                     const size_t off = (size_t)row * 1024 + col0 + bj * 128;
;                     const u32x4 tv = *(const u32x4*)(Tm + off);
;                     u32x4 pv = (u32x4){0u, 0u, 0u, 0u};
;                     if (ACC) pv = *(const u32x4*)(M + off);
;                     const f32x4 a0 = acc[ai][bj][m][0] * s, a1 = acc[ai][bj][m][1] * s;
;                     float o[8];
;                     o[0] = sigm(a0[0]) * lo16(tv.x); o[1] = sigm(a0[1]) * hi16(tv.x); o[2] = sigm(a0[2]) * lo16(tv.y); o[3] = sigm(a0[3]) * hi16(tv.y);
;                     o[4] = sigm(a1[0]) * lo16(tv.z); o[5] = sigm(a1[1]) * hi16(tv.z); o[6] = sigm(a1[2]) * lo16(tv.w); o[7] = sigm(a1[3]) * hi16(tv.w);
;                     if (ACC) { o[0] += lo16(pv.x); o[1] += hi16(pv.x); o[2] += lo16(pv.y); o[3] += hi16(pv.y); o[4] += lo16(pv.z); o[5] += hi16(pv.z); o[6] += lo16(pv.w); o[7] += hi16(pv.w); }
;                     u32x4 w; w.x = cvt_pk_bf16(o[0], o[1]); w.y = cvt_pk_bf16(o[2], o[3]); w.z = cvt_pk_bf16(o[4], o[5]); w.w = cvt_pk_bf16(o[6], o[7]);
;                     *(u32x4*)(M + off) = w; } }
	v_mul_f32_e32 v93, 0xbfb8aa3b, v93
	v_exp_f32_e32 v88, v88
	v_exp_f32_e32 v89, v89
	v_mul_f32_e32 v90, 0xbfb8aa3b, v90
	v_mul_f32_e32 v91, 0xbfb8aa3b, v91
	v_exp_f32_e32 v92, v92
	v_exp_f32_e32 v93, v93
	v_exp_f32_e32 v90, v90
	v_exp_f32_e32 v91, v91
	v_add_f32_e32 v94, 1.0, v94
	v_add_f32_e32 v95, 1.0, v95
	v_rcp_f32_e32 v94, v94
	v_rcp_f32_e32 v95, v95
	v_add_f32_e32 v88, 1.0, v88
	v_add_f32_e32 v89, 1.0, v89
	v_add_f32_e32 v92, 1.0, v92
	v_add_f32_e32 v93, 1.0, v93
	v_rcp_f32_e32 v88, v88
	v_rcp_f32_e32 v89, v89
	v_add_f32_e32 v90, 1.0, v90
	v_add_f32_e32 v91, 1.0, v91
	v_rcp_f32_e32 v92, v92
	v_rcp_f32_e32 v93, v93
	v_rcp_f32_e32 v90, v90
	v_rcp_f32_e32 v91, v91
	v_lshlrev_b32_e32 v100, 16, v101
	v_and_b32_e32 v101, 0xffff0000, v101
	v_lshlrev_b32_e32 v104, 16, v105
	v_and_b32_e32 v105, 0xffff0000, v105
	v_pk_fma_f32 v[94:95], v[94:95], v[100:101], v[104:105]
	v_lshlrev_b32_e32 v100, 16, v102
	v_and_b32_e32 v101, 0xffff0000, v102
	v_lshlrev_b32_e32 v104, 16, v106
	v_and_b32_e32 v105, 0xffff0000, v106
	v_pk_fma_f32 v[100:101], v[88:89], v[100:101], v[104:105]
	v_lshlrev_b32_e32 v88, 16, v103
	v_and_b32_e32 v89, 0xffff0000, v103
	v_lshlrev_b32_e32 v102, 16, v107
	v_and_b32_e32 v103, 0xffff0000, v107
	v_pk_fma_f32 v[92:93], v[92:93], v[110:111], v[112:113]
	v_pk_fma_f32 v[102:103], v[90:91], v[88:89], v[102:103]
	v_cvt_pk_bf16_f32 v88, v92, v93
	v_cvt_pk_bf16_f32 v89, v94, v95
	v_cvt_pk_bf16_f32 v90, v100, v101
	v_cvt_pk_bf16_f32 v91, v102, v103
	global_store_dwordx4 v[108:109], v[88:91], off
	v_pk_mul_f32 v[86:87], v[86:87], v[96:97] op_sel_hi:[1,0]
	v_pk_mul_f32 v[80:81], v[80:81], v[96:97] op_sel_hi:[1,0]
	v_lshl_add_u64 v[88:89], s[30:31], 0, v[98:99]
	v_lshl_add_u64 v[98:99], s[0:1], 0, v[98:99]
	s_nop 1
	v_mov_b32_e32 v92, v232
	v_mov_b32_e32 v93, v233
	v_mov_b32_e32 v94, v234
	v_mov_b32_e32 v95, v235
	v_mul_f32_e32 v86, 0xbfb8aa3b, v86
	s_nop 1
	v_mov_b32_e32 v88, v236
	v_mov_b32_e32 v89, v237
	v_mov_b32_e32 v90, v238
	v_mov_b32_e32 v91, v239
	v_add_u32_e32 v250, 0x48000, v249
	global_load_dwordx4 v[224:227], v250, s[30:31]
	global_load_dwordx4 v[228:231], v250, s[0:1]
	global_load_dwordx4 v[232:235], v250, s[30:31] offset:256
	global_load_dwordx4 v[236:239], v250, s[0:1] offset:256
	v_mul_f32_e32 v87, 0xbfb8aa3b, v87
	v_pk_mul_f32 v[84:85], v[84:85], v[96:97] op_sel_hi:[1,0]
	v_pk_mul_f32 v[82:83], v[82:83], v[96:97] op_sel_hi:[1,0]
	v_exp_f32_e32 v86, v86
	v_exp_f32_e32 v87, v87
	v_mul_f32_e32 v80, 0xbfb8aa3b, v80
	v_mul_f32_e32 v81, 0xbfb8aa3b, v81
	v_mul_f32_e32 v84, 0xbfb8aa3b, v84
	v_mul_f32_e32 v85, 0xbfb8aa3b, v85
	v_exp_f32_e32 v80, v80
	v_exp_f32_e32 v81, v81
	v_mul_f32_e32 v82, 0xbfb8aa3b, v82
	v_mul_f32_e32 v83, 0xbfb8aa3b, v83
	v_exp_f32_e32 v84, v84
	v_exp_f32_e32 v85, v85
	v_exp_f32_e32 v82, v82
	v_exp_f32_e32 v83, v83
	v_add_f32_e32 v86, 1.0, v86
	v_add_f32_e32 v87, 1.0, v87
	v_rcp_f32_e32 v86, v86
	v_rcp_f32_e32 v87, v87
	v_add_f32_e32 v80, 1.0, v80
	v_add_f32_e32 v81, 1.0, v81
	v_add_f32_e32 v84, 1.0, v84
	v_add_f32_e32 v85, 1.0, v85
	v_rcp_f32_e32 v80, v80
	v_rcp_f32_e32 v81, v81
	v_add_f32_e32 v82, 1.0, v82
	v_add_f32_e32 v83, 1.0, v83
	v_rcp_f32_e32 v84, v84
	v_rcp_f32_e32 v85, v85
	v_rcp_f32_e32 v82, v82
	v_rcp_f32_e32 v83, v83
	v_lshlrev_b32_e32 v96, 16, v92
	v_and_b32_e32 v97, 0xffff0000, v92
	v_lshlrev_b32_e32 v100, 16, v88
	v_and_b32_e32 v101, 0xffff0000, v88
	v_lshlrev_b32_e32 v92, 16, v93
	v_and_b32_e32 v93, 0xffff0000, v93
	v_lshlrev_b32_e32 v88, 16, v89
	v_and_b32_e32 v89, 0xffff0000, v89
	v_pk_fma_f32 v[86:87], v[86:87], v[92:93], v[88:89]
	v_lshlrev_b32_e32 v88, 16, v94
	v_and_b32_e32 v89, 0xffff0000, v94
	v_lshlrev_b32_e32 v92, 16, v90
	v_and_b32_e32 v93, 0xffff0000, v90
	v_pk_fma_f32 v[88:89], v[80:81], v[88:89], v[92:93]
	v_lshlrev_b32_e32 v80, 16, v95
	v_and_b32_e32 v81, 0xffff0000, v95
	v_lshlrev_b32_e32 v90, 16, v91
	v_and_b32_e32 v91, 0xffff0000, v91
	v_pk_fma_f32 v[84:85], v[84:85], v[96:97], v[100:101]
	v_pk_fma_f32 v[90:91], v[82:83], v[80:81], v[90:91]
	v_cvt_pk_bf16_f32 v80, v84, v85
	v_cvt_pk_bf16_f32 v81, v86, v87
	v_cvt_pk_bf16_f32 v82, v88, v89
	v_cvt_pk_bf16_f32 v83, v90, v91
	global_store_dwordx4 v[98:99], v[80:83], off
	s_nop 1
	v_mov_b32_e32 v80, v244
	s_nop 0
	v_or_b32_e32 v82, 48, v164
	v_ashrrev_i32_e32 v83, 31, v82
	v_lshlrev_b64 v[82:83], 10, v[82:83]
	v_lshl_add_u64 v[82:83], v[82:83], 0, v[162:163]
	v_lshlrev_b64 v[82:83], 1, v[82:83]
	v_lshl_add_u64 v[84:85], s[30:31], 0, v[82:83]
	v_lshl_add_u64 v[92:93], s[0:1], 0, v[82:83]
	s_waitcnt vmcnt(13)
; __device__ __forceinline__ unsigned cvt_pk_bf16(float lo, float hi) { const f32x2_cv v = {lo, hi}; const bf16x2_cv b = __builtin_convertvector(v, bf16x2_cv); return __builtin_bit_cast(unsigned, b); }
; __device__ __forceinline__ float sigm(float x) { return __builtin_amdgcn_rcpf(1.0f + __expf(-x)); }
; __device__ __forceinline__ float lo16(unsigned w) { return __uint_as_float(w << 16); }
; __device__ __forceinline__ float hi16(unsigned w) { return __uint_as_float(w & 0xffff0000u); }
; __device__ __forceinline__ float rstd_of(const float* rowss, int row) { return rsqrtf(rowss[row] * (1.0f / 1024.0f) + 1e-6f); }
;     __device__ __forceinline__ void operator()(const f32x4 (&acc)[2][2][4][2], const pg8::Unit& u, int wr, int wc, int fr, int fq) const {
;     ...
;                 const int row = row0 + ai * 128 + m * 16;
;                 const float s = rstd_of(rowss, row);
; #pragma unroll
;                 for (int bj = 0; bj < 2; ++bj) {
;                     const size_t off = (size_t)row * 1024 + col0 + bj * 128;
;                     const u32x4 tv = *(const u32x4*)(Tm + off);
;                     u32x4 pv = (u32x4){0u, 0u, 0u, 0u};
;                     if (ACC) pv = *(const u32x4*)(M + off);
;                     const f32x4 a0 = acc[ai][bj][m][0] * s, a1 = acc[ai][bj][m][1] * s;
;                     float o[8];
;                     o[0] = sigm(a0[0]) * lo16(tv.x); o[1] = sigm(a0[1]) * hi16(tv.x); o[2] = sigm(a0[2]) * lo16(tv.y); o[3] = sigm(a0[3]) * hi16(tv.y);
;                     o[4] = sigm(a1[0]) * lo16(tv.z); o[5] = sigm(a1[1]) * hi16(tv.z); o[6] = sigm(a1[2]) * lo16(tv.w); o[7] = sigm(a1[3]) * hi16(tv.w);
;                     if (ACC) { o[0] += lo16(pv.x); o[1] += hi16(pv.x); o[2] += lo16(pv.y); o[3] += hi16(pv.y); o[4] += lo16(pv.z); o[5] += hi16(pv.z); o[6] += lo16(pv.w); o[7] += hi16(pv.w); }
;                     u32x4 w; w.x = cvt_pk_bf16(o[0], o[1]); w.y = cvt_pk_bf16(o[2], o[3]); w.z = cvt_pk_bf16(o[4], o[5]); w.w = cvt_pk_bf16(o[6], o[7]);
;                     *(u32x4*)(M + off) = w; } }
	s_nop 1
	v_mov_b32_e32 v84, v192
	v_mov_b32_e32 v85, v193
	v_mov_b32_e32 v86, v194
	v_mov_b32_e32 v87, v195
	v_or_b32_e32 v82, 0x100, v82
	s_nop 1
	v_mov_b32_e32 v88, v196
	v_mov_b32_e32 v89, v197
	v_mov_b32_e32 v90, v198
	v_mov_b32_e32 v91, v199
	v_fmamk_f32 v80, v80, 0x3a800000, v187
	v_cmp_gt_f32_e32 vcc, s67, v80
	v_mul_f32_e32 v81, 0x4b800000, v80
	v_lshlrev_b32_e32 v94, 16, v84
	v_cndmask_b32_e32 v80, v80, v81, vcc
	v_rsq_f32_e32 v80, v80
	v_and_b32_e32 v95, 0xffff0000, v84
	v_lshlrev_b32_e32 v96, 16, v88
	v_and_b32_e32 v97, 0xffff0000, v88
	v_mul_f32_e32 v81, 0x45800000, v80
	v_cndmask_b32_e32 v80, v80, v81, vcc
	v_pk_mul_f32 v[78:79], v[78:79], v[80:81] op_sel_hi:[1,0]
	v_pk_mul_f32 v[72:73], v[72:73], v[80:81] op_sel_hi:[1,0]
	v_mul_f32_e32 v78, 0xbfb8aa3b, v78
	v_mul_f32_e32 v79, 0xbfb8aa3b, v79
	v_pk_mul_f32 v[76:77], v[76:77], v[80:81] op_sel_hi:[1,0]
	v_pk_mul_f32 v[74:75], v[74:75], v[80:81] op_sel_hi:[1,0]
	v_exp_f32_e32 v78, v78
	v_exp_f32_e32 v79, v79
	v_mul_f32_e32 v72, 0xbfb8aa3b, v72
	v_mul_f32_e32 v73, 0xbfb8aa3b, v73
	v_mul_f32_e32 v76, 0xbfb8aa3b, v76
	v_mul_f32_e32 v77, 0xbfb8aa3b, v77
	v_exp_f32_e32 v72, v72
	v_exp_f32_e32 v73, v73
	v_mul_f32_e32 v74, 0xbfb8aa3b, v74
	v_mul_f32_e32 v75, 0xbfb8aa3b, v75
	v_exp_f32_e32 v76, v76
	v_exp_f32_e32 v77, v77
	v_exp_f32_e32 v74, v74
	v_exp_f32_e32 v75, v75
	v_add_f32_e32 v78, 1.0, v78
	v_add_f32_e32 v79, 1.0, v79
	v_rcp_f32_e32 v78, v78
	v_rcp_f32_e32 v79, v79
	v_add_f32_e32 v72, 1.0, v72
	v_add_f32_e32 v73, 1.0, v73
	v_add_f32_e32 v76, 1.0, v76
	v_add_f32_e32 v77, 1.0, v77
	v_rcp_f32_e32 v72, v72
	v_rcp_f32_e32 v73, v73
	v_add_f32_e32 v74, 1.0, v74
	v_add_f32_e32 v75, 1.0, v75
	v_rcp_f32_e32 v76, v76
	v_rcp_f32_e32 v77, v77
	v_rcp_f32_e32 v74, v74
	v_rcp_f32_e32 v75, v75
	v_lshlrev_b32_e32 v84, 16, v85
	v_and_b32_e32 v85, 0xffff0000, v85
	v_lshlrev_b32_e32 v88, 16, v89
	v_and_b32_e32 v89, 0xffff0000, v89
	v_pk_fma_f32 v[78:79], v[78:79], v[84:85], v[88:89]
	v_lshlrev_b32_e32 v84, 16, v86
	v_and_b32_e32 v85, 0xffff0000, v86
	v_lshlrev_b32_e32 v88, 16, v90
	v_and_b32_e32 v89, 0xffff0000, v90
	v_pk_fma_f32 v[84:85], v[72:73], v[84:85], v[88:89]
	v_lshlrev_b32_e32 v72, 16, v87
	v_and_b32_e32 v73, 0xffff0000, v87
	v_lshlrev_b32_e32 v86, 16, v91
	v_and_b32_e32 v87, 0xffff0000, v91
	v_pk_fma_f32 v[76:77], v[76:77], v[94:95], v[96:97]
	v_pk_fma_f32 v[86:87], v[74:75], v[72:73], v[86:87]
	v_cvt_pk_bf16_f32 v72, v76, v77
	v_cvt_pk_bf16_f32 v73, v78, v79
	v_cvt_pk_bf16_f32 v74, v84, v85
	v_cvt_pk_bf16_f32 v75, v86, v87
	global_store_dwordx4 v[92:93], v[72:75], off
	v_pk_mul_f32 v[70:71], v[70:71], v[80:81] op_sel_hi:[1,0]
	v_pk_mul_f32 v[64:65], v[64:65], v[80:81] op_sel_hi:[1,0]
	v_lshl_add_u64 v[72:73], s[30:31], 0, v[82:83]
	v_lshl_add_u64 v[82:83], s[0:1], 0, v[82:83]
	s_nop 1
	v_mov_b32_e32 v76, v200
	v_mov_b32_e32 v77, v201
	v_mov_b32_e32 v78, v202
	v_mov_b32_e32 v79, v203
	v_mul_f32_e32 v70, 0xbfb8aa3b, v70
	s_nop 1
	v_mov_b32_e32 v72, v204
	v_mov_b32_e32 v73, v205
	v_mov_b32_e32 v74, v206
	v_mov_b32_e32 v75, v207
	v_add_u32_e32 v250, 0x50000, v249
	global_load_dwordx4 v[192:195], v250, s[30:31]
	global_load_dwordx4 v[196:199], v250, s[0:1]
	global_load_dwordx4 v[200:203], v250, s[30:31] offset:256
	global_load_dwordx4 v[204:207], v250, s[0:1] offset:256
	v_mul_f32_e32 v71, 0xbfb8aa3b, v71
	v_pk_mul_f32 v[68:69], v[68:69], v[80:81] op_sel_hi:[1,0]
	v_pk_mul_f32 v[66:67], v[66:67], v[80:81] op_sel_hi:[1,0]
	v_exp_f32_e32 v70, v70
	v_exp_f32_e32 v71, v71
	v_mul_f32_e32 v64, 0xbfb8aa3b, v64
	v_mul_f32_e32 v65, 0xbfb8aa3b, v65
	v_mul_f32_e32 v68, 0xbfb8aa3b, v68
	v_mul_f32_e32 v69, 0xbfb8aa3b, v69
	v_exp_f32_e32 v64, v64
	v_exp_f32_e32 v65, v65
	v_mul_f32_e32 v66, 0xbfb8aa3b, v66
	v_mul_f32_e32 v67, 0xbfb8aa3b, v67
	v_exp_f32_e32 v68, v68
	v_exp_f32_e32 v69, v69
	v_exp_f32_e32 v66, v66
	v_exp_f32_e32 v67, v67
	v_add_f32_e32 v70, 1.0, v70
	v_add_f32_e32 v71, 1.0, v71
	v_rcp_f32_e32 v70, v70
	v_rcp_f32_e32 v71, v71
	v_add_f32_e32 v64, 1.0, v64
	v_add_f32_e32 v65, 1.0, v65
	v_add_f32_e32 v68, 1.0, v68
	v_add_f32_e32 v69, 1.0, v69
	v_rcp_f32_e32 v64, v64
	v_rcp_f32_e32 v65, v65
	v_add_f32_e32 v66, 1.0, v66
	v_add_f32_e32 v67, 1.0, v67
	v_rcp_f32_e32 v68, v68
	v_rcp_f32_e32 v69, v69
	v_rcp_f32_e32 v66, v66
	v_rcp_f32_e32 v67, v67
	v_lshlrev_b32_e32 v80, 16, v76
	v_and_b32_e32 v81, 0xffff0000, v76
	v_lshlrev_b32_e32 v84, 16, v72
	v_and_b32_e32 v85, 0xffff0000, v72
	v_lshlrev_b32_e32 v76, 16, v77
	v_and_b32_e32 v77, 0xffff0000, v77
	v_lshlrev_b32_e32 v72, 16, v73
	v_and_b32_e32 v73, 0xffff0000, v73
	v_pk_fma_f32 v[70:71], v[70:71], v[76:77], v[72:73]
	v_lshlrev_b32_e32 v72, 16, v78
	v_and_b32_e32 v73, 0xffff0000, v78
	v_lshlrev_b32_e32 v76, 16, v74
	v_and_b32_e32 v77, 0xffff0000, v74
	v_pk_fma_f32 v[72:73], v[64:65], v[72:73], v[76:77]
	v_lshlrev_b32_e32 v64, 16, v79
	v_and_b32_e32 v65, 0xffff0000, v79
	v_lshlrev_b32_e32 v74, 16, v75
	v_and_b32_e32 v75, 0xffff0000, v75
	v_pk_fma_f32 v[68:69], v[68:69], v[80:81], v[84:85]
	v_pk_fma_f32 v[74:75], v[66:67], v[64:65], v[74:75]
	v_cvt_pk_bf16_f32 v64, v68, v69
	v_cvt_pk_bf16_f32 v65, v70, v71
	v_cvt_pk_bf16_f32 v66, v72, v73
	v_cvt_pk_bf16_f32 v67, v74, v75
	global_store_dwordx4 v[82:83], v[64:67], off
	s_nop 1
	v_mov_b32_e32 v64, v245
	v_lshl_add_u64 v[70:71], v[158:159], 0, s[2:3]
	v_lshl_add_u64 v[66:67], s[30:31], 0, v[70:71]
	v_lshl_add_u64 v[74:75], s[0:1], 0, v[70:71]
	s_waitcnt vmcnt(13)
; __device__ __forceinline__ unsigned cvt_pk_bf16(float lo, float hi) { const f32x2_cv v = {lo, hi}; const bf16x2_cv b = __builtin_convertvector(v, bf16x2_cv); return __builtin_bit_cast(unsigned, b); }
; __device__ __forceinline__ float sigm(float x) { return __builtin_amdgcn_rcpf(1.0f + __expf(-x)); }
; __device__ __forceinline__ float lo16(unsigned w) { return __uint_as_float(w << 16); }
; __device__ __forceinline__ float hi16(unsigned w) { return __uint_as_float(w & 0xffff0000u); }
; __device__ __forceinline__ float rstd_of(const float* rowss, int row) { return rsqrtf(rowss[row] * (1.0f / 1024.0f) + 1e-6f); }
;     __device__ __forceinline__ void operator()(const f32x4 (&acc)[2][2][4][2], const pg8::Unit& u, int wr, int wc, int fr, int fq) const {
;     ...
;                 const int row = row0 + ai * 128 + m * 16;
;                 const float s = rstd_of(rowss, row);
; #pragma unroll
;                 for (int bj = 0; bj < 2; ++bj) {
;                     const size_t off = (size_t)row * 1024 + col0 + bj * 128;
;                     const u32x4 tv = *(const u32x4*)(Tm + off);
;                     u32x4 pv = (u32x4){0u, 0u, 0u, 0u};
;                     if (ACC) pv = *(const u32x4*)(M + off);
;                     const f32x4 a0 = acc[ai][bj][m][0] * s, a1 = acc[ai][bj][m][1] * s;
;                     float o[8];
;                     o[0] = sigm(a0[0]) * lo16(tv.x); o[1] = sigm(a0[1]) * hi16(tv.x); o[2] = sigm(a0[2]) * lo16(tv.y); o[3] = sigm(a0[3]) * hi16(tv.y);
;                     o[4] = sigm(a1[0]) * lo16(tv.z); o[5] = sigm(a1[1]) * hi16(tv.z); o[6] = sigm(a1[2]) * lo16(tv.w); o[7] = sigm(a1[3]) * hi16(tv.w);
;                     if (ACC) { o[0] += lo16(pv.x); o[1] += hi16(pv.x); o[2] += lo16(pv.y); o[3] += hi16(pv.y); o[4] += lo16(pv.z); o[5] += hi16(pv.z); o[6] += lo16(pv.w); o[7] += hi16(pv.w); }
;                     u32x4 w; w.x = cvt_pk_bf16(o[0], o[1]); w.y = cvt_pk_bf16(o[2], o[3]); w.z = cvt_pk_bf16(o[4], o[5]); w.w = cvt_pk_bf16(o[6], o[7]);
;                     *(u32x4*)(M + off) = w; } }
	s_nop 1
	v_mov_b32_e32 v66, v208
	v_mov_b32_e32 v67, v209
	v_mov_b32_e32 v68, v210
	v_mov_b32_e32 v69, v211
	s_mov_b64 s[2:3], 0x40100
	s_nop 1
	v_mov_b32_e32 v70, v212
	v_mov_b32_e32 v71, v213
	v_mov_b32_e32 v72, v214
	v_mov_b32_e32 v73, v215
	v_fmamk_f32 v64, v64, 0x3a800000, v187
	v_cmp_gt_f32_e32 vcc, s67, v64
	v_mul_f32_e32 v65, 0x4b800000, v64
	v_lshlrev_b32_e32 v76, 16, v66
	v_cndmask_b32_e32 v64, v64, v65, vcc
	v_rsq_f32_e32 v64, v64
	v_and_b32_e32 v77, 0xffff0000, v66
	v_lshlrev_b32_e32 v78, 16, v70
	v_and_b32_e32 v79, 0xffff0000, v70
	v_mul_f32_e32 v65, 0x45800000, v64
	v_cndmask_b32_e32 v64, v64, v65, vcc
	v_pk_mul_f32 v[62:63], v[62:63], v[64:65] op_sel_hi:[1,0]
	v_pk_mul_f32 v[56:57], v[56:57], v[64:65] op_sel_hi:[1,0]
	v_mul_f32_e32 v62, 0xbfb8aa3b, v62
	v_mul_f32_e32 v63, 0xbfb8aa3b, v63
	v_pk_mul_f32 v[60:61], v[60:61], v[64:65] op_sel_hi:[1,0]
	v_pk_mul_f32 v[58:59], v[58:59], v[64:65] op_sel_hi:[1,0]
	v_exp_f32_e32 v62, v62
	v_exp_f32_e32 v63, v63
	v_mul_f32_e32 v56, 0xbfb8aa3b, v56
	v_mul_f32_e32 v57, 0xbfb8aa3b, v57
	v_mul_f32_e32 v60, 0xbfb8aa3b, v60
	v_mul_f32_e32 v61, 0xbfb8aa3b, v61
	v_exp_f32_e32 v56, v56
	v_exp_f32_e32 v57, v57
	v_mul_f32_e32 v58, 0xbfb8aa3b, v58
	v_mul_f32_e32 v59, 0xbfb8aa3b, v59
	v_exp_f32_e32 v60, v60
	v_exp_f32_e32 v61, v61
	v_exp_f32_e32 v58, v58
	v_exp_f32_e32 v59, v59
	v_add_f32_e32 v62, 1.0, v62
	v_add_f32_e32 v63, 1.0, v63
	v_rcp_f32_e32 v62, v62
	v_rcp_f32_e32 v63, v63
	v_add_f32_e32 v56, 1.0, v56
	v_add_f32_e32 v57, 1.0, v57
	v_add_f32_e32 v60, 1.0, v60
	v_add_f32_e32 v61, 1.0, v61
	v_rcp_f32_e32 v56, v56
	v_rcp_f32_e32 v57, v57
	v_add_f32_e32 v58, 1.0, v58
	v_add_f32_e32 v59, 1.0, v59
	v_rcp_f32_e32 v60, v60
	v_rcp_f32_e32 v61, v61
	v_rcp_f32_e32 v58, v58
	v_rcp_f32_e32 v59, v59
	v_lshlrev_b32_e32 v66, 16, v67
	v_and_b32_e32 v67, 0xffff0000, v67
	v_lshlrev_b32_e32 v70, 16, v71
	v_and_b32_e32 v71, 0xffff0000, v71
	v_pk_fma_f32 v[62:63], v[62:63], v[66:67], v[70:71]
	v_lshlrev_b32_e32 v66, 16, v68
	v_and_b32_e32 v67, 0xffff0000, v68
	v_lshlrev_b32_e32 v70, 16, v72
	v_and_b32_e32 v71, 0xffff0000, v72
	v_pk_fma_f32 v[66:67], v[56:57], v[66:67], v[70:71]
	v_lshlrev_b32_e32 v56, 16, v69
	v_and_b32_e32 v57, 0xffff0000, v69
	v_lshlrev_b32_e32 v68, 16, v73
	v_and_b32_e32 v69, 0xffff0000, v73
	v_pk_fma_f32 v[60:61], v[60:61], v[76:77], v[78:79]
	v_pk_fma_f32 v[68:69], v[58:59], v[56:57], v[68:69]
	v_cvt_pk_bf16_f32 v56, v60, v61
	v_cvt_pk_bf16_f32 v57, v62, v63
	v_cvt_pk_bf16_f32 v58, v66, v67
	v_cvt_pk_bf16_f32 v59, v68, v69
	global_store_dwordx4 v[74:75], v[56:59], off
	v_pk_mul_f32 v[54:55], v[54:55], v[64:65] op_sel_hi:[1,0]
	v_pk_mul_f32 v[48:49], v[48:49], v[64:65] op_sel_hi:[1,0]
	v_lshl_add_u64 v[56:57], v[158:159], 0, s[2:3]
	v_lshl_add_u64 v[58:59], s[30:31], 0, v[56:57]
	v_lshl_add_u64 v[66:67], s[0:1], 0, v[56:57]
	s_nop 1
	v_mov_b32_e32 v60, v216
	v_mov_b32_e32 v61, v217
	v_mov_b32_e32 v62, v218
	v_mov_b32_e32 v63, v219
	v_mul_f32_e32 v54, 0xbfb8aa3b, v54
	s_nop 1
	v_mov_b32_e32 v56, v220
	v_mov_b32_e32 v57, v221
	v_mov_b32_e32 v58, v222
	v_mov_b32_e32 v59, v223
	v_add_u32_e32 v250, 0x58000, v249
	global_load_dwordx4 v[208:211], v250, s[30:31]
	global_load_dwordx4 v[212:215], v250, s[0:1]
	global_load_dwordx4 v[216:219], v250, s[30:31] offset:256
	global_load_dwordx4 v[220:223], v250, s[0:1] offset:256
	v_mul_f32_e32 v55, 0xbfb8aa3b, v55
	v_pk_mul_f32 v[52:53], v[52:53], v[64:65] op_sel_hi:[1,0]
	v_pk_mul_f32 v[50:51], v[50:51], v[64:65] op_sel_hi:[1,0]
	v_exp_f32_e32 v54, v54
	v_exp_f32_e32 v55, v55
	v_mul_f32_e32 v48, 0xbfb8aa3b, v48
	v_mul_f32_e32 v49, 0xbfb8aa3b, v49
	v_mul_f32_e32 v52, 0xbfb8aa3b, v52
	v_mul_f32_e32 v53, 0xbfb8aa3b, v53
	v_exp_f32_e32 v48, v48
	v_exp_f32_e32 v49, v49
	v_mul_f32_e32 v50, 0xbfb8aa3b, v50
	v_mul_f32_e32 v51, 0xbfb8aa3b, v51
	v_exp_f32_e32 v52, v52
	v_exp_f32_e32 v53, v53
	v_exp_f32_e32 v50, v50
	v_exp_f32_e32 v51, v51
	v_add_f32_e32 v54, 1.0, v54
	v_add_f32_e32 v55, 1.0, v55
	v_rcp_f32_e32 v54, v54
	v_rcp_f32_e32 v55, v55
	v_add_f32_e32 v48, 1.0, v48
	v_add_f32_e32 v49, 1.0, v49
	v_add_f32_e32 v52, 1.0, v52
	v_add_f32_e32 v53, 1.0, v53
	v_rcp_f32_e32 v48, v48
	v_rcp_f32_e32 v49, v49
	v_add_f32_e32 v50, 1.0, v50
	v_add_f32_e32 v51, 1.0, v51
	v_rcp_f32_e32 v52, v52
	v_rcp_f32_e32 v53, v53
	v_rcp_f32_e32 v50, v50
	v_rcp_f32_e32 v51, v51
	s_mov_b64 s[2:3], 0x48000
	v_lshlrev_b32_e32 v64, 16, v60
	v_and_b32_e32 v65, 0xffff0000, v60
	v_lshlrev_b32_e32 v68, 16, v56
	v_and_b32_e32 v69, 0xffff0000, v56
	v_lshlrev_b32_e32 v60, 16, v61
	v_and_b32_e32 v61, 0xffff0000, v61
	v_lshlrev_b32_e32 v56, 16, v57
	v_and_b32_e32 v57, 0xffff0000, v57
	v_pk_fma_f32 v[54:55], v[54:55], v[60:61], v[56:57]
	v_lshlrev_b32_e32 v56, 16, v62
	v_and_b32_e32 v57, 0xffff0000, v62
	v_lshlrev_b32_e32 v60, 16, v58
	v_and_b32_e32 v61, 0xffff0000, v58
	v_pk_fma_f32 v[56:57], v[48:49], v[56:57], v[60:61]
	v_lshlrev_b32_e32 v48, 16, v63
	v_and_b32_e32 v49, 0xffff0000, v63
	v_lshlrev_b32_e32 v58, 16, v59
	v_and_b32_e32 v59, 0xffff0000, v59
	v_pk_fma_f32 v[52:53], v[52:53], v[64:65], v[68:69]
	v_pk_fma_f32 v[58:59], v[50:51], v[48:49], v[58:59]
	v_cvt_pk_bf16_f32 v48, v52, v53
	v_cvt_pk_bf16_f32 v49, v54, v55
	v_cvt_pk_bf16_f32 v50, v56, v57
	v_cvt_pk_bf16_f32 v51, v58, v59
	global_store_dwordx4 v[66:67], v[48:51], off
	s_nop 1
	v_mov_b32_e32 v48, v246
	v_lshl_add_u64 v[54:55], v[158:159], 0, s[2:3]
	v_lshl_add_u64 v[50:51], s[30:31], 0, v[54:55]
	v_lshl_add_u64 v[58:59], s[0:1], 0, v[54:55]
	s_waitcnt vmcnt(13)
; __device__ __forceinline__ unsigned cvt_pk_bf16(float lo, float hi) { const f32x2_cv v = {lo, hi}; const bf16x2_cv b = __builtin_convertvector(v, bf16x2_cv); return __builtin_bit_cast(unsigned, b); }
; __device__ __forceinline__ float sigm(float x) { return __builtin_amdgcn_rcpf(1.0f + __expf(-x)); }
; __device__ __forceinline__ float lo16(unsigned w) { return __uint_as_float(w << 16); }
; __device__ __forceinline__ float hi16(unsigned w) { return __uint_as_float(w & 0xffff0000u); }
; __device__ __forceinline__ float rstd_of(const float* rowss, int row) { return rsqrtf(rowss[row] * (1.0f / 1024.0f) + 1e-6f); }
;     __device__ __forceinline__ void operator()(const f32x4 (&acc)[2][2][4][2], const pg8::Unit& u, int wr, int wc, int fr, int fq) const {
;     ...
;                 const int row = row0 + ai * 128 + m * 16;
;                 const float s = rstd_of(rowss, row);
; #pragma unroll
;                 for (int bj = 0; bj < 2; ++bj) {
;                     const size_t off = (size_t)row * 1024 + col0 + bj * 128;
;                     const u32x4 tv = *(const u32x4*)(Tm + off);
;                     u32x4 pv = (u32x4){0u, 0u, 0u, 0u};
;                     if (ACC) pv = *(const u32x4*)(M + off);
;                     const f32x4 a0 = acc[ai][bj][m][0] * s, a1 = acc[ai][bj][m][1] * s;
;                     float o[8];
;                     o[0] = sigm(a0[0]) * lo16(tv.x); o[1] = sigm(a0[1]) * hi16(tv.x); o[2] = sigm(a0[2]) * lo16(tv.y); o[3] = sigm(a0[3]) * hi16(tv.y);
;                     o[4] = sigm(a1[0]) * lo16(tv.z); o[5] = sigm(a1[1]) * hi16(tv.z); o[6] = sigm(a1[2]) * lo16(tv.w); o[7] = sigm(a1[3]) * hi16(tv.w);
;                     if (ACC) { o[0] += lo16(pv.x); o[1] += hi16(pv.x); o[2] += lo16(pv.y); o[3] += hi16(pv.y); o[4] += lo16(pv.z); o[5] += hi16(pv.z); o[6] += lo16(pv.w); o[7] += hi16(pv.w); }
;                     u32x4 w; w.x = cvt_pk_bf16(o[0], o[1]); w.y = cvt_pk_bf16(o[2], o[3]); w.z = cvt_pk_bf16(o[4], o[5]); w.w = cvt_pk_bf16(o[6], o[7]);
;                     *(u32x4*)(M + off) = w; } }
	s_nop 1
	v_mov_b32_e32 v50, v224
	v_mov_b32_e32 v51, v225
	v_mov_b32_e32 v52, v226
	v_mov_b32_e32 v53, v227
	s_mov_b64 s[2:3], 0x48100
	s_nop 1
	v_mov_b32_e32 v54, v228
	v_mov_b32_e32 v55, v229
	v_mov_b32_e32 v56, v230
	v_mov_b32_e32 v57, v231
	v_fmamk_f32 v48, v48, 0x3a800000, v187
	v_cmp_gt_f32_e32 vcc, s67, v48
	v_mul_f32_e32 v49, 0x4b800000, v48
	v_lshlrev_b32_e32 v60, 16, v50
	v_cndmask_b32_e32 v48, v48, v49, vcc
	v_rsq_f32_e32 v48, v48
	v_and_b32_e32 v61, 0xffff0000, v50
	v_lshlrev_b32_e32 v62, 16, v54
	v_and_b32_e32 v63, 0xffff0000, v54
	v_mul_f32_e32 v49, 0x45800000, v48
	v_cndmask_b32_e32 v48, v48, v49, vcc
	v_pk_mul_f32 v[46:47], v[46:47], v[48:49] op_sel_hi:[1,0]
	v_pk_mul_f32 v[40:41], v[40:41], v[48:49] op_sel_hi:[1,0]
	v_mul_f32_e32 v46, 0xbfb8aa3b, v46
	v_mul_f32_e32 v47, 0xbfb8aa3b, v47
	v_pk_mul_f32 v[44:45], v[44:45], v[48:49] op_sel_hi:[1,0]
	v_pk_mul_f32 v[42:43], v[42:43], v[48:49] op_sel_hi:[1,0]
	v_exp_f32_e32 v46, v46
	v_exp_f32_e32 v47, v47
	v_mul_f32_e32 v40, 0xbfb8aa3b, v40
	v_mul_f32_e32 v41, 0xbfb8aa3b, v41
	v_mul_f32_e32 v44, 0xbfb8aa3b, v44
	v_mul_f32_e32 v45, 0xbfb8aa3b, v45
	v_exp_f32_e32 v40, v40
	v_exp_f32_e32 v41, v41
	v_mul_f32_e32 v42, 0xbfb8aa3b, v42
	v_mul_f32_e32 v43, 0xbfb8aa3b, v43
	v_exp_f32_e32 v44, v44
	v_exp_f32_e32 v45, v45
	v_exp_f32_e32 v42, v42
	v_exp_f32_e32 v43, v43
	v_add_f32_e32 v46, 1.0, v46
	v_add_f32_e32 v47, 1.0, v47
	v_rcp_f32_e32 v46, v46
	v_rcp_f32_e32 v47, v47
	v_add_f32_e32 v40, 1.0, v40
	v_add_f32_e32 v41, 1.0, v41
	v_add_f32_e32 v44, 1.0, v44
	v_add_f32_e32 v45, 1.0, v45
	v_rcp_f32_e32 v40, v40
	v_rcp_f32_e32 v41, v41
	v_add_f32_e32 v42, 1.0, v42
	v_add_f32_e32 v43, 1.0, v43
	v_rcp_f32_e32 v44, v44
	v_rcp_f32_e32 v45, v45
	v_rcp_f32_e32 v42, v42
	v_rcp_f32_e32 v43, v43
	v_lshlrev_b32_e32 v50, 16, v51
	v_and_b32_e32 v51, 0xffff0000, v51
	v_lshlrev_b32_e32 v54, 16, v55
	v_and_b32_e32 v55, 0xffff0000, v55
	v_pk_fma_f32 v[46:47], v[46:47], v[50:51], v[54:55]
	v_lshlrev_b32_e32 v50, 16, v52
	v_and_b32_e32 v51, 0xffff0000, v52
	v_lshlrev_b32_e32 v54, 16, v56
	v_and_b32_e32 v55, 0xffff0000, v56
	v_pk_fma_f32 v[50:51], v[40:41], v[50:51], v[54:55]
	v_lshlrev_b32_e32 v40, 16, v53
	v_and_b32_e32 v41, 0xffff0000, v53
	v_lshlrev_b32_e32 v52, 16, v57
	v_and_b32_e32 v53, 0xffff0000, v57
	v_pk_fma_f32 v[44:45], v[44:45], v[60:61], v[62:63]
	v_pk_fma_f32 v[52:53], v[42:43], v[40:41], v[52:53]
	v_cvt_pk_bf16_f32 v40, v44, v45
	v_cvt_pk_bf16_f32 v41, v46, v47
	v_cvt_pk_bf16_f32 v42, v50, v51
	v_cvt_pk_bf16_f32 v43, v52, v53
	global_store_dwordx4 v[58:59], v[40:43], off
	v_pk_mul_f32 v[38:39], v[38:39], v[48:49] op_sel_hi:[1,0]
	v_pk_mul_f32 v[32:33], v[32:33], v[48:49] op_sel_hi:[1,0]
	v_lshl_add_u64 v[40:41], v[158:159], 0, s[2:3]
	v_lshl_add_u64 v[42:43], s[30:31], 0, v[40:41]
	v_lshl_add_u64 v[50:51], s[0:1], 0, v[40:41]
	s_nop 1
	v_mov_b32_e32 v44, v232
	v_mov_b32_e32 v45, v233
	v_mov_b32_e32 v46, v234
	v_mov_b32_e32 v47, v235
	v_mul_f32_e32 v38, 0xbfb8aa3b, v38
	s_nop 1
	v_mov_b32_e32 v40, v236
	v_mov_b32_e32 v41, v237
	v_mov_b32_e32 v42, v238
	v_mov_b32_e32 v43, v239
	v_mul_f32_e32 v39, 0xbfb8aa3b, v39
	v_pk_mul_f32 v[36:37], v[36:37], v[48:49] op_sel_hi:[1,0]
	v_pk_mul_f32 v[34:35], v[34:35], v[48:49] op_sel_hi:[1,0]
	v_exp_f32_e32 v38, v38
	v_exp_f32_e32 v39, v39
	v_mul_f32_e32 v32, 0xbfb8aa3b, v32
	v_mul_f32_e32 v33, 0xbfb8aa3b, v33
	v_mul_f32_e32 v36, 0xbfb8aa3b, v36
	v_mul_f32_e32 v37, 0xbfb8aa3b, v37
	v_exp_f32_e32 v32, v32
	v_exp_f32_e32 v33, v33
	v_mul_f32_e32 v34, 0xbfb8aa3b, v34
	v_mul_f32_e32 v35, 0xbfb8aa3b, v35
	v_exp_f32_e32 v36, v36
	v_exp_f32_e32 v37, v37
	v_exp_f32_e32 v34, v34
	v_exp_f32_e32 v35, v35
	v_add_f32_e32 v38, 1.0, v38
	v_add_f32_e32 v39, 1.0, v39
	v_rcp_f32_e32 v38, v38
	v_rcp_f32_e32 v39, v39
	v_add_f32_e32 v32, 1.0, v32
	v_add_f32_e32 v33, 1.0, v33
	v_add_f32_e32 v36, 1.0, v36
	v_add_f32_e32 v37, 1.0, v37
	v_rcp_f32_e32 v32, v32
	v_rcp_f32_e32 v33, v33
	v_add_f32_e32 v34, 1.0, v34
	v_add_f32_e32 v35, 1.0, v35
	v_rcp_f32_e32 v36, v36
	v_rcp_f32_e32 v37, v37
	v_rcp_f32_e32 v34, v34
	v_rcp_f32_e32 v35, v35
	s_mov_b64 s[2:3], 0x50000
	v_lshlrev_b32_e32 v48, 16, v44
	v_and_b32_e32 v49, 0xffff0000, v44
	v_lshlrev_b32_e32 v52, 16, v40
	v_and_b32_e32 v53, 0xffff0000, v40
	v_lshlrev_b32_e32 v44, 16, v45
	v_and_b32_e32 v45, 0xffff0000, v45
	v_lshlrev_b32_e32 v40, 16, v41
	v_and_b32_e32 v41, 0xffff0000, v41
	v_pk_fma_f32 v[38:39], v[38:39], v[44:45], v[40:41]
	v_lshlrev_b32_e32 v40, 16, v46
	v_and_b32_e32 v41, 0xffff0000, v46
	v_lshlrev_b32_e32 v44, 16, v42
	v_and_b32_e32 v45, 0xffff0000, v42
	v_pk_fma_f32 v[40:41], v[32:33], v[40:41], v[44:45]
	v_lshlrev_b32_e32 v32, 16, v47
	v_and_b32_e32 v33, 0xffff0000, v47
	v_lshlrev_b32_e32 v42, 16, v43
	v_and_b32_e32 v43, 0xffff0000, v43
	v_pk_fma_f32 v[36:37], v[36:37], v[48:49], v[52:53]
	v_pk_fma_f32 v[42:43], v[34:35], v[32:33], v[42:43]
	v_cvt_pk_bf16_f32 v32, v36, v37
	v_cvt_pk_bf16_f32 v33, v38, v39
	v_cvt_pk_bf16_f32 v34, v40, v41
	v_cvt_pk_bf16_f32 v35, v42, v43
	global_store_dwordx4 v[50:51], v[32:35], off
	s_nop 1
	v_mov_b32_e32 v32, v247
	v_lshl_add_u64 v[38:39], v[158:159], 0, s[2:3]
	v_lshl_add_u64 v[34:35], s[30:31], 0, v[38:39]
	v_lshl_add_u64 v[42:43], s[0:1], 0, v[38:39]
	s_waitcnt vmcnt(9)
; __device__ __forceinline__ unsigned cvt_pk_bf16(float lo, float hi) { const f32x2_cv v = {lo, hi}; const bf16x2_cv b = __builtin_convertvector(v, bf16x2_cv); return __builtin_bit_cast(unsigned, b); }
; __device__ __forceinline__ float sigm(float x) { return __builtin_amdgcn_rcpf(1.0f + __expf(-x)); }
; __device__ __forceinline__ float lo16(unsigned w) { return __uint_as_float(w << 16); }
; __device__ __forceinline__ float hi16(unsigned w) { return __uint_as_float(w & 0xffff0000u); }
; __device__ __forceinline__ float rstd_of(const float* rowss, int row) { return rsqrtf(rowss[row] * (1.0f / 1024.0f) + 1e-6f); }
;     __device__ __forceinline__ void operator()(const f32x4 (&acc)[2][2][4][2], const pg8::Unit& u, int wr, int wc, int fr, int fq) const {
;     ...
;                 const int row = row0 + ai * 128 + m * 16;
;                 const float s = rstd_of(rowss, row);
; #pragma unroll
;                 for (int bj = 0; bj < 2; ++bj) {
;                     const size_t off = (size_t)row * 1024 + col0 + bj * 128;
;                     const u32x4 tv = *(const u32x4*)(Tm + off);
;                     u32x4 pv = (u32x4){0u, 0u, 0u, 0u};
;                     if (ACC) pv = *(const u32x4*)(M + off);
;                     const f32x4 a0 = acc[ai][bj][m][0] * s, a1 = acc[ai][bj][m][1] * s;
;                     float o[8];
;                     o[0] = sigm(a0[0]) * lo16(tv.x); o[1] = sigm(a0[1]) * hi16(tv.x); o[2] = sigm(a0[2]) * lo16(tv.y); o[3] = sigm(a0[3]) * hi16(tv.y);
;                     o[4] = sigm(a1[0]) * lo16(tv.z); o[5] = sigm(a1[1]) * hi16(tv.z); o[6] = sigm(a1[2]) * lo16(tv.w); o[7] = sigm(a1[3]) * hi16(tv.w);
;                     if (ACC) { o[0] += lo16(pv.x); o[1] += hi16(pv.x); o[2] += lo16(pv.y); o[3] += hi16(pv.y); o[4] += lo16(pv.z); o[5] += hi16(pv.z); o[6] += lo16(pv.w); o[7] += hi16(pv.w); }
;                     u32x4 w; w.x = cvt_pk_bf16(o[0], o[1]); w.y = cvt_pk_bf16(o[2], o[3]); w.z = cvt_pk_bf16(o[4], o[5]); w.w = cvt_pk_bf16(o[6], o[7]);
;                     *(u32x4*)(M + off) = w; } }
	s_nop 1
	v_mov_b32_e32 v34, v192
	v_mov_b32_e32 v35, v193
	v_mov_b32_e32 v36, v194
	v_mov_b32_e32 v37, v195
	s_mov_b64 s[2:3], 0x50100
	s_nop 1
	v_mov_b32_e32 v38, v196
	v_mov_b32_e32 v39, v197
	v_mov_b32_e32 v40, v198
	v_mov_b32_e32 v41, v199
	v_fmamk_f32 v32, v32, 0x3a800000, v187
	v_cmp_gt_f32_e32 vcc, s67, v32
	v_mul_f32_e32 v33, 0x4b800000, v32
	v_lshlrev_b32_e32 v44, 16, v34
	v_cndmask_b32_e32 v32, v32, v33, vcc
	v_rsq_f32_e32 v32, v32
	v_and_b32_e32 v45, 0xffff0000, v34
	v_lshlrev_b32_e32 v46, 16, v38
	v_and_b32_e32 v47, 0xffff0000, v38
	v_mul_f32_e32 v33, 0x45800000, v32
	v_cndmask_b32_e32 v32, v32, v33, vcc
	v_pk_mul_f32 v[30:31], v[30:31], v[32:33] op_sel_hi:[1,0]
	v_pk_mul_f32 v[24:25], v[24:25], v[32:33] op_sel_hi:[1,0]
	v_mul_f32_e32 v30, 0xbfb8aa3b, v30
	v_mul_f32_e32 v31, 0xbfb8aa3b, v31
	v_pk_mul_f32 v[28:29], v[28:29], v[32:33] op_sel_hi:[1,0]
	v_pk_mul_f32 v[26:27], v[26:27], v[32:33] op_sel_hi:[1,0]
	v_exp_f32_e32 v30, v30
	v_exp_f32_e32 v31, v31
	v_mul_f32_e32 v24, 0xbfb8aa3b, v24
	v_mul_f32_e32 v25, 0xbfb8aa3b, v25
	v_mul_f32_e32 v28, 0xbfb8aa3b, v28
	v_mul_f32_e32 v29, 0xbfb8aa3b, v29
	v_exp_f32_e32 v24, v24
	v_exp_f32_e32 v25, v25
	v_mul_f32_e32 v26, 0xbfb8aa3b, v26
	v_mul_f32_e32 v27, 0xbfb8aa3b, v27
	v_exp_f32_e32 v28, v28
	v_exp_f32_e32 v29, v29
	v_exp_f32_e32 v26, v26
	v_exp_f32_e32 v27, v27
	v_add_f32_e32 v30, 1.0, v30
	v_add_f32_e32 v31, 1.0, v31
	v_rcp_f32_e32 v30, v30
	v_rcp_f32_e32 v31, v31
	v_add_f32_e32 v24, 1.0, v24
	v_add_f32_e32 v25, 1.0, v25
	v_add_f32_e32 v28, 1.0, v28
	v_add_f32_e32 v29, 1.0, v29
	v_rcp_f32_e32 v24, v24
	v_rcp_f32_e32 v25, v25
	v_add_f32_e32 v26, 1.0, v26
	v_add_f32_e32 v27, 1.0, v27
	v_rcp_f32_e32 v28, v28
	v_rcp_f32_e32 v29, v29
	v_rcp_f32_e32 v26, v26
	v_rcp_f32_e32 v27, v27
	v_lshlrev_b32_e32 v34, 16, v35
	v_and_b32_e32 v35, 0xffff0000, v35
	v_lshlrev_b32_e32 v38, 16, v39
	v_and_b32_e32 v39, 0xffff0000, v39
	v_pk_fma_f32 v[30:31], v[30:31], v[34:35], v[38:39]
	v_lshlrev_b32_e32 v34, 16, v36
	v_and_b32_e32 v35, 0xffff0000, v36
	v_lshlrev_b32_e32 v38, 16, v40
	v_and_b32_e32 v39, 0xffff0000, v40
	v_pk_fma_f32 v[34:35], v[24:25], v[34:35], v[38:39]
	v_lshlrev_b32_e32 v24, 16, v37
	v_and_b32_e32 v25, 0xffff0000, v37
	v_lshlrev_b32_e32 v36, 16, v41
	v_and_b32_e32 v37, 0xffff0000, v41
	v_pk_fma_f32 v[28:29], v[28:29], v[44:45], v[46:47]
	v_pk_fma_f32 v[36:37], v[26:27], v[24:25], v[36:37]
	v_cvt_pk_bf16_f32 v24, v28, v29
	v_cvt_pk_bf16_f32 v25, v30, v31
	v_cvt_pk_bf16_f32 v26, v34, v35
	v_cvt_pk_bf16_f32 v27, v36, v37
	global_store_dwordx4 v[42:43], v[24:27], off
	v_pk_mul_f32 v[22:23], v[22:23], v[32:33] op_sel_hi:[1,0]
	v_pk_mul_f32 v[16:17], v[16:17], v[32:33] op_sel_hi:[1,0]
	v_lshl_add_u64 v[24:25], v[158:159], 0, s[2:3]
	v_lshl_add_u64 v[26:27], s[30:31], 0, v[24:25]
	v_lshl_add_u64 v[34:35], s[0:1], 0, v[24:25]
	s_nop 1
	v_mov_b32_e32 v28, v200
	v_mov_b32_e32 v29, v201
	v_mov_b32_e32 v30, v202
	v_mov_b32_e32 v31, v203
	v_mul_f32_e32 v22, 0xbfb8aa3b, v22
	s_nop 1
	v_mov_b32_e32 v24, v204
	v_mov_b32_e32 v25, v205
	v_mov_b32_e32 v26, v206
	v_mov_b32_e32 v27, v207
	v_mul_f32_e32 v23, 0xbfb8aa3b, v23
	v_pk_mul_f32 v[20:21], v[20:21], v[32:33] op_sel_hi:[1,0]
	v_pk_mul_f32 v[18:19], v[18:19], v[32:33] op_sel_hi:[1,0]
	v_exp_f32_e32 v22, v22
	v_exp_f32_e32 v23, v23
	v_mul_f32_e32 v16, 0xbfb8aa3b, v16
	v_mul_f32_e32 v17, 0xbfb8aa3b, v17
	v_mul_f32_e32 v20, 0xbfb8aa3b, v20
	v_mul_f32_e32 v21, 0xbfb8aa3b, v21
	v_exp_f32_e32 v16, v16
	v_exp_f32_e32 v17, v17
	v_mul_f32_e32 v18, 0xbfb8aa3b, v18
	v_mul_f32_e32 v19, 0xbfb8aa3b, v19
	v_exp_f32_e32 v20, v20
	v_exp_f32_e32 v21, v21
	v_exp_f32_e32 v18, v18
	v_exp_f32_e32 v19, v19
	v_add_f32_e32 v22, 1.0, v22
	v_add_f32_e32 v23, 1.0, v23
	v_rcp_f32_e32 v22, v22
	v_rcp_f32_e32 v23, v23
	v_add_f32_e32 v16, 1.0, v16
	v_add_f32_e32 v17, 1.0, v17
	v_add_f32_e32 v20, 1.0, v20
	v_add_f32_e32 v21, 1.0, v21
	v_rcp_f32_e32 v16, v16
	v_rcp_f32_e32 v17, v17
	v_add_f32_e32 v18, 1.0, v18
	v_add_f32_e32 v19, 1.0, v19
	v_rcp_f32_e32 v20, v20
	v_rcp_f32_e32 v21, v21
	v_rcp_f32_e32 v18, v18
	v_rcp_f32_e32 v19, v19
	s_mov_b64 s[2:3], 0x58000
	v_lshlrev_b32_e32 v32, 16, v28
	v_and_b32_e32 v33, 0xffff0000, v28
	v_lshlrev_b32_e32 v36, 16, v24
	v_and_b32_e32 v37, 0xffff0000, v24
	v_lshlrev_b32_e32 v28, 16, v29
	v_and_b32_e32 v29, 0xffff0000, v29
	v_lshlrev_b32_e32 v24, 16, v25
	v_and_b32_e32 v25, 0xffff0000, v25
	v_pk_fma_f32 v[22:23], v[22:23], v[28:29], v[24:25]
	v_lshlrev_b32_e32 v24, 16, v30
	v_and_b32_e32 v25, 0xffff0000, v30
	v_lshlrev_b32_e32 v28, 16, v26
	v_and_b32_e32 v29, 0xffff0000, v26
	v_pk_fma_f32 v[24:25], v[16:17], v[24:25], v[28:29]
	v_lshlrev_b32_e32 v16, 16, v31
	v_and_b32_e32 v17, 0xffff0000, v31
	v_lshlrev_b32_e32 v26, 16, v27
	v_and_b32_e32 v27, 0xffff0000, v27
	v_pk_fma_f32 v[20:21], v[20:21], v[32:33], v[36:37]
	v_pk_fma_f32 v[26:27], v[18:19], v[16:17], v[26:27]
	v_cvt_pk_bf16_f32 v16, v20, v21
	v_cvt_pk_bf16_f32 v17, v22, v23
	v_cvt_pk_bf16_f32 v18, v24, v25
	v_cvt_pk_bf16_f32 v19, v26, v27
	global_store_dwordx4 v[34:35], v[16:19], off
	s_nop 1
	v_mov_b32_e32 v16, v248
	v_lshl_add_u64 v[22:23], v[158:159], 0, s[2:3]
	v_lshl_add_u64 v[18:19], s[30:31], 0, v[22:23]
	v_lshl_add_u64 v[26:27], s[0:1], 0, v[22:23]
	s_waitcnt vmcnt(5)
; __device__ __forceinline__ unsigned cvt_pk_bf16(float lo, float hi) { const f32x2_cv v = {lo, hi}; const bf16x2_cv b = __builtin_convertvector(v, bf16x2_cv); return __builtin_bit_cast(unsigned, b); }
; __device__ __forceinline__ float sigm(float x) { return __builtin_amdgcn_rcpf(1.0f + __expf(-x)); }
; __device__ __forceinline__ float lo16(unsigned w) { return __uint_as_float(w << 16); }
; __device__ __forceinline__ float hi16(unsigned w) { return __uint_as_float(w & 0xffff0000u); }
; __device__ __forceinline__ float rstd_of(const float* rowss, int row) { return rsqrtf(rowss[row] * (1.0f / 1024.0f) + 1e-6f); }
;     __device__ __forceinline__ void operator()(const f32x4 (&acc)[2][2][4][2], const pg8::Unit& u, int wr, int wc, int fr, int fq) const {
;     ...
;                 const int row = row0 + ai * 128 + m * 16;
;                 const float s = rstd_of(rowss, row);
; #pragma unroll
;                 for (int bj = 0; bj < 2; ++bj) {
;                     const size_t off = (size_t)row * 1024 + col0 + bj * 128;
;                     const u32x4 tv = *(const u32x4*)(Tm + off);
;                     u32x4 pv = (u32x4){0u, 0u, 0u, 0u};
;                     if (ACC) pv = *(const u32x4*)(M + off);
;                     const f32x4 a0 = acc[ai][bj][m][0] * s, a1 = acc[ai][bj][m][1] * s;
;                     float o[8];
;                     o[0] = sigm(a0[0]) * lo16(tv.x); o[1] = sigm(a0[1]) * hi16(tv.x); o[2] = sigm(a0[2]) * lo16(tv.y); o[3] = sigm(a0[3]) * hi16(tv.y);
;                     o[4] = sigm(a1[0]) * lo16(tv.z); o[5] = sigm(a1[1]) * hi16(tv.z); o[6] = sigm(a1[2]) * lo16(tv.w); o[7] = sigm(a1[3]) * hi16(tv.w);
;                     if (ACC) { o[0] += lo16(pv.x); o[1] += hi16(pv.x); o[2] += lo16(pv.y); o[3] += hi16(pv.y); o[4] += lo16(pv.z); o[5] += hi16(pv.z); o[6] += lo16(pv.w); o[7] += hi16(pv.w); }
;                     u32x4 w; w.x = cvt_pk_bf16(o[0], o[1]); w.y = cvt_pk_bf16(o[2], o[3]); w.z = cvt_pk_bf16(o[4], o[5]); w.w = cvt_pk_bf16(o[6], o[7]);
;                     *(u32x4*)(M + off) = w; } }
	s_nop 1
	v_mov_b32_e32 v18, v208
	v_mov_b32_e32 v19, v209
	v_mov_b32_e32 v20, v210
	v_mov_b32_e32 v21, v211
	s_mov_b64 s[2:3], 0x58100
	s_nop 1
	v_mov_b32_e32 v22, v212
	v_mov_b32_e32 v23, v213
	v_mov_b32_e32 v24, v214
	v_mov_b32_e32 v25, v215
	v_fmamk_f32 v16, v16, 0x3a800000, v187
	v_cmp_gt_f32_e32 vcc, s67, v16
	v_mul_f32_e32 v17, 0x4b800000, v16
	v_lshlrev_b32_e32 v28, 16, v18
	v_cndmask_b32_e32 v16, v16, v17, vcc
	v_rsq_f32_e32 v16, v16
	v_and_b32_e32 v29, 0xffff0000, v18
	v_lshlrev_b32_e32 v30, 16, v22
	v_and_b32_e32 v31, 0xffff0000, v22
	v_mul_f32_e32 v17, 0x45800000, v16
	v_cndmask_b32_e32 v16, v16, v17, vcc
	v_pk_mul_f32 v[14:15], v[14:15], v[16:17] op_sel_hi:[1,0]
	v_pk_mul_f32 v[8:9], v[8:9], v[16:17] op_sel_hi:[1,0]
	v_mul_f32_e32 v14, 0xbfb8aa3b, v14
	v_mul_f32_e32 v15, 0xbfb8aa3b, v15
	v_pk_mul_f32 v[12:13], v[12:13], v[16:17] op_sel_hi:[1,0]
	v_pk_mul_f32 v[10:11], v[10:11], v[16:17] op_sel_hi:[1,0]
	v_exp_f32_e32 v14, v14
	v_exp_f32_e32 v15, v15
	v_mul_f32_e32 v8, 0xbfb8aa3b, v8
	v_mul_f32_e32 v9, 0xbfb8aa3b, v9
	v_mul_f32_e32 v12, 0xbfb8aa3b, v12
	v_mul_f32_e32 v13, 0xbfb8aa3b, v13
	v_exp_f32_e32 v8, v8
	v_exp_f32_e32 v9, v9
	v_mul_f32_e32 v10, 0xbfb8aa3b, v10
	v_mul_f32_e32 v11, 0xbfb8aa3b, v11
	v_exp_f32_e32 v12, v12
	v_exp_f32_e32 v13, v13
	v_exp_f32_e32 v10, v10
	v_exp_f32_e32 v11, v11
	v_add_f32_e32 v14, 1.0, v14
	v_add_f32_e32 v15, 1.0, v15
	v_rcp_f32_e32 v14, v14
	v_rcp_f32_e32 v15, v15
	v_add_f32_e32 v8, 1.0, v8
	v_add_f32_e32 v9, 1.0, v9
	v_add_f32_e32 v12, 1.0, v12
	v_add_f32_e32 v13, 1.0, v13
	v_rcp_f32_e32 v8, v8
	v_rcp_f32_e32 v9, v9
	v_add_f32_e32 v10, 1.0, v10
	v_add_f32_e32 v11, 1.0, v11
	v_rcp_f32_e32 v12, v12
	v_rcp_f32_e32 v13, v13
	v_rcp_f32_e32 v10, v10
	v_rcp_f32_e32 v11, v11
	v_lshlrev_b32_e32 v18, 16, v19
	v_and_b32_e32 v19, 0xffff0000, v19
	v_lshlrev_b32_e32 v22, 16, v23
	v_and_b32_e32 v23, 0xffff0000, v23
	v_pk_fma_f32 v[14:15], v[14:15], v[18:19], v[22:23]
	v_lshlrev_b32_e32 v18, 16, v20
	v_and_b32_e32 v19, 0xffff0000, v20
	v_lshlrev_b32_e32 v22, 16, v24
	v_and_b32_e32 v23, 0xffff0000, v24
	v_pk_fma_f32 v[18:19], v[8:9], v[18:19], v[22:23]
	v_lshlrev_b32_e32 v8, 16, v21
	v_and_b32_e32 v9, 0xffff0000, v21
	v_lshlrev_b32_e32 v20, 16, v25
	v_and_b32_e32 v21, 0xffff0000, v25
	v_pk_fma_f32 v[12:13], v[12:13], v[28:29], v[30:31]
	v_pk_fma_f32 v[20:21], v[10:11], v[8:9], v[20:21]
	v_cvt_pk_bf16_f32 v8, v12, v13
	v_cvt_pk_bf16_f32 v9, v14, v15
	v_cvt_pk_bf16_f32 v10, v18, v19
	v_cvt_pk_bf16_f32 v11, v20, v21
	global_store_dwordx4 v[26:27], v[8:11], off
	v_pk_mul_f32 v[6:7], v[6:7], v[16:17] op_sel_hi:[1,0]
	v_pk_mul_f32 v[0:1], v[0:1], v[16:17] op_sel_hi:[1,0]
	v_lshl_add_u64 v[8:9], v[158:159], 0, s[2:3]
	v_lshl_add_u64 v[10:11], s[30:31], 0, v[8:9]
	v_lshl_add_u64 v[18:19], s[0:1], 0, v[8:9]
	s_nop 1
	v_mov_b32_e32 v12, v216
	v_mov_b32_e32 v13, v217
	v_mov_b32_e32 v14, v218
	v_mov_b32_e32 v15, v219
	v_mul_f32_e32 v6, 0xbfb8aa3b, v6
	s_nop 1
	v_mov_b32_e32 v8, v220
	v_mov_b32_e32 v9, v221
	v_mov_b32_e32 v10, v222
	v_mov_b32_e32 v11, v223
	v_mul_f32_e32 v7, 0xbfb8aa3b, v7
	v_pk_mul_f32 v[4:5], v[4:5], v[16:17] op_sel_hi:[1,0]
	v_pk_mul_f32 v[2:3], v[2:3], v[16:17] op_sel_hi:[1,0]
	v_exp_f32_e32 v6, v6
	v_exp_f32_e32 v7, v7
	v_mul_f32_e32 v0, 0xbfb8aa3b, v0
	v_mul_f32_e32 v1, 0xbfb8aa3b, v1
	v_mul_f32_e32 v4, 0xbfb8aa3b, v4
	v_mul_f32_e32 v5, 0xbfb8aa3b, v5
	v_exp_f32_e32 v0, v0
	v_exp_f32_e32 v1, v1
	v_mul_f32_e32 v2, 0xbfb8aa3b, v2
	v_mul_f32_e32 v3, 0xbfb8aa3b, v3
	v_exp_f32_e32 v4, v4
	v_exp_f32_e32 v5, v5
	v_exp_f32_e32 v2, v2
	v_exp_f32_e32 v3, v3
	v_add_f32_e32 v6, 1.0, v6
	v_add_f32_e32 v7, 1.0, v7
	v_rcp_f32_e32 v6, v6
	v_rcp_f32_e32 v7, v7
	v_add_f32_e32 v0, 1.0, v0
	v_add_f32_e32 v1, 1.0, v1
	v_add_f32_e32 v4, 1.0, v4
	v_add_f32_e32 v5, 1.0, v5
	v_rcp_f32_e32 v0, v0
	v_rcp_f32_e32 v1, v1
	v_add_f32_e32 v2, 1.0, v2
	v_add_f32_e32 v3, 1.0, v3
	v_rcp_f32_e32 v4, v4
	v_rcp_f32_e32 v5, v5
	v_rcp_f32_e32 v2, v2
	v_rcp_f32_e32 v3, v3
	s_and_b64 vcc, exec, s[38:39]
	s_mov_b32 s3, s26
	s_mov_b32 s2, s12
	v_lshlrev_b32_e32 v16, 16, v12
	v_and_b32_e32 v17, 0xffff0000, v12
	v_lshlrev_b32_e32 v20, 16, v8
	v_and_b32_e32 v21, 0xffff0000, v8
	v_lshlrev_b32_e32 v12, 16, v13
	v_and_b32_e32 v13, 0xffff0000, v13
	v_lshlrev_b32_e32 v8, 16, v9
	v_and_b32_e32 v9, 0xffff0000, v9
	v_pk_fma_f32 v[6:7], v[6:7], v[12:13], v[8:9]
	v_lshlrev_b32_e32 v8, 16, v14
	v_and_b32_e32 v9, 0xffff0000, v14
	v_lshlrev_b32_e32 v12, 16, v10
	v_and_b32_e32 v13, 0xffff0000, v10
	v_pk_fma_f32 v[8:9], v[0:1], v[8:9], v[12:13]
	v_lshlrev_b32_e32 v0, 16, v15
	v_and_b32_e32 v1, 0xffff0000, v15
	v_lshlrev_b32_e32 v10, 16, v11
	v_and_b32_e32 v11, 0xffff0000, v11
	v_pk_fma_f32 v[4:5], v[4:5], v[16:17], v[20:21]
	v_pk_fma_f32 v[10:11], v[2:3], v[0:1], v[10:11]
	v_cvt_pk_bf16_f32 v0, v4, v5
	v_cvt_pk_bf16_f32 v1, v6, v7
	v_cvt_pk_bf16_f32 v2, v8, v9
	v_cvt_pk_bf16_f32 v3, v10, v11
	global_store_dwordx4 v[18:19], v[0:3], off
	s_cbranch_vccz .LBB0_346
	s_cmpk_gt_u32 s70, 0xff
	s_cbranch_scc1 .LBB0_357
	s_barrier

; #define PG8_STAGE(bufoff, gbase, voff) do { _Pragma("unroll") for (int _i = 0; _i < 2; ++_i) \
;         __builtin_amdgcn_global_load_lds((const unsigned*)((const char*)(gbase) + (voff)[_i]), (PG8_LAS unsigned*)(lds + (bufoff) + ldsw + _i * 8192), 16, 0, 0); } while (0)
; #define PG8_LDA(dst, b, h) do { _Pragma("unroll") for (int m = 0; m < 4; ++m) _Pragma("unroll") for (int k = 0; k < 2; ++k) dst[m][k] = *(const PG8_LAS bf16x8*)(lds + PG8_SA(b, h) + aoff + m * 2048 + k * 1024); } while (0)
; #define PG8_LDB(dst, b, h) do { _Pragma("unroll") for (int n = 0; n < 2; ++n) _Pragma("unroll") for (int k = 0; k < 2; ++k) dst[n][k] = *(const PG8_LAS bf16x8*)(lds + PG8_SB(b, h) + boff + n * 2048 + k * 1024); } while (0)
; #define PG8_MMA(ai, bj, At, Bt) do { __builtin_amdgcn_s_setprio(1); _Pragma("unroll") for (int m = 0; m < 4; ++m) _Pragma("unroll") for (int n = 0; n < 2; ++n) _Pragma("unroll") for (int k = 0; k < 2; ++k) \
;         acc[ai][bj][m][n] = __builtin_amdgcn_mfma_f32_16x16x32_bf16(Bt[n][k], At[m][k], acc[ai][bj][m][n], 0, 0, 0); __builtin_amdgcn_s_setprio(0); } while (0)
; #define PG8_WAIT_L(n) asm volatile("s_waitcnt lgkmcnt(" #n ")" ::: "memory")
; #define PG8_BAR __builtin_amdgcn_s_barrier()
; #define PG8_SCHED __builtin_amdgcn_sched_barrier(0)
; template <class Epi, class Sched, bool STAMP = false>
; __device__ __forceinline__ void gemm_phase(PG8_LAS unsigned char* lds, const Gemm g, const Sched& S, const Epi& E, unsigned long long* stamps) {
;     ...
;             const bool last = (t == nt - 2);
;             const char* a1 = cA + (size_t)(t + 1) * kstep;
;             const char* a2 = last ? nA : cA + (size_t)(t + 2) * kstep; const char* b2 = last ? nB : cB + (size_t)(t + 2) * kstep;
;             const char* a3 = a2 + kstep; const char* b3 = b2 + kstep;
;             if (last && has_next) S.a_ready(nxt);
;             PG8_LDB(B0, 0, 0); PG8_SCHED; PG8_LDA(At, 0, 0); PG8_STAGE(PG8_SA(1, 1), a1 + hstep, voffA);
;             PG8_WAIT_L(8); PG8_BAR; PG8_WAIT_L(0); PG8_MMA(0, 0, At, B0); PG8_BAR; PG8_SCHED;
;             PG8_LDB(B1, 0, 1); PG8_STAGE(PG8_SB(0, 0), b2, voffB);
;             PG8_BAR; PG8_WAIT_L(0); PG8_MMA(0, 1, At, B1); PG8_BAR;
;             PG8_LDA(At, 0, 1); PG8_STAGE(PG8_SA(0, 0), a2, voffA);
;             PG8_BAR; PG8_WAIT_L(0); PG8_MMA(1, 0, At, B0); PG8_BAR; PG8_SCHED;
.LBB0_374:
	s_add_i32 s15, s14, 0x100
	s_and_b64 s[16:17], s[22:23], exec
	s_cselect_b32 s15, 0, s15
	s_cselect_b32 s16, 0, 0
	s_add_u32 s26, s6, s15
	s_addc_u32 s27, s7, s16
	s_add_i32 s52, 0, 0x10000
	s_add_u32 s30, s4, s15
	s_addc_u32 s31, s5, s16
	s_add_u32 s36, s12, s14
	s_addc_u32 s37, s13, 0
	s_add_i32 s62, s52, s46
	v_add_u32_e32 v153, s52, v151
	s_add_i32 m0, s42, 0xc000
	s_add_i32 s61, s42, 0xe000
	s_add_i32 s60, 0, 0x14000
	s_add_i32 s59, s62, 0x2000
	ds_read_b128 v[154:157], v153
	ds_read_b128 v[158:161], v153 offset:1024
	ds_read_b128 v[162:165], v153 offset:2048
	ds_read_b128 v[166:169], v153 offset:3072
	s_add_u32 s24, s30, s45
	s_addc_u32 s25, s31, 0
	s_add_i32 s29, s60, s46
	s_add_i32 s17, s29, 0x2000
	s_add_i32 s16, 0, 0x18000
	s_add_u32 s22, s26, s45
	s_addc_u32 s23, s27, 0
	s_add_i32 s14, 0, 0x1c000
	s_add_i32 s15, s16, s46
	s_add_i32 s58, s14, s46
	s_add_i32 s63, s15, 0x2000
	s_add_i32 s52, s58, 0x2000
	v_lshl_add_u64 v[182:183], s[36:37], 0, v[128:129]
	v_lshl_add_u64 v[182:183], v[182:183], 0, s[18:19]
	ds_read_b128 v[170:173], v152
	ds_read_b128 v[174:177], v152 offset:1024
	ds_read_b128 v[178:181], v152 offset:2048
	ds_read_b128 v[192:195], v152 offset:3072
	ds_read_b128 v[196:199], v152 offset:4096
	ds_read_b128 v[200:203], v152 offset:5120
	ds_read_b128 v[204:207], v152 offset:6144
	ds_read_b128 v[208:211], v152 offset:7168
	global_load_lds_dwordx4 v[182:183], off
	v_lshl_add_u64 v[182:183], s[36:37], 0, v[148:149]
	v_lshl_add_u64 v[182:183], v[182:183], 0, s[18:19]
	s_mov_b32 m0, s61
	s_nop 0
	global_load_lds_dwordx4 v[182:183], off
	s_waitcnt lgkmcnt(8)
	s_barrier
	s_waitcnt lgkmcnt(0)
	s_waitcnt lgkmcnt(0)
	v_mfma_f32_16x16x32_bf16 v[124:127], v[154:157], v[170:173], v[124:127]
	v_mfma_f32_16x16x32_bf16 v[120:123], v[162:165], v[170:173], v[120:123]
	v_mfma_f32_16x16x32_bf16 v[116:119], v[154:157], v[178:181], v[116:119]
	v_mfma_f32_16x16x32_bf16 v[112:115], v[162:165], v[178:181], v[112:115]
	v_mfma_f32_16x16x32_bf16 v[104:107], v[154:157], v[196:199], v[104:107]
	v_mfma_f32_16x16x32_bf16 v[96:99], v[162:165], v[196:199], v[96:99]
	v_mfma_f32_16x16x32_bf16 v[88:91], v[154:157], v[204:207], v[88:91]
	v_mfma_f32_16x16x32_bf16 v[80:83], v[162:165], v[204:207], v[80:83]
	v_mfma_f32_16x16x32_bf16 v[124:127], v[158:161], v[174:177], v[124:127]
	v_mfma_f32_16x16x32_bf16 v[120:123], v[166:169], v[174:177], v[120:123]
	v_mfma_f32_16x16x32_bf16 v[116:119], v[158:161], v[192:195], v[116:119]
	v_mfma_f32_16x16x32_bf16 v[112:115], v[166:169], v[192:195], v[112:115]
	v_mfma_f32_16x16x32_bf16 v[104:107], v[158:161], v[200:203], v[104:107]
	v_mfma_f32_16x16x32_bf16 v[96:99], v[166:169], v[200:203], v[96:99]
	v_mfma_f32_16x16x32_bf16 v[88:91], v[158:161], v[208:211], v[88:91]
	v_mfma_f32_16x16x32_bf16 v[80:83], v[166:169], v[208:211], v[80:83]
	s_barrier
	s_mov_b32 m0, s62
	v_add_u32_e32 v153, s60, v151
	v_lshl_add_u64 v[182:183], s[30:31], 0, v[128:129]
	ds_read_b128 v[212:215], v153
	ds_read_b128 v[216:219], v153 offset:1024
	ds_read_b128 v[220:223], v153 offset:2048
	ds_read_b128 v[224:227], v153 offset:3072
	global_load_lds_dwordx4 v[182:183], off
	v_lshl_add_u64 v[228:229], s[30:31], 0, v[148:149]
	s_mov_b32 m0, s59
	s_nop 0
	global_load_lds_dwordx4 v[228:229], off
	s_barrier
	s_waitcnt lgkmcnt(0)
	s_waitcnt lgkmcnt(0)
	v_mfma_f32_16x16x32_bf16 v[108:111], v[212:215], v[170:173], v[108:111]
	v_mfma_f32_16x16x32_bf16 v[100:103], v[220:223], v[170:173], v[100:103]
	v_mfma_f32_16x16x32_bf16 v[92:95], v[212:215], v[178:181], v[92:95]
	v_mfma_f32_16x16x32_bf16 v[84:87], v[220:223], v[178:181], v[84:87]
	v_mfma_f32_16x16x32_bf16 v[76:79], v[212:215], v[196:199], v[76:79]
	v_mfma_f32_16x16x32_bf16 v[72:75], v[220:223], v[196:199], v[72:75]
	v_mfma_f32_16x16x32_bf16 v[68:71], v[212:215], v[204:207], v[68:71]
	v_mfma_f32_16x16x32_bf16 v[64:67], v[220:223], v[204:207], v[64:67]
	v_mfma_f32_16x16x32_bf16 v[108:111], v[216:219], v[174:177], v[108:111]
	v_mfma_f32_16x16x32_bf16 v[100:103], v[224:227], v[174:177], v[100:103]
	v_mfma_f32_16x16x32_bf16 v[92:95], v[216:219], v[192:195], v[92:95]
	v_mfma_f32_16x16x32_bf16 v[84:87], v[224:227], v[192:195], v[84:87]
	v_mfma_f32_16x16x32_bf16 v[76:79], v[216:219], v[200:203], v[76:79]
	v_mfma_f32_16x16x32_bf16 v[72:75], v[224:227], v[200:203], v[72:75]
	v_mfma_f32_16x16x32_bf16 v[68:71], v[216:219], v[208:211], v[68:71]
	v_mfma_f32_16x16x32_bf16 v[64:67], v[224:227], v[208:211], v[64:67]
	s_mov_b32 m0, s42
	v_lshl_add_u64 v[230:231], s[26:27], 0, v[128:129]
	s_barrier
	ds_read_b128 v[170:173], v152 offset:16384
	ds_read_b128 v[174:177], v152 offset:17408
	ds_read_b128 v[178:181], v152 offset:18432
	ds_read_b128 v[192:195], v152 offset:19456
	ds_read_b128 v[196:199], v152 offset:20480
	ds_read_b128 v[200:203], v152 offset:21504
	ds_read_b128 v[204:207], v152 offset:22528
	ds_read_b128 v[208:211], v152 offset:23552
	global_load_lds_dwordx4 v[230:231], off
	v_lshl_add_u64 v[232:233], s[26:27], 0, v[148:149]
	s_mov_b32 m0, s43
	s_nop 0
	global_load_lds_dwordx4 v[232:233], off
	s_barrier
	s_waitcnt lgkmcnt(0)
	s_waitcnt lgkmcnt(0)
	v_mfma_f32_16x16x32_bf16 v[60:63], v[154:157], v[170:173], v[60:63]
	v_mfma_f32_16x16x32_bf16 v[56:59], v[162:165], v[170:173], v[56:59]
	v_mfma_f32_16x16x32_bf16 v[52:55], v[154:157], v[178:181], v[52:55]
	v_mfma_f32_16x16x32_bf16 v[48:51], v[162:165], v[178:181], v[48:51]
	v_mfma_f32_16x16x32_bf16 v[36:39], v[154:157], v[196:199], v[36:39]
	v_mfma_f32_16x16x32_bf16 v[32:35], v[162:165], v[196:199], v[32:35]
	v_mfma_f32_16x16x32_bf16 v[20:23], v[154:157], v[204:207], v[20:23]
	v_mfma_f32_16x16x32_bf16 v[16:19], v[162:165], v[204:207], v[16:19]
	v_mfma_f32_16x16x32_bf16 v[60:63], v[158:161], v[174:177], v[60:63]
	v_mfma_f32_16x16x32_bf16 v[56:59], v[166:169], v[174:177], v[56:59]
	v_mfma_f32_16x16x32_bf16 v[52:55], v[158:161], v[192:195], v[52:55]
	v_mfma_f32_16x16x32_bf16 v[48:51], v[166:169], v[192:195], v[48:51]
	v_mfma_f32_16x16x32_bf16 v[36:39], v[158:161], v[200:203], v[36:39]
	v_mfma_f32_16x16x32_bf16 v[32:35], v[166:169], v[200:203], v[32:35]
	v_mfma_f32_16x16x32_bf16 v[20:23], v[158:161], v[208:211], v[20:23]
	v_mfma_f32_16x16x32_bf16 v[16:19], v[166:169], v[208:211], v[16:19]
	s_barrier
; #define PG8_STAGE(bufoff, gbase, voff) do { _Pragma("unroll") for (int _i = 0; _i < 2; ++_i) \
;         __builtin_amdgcn_global_load_lds((const unsigned*)((const char*)(gbase) + (voff)[_i]), (PG8_LAS unsigned*)(lds + (bufoff) + ldsw + _i * 8192), 16, 0, 0); } while (0)
; #define PG8_LDA(dst, b, h) do { _Pragma("unroll") for (int m = 0; m < 4; ++m) _Pragma("unroll") for (int k = 0; k < 2; ++k) dst[m][k] = *(const PG8_LAS bf16x8*)(lds + PG8_SA(b, h) + aoff + m * 2048 + k * 1024); } while (0)
; #define PG8_LDB(dst, b, h) do { _Pragma("unroll") for (int n = 0; n < 2; ++n) _Pragma("unroll") for (int k = 0; k < 2; ++k) dst[n][k] = *(const PG8_LAS bf16x8*)(lds + PG8_SB(b, h) + boff + n * 2048 + k * 1024); } while (0)
; #define PG8_MMA(ai, bj, At, Bt) do { __builtin_amdgcn_s_setprio(1); _Pragma("unroll") for (int m = 0; m < 4; ++m) _Pragma("unroll") for (int n = 0; n < 2; ++n) _Pragma("unroll") for (int k = 0; k < 2; ++k) \
;         acc[ai][bj][m][n] = __builtin_amdgcn_mfma_f32_16x16x32_bf16(Bt[n][k], At[m][k], acc[ai][bj][m][n], 0, 0, 0); __builtin_amdgcn_s_setprio(0); } while (0)
; #define PG8_WAIT_V(n) asm volatile("s_waitcnt vmcnt(" #n ")" ::: "memory")
; #define PG8_WAIT_L(n) asm volatile("s_waitcnt lgkmcnt(" #n ")" ::: "memory")
; #define PG8_BAR __builtin_amdgcn_s_barrier()
; #define PG8_SCHED __builtin_amdgcn_sched_barrier(0)
; template <class Epi, class Sched, bool STAMP = false>
; __device__ __forceinline__ void gemm_phase(PG8_LAS unsigned char* lds, const Gemm g, const Sched& S, const Epi& E, unsigned long long* stamps) {
;     ...
;             PG8_STAGE(PG8_SB(0, 1), b2 + hstep, voffB);
;             PG8_WAIT_V(6); PG8_BAR; PG8_MMA(1, 1, At, B1); PG8_BAR;
;             PG8_LDB(B0, 1, 0); PG8_SCHED; PG8_LDA(At, 1, 0); PG8_STAGE(PG8_SA(0, 1), a2 + hstep, voffA);
;             PG8_WAIT_L(8); PG8_BAR; PG8_WAIT_L(0); PG8_MMA(0, 0, At, B0); PG8_BAR; PG8_SCHED;
;             PG8_LDB(B1, 1, 1); PG8_STAGE(PG8_SB(1, 0), b3, voffB);
;             PG8_BAR; PG8_WAIT_L(0); PG8_MMA(0, 1, At, B1); PG8_BAR;
;             PG8_LDA(At, 1, 1); PG8_STAGE(PG8_SA(1, 0), a3, voffA);
	s_mov_b32 m0, s29
	v_lshl_add_u64 v[234:235], s[24:25], 0, v[128:129]
	global_load_lds_dwordx4 v[234:235], off
	v_lshl_add_u64 v[236:237], s[24:25], 0, v[148:149]
	s_mov_b32 m0, s17
	s_nop 0
	global_load_lds_dwordx4 v[236:237], off
	s_waitcnt vmcnt(6)
	s_barrier
	v_mfma_f32_16x16x32_bf16 v[44:47], v[212:215], v[170:173], v[44:47]
	v_mfma_f32_16x16x32_bf16 v[40:43], v[220:223], v[170:173], v[40:43]
	v_mfma_f32_16x16x32_bf16 v[28:31], v[212:215], v[178:181], v[28:31]
	v_mfma_f32_16x16x32_bf16 v[24:27], v[220:223], v[178:181], v[24:27]
	v_mfma_f32_16x16x32_bf16 v[12:15], v[212:215], v[196:199], v[12:15]
	v_mfma_f32_16x16x32_bf16 v[8:11], v[220:223], v[196:199], v[8:11]
	v_mfma_f32_16x16x32_bf16 v[4:7], v[212:215], v[204:207], v[4:7]
	v_mfma_f32_16x16x32_bf16 v[0:3], v[220:223], v[204:207], v[0:3]
	v_mfma_f32_16x16x32_bf16 v[44:47], v[216:219], v[174:177], v[44:47]
	v_mfma_f32_16x16x32_bf16 v[40:43], v[224:227], v[174:177], v[40:43]
	v_mfma_f32_16x16x32_bf16 v[28:31], v[216:219], v[192:195], v[28:31]
	v_mfma_f32_16x16x32_bf16 v[24:27], v[224:227], v[192:195], v[24:27]
	v_mfma_f32_16x16x32_bf16 v[12:15], v[216:219], v[200:203], v[12:15]
	v_mfma_f32_16x16x32_bf16 v[8:11], v[224:227], v[200:203], v[8:11]
	v_mfma_f32_16x16x32_bf16 v[4:7], v[216:219], v[208:211], v[4:7]
	v_mfma_f32_16x16x32_bf16 v[0:3], v[224:227], v[208:211], v[0:3]
	v_add_u32_e32 v153, s16, v151
	s_barrier
	ds_read_b128 v[154:157], v153
	ds_read_b128 v[158:161], v153 offset:1024
	ds_read_b128 v[162:165], v153 offset:2048
	ds_read_b128 v[166:169], v153 offset:3072
	s_mov_b32 m0, s47
	v_lshl_add_u64 v[212:213], s[22:23], 0, v[128:129]
	ds_read_b128 v[170:173], v152 offset:32768
	ds_read_b128 v[174:177], v152 offset:33792
	ds_read_b128 v[178:181], v152 offset:34816
	ds_read_b128 v[192:195], v152 offset:35840
	ds_read_b128 v[196:199], v152 offset:36864
	ds_read_b128 v[200:203], v152 offset:37888
	ds_read_b128 v[204:207], v152 offset:38912
	ds_read_b128 v[208:211], v152 offset:39936
	global_load_lds_dwordx4 v[212:213], off
	v_lshl_add_u64 v[212:213], s[22:23], 0, v[148:149]
	s_mov_b32 m0, s48
	s_nop 0
	global_load_lds_dwordx4 v[212:213], off
	s_waitcnt lgkmcnt(8)
	s_barrier
	s_waitcnt lgkmcnt(0)
	s_waitcnt lgkmcnt(0)
	v_mfma_f32_16x16x32_bf16 v[124:127], v[154:157], v[170:173], v[124:127]
	v_mfma_f32_16x16x32_bf16 v[120:123], v[162:165], v[170:173], v[120:123]
	v_mfma_f32_16x16x32_bf16 v[116:119], v[154:157], v[178:181], v[116:119]
	v_mfma_f32_16x16x32_bf16 v[112:115], v[162:165], v[178:181], v[112:115]
	v_mfma_f32_16x16x32_bf16 v[104:107], v[154:157], v[196:199], v[104:107]
	v_mfma_f32_16x16x32_bf16 v[96:99], v[162:165], v[196:199], v[96:99]
	v_mfma_f32_16x16x32_bf16 v[88:91], v[154:157], v[204:207], v[88:91]
	v_mfma_f32_16x16x32_bf16 v[80:83], v[162:165], v[204:207], v[80:83]
	v_mfma_f32_16x16x32_bf16 v[124:127], v[158:161], v[174:177], v[124:127]
	v_mfma_f32_16x16x32_bf16 v[120:123], v[166:169], v[174:177], v[120:123]
	v_mfma_f32_16x16x32_bf16 v[116:119], v[158:161], v[192:195], v[116:119]
	v_mfma_f32_16x16x32_bf16 v[112:115], v[166:169], v[192:195], v[112:115]
	v_mfma_f32_16x16x32_bf16 v[104:107], v[158:161], v[200:203], v[104:107]
	v_mfma_f32_16x16x32_bf16 v[96:99], v[166:169], v[200:203], v[96:99]
	v_mfma_f32_16x16x32_bf16 v[88:91], v[158:161], v[208:211], v[88:91]
	v_mfma_f32_16x16x32_bf16 v[80:83], v[166:169], v[208:211], v[80:83]
	s_barrier
	s_mov_b32 m0, s15
	v_add_u32_e32 v153, s14, v151
	v_lshl_add_u64 v[182:183], v[182:183], 0, s[18:19]
	ds_read_b128 v[212:215], v153
	ds_read_b128 v[216:219], v153 offset:1024
	ds_read_b128 v[220:223], v153 offset:2048
	ds_read_b128 v[224:227], v153 offset:3072
	global_load_lds_dwordx4 v[182:183], off
	v_lshl_add_u64 v[182:183], v[228:229], 0, s[18:19]
	s_mov_b32 m0, s63
	s_nop 0
	global_load_lds_dwordx4 v[182:183], off
	s_barrier
	s_waitcnt lgkmcnt(0)
	s_waitcnt lgkmcnt(0)
	v_mfma_f32_16x16x32_bf16 v[108:111], v[212:215], v[170:173], v[108:111]
	v_mfma_f32_16x16x32_bf16 v[100:103], v[220:223], v[170:173], v[100:103]
	v_mfma_f32_16x16x32_bf16 v[92:95], v[212:215], v[178:181], v[92:95]
	v_mfma_f32_16x16x32_bf16 v[84:87], v[220:223], v[178:181], v[84:87]
	v_mfma_f32_16x16x32_bf16 v[76:79], v[212:215], v[196:199], v[76:79]
	v_mfma_f32_16x16x32_bf16 v[72:75], v[220:223], v[196:199], v[72:75]
	v_mfma_f32_16x16x32_bf16 v[68:71], v[212:215], v[204:207], v[68:71]
	v_mfma_f32_16x16x32_bf16 v[64:67], v[220:223], v[204:207], v[64:67]
	v_mfma_f32_16x16x32_bf16 v[108:111], v[216:219], v[174:177], v[108:111]
	v_mfma_f32_16x16x32_bf16 v[100:103], v[224:227], v[174:177], v[100:103]
	v_mfma_f32_16x16x32_bf16 v[92:95], v[216:219], v[192:195], v[92:95]
	v_mfma_f32_16x16x32_bf16 v[84:87], v[224:227], v[192:195], v[84:87]
	v_mfma_f32_16x16x32_bf16 v[76:79], v[216:219], v[200:203], v[76:79]
	v_mfma_f32_16x16x32_bf16 v[72:75], v[224:227], v[200:203], v[72:75]
	v_mfma_f32_16x16x32_bf16 v[68:71], v[216:219], v[208:211], v[68:71]
	v_mfma_f32_16x16x32_bf16 v[64:67], v[224:227], v[208:211], v[64:67]
	s_mov_b32 m0, s56
	v_lshl_add_u64 v[182:183], v[230:231], 0, s[18:19]
	s_barrier
	ds_read_b128 v[170:173], v152 offset:49152
	ds_read_b128 v[174:177], v152 offset:50176
	ds_read_b128 v[178:181], v152 offset:51200
	ds_read_b128 v[192:195], v152 offset:52224
	ds_read_b128 v[196:199], v152 offset:53248
	ds_read_b128 v[200:203], v152 offset:54272
	ds_read_b128 v[204:207], v152 offset:55296
	ds_read_b128 v[208:211], v152 offset:56320
	global_load_lds_dwordx4 v[182:183], off
	v_lshl_add_u64 v[182:183], v[232:233], 0, s[18:19]
	s_mov_b32 m0, s57
	s_nop 0
	global_load_lds_dwordx4 v[182:183], off
	s_barrier
; #define PG8_STAGE(bufoff, gbase, voff) do { _Pragma("unroll") for (int _i = 0; _i < 2; ++_i) \
;         __builtin_amdgcn_global_load_lds((const unsigned*)((const char*)(gbase) + (voff)[_i]), (PG8_LAS unsigned*)(lds + (bufoff) + ldsw + _i * 8192), 16, 0, 0); } while (0)
; #define PG8_MMA(ai, bj, At, Bt) do { __builtin_amdgcn_s_setprio(1); _Pragma("unroll") for (int m = 0; m < 4; ++m) _Pragma("unroll") for (int n = 0; n < 2; ++n) _Pragma("unroll") for (int k = 0; k < 2; ++k) \
;         acc[ai][bj][m][n] = __builtin_amdgcn_mfma_f32_16x16x32_bf16(Bt[n][k], At[m][k], acc[ai][bj][m][n], 0, 0, 0); __builtin_amdgcn_s_setprio(0); } while (0)
; #define PG8_WAIT_V(n) asm volatile("s_waitcnt vmcnt(" #n ")" ::: "memory")
; #define PG8_WAIT_L(n) asm volatile("s_waitcnt lgkmcnt(" #n ")" ::: "memory")
; #define PG8_BAR __builtin_amdgcn_s_barrier()
; #define PG8_SCHED __builtin_amdgcn_sched_barrier(0)
; template <class Epi, class Sched, bool STAMP = false>
; __device__ __forceinline__ void gemm_phase(PG8_LAS unsigned char* lds, const Gemm g, const Sched& S, const Epi& E, unsigned long long* stamps) {
;     ...
;             PG8_BAR; PG8_WAIT_L(0); PG8_MMA(1, 0, At, B0); PG8_BAR; PG8_SCHED;
;             PG8_STAGE(PG8_SB(1, 1), b3 + hstep, voffB);
;             PG8_WAIT_V(6); PG8_BAR; PG8_MMA(1, 1, At, B1); PG8_BAR;
;     __device__ __forceinline__ void operator()(const f32x4 (&acc)[2][2][4][2], const pg8::Unit& u, int wr, int wc, int fr, int fq) const {
;         const int row0 = (u.pm - 64) * 256 + wr * 64 + fr, col0 = u.pn * 256 + wc * 32 + 4 * fq;
; #pragma unroll
;         for (int ai = 0; ai < 2; ++ai)
; #pragma unroll
;             for (int m = 0; m < 4; ++m) { float* xp = PART + (size_t)(row0 + ai * 128 + m * 16) * ldp + col0;
; #pragma unroll
;                 for (int bj = 0; bj < 2; ++bj)
; #pragma unroll
;                     for (int n = 0; n < 2; ++n) *(f32x4*)(xp + bj * 128 + n * 16) = acc[ai][bj][m][n]; }
	s_waitcnt lgkmcnt(0)
	s_waitcnt lgkmcnt(0)
	v_mfma_f32_16x16x32_bf16 v[60:63], v[154:157], v[170:173], v[60:63]
	v_mfma_f32_16x16x32_bf16 v[56:59], v[162:165], v[170:173], v[56:59]
	v_mfma_f32_16x16x32_bf16 v[52:55], v[154:157], v[178:181], v[52:55]
	v_mfma_f32_16x16x32_bf16 v[48:51], v[162:165], v[178:181], v[48:51]
	v_mfma_f32_16x16x32_bf16 v[36:39], v[154:157], v[196:199], v[36:39]
	v_mfma_f32_16x16x32_bf16 v[32:35], v[162:165], v[196:199], v[32:35]
	v_mfma_f32_16x16x32_bf16 v[20:23], v[154:157], v[204:207], v[20:23]
	v_mfma_f32_16x16x32_bf16 v[16:19], v[162:165], v[204:207], v[16:19]
	v_mfma_f32_16x16x32_bf16 v[60:63], v[158:161], v[174:177], v[60:63]
	v_mfma_f32_16x16x32_bf16 v[56:59], v[166:169], v[174:177], v[56:59]
	v_mfma_f32_16x16x32_bf16 v[52:55], v[158:161], v[192:195], v[52:55]
	v_mfma_f32_16x16x32_bf16 v[48:51], v[166:169], v[192:195], v[48:51]
	v_mfma_f32_16x16x32_bf16 v[36:39], v[158:161], v[200:203], v[36:39]
	v_mfma_f32_16x16x32_bf16 v[32:35], v[166:169], v[200:203], v[32:35]
	v_mfma_f32_16x16x32_bf16 v[20:23], v[158:161], v[208:211], v[20:23]
	v_mfma_f32_16x16x32_bf16 v[16:19], v[166:169], v[208:211], v[16:19]
	s_barrier
	s_mov_b32 m0, s58
	v_lshl_add_u64 v[154:155], v[234:235], 0, s[18:19]
	global_load_lds_dwordx4 v[154:155], off
	v_lshl_add_u64 v[154:155], v[236:237], 0, s[18:19]
	s_mov_b32 m0, s52
	s_nop 0
	global_load_lds_dwordx4 v[154:155], off
	s_waitcnt vmcnt(6)
	s_barrier
	v_mfma_f32_16x16x32_bf16 v[44:47], v[212:215], v[170:173], v[44:47]
	v_mfma_f32_16x16x32_bf16 v[40:43], v[220:223], v[170:173], v[40:43]
	v_mfma_f32_16x16x32_bf16 v[28:31], v[212:215], v[178:181], v[28:31]
	v_mfma_f32_16x16x32_bf16 v[24:27], v[220:223], v[178:181], v[24:27]
	v_mfma_f32_16x16x32_bf16 v[12:15], v[212:215], v[196:199], v[12:15]
	v_mfma_f32_16x16x32_bf16 v[8:11], v[220:223], v[196:199], v[8:11]
	v_mfma_f32_16x16x32_bf16 v[4:7], v[212:215], v[204:207], v[4:7]
	v_mfma_f32_16x16x32_bf16 v[0:3], v[220:223], v[204:207], v[0:3]
	v_mfma_f32_16x16x32_bf16 v[44:47], v[216:219], v[174:177], v[44:47]
	v_mfma_f32_16x16x32_bf16 v[40:43], v[224:227], v[174:177], v[40:43]
	v_mfma_f32_16x16x32_bf16 v[28:31], v[216:219], v[192:195], v[28:31]
	v_mfma_f32_16x16x32_bf16 v[24:27], v[224:227], v[192:195], v[24:27]
	v_mfma_f32_16x16x32_bf16 v[12:15], v[216:219], v[200:203], v[12:15]
	v_mfma_f32_16x16x32_bf16 v[8:11], v[224:227], v[200:203], v[8:11]
	v_mfma_f32_16x16x32_bf16 v[4:7], v[216:219], v[208:211], v[4:7]
	v_mfma_f32_16x16x32_bf16 v[0:3], v[224:227], v[208:211], v[0:3]
	s_andn2_b64 vcc, exec, s[20:21]
	s_mov_b64 s[22:23], -1
	s_mov_b64 s[20:21], 0
	s_movk_i32 s14, 0x100
	s_barrier
	s_cbranch_vccz .LBB0_374
	s_lshl_b64 s[4:5], s[10:11], 22
	s_add_u32 s4, s2, s4
	s_addc_u32 s5, s3, s5
	s_lshl_b32 s6, s44, 8
	s_addk_i32 s6, 0xc000
	v_or_b32_e32 v128, s6, v150
	v_add_u32_e32 v148, s49, v128
	s_lshl_b32 s6, s39, 8
	v_lshl_or_b32 v128, v139, 2, s6
	v_ashrrev_i32_e32 v149, 31, v148
	v_or_b32_e32 v128, s53, v128
	v_lshlrev_b64 v[150:151], 12, v[148:149]
	v_lshl_add_u64 v[150:151], s[4:5], 0, v[150:151]
	v_lshlrev_b32_e32 v128, 2, v128
	v_lshl_add_u64 v[150:151], v[150:151], 0, v[128:129]
	global_store_dwordx4 v[150:151], v[124:127], off
	global_store_dwordx4 v[150:151], v[120:123], off offset:64
	global_store_dwordx4 v[150:151], v[108:111], off offset:512
	global_store_dwordx4 v[150:151], v[100:103], off offset:576
	s_cmpk_lt_u32 s38, 0x100
	s_nop 0
	v_or_b32_e32 v100, 16, v148
	v_ashrrev_i32_e32 v101, 31, v100
	v_lshlrev_b64 v[100:101], 12, v[100:101]
	v_lshl_add_u64 v[100:101], s[4:5], 0, v[100:101]
	v_lshl_add_u64 v[100:101], v[100:101], 0, v[128:129]
	global_store_dwordx4 v[100:101], v[116:119], off
	global_store_dwordx4 v[100:101], v[112:115], off offset:64
	global_store_dwordx4 v[100:101], v[92:95], off offset:512
	global_store_dwordx4 v[100:101], v[84:87], off offset:576
	s_nop 1
	v_or_b32_e32 v84, 32, v148
	v_ashrrev_i32_e32 v85, 31, v84
	v_lshlrev_b64 v[84:85], 12, v[84:85]
	v_lshl_add_u64 v[84:85], s[4:5], 0, v[84:85]
	v_lshl_add_u64 v[84:85], v[84:85], 0, v[128:129]
	global_store_dwordx4 v[84:85], v[104:107], off
	global_store_dwordx4 v[84:85], v[96:99], off offset:64
	global_store_dwordx4 v[84:85], v[76:79], off offset:512
	global_store_dwordx4 v[84:85], v[72:75], off offset:576
	s_nop 1
	v_or_b32_e32 v72, 48, v148
	v_ashrrev_i32_e32 v73, 31, v72
	v_lshlrev_b64 v[72:73], 12, v[72:73]
	v_lshl_add_u64 v[72:73], s[4:5], 0, v[72:73]
	v_lshl_add_u64 v[72:73], v[72:73], 0, v[128:129]
	s_mov_b64 s[4:5], 0x80000
	global_store_dwordx4 v[72:73], v[88:91], off
	global_store_dwordx4 v[72:73], v[80:83], off offset:64
	global_store_dwordx4 v[72:73], v[68:71], off offset:512
	global_store_dwordx4 v[72:73], v[64:67], off offset:576
	s_nop 1
	v_lshl_add_u64 v[64:65], v[150:151], 0, s[4:5]
	s_mov_b32 s4, 0x80000
	v_add_co_u32_e32 v66, vcc, s4, v150
	s_mov_b64 s[4:5], 0x90000
	s_nop 0
	v_addc_co_u32_e32 v67, vcc, 0, v151, vcc
	global_store_dwordx4 v[66:67], v[60:63], off
	global_store_dwordx4 v[64:65], v[56:59], off offset:64
	global_store_dwordx4 v[64:65], v[44:47], off offset:512
	global_store_dwordx4 v[64:65], v[40:43], off offset:576
	s_nop 1
	v_lshl_add_u64 v[40:41], v[150:151], 0, s[4:5]
	s_mov_b32 s4, 0x90000
	v_add_co_u32_e32 v42, vcc, s4, v150
	s_mov_b64 s[4:5], 0xa0000
	s_nop 0
	v_addc_co_u32_e32 v43, vcc, 0, v151, vcc
	global_store_dwordx4 v[42:43], v[52:55], off
	global_store_dwordx4 v[40:41], v[48:51], off offset:64
	global_store_dwordx4 v[40:41], v[28:31], off offset:512
	global_store_dwordx4 v[40:41], v[24:27], off offset:576
	s_nop 1
	v_lshl_add_u64 v[24:25], v[150:151], 0, s[4:5]
	s_mov_b32 s4, 0xa0000
	v_add_co_u32_e32 v26, vcc, s4, v150
	s_mov_b64 s[4:5], 0xb0000
	s_nop 0
	v_addc_co_u32_e32 v27, vcc, 0, v151, vcc
	global_store_dwordx4 v[26:27], v[36:39], off
	global_store_dwordx4 v[24:25], v[32:35], off offset:64
	global_store_dwordx4 v[24:25], v[12:15], off offset:512
	global_store_dwordx4 v[24:25], v[8:11], off offset:576
	s_nop 1
	v_add_co_u32_e32 v10, vcc, 0xb0000, v150
	v_lshl_add_u64 v[8:9], v[150:151], 0, s[4:5]
	s_nop 0
	v_addc_co_u32_e32 v11, vcc, 0, v151, vcc
	global_store_dwordx4 v[10:11], v[20:23], off
	global_store_dwordx4 v[8:9], v[16:19], off offset:64
	global_store_dwordx4 v[8:9], v[4:7], off offset:512
	global_store_dwordx4 v[8:9], v[0:3], off offset:576
	s_waitcnt vmcnt(0)
	s_cbranch_scc0 .LBB0_377
	s_barrier

; #define PG8_STAGE(bufoff, gbase, voff) do { _Pragma("unroll") for (int _i = 0; _i < 2; ++_i) \
;         __builtin_amdgcn_global_load_lds((const unsigned*)((const char*)(gbase) + (voff)[_i]), (PG8_LAS unsigned*)(lds + (bufoff) + ldsw + _i * 8192), 16, 0, 0); } while (0)
; #define PG8_LDA(dst, b, h) do { _Pragma("unroll") for (int m = 0; m < 4; ++m) _Pragma("unroll") for (int k = 0; k < 2; ++k) dst[m][k] = *(const PG8_LAS bf16x8*)(lds + PG8_SA(b, h) + aoff + m * 2048 + k * 1024); } while (0)
; #define PG8_LDB(dst, b, h) do { _Pragma("unroll") for (int n = 0; n < 2; ++n) _Pragma("unroll") for (int k = 0; k < 2; ++k) dst[n][k] = *(const PG8_LAS bf16x8*)(lds + PG8_SB(b, h) + boff + n * 2048 + k * 1024); } while (0)
; #define PG8_MMA(ai, bj, At, Bt) do { __builtin_amdgcn_s_setprio(1); _Pragma("unroll") for (int m = 0; m < 4; ++m) _Pragma("unroll") for (int n = 0; n < 2; ++n) _Pragma("unroll") for (int k = 0; k < 2; ++k) \
;         acc[ai][bj][m][n] = __builtin_amdgcn_mfma_f32_16x16x32_bf16(Bt[n][k], At[m][k], acc[ai][bj][m][n], 0, 0, 0); __builtin_amdgcn_s_setprio(0); } while (0)
; #define PG8_WAIT_L(n) asm volatile("s_waitcnt lgkmcnt(" #n ")" ::: "memory")
; #define PG8_BAR __builtin_amdgcn_s_barrier()
; #define PG8_SCHED __builtin_amdgcn_sched_barrier(0)
; template <class Epi, class Sched, bool STAMP = false>
; __device__ __forceinline__ void gemm_phase(PG8_LAS unsigned char* lds, const Gemm g, const Sched& S, const Epi& E, unsigned long long* stamps) {
;     ...
;             const bool last = (t == nt - 2);
;             const char* a1 = cA + (size_t)(t + 1) * kstep;
;             const char* a2 = last ? nA : cA + (size_t)(t + 2) * kstep; const char* b2 = last ? nB : cB + (size_t)(t + 2) * kstep;
;             const char* a3 = a2 + kstep; const char* b3 = b2 + kstep;
;             if (last && has_next) S.a_ready(nxt);
;             PG8_LDB(B0, 0, 0); PG8_SCHED; PG8_LDA(At, 0, 0); PG8_STAGE(PG8_SA(1, 1), a1 + hstep, voffA);
;             PG8_WAIT_L(8); PG8_BAR; PG8_WAIT_L(0); PG8_MMA(0, 0, At, B0); PG8_BAR; PG8_SCHED;
;             PG8_LDB(B1, 0, 1); PG8_STAGE(PG8_SB(0, 0), b2, voffB);
;             PG8_BAR; PG8_WAIT_L(0); PG8_MMA(0, 1, At, B1); PG8_BAR;
;             PG8_LDA(At, 0, 1); PG8_STAGE(PG8_SA(0, 0), a2, voffA);
;             PG8_BAR; PG8_WAIT_L(0); PG8_MMA(1, 0, At, B0); PG8_BAR; PG8_SCHED;
.LBB0_495:
	s_add_u32 s14, s24, 0xfffc0080
	s_addc_u32 s15, s25, -1
	s_add_i32 s16, 0, 0x10000
	v_add_u32_e32 v169, s16, v166
	ds_read_b128 v[158:161], v169
	ds_read_b128 v[162:165], v169 offset:1024
	ds_read_b128 v[170:173], v169 offset:2048
	ds_read_b128 v[174:177], v169 offset:3072
	s_cmp_eq_u32 s61, 12
	s_cselect_b32 s31, s7, s15
	s_cselect_b32 s30, s57, s14
	s_cselect_b32 s27, s5, s60
	s_cselect_b32 s26, s58, s59
	v_lshl_add_u64 v[182:183], s[24:25], 0, v[154:155]
	s_add_i32 m0, s23, 0xc000
	ds_read_b128 v[178:181], v168
	ds_read_b128 v[192:195], v168 offset:1024
	ds_read_b128 v[196:199], v168 offset:2048
	ds_read_b128 v[200:203], v168 offset:3072
	ds_read_b128 v[204:207], v168 offset:4096
	ds_read_b128 v[208:211], v168 offset:5120
	ds_read_b128 v[212:215], v168 offset:6144
	ds_read_b128 v[216:219], v168 offset:7168
	global_load_lds_dwordx4 v[182:183], off
	v_lshl_add_u64 v[182:183], s[24:25], 0, v[156:157]
	s_add_i32 m0, s23, 0xe000
	s_nop 0
	global_load_lds_dwordx4 v[182:183], off
	s_waitcnt lgkmcnt(8)
	s_barrier
	s_waitcnt lgkmcnt(0)
	s_waitcnt lgkmcnt(0)
	v_mfma_f32_16x16x32_bf16 v[124:127], v[158:161], v[178:181], v[124:127]
	v_mfma_f32_16x16x32_bf16 v[120:123], v[170:173], v[178:181], v[120:123]
	v_mfma_f32_16x16x32_bf16 v[108:111], v[158:161], v[196:199], v[108:111]
	v_mfma_f32_16x16x32_bf16 v[104:107], v[170:173], v[196:199], v[104:107]
	v_mfma_f32_16x16x32_bf16 v[92:95], v[158:161], v[204:207], v[92:95]
	v_mfma_f32_16x16x32_bf16 v[88:91], v[170:173], v[204:207], v[88:91]
	v_mfma_f32_16x16x32_bf16 v[76:79], v[158:161], v[212:215], v[76:79]
	v_mfma_f32_16x16x32_bf16 v[72:75], v[170:173], v[212:215], v[72:75]
	v_mfma_f32_16x16x32_bf16 v[124:127], v[162:165], v[192:195], v[124:127]
	v_mfma_f32_16x16x32_bf16 v[120:123], v[174:177], v[192:195], v[120:123]
	v_mfma_f32_16x16x32_bf16 v[108:111], v[162:165], v[200:203], v[108:111]
	v_mfma_f32_16x16x32_bf16 v[104:107], v[174:177], v[200:203], v[104:107]
	v_mfma_f32_16x16x32_bf16 v[92:95], v[162:165], v[208:211], v[92:95]
	v_mfma_f32_16x16x32_bf16 v[88:91], v[174:177], v[208:211], v[88:91]
	v_mfma_f32_16x16x32_bf16 v[76:79], v[162:165], v[216:219], v[76:79]
	v_mfma_f32_16x16x32_bf16 v[72:75], v[174:177], v[216:219], v[72:75]
	s_barrier
	s_add_i32 s17, 0, 0x14000
	s_add_i32 s14, s16, s43
	v_add_u32_e32 v169, s17, v166
	v_lshl_add_u64 v[182:183], s[26:27], 0, v[128:129]
	s_mov_b32 m0, s14
	ds_read_b128 v[220:223], v169
	ds_read_b128 v[224:227], v169 offset:1024
	ds_read_b128 v[228:231], v169 offset:2048
	ds_read_b128 v[232:235], v169 offset:3072
	global_load_lds_dwordx4 v[182:183], off
	v_lshl_add_u64 v[236:237], s[26:27], 0, v[148:149]
	s_add_i32 m0, s14, 0x2000
	s_nop 0
	global_load_lds_dwordx4 v[236:237], off
	s_barrier
	s_waitcnt lgkmcnt(0)
	s_waitcnt lgkmcnt(0)
	v_mfma_f32_16x16x32_bf16 v[116:119], v[220:223], v[178:181], v[116:119]
	v_mfma_f32_16x16x32_bf16 v[112:115], v[228:231], v[178:181], v[112:115]
	v_mfma_f32_16x16x32_bf16 v[100:103], v[220:223], v[196:199], v[100:103]
	v_mfma_f32_16x16x32_bf16 v[96:99], v[228:231], v[196:199], v[96:99]
	v_mfma_f32_16x16x32_bf16 v[84:87], v[220:223], v[204:207], v[84:87]
	v_mfma_f32_16x16x32_bf16 v[80:83], v[228:231], v[204:207], v[80:83]
	v_mfma_f32_16x16x32_bf16 v[68:71], v[220:223], v[212:215], v[68:71]
	v_mfma_f32_16x16x32_bf16 v[64:67], v[228:231], v[212:215], v[64:67]
	v_mfma_f32_16x16x32_bf16 v[116:119], v[224:227], v[192:195], v[116:119]
	v_mfma_f32_16x16x32_bf16 v[112:115], v[232:235], v[192:195], v[112:115]
	v_mfma_f32_16x16x32_bf16 v[100:103], v[224:227], v[200:203], v[100:103]
	v_mfma_f32_16x16x32_bf16 v[96:99], v[232:235], v[200:203], v[96:99]
	v_mfma_f32_16x16x32_bf16 v[84:87], v[224:227], v[208:211], v[84:87]
	v_mfma_f32_16x16x32_bf16 v[80:83], v[232:235], v[208:211], v[80:83]
	v_mfma_f32_16x16x32_bf16 v[68:71], v[224:227], v[216:219], v[68:71]
	v_mfma_f32_16x16x32_bf16 v[64:67], v[232:235], v[216:219], v[64:67]
	s_mov_b32 m0, s23
	v_lshl_add_u64 v[238:239], s[30:31], 0, v[152:153]
	s_barrier
	ds_read_b128 v[178:181], v168 offset:16384
	ds_read_b128 v[192:195], v168 offset:17408
	ds_read_b128 v[196:199], v168 offset:18432
	ds_read_b128 v[200:203], v168 offset:19456
	ds_read_b128 v[204:207], v168 offset:20480
	ds_read_b128 v[208:211], v168 offset:21504
	ds_read_b128 v[212:215], v168 offset:22528
	ds_read_b128 v[216:219], v168 offset:23552
	global_load_lds_dwordx4 v[238:239], off
	v_lshl_add_u64 v[240:241], s[30:31], 0, v[150:151]
	s_mov_b32 m0, s45
	s_nop 0
	global_load_lds_dwordx4 v[240:241], off
	s_barrier
	s_waitcnt lgkmcnt(0)
	s_waitcnt lgkmcnt(0)
	v_mfma_f32_16x16x32_bf16 v[60:63], v[158:161], v[178:181], v[60:63]
	v_mfma_f32_16x16x32_bf16 v[56:59], v[170:173], v[178:181], v[56:59]
	v_mfma_f32_16x16x32_bf16 v[44:47], v[158:161], v[196:199], v[44:47]
	v_mfma_f32_16x16x32_bf16 v[40:43], v[170:173], v[196:199], v[40:43]
	v_mfma_f32_16x16x32_bf16 v[28:31], v[158:161], v[204:207], v[28:31]
	v_mfma_f32_16x16x32_bf16 v[24:27], v[170:173], v[204:207], v[24:27]
	v_mfma_f32_16x16x32_bf16 v[12:15], v[158:161], v[212:215], v[12:15]
	v_mfma_f32_16x16x32_bf16 v[8:11], v[170:173], v[212:215], v[8:11]
	v_mfma_f32_16x16x32_bf16 v[60:63], v[162:165], v[192:195], v[60:63]
	v_mfma_f32_16x16x32_bf16 v[56:59], v[174:177], v[192:195], v[56:59]
	v_mfma_f32_16x16x32_bf16 v[44:47], v[162:165], v[200:203], v[44:47]
	v_mfma_f32_16x16x32_bf16 v[40:43], v[174:177], v[200:203], v[40:43]
	v_mfma_f32_16x16x32_bf16 v[28:31], v[162:165], v[208:211], v[28:31]
	v_mfma_f32_16x16x32_bf16 v[24:27], v[174:177], v[208:211], v[24:27]
	v_mfma_f32_16x16x32_bf16 v[12:15], v[162:165], v[216:219], v[12:15]
	v_mfma_f32_16x16x32_bf16 v[8:11], v[174:177], v[216:219], v[8:11]
	s_barrier
; #define PG8_STAGE(bufoff, gbase, voff) do { _Pragma("unroll") for (int _i = 0; _i < 2; ++_i) \
;         __builtin_amdgcn_global_load_lds((const unsigned*)((const char*)(gbase) + (voff)[_i]), (PG8_LAS unsigned*)(lds + (bufoff) + ldsw + _i * 8192), 16, 0, 0); } while (0)
; #define PG8_LDA(dst, b, h) do { _Pragma("unroll") for (int m = 0; m < 4; ++m) _Pragma("unroll") for (int k = 0; k < 2; ++k) dst[m][k] = *(const PG8_LAS bf16x8*)(lds + PG8_SA(b, h) + aoff + m * 2048 + k * 1024); } while (0)
; #define PG8_LDB(dst, b, h) do { _Pragma("unroll") for (int n = 0; n < 2; ++n) _Pragma("unroll") for (int k = 0; k < 2; ++k) dst[n][k] = *(const PG8_LAS bf16x8*)(lds + PG8_SB(b, h) + boff + n * 2048 + k * 1024); } while (0)
; #define PG8_MMA(ai, bj, At, Bt) do { __builtin_amdgcn_s_setprio(1); _Pragma("unroll") for (int m = 0; m < 4; ++m) _Pragma("unroll") for (int n = 0; n < 2; ++n) _Pragma("unroll") for (int k = 0; k < 2; ++k) \
;         acc[ai][bj][m][n] = __builtin_amdgcn_mfma_f32_16x16x32_bf16(Bt[n][k], At[m][k], acc[ai][bj][m][n], 0, 0, 0); __builtin_amdgcn_s_setprio(0); } while (0)
; #define PG8_WAIT_V(n) asm volatile("s_waitcnt vmcnt(" #n ")" ::: "memory")
; #define PG8_WAIT_L(n) asm volatile("s_waitcnt lgkmcnt(" #n ")" ::: "memory")
; #define PG8_BAR __builtin_amdgcn_s_barrier()
; #define PG8_SCHED __builtin_amdgcn_sched_barrier(0)
; template <class Epi, class Sched, bool STAMP = false>
; __device__ __forceinline__ void gemm_phase(PG8_LAS unsigned char* lds, const Gemm g, const Sched& S, const Epi& E, unsigned long long* stamps) {
;     ...
;             PG8_STAGE(PG8_SB(0, 1), b2 + hstep, voffB);
;             PG8_WAIT_V(6); PG8_BAR; PG8_MMA(1, 1, At, B1); PG8_BAR;
;             PG8_LDB(B0, 1, 0); PG8_SCHED; PG8_LDA(At, 1, 0); PG8_STAGE(PG8_SA(0, 1), a2 + hstep, voffA);
;             PG8_WAIT_L(8); PG8_BAR; PG8_WAIT_L(0); PG8_MMA(0, 0, At, B0); PG8_BAR; PG8_SCHED;
;             PG8_LDB(B1, 1, 1); PG8_STAGE(PG8_SB(1, 0), b3, voffB);
;             PG8_BAR; PG8_WAIT_L(0); PG8_MMA(0, 1, At, B1); PG8_BAR;
;             PG8_LDA(At, 1, 1); PG8_STAGE(PG8_SA(1, 0), a3, voffA);
	s_add_u32 s14, s26, 0x40000
	s_addc_u32 s15, s27, 0
	s_add_i32 s16, s17, s43
	v_lshl_add_u64 v[158:159], s[14:15], 0, v[128:129]
	s_mov_b32 m0, s16
	s_nop 0
	global_load_lds_dwordx4 v[158:159], off
	v_lshl_add_u64 v[158:159], s[14:15], 0, v[148:149]
	s_add_i32 m0, s16, 0x2000
	s_nop 0
	global_load_lds_dwordx4 v[158:159], off
	s_waitcnt vmcnt(6)
	s_barrier
	v_mfma_f32_16x16x32_bf16 v[52:55], v[220:223], v[178:181], v[52:55]
	v_mfma_f32_16x16x32_bf16 v[48:51], v[228:231], v[178:181], v[48:51]
	v_mfma_f32_16x16x32_bf16 v[36:39], v[220:223], v[196:199], v[36:39]
	v_mfma_f32_16x16x32_bf16 v[32:35], v[228:231], v[196:199], v[32:35]
	v_mfma_f32_16x16x32_bf16 v[20:23], v[220:223], v[204:207], v[20:23]
	v_mfma_f32_16x16x32_bf16 v[16:19], v[228:231], v[204:207], v[16:19]
	v_mfma_f32_16x16x32_bf16 v[4:7], v[220:223], v[212:215], v[4:7]
	v_mfma_f32_16x16x32_bf16 v[0:3], v[228:231], v[212:215], v[0:3]
	v_mfma_f32_16x16x32_bf16 v[52:55], v[224:227], v[192:195], v[52:55]
	v_mfma_f32_16x16x32_bf16 v[48:51], v[232:235], v[192:195], v[48:51]
	v_mfma_f32_16x16x32_bf16 v[36:39], v[224:227], v[200:203], v[36:39]
	v_mfma_f32_16x16x32_bf16 v[32:35], v[232:235], v[200:203], v[32:35]
	v_mfma_f32_16x16x32_bf16 v[20:23], v[224:227], v[208:211], v[20:23]
	v_mfma_f32_16x16x32_bf16 v[16:19], v[232:235], v[208:211], v[16:19]
	v_mfma_f32_16x16x32_bf16 v[4:7], v[224:227], v[216:219], v[4:7]
	v_mfma_f32_16x16x32_bf16 v[0:3], v[232:235], v[216:219], v[0:3]
	s_add_i32 s16, 0, 0x18000
	v_add_u32_e32 v169, s16, v166
	s_barrier
	ds_read_b128 v[158:161], v169
	ds_read_b128 v[162:165], v169 offset:1024
	ds_read_b128 v[170:173], v169 offset:2048
	ds_read_b128 v[174:177], v169 offset:3072
	s_add_u32 s14, s30, 0x40000
	s_addc_u32 s15, s31, 0
	s_mov_b32 m0, s46
	v_lshl_add_u64 v[220:221], s[14:15], 0, v[152:153]
	ds_read_b128 v[178:181], v168 offset:32768
	ds_read_b128 v[192:195], v168 offset:33792
	ds_read_b128 v[196:199], v168 offset:34816
	ds_read_b128 v[200:203], v168 offset:35840
	ds_read_b128 v[204:207], v168 offset:36864
	ds_read_b128 v[208:211], v168 offset:37888
	ds_read_b128 v[212:215], v168 offset:38912
	ds_read_b128 v[216:219], v168 offset:39936
	global_load_lds_dwordx4 v[220:221], off
	v_lshl_add_u64 v[220:221], s[14:15], 0, v[150:151]
	s_mov_b32 m0, s47
	s_nop 0
	global_load_lds_dwordx4 v[220:221], off
	s_waitcnt lgkmcnt(8)
	s_barrier
	s_waitcnt lgkmcnt(0)
	s_waitcnt lgkmcnt(0)
	v_mfma_f32_16x16x32_bf16 v[124:127], v[158:161], v[178:181], v[124:127]
	v_mfma_f32_16x16x32_bf16 v[120:123], v[170:173], v[178:181], v[120:123]
	v_mfma_f32_16x16x32_bf16 v[108:111], v[158:161], v[196:199], v[108:111]
	v_mfma_f32_16x16x32_bf16 v[104:107], v[170:173], v[196:199], v[104:107]
	v_mfma_f32_16x16x32_bf16 v[92:95], v[158:161], v[204:207], v[92:95]
	v_mfma_f32_16x16x32_bf16 v[88:91], v[170:173], v[204:207], v[88:91]
	v_mfma_f32_16x16x32_bf16 v[76:79], v[158:161], v[212:215], v[76:79]
	v_mfma_f32_16x16x32_bf16 v[72:75], v[170:173], v[212:215], v[72:75]
	v_mfma_f32_16x16x32_bf16 v[124:127], v[162:165], v[192:195], v[124:127]
	v_mfma_f32_16x16x32_bf16 v[120:123], v[174:177], v[192:195], v[120:123]
	v_mfma_f32_16x16x32_bf16 v[108:111], v[162:165], v[200:203], v[108:111]
	v_mfma_f32_16x16x32_bf16 v[104:107], v[174:177], v[200:203], v[104:107]
	v_mfma_f32_16x16x32_bf16 v[92:95], v[162:165], v[208:211], v[92:95]
	v_mfma_f32_16x16x32_bf16 v[88:91], v[174:177], v[208:211], v[88:91]
	v_mfma_f32_16x16x32_bf16 v[76:79], v[162:165], v[216:219], v[76:79]
	v_mfma_f32_16x16x32_bf16 v[72:75], v[174:177], v[216:219], v[72:75]
	s_barrier
	s_add_i32 s17, 0, 0x1c000
	s_add_i32 s14, s16, s43
	v_add_u32_e32 v169, s17, v166
	v_lshl_add_u64 v[182:183], v[182:183], 0, s[18:19]
	s_mov_b32 m0, s14
	ds_read_b128 v[220:223], v169
	ds_read_b128 v[224:227], v169 offset:1024
	ds_read_b128 v[228:231], v169 offset:2048
	ds_read_b128 v[232:235], v169 offset:3072
	global_load_lds_dwordx4 v[182:183], off
	v_lshl_add_u64 v[182:183], v[236:237], 0, s[18:19]
	s_add_i32 m0, s14, 0x2000
	s_nop 0
	global_load_lds_dwordx4 v[182:183], off
	s_barrier
	s_waitcnt lgkmcnt(0)
	s_waitcnt lgkmcnt(0)
	v_mfma_f32_16x16x32_bf16 v[116:119], v[220:223], v[178:181], v[116:119]
	v_mfma_f32_16x16x32_bf16 v[112:115], v[228:231], v[178:181], v[112:115]
	v_mfma_f32_16x16x32_bf16 v[100:103], v[220:223], v[196:199], v[100:103]
	v_mfma_f32_16x16x32_bf16 v[96:99], v[228:231], v[196:199], v[96:99]
	v_mfma_f32_16x16x32_bf16 v[84:87], v[220:223], v[204:207], v[84:87]
	v_mfma_f32_16x16x32_bf16 v[80:83], v[228:231], v[204:207], v[80:83]
	v_mfma_f32_16x16x32_bf16 v[68:71], v[220:223], v[212:215], v[68:71]
	v_mfma_f32_16x16x32_bf16 v[64:67], v[228:231], v[212:215], v[64:67]
	v_mfma_f32_16x16x32_bf16 v[116:119], v[224:227], v[192:195], v[116:119]
	v_mfma_f32_16x16x32_bf16 v[112:115], v[232:235], v[192:195], v[112:115]
	v_mfma_f32_16x16x32_bf16 v[100:103], v[224:227], v[200:203], v[100:103]
	v_mfma_f32_16x16x32_bf16 v[96:99], v[232:235], v[200:203], v[96:99]
	v_mfma_f32_16x16x32_bf16 v[84:87], v[224:227], v[208:211], v[84:87]
	v_mfma_f32_16x16x32_bf16 v[80:83], v[232:235], v[208:211], v[80:83]
	v_mfma_f32_16x16x32_bf16 v[68:71], v[224:227], v[216:219], v[68:71]
	v_mfma_f32_16x16x32_bf16 v[64:67], v[232:235], v[216:219], v[64:67]
	s_mov_b32 m0, s49
	v_lshl_add_u64 v[182:183], v[238:239], 0, s[18:19]
	s_barrier
	ds_read_b128 v[178:181], v168 offset:49152
	ds_read_b128 v[192:195], v168 offset:50176
	ds_read_b128 v[196:199], v168 offset:51200
	ds_read_b128 v[200:203], v168 offset:52224
	ds_read_b128 v[204:207], v168 offset:53248
	ds_read_b128 v[208:211], v168 offset:54272
	ds_read_b128 v[212:215], v168 offset:55296
	ds_read_b128 v[216:219], v168 offset:56320
	global_load_lds_dwordx4 v[182:183], off
	v_lshl_add_u64 v[182:183], v[240:241], 0, s[18:19]
	s_mov_b32 m0, s53
	s_nop 0
	global_load_lds_dwordx4 v[182:183], off
	s_barrier
; __device__ __forceinline__ unsigned cvt_pk_bf16(float lo, float hi) { const f32x2_cv v = {lo, hi}; const bf16x2_cv b = __builtin_convertvector(v, bf16x2_cv); return __builtin_bit_cast(unsigned, b); }
; #define PG8_STAGE(bufoff, gbase, voff) do { _Pragma("unroll") for (int _i = 0; _i < 2; ++_i) \
;         __builtin_amdgcn_global_load_lds((const unsigned*)((const char*)(gbase) + (voff)[_i]), (PG8_LAS unsigned*)(lds + (bufoff) + ldsw + _i * 8192), 16, 0, 0); } while (0)
; #define PG8_MMA(ai, bj, At, Bt) do { __builtin_amdgcn_s_setprio(1); _Pragma("unroll") for (int m = 0; m < 4; ++m) _Pragma("unroll") for (int n = 0; n < 2; ++n) _Pragma("unroll") for (int k = 0; k < 2; ++k) \
;         acc[ai][bj][m][n] = __builtin_amdgcn_mfma_f32_16x16x32_bf16(Bt[n][k], At[m][k], acc[ai][bj][m][n], 0, 0, 0); __builtin_amdgcn_s_setprio(0); } while (0)
; template <class Epi, class Sched, bool STAMP = false>
; __device__ __forceinline__ void gemm_phase(PG8_LAS unsigned char* lds, const Gemm g, const Sched& S, const Epi& E, unsigned long long* stamps) {
;     ...
;             PG8_BAR; PG8_WAIT_L(0); PG8_MMA(1, 0, At, B0); PG8_BAR; PG8_SCHED;
;             PG8_STAGE(PG8_SB(1, 1), b3 + hstep, voffB);
;             PG8_WAIT_V(6); PG8_BAR; PG8_MMA(1, 1, At, B1); PG8_BAR;
;     __device__ __forceinline__ void operator()(const f32x4 (&acc)[2][2][4][2], const pg8::Unit& u, int wr, int wc, int fr, int fq) const {
;         const int row0 = u.pm * 256 + wr * 64 + fr, col0 = u.pn * 256 + wc * 32 + 8 * fq;
; #pragma unroll
;         for (int ai = 0; ai < 2; ++ai)
; #pragma unroll
;             for (int m = 0; m < 4; ++m) {
;                 const int row = row0 + ai * 128 + m * 16;
;                 const float s = (MODE == 2) ? 1.0f : rstd_of(rowss, row);
;                 bf16_t* rowp = O + (size_t)row * ldc + col0;
; #pragma unroll
;                 for (int bj = 0; bj < 2; ++bj) {
;                     f32x4 v0 = acc[ai][bj][m][0] * s, v1 = acc[ai][bj][m][1] * s;
;                     if (MODE == 1) {
; #pragma unroll
;                         for (int j = 0; j < 4; ++j) { const float a = fmaxf(v0[j], 0.f), b = fmaxf(v1[j], 0.f); v0[j] = a * a; v1[j] = b * b; } }
;                     u32x4 w; w.x = cvt_pk_bf16(v0[0], v0[1]); w.y = cvt_pk_bf16(v0[2], v0[3]); w.z = cvt_pk_bf16(v1[0], v1[1]); w.w = cvt_pk_bf16(v1[2], v1[3]);
;                     *(u32x4*)(rowp + bj * 128) = w; } }
	s_waitcnt lgkmcnt(0)
	s_waitcnt lgkmcnt(0)
	v_mfma_f32_16x16x32_bf16 v[60:63], v[158:161], v[178:181], v[60:63]
	v_mfma_f32_16x16x32_bf16 v[56:59], v[170:173], v[178:181], v[56:59]
	v_mfma_f32_16x16x32_bf16 v[44:47], v[158:161], v[196:199], v[44:47]
	v_mfma_f32_16x16x32_bf16 v[40:43], v[170:173], v[196:199], v[40:43]
	v_mfma_f32_16x16x32_bf16 v[28:31], v[158:161], v[204:207], v[28:31]
	v_mfma_f32_16x16x32_bf16 v[24:27], v[170:173], v[204:207], v[24:27]
	v_mfma_f32_16x16x32_bf16 v[12:15], v[158:161], v[212:215], v[12:15]
	v_mfma_f32_16x16x32_bf16 v[8:11], v[170:173], v[212:215], v[8:11]
	v_mfma_f32_16x16x32_bf16 v[60:63], v[162:165], v[192:195], v[60:63]
	v_mfma_f32_16x16x32_bf16 v[56:59], v[174:177], v[192:195], v[56:59]
	v_mfma_f32_16x16x32_bf16 v[44:47], v[162:165], v[200:203], v[44:47]
	v_mfma_f32_16x16x32_bf16 v[40:43], v[174:177], v[200:203], v[40:43]
	v_mfma_f32_16x16x32_bf16 v[28:31], v[162:165], v[208:211], v[28:31]
	v_mfma_f32_16x16x32_bf16 v[24:27], v[174:177], v[208:211], v[24:27]
	v_mfma_f32_16x16x32_bf16 v[12:15], v[162:165], v[216:219], v[12:15]
	v_mfma_f32_16x16x32_bf16 v[8:11], v[174:177], v[216:219], v[8:11]
	s_barrier
	s_add_u32 s14, s26, 0x40080
	s_addc_u32 s15, s27, 0
	s_add_i32 s16, s17, s43
	v_lshl_add_u64 v[158:159], s[14:15], 0, v[128:129]
	s_mov_b32 m0, s16
	s_nop 0
	global_load_lds_dwordx4 v[158:159], off
	v_lshl_add_u64 v[158:159], s[14:15], 0, v[148:149]
	s_add_i32 m0, s16, 0x2000
	s_nop 0
	global_load_lds_dwordx4 v[158:159], off
	s_waitcnt vmcnt(6)
	s_barrier
	v_mfma_f32_16x16x32_bf16 v[52:55], v[220:223], v[178:181], v[52:55]
	v_mfma_f32_16x16x32_bf16 v[48:51], v[228:231], v[178:181], v[48:51]
	v_mfma_f32_16x16x32_bf16 v[36:39], v[220:223], v[196:199], v[36:39]
	v_mfma_f32_16x16x32_bf16 v[32:35], v[228:231], v[196:199], v[32:35]
	v_mfma_f32_16x16x32_bf16 v[20:23], v[220:223], v[204:207], v[20:23]
	v_mfma_f32_16x16x32_bf16 v[16:19], v[228:231], v[204:207], v[16:19]
	v_mfma_f32_16x16x32_bf16 v[4:7], v[220:223], v[212:215], v[4:7]
	v_mfma_f32_16x16x32_bf16 v[0:3], v[228:231], v[212:215], v[0:3]
	v_mfma_f32_16x16x32_bf16 v[52:55], v[224:227], v[192:195], v[52:55]
	v_mfma_f32_16x16x32_bf16 v[48:51], v[232:235], v[192:195], v[48:51]
	v_mfma_f32_16x16x32_bf16 v[36:39], v[224:227], v[200:203], v[36:39]
	v_mfma_f32_16x16x32_bf16 v[32:35], v[232:235], v[200:203], v[32:35]
	v_mfma_f32_16x16x32_bf16 v[20:23], v[224:227], v[208:211], v[20:23]
	v_mfma_f32_16x16x32_bf16 v[16:19], v[232:235], v[208:211], v[16:19]
	v_mfma_f32_16x16x32_bf16 v[4:7], v[224:227], v[216:219], v[4:7]
	v_mfma_f32_16x16x32_bf16 v[0:3], v[232:235], v[216:219], v[0:3]
	s_add_i32 s61, s61, 2
	s_add_u32 s24, s24, 0x100
	s_addc_u32 s25, s25, 0
	s_add_u32 s59, s59, 0x100
	s_addc_u32 s60, s60, 0
	s_cmp_gt_u32 s61, 13
	s_barrier
	s_cbranch_scc0 .LBB0_495
	v_lshl_add_u32 v162, s22, 8, v139
	v_ashrrev_i32_e32 v163, 31, v162
	v_lshl_add_u64 v[158:159], v[162:163], 2, s[0:1]
	global_load_dword v164, v[158:159], off
	global_load_dword v193, v[158:159], off offset:64
	global_load_dword v194, v[158:159], off offset:128
	global_load_dword v195, v[158:159], off offset:192
	global_load_dword v196, v[158:159], off offset:512
	global_load_dword v197, v[158:159], off offset:576
	global_load_dword v198, v[158:159], off offset:640
	global_load_dword v199, v[158:159], off offset:704
	v_lshl_or_b32 v160, s56, 8, v167
	v_ashrrev_i32_e32 v161, 31, v160
	s_mov_b32 s5, 0x80000
	s_mov_b64 s[14:15], 0x80000
	s_mov_b32 s56, s4
	s_mov_b32 s22, s6
	s_mov_b64 s[26:27], s[20:21]
	s_mov_b64 s[24:25], s[12:13]
	s_waitcnt vmcnt(0)
	v_fmamk_f32 v164, v164, 0x3a800000, v187
	v_cmp_gt_f32_e32 vcc, s67, v164
	v_mul_f32_e32 v165, 0x4b800000, v164
	s_nop 0
	v_cndmask_b32_e32 v164, v164, v165, vcc
	v_rsq_f32_e32 v164, v164
	s_nop 0
	v_mul_f32_e32 v165, 0x45800000, v164
	v_cndmask_b32_e32 v170, v164, v165, vcc
	v_lshlrev_b64 v[164:165], 12, v[162:163]
	v_lshl_add_u64 v[172:173], s[2:3], 0, v[164:165]
	v_lshlrev_b64 v[164:165], 1, v[160:161]
	v_lshl_add_u64 v[160:161], v[172:173], 0, v[164:165]
	v_pk_mul_f32 v[126:127], v[126:127], v[170:171] op_sel_hi:[1,0]
	v_pk_mul_f32 v[124:125], v[124:125], v[170:171] op_sel_hi:[1,0]
	v_pk_mul_f32 v[172:173], v[122:123], v[170:171] op_sel_hi:[1,0]
	v_pk_mul_f32 v[122:123], v[120:121], v[170:171] op_sel_hi:[1,0]
	v_cvt_pk_bf16_f32 v120, v124, v125
	v_cvt_pk_bf16_f32 v121, v126, v127
	v_cvt_pk_bf16_f32 v122, v122, v123
	v_cvt_pk_bf16_f32 v123, v172, v173
	global_store_dwordx4 v[160:161], v[120:123], off
	v_pk_mul_f32 v[118:119], v[118:119], v[170:171] op_sel_hi:[1,0]
	v_pk_mul_f32 v[116:117], v[116:117], v[170:171] op_sel_hi:[1,0]
	v_pk_mul_f32 v[120:121], v[114:115], v[170:171] op_sel_hi:[1,0]
	v_pk_mul_f32 v[114:115], v[112:113], v[170:171] op_sel_hi:[1,0]
	v_cvt_pk_bf16_f32 v112, v116, v117
	v_cvt_pk_bf16_f32 v113, v118, v119
	v_cvt_pk_bf16_f32 v114, v114, v115
	v_cvt_pk_bf16_f32 v115, v120, v121
	global_store_dwordx4 v[160:161], v[112:115], off offset:256
	s_nop 1
	v_mov_b32_e32 v114, v193
	s_nop 0
	v_or_b32_e32 v112, 16, v162
	v_ashrrev_i32_e32 v113, 31, v112
	v_lshlrev_b64 v[112:113], 12, v[112:113]
	v_lshl_add_u64 v[112:113], s[2:3], 0, v[112:113]
	v_lshl_add_u64 v[112:113], v[112:113], 0, v[164:165]
	v_fmamk_f32 v114, v114, 0x3a800000, v187
	v_cmp_gt_f32_e32 vcc, s67, v114
	v_mul_f32_e32 v115, 0x4b800000, v114
	s_nop 0
	v_cndmask_b32_e32 v114, v114, v115, vcc
	v_rsq_f32_e32 v114, v114
	s_nop 0
	v_mul_f32_e32 v115, 0x45800000, v114
	v_cndmask_b32_e32 v114, v114, v115, vcc
	v_pk_mul_f32 v[110:111], v[110:111], v[114:115] op_sel_hi:[1,0]
	v_pk_mul_f32 v[108:109], v[108:109], v[114:115] op_sel_hi:[1,0]
	v_pk_mul_f32 v[116:117], v[106:107], v[114:115] op_sel_hi:[1,0]
; __device__ __forceinline__ unsigned cvt_pk_bf16(float lo, float hi) { const f32x2_cv v = {lo, hi}; const bf16x2_cv b = __builtin_convertvector(v, bf16x2_cv); return __builtin_bit_cast(unsigned, b); }
; __device__ __forceinline__ float rstd_of(const float* rowss, int row) { return rsqrtf(rowss[row] * (1.0f / 1024.0f) + 1e-6f); }
;     __device__ __forceinline__ void operator()(const f32x4 (&acc)[2][2][4][2], const pg8::Unit& u, int wr, int wc, int fr, int fq) const {
;     ...
;             for (int m = 0; m < 4; ++m) {
;                 const int row = row0 + ai * 128 + m * 16;
;                 const float s = (MODE == 2) ? 1.0f : rstd_of(rowss, row);
;                 bf16_t* rowp = O + (size_t)row * ldc + col0;
; #pragma unroll
;                 for (int bj = 0; bj < 2; ++bj) {
;                     f32x4 v0 = acc[ai][bj][m][0] * s, v1 = acc[ai][bj][m][1] * s;
;                     if (MODE == 1) {
; #pragma unroll
;                         for (int j = 0; j < 4; ++j) { const float a = fmaxf(v0[j], 0.f), b = fmaxf(v1[j], 0.f); v0[j] = a * a; v1[j] = b * b; } }
;                     u32x4 w; w.x = cvt_pk_bf16(v0[0], v0[1]); w.y = cvt_pk_bf16(v0[2], v0[3]); w.z = cvt_pk_bf16(v1[0], v1[1]); w.w = cvt_pk_bf16(v1[2], v1[3]);
;                     *(u32x4*)(rowp + bj * 128) = w; } }
	v_pk_mul_f32 v[106:107], v[104:105], v[114:115] op_sel_hi:[1,0]
	v_cvt_pk_bf16_f32 v104, v108, v109
	v_cvt_pk_bf16_f32 v105, v110, v111
	v_cvt_pk_bf16_f32 v106, v106, v107
	v_cvt_pk_bf16_f32 v107, v116, v117
	global_store_dwordx4 v[112:113], v[104:107], off
	v_pk_mul_f32 v[102:103], v[102:103], v[114:115] op_sel_hi:[1,0]
	v_pk_mul_f32 v[100:101], v[100:101], v[114:115] op_sel_hi:[1,0]
	v_pk_mul_f32 v[104:105], v[98:99], v[114:115] op_sel_hi:[1,0]
	v_pk_mul_f32 v[98:99], v[96:97], v[114:115] op_sel_hi:[1,0]
	v_cvt_pk_bf16_f32 v96, v100, v101
	v_cvt_pk_bf16_f32 v97, v102, v103
	v_cvt_pk_bf16_f32 v98, v98, v99
	v_cvt_pk_bf16_f32 v99, v104, v105
	global_store_dwordx4 v[112:113], v[96:99], off offset:256
	s_nop 1
	v_mov_b32_e32 v98, v194
	s_nop 0
	v_or_b32_e32 v96, 32, v162
	v_ashrrev_i32_e32 v97, 31, v96
	v_lshlrev_b64 v[96:97], 12, v[96:97]
	v_lshl_add_u64 v[96:97], s[2:3], 0, v[96:97]
	v_lshl_add_u64 v[96:97], v[96:97], 0, v[164:165]
	v_fmamk_f32 v98, v98, 0x3a800000, v187
	v_cmp_gt_f32_e32 vcc, s67, v98
	v_mul_f32_e32 v99, 0x4b800000, v98
	s_nop 0
	v_cndmask_b32_e32 v98, v98, v99, vcc
	v_rsq_f32_e32 v98, v98
	s_nop 0
	v_mul_f32_e32 v99, 0x45800000, v98
	v_cndmask_b32_e32 v98, v98, v99, vcc
	v_pk_mul_f32 v[94:95], v[94:95], v[98:99] op_sel_hi:[1,0]
	v_pk_mul_f32 v[92:93], v[92:93], v[98:99] op_sel_hi:[1,0]
	v_pk_mul_f32 v[100:101], v[90:91], v[98:99] op_sel_hi:[1,0]
	v_pk_mul_f32 v[90:91], v[88:89], v[98:99] op_sel_hi:[1,0]
	v_cvt_pk_bf16_f32 v88, v92, v93
	v_cvt_pk_bf16_f32 v89, v94, v95
	v_cvt_pk_bf16_f32 v90, v90, v91
	v_cvt_pk_bf16_f32 v91, v100, v101
	global_store_dwordx4 v[96:97], v[88:91], off
	v_pk_mul_f32 v[86:87], v[86:87], v[98:99] op_sel_hi:[1,0]
	v_pk_mul_f32 v[84:85], v[84:85], v[98:99] op_sel_hi:[1,0]
	v_pk_mul_f32 v[88:89], v[82:83], v[98:99] op_sel_hi:[1,0]
	v_pk_mul_f32 v[82:83], v[80:81], v[98:99] op_sel_hi:[1,0]
	v_cvt_pk_bf16_f32 v80, v84, v85
	v_cvt_pk_bf16_f32 v81, v86, v87
	v_cvt_pk_bf16_f32 v82, v82, v83
	v_cvt_pk_bf16_f32 v83, v88, v89
	global_store_dwordx4 v[96:97], v[80:83], off offset:256
	s_nop 1
	v_mov_b32_e32 v82, v195
	s_nop 0
	v_or_b32_e32 v80, 48, v162
	v_ashrrev_i32_e32 v81, 31, v80
	v_lshlrev_b64 v[80:81], 12, v[80:81]
	v_lshl_add_u64 v[80:81], s[2:3], 0, v[80:81]
	v_lshl_add_u64 v[80:81], v[80:81], 0, v[164:165]
	v_fmamk_f32 v82, v82, 0x3a800000, v187
	v_cmp_gt_f32_e32 vcc, s67, v82
	v_mul_f32_e32 v83, 0x4b800000, v82
	s_nop 0
	v_cndmask_b32_e32 v82, v82, v83, vcc
	v_rsq_f32_e32 v82, v82
	s_nop 0
	v_mul_f32_e32 v83, 0x45800000, v82
	v_cndmask_b32_e32 v82, v82, v83, vcc
	v_pk_mul_f32 v[78:79], v[78:79], v[82:83] op_sel_hi:[1,0]
	v_pk_mul_f32 v[76:77], v[76:77], v[82:83] op_sel_hi:[1,0]
	v_pk_mul_f32 v[84:85], v[74:75], v[82:83] op_sel_hi:[1,0]
	v_pk_mul_f32 v[74:75], v[72:73], v[82:83] op_sel_hi:[1,0]
	v_cvt_pk_bf16_f32 v72, v76, v77
	v_cvt_pk_bf16_f32 v73, v78, v79
	v_cvt_pk_bf16_f32 v74, v74, v75
	v_cvt_pk_bf16_f32 v75, v84, v85
	global_store_dwordx4 v[80:81], v[72:75], off
	v_pk_mul_f32 v[70:71], v[70:71], v[82:83] op_sel_hi:[1,0]
	v_pk_mul_f32 v[68:69], v[68:69], v[82:83] op_sel_hi:[1,0]
	v_pk_mul_f32 v[72:73], v[66:67], v[82:83] op_sel_hi:[1,0]
	v_pk_mul_f32 v[66:67], v[64:65], v[82:83] op_sel_hi:[1,0]
	v_cvt_pk_bf16_f32 v64, v68, v69
	v_cvt_pk_bf16_f32 v65, v70, v71
	v_cvt_pk_bf16_f32 v66, v66, v67
	v_cvt_pk_bf16_f32 v67, v72, v73
	global_store_dwordx4 v[80:81], v[64:67], off offset:256
	s_nop 1
	v_mov_b32_e32 v64, v196
	s_nop 0
	v_lshl_add_u64 v[66:67], v[160:161], 0, s[14:15]
	s_mov_b64 s[14:15], 0x90000
	v_fmamk_f32 v64, v64, 0x3a800000, v187
	v_cmp_gt_f32_e32 vcc, s67, v64
	v_mul_f32_e32 v65, 0x4b800000, v64
	s_nop 0
	v_cndmask_b32_e32 v64, v64, v65, vcc
	v_rsq_f32_e32 v64, v64
	s_nop 0
	v_mul_f32_e32 v65, 0x45800000, v64
	v_cndmask_b32_e32 v64, v64, v65, vcc
	v_pk_mul_f32 v[60:61], v[60:61], v[64:65] op_sel_hi:[1,0]
	v_pk_mul_f32 v[62:63], v[62:63], v[64:65] op_sel_hi:[1,0]
	v_pk_mul_f32 v[68:69], v[58:59], v[64:65] op_sel_hi:[1,0]
	v_pk_mul_f32 v[58:59], v[56:57], v[64:65] op_sel_hi:[1,0]
	v_cvt_pk_bf16_f32 v56, v60, v61
	v_add_co_u32_e32 v60, vcc, s5, v160
	v_cvt_pk_bf16_f32 v57, v62, v63
	v_cvt_pk_bf16_f32 v58, v58, v59
	v_cvt_pk_bf16_f32 v59, v68, v69
	v_addc_co_u32_e32 v61, vcc, 0, v161, vcc
	global_store_dwordx4 v[60:61], v[56:59], off
	v_pk_mul_f32 v[54:55], v[54:55], v[64:65] op_sel_hi:[1,0]
	v_pk_mul_f32 v[52:53], v[52:53], v[64:65] op_sel_hi:[1,0]
; __device__ __forceinline__ unsigned cvt_pk_bf16(float lo, float hi) { const f32x2_cv v = {lo, hi}; const bf16x2_cv b = __builtin_convertvector(v, bf16x2_cv); return __builtin_bit_cast(unsigned, b); }
; __device__ __forceinline__ float rstd_of(const float* rowss, int row) { return rsqrtf(rowss[row] * (1.0f / 1024.0f) + 1e-6f); }
;     __device__ __forceinline__ void operator()(const f32x4 (&acc)[2][2][4][2], const pg8::Unit& u, int wr, int wc, int fr, int fq) const {
;     ...
;             for (int m = 0; m < 4; ++m) {
;                 const int row = row0 + ai * 128 + m * 16;
;                 const float s = (MODE == 2) ? 1.0f : rstd_of(rowss, row);
;                 bf16_t* rowp = O + (size_t)row * ldc + col0;
; #pragma unroll
;                 for (int bj = 0; bj < 2; ++bj) {
;                     f32x4 v0 = acc[ai][bj][m][0] * s, v1 = acc[ai][bj][m][1] * s;
;                     if (MODE == 1) {
; #pragma unroll
;                         for (int j = 0; j < 4; ++j) { const float a = fmaxf(v0[j], 0.f), b = fmaxf(v1[j], 0.f); v0[j] = a * a; v1[j] = b * b; } }
;                     u32x4 w; w.x = cvt_pk_bf16(v0[0], v0[1]); w.y = cvt_pk_bf16(v0[2], v0[3]); w.z = cvt_pk_bf16(v1[0], v1[1]); w.w = cvt_pk_bf16(v1[2], v1[3]);
;                     *(u32x4*)(rowp + bj * 128) = w; } }
	v_pk_mul_f32 v[56:57], v[50:51], v[64:65] op_sel_hi:[1,0]
	v_pk_mul_f32 v[50:51], v[48:49], v[64:65] op_sel_hi:[1,0]
	v_cvt_pk_bf16_f32 v48, v52, v53
	v_cvt_pk_bf16_f32 v49, v54, v55
	v_cvt_pk_bf16_f32 v50, v50, v51
	v_cvt_pk_bf16_f32 v51, v56, v57
	global_store_dwordx4 v[66:67], v[48:51], off offset:256
	s_nop 1
	v_mov_b32_e32 v48, v197
	s_mov_b32 s5, 0x90000
	v_lshl_add_u64 v[50:51], v[160:161], 0, s[14:15]
	s_mov_b64 s[14:15], 0xa0000
	v_fmamk_f32 v48, v48, 0x3a800000, v187
	v_cmp_gt_f32_e32 vcc, s67, v48
	v_mul_f32_e32 v49, 0x4b800000, v48
	s_nop 0
	v_cndmask_b32_e32 v48, v48, v49, vcc
	v_rsq_f32_e32 v48, v48
	s_nop 0
	v_mul_f32_e32 v49, 0x45800000, v48
	v_cndmask_b32_e32 v48, v48, v49, vcc
	v_pk_mul_f32 v[44:45], v[44:45], v[48:49] op_sel_hi:[1,0]
	v_pk_mul_f32 v[46:47], v[46:47], v[48:49] op_sel_hi:[1,0]
	v_pk_mul_f32 v[52:53], v[42:43], v[48:49] op_sel_hi:[1,0]
	v_pk_mul_f32 v[42:43], v[40:41], v[48:49] op_sel_hi:[1,0]
	v_cvt_pk_bf16_f32 v40, v44, v45
	v_add_co_u32_e32 v44, vcc, s5, v160
	v_cvt_pk_bf16_f32 v41, v46, v47
	v_cvt_pk_bf16_f32 v42, v42, v43
	v_cvt_pk_bf16_f32 v43, v52, v53
	v_addc_co_u32_e32 v45, vcc, 0, v161, vcc
	global_store_dwordx4 v[44:45], v[40:43], off
	v_pk_mul_f32 v[38:39], v[38:39], v[48:49] op_sel_hi:[1,0]
	v_pk_mul_f32 v[36:37], v[36:37], v[48:49] op_sel_hi:[1,0]
	v_pk_mul_f32 v[40:41], v[34:35], v[48:49] op_sel_hi:[1,0]
	v_pk_mul_f32 v[34:35], v[32:33], v[48:49] op_sel_hi:[1,0]
	v_cvt_pk_bf16_f32 v32, v36, v37
	v_cvt_pk_bf16_f32 v33, v38, v39
	v_cvt_pk_bf16_f32 v34, v34, v35
	v_cvt_pk_bf16_f32 v35, v40, v41
	global_store_dwordx4 v[50:51], v[32:35], off offset:256
	s_nop 1
	v_mov_b32_e32 v32, v198
	s_mov_b32 s5, 0xa0000
	v_lshl_add_u64 v[34:35], v[160:161], 0, s[14:15]
	s_mov_b64 s[14:15], 0xb0000
	v_fmamk_f32 v32, v32, 0x3a800000, v187
	v_cmp_gt_f32_e32 vcc, s67, v32
	v_mul_f32_e32 v33, 0x4b800000, v32
	s_nop 0
	v_cndmask_b32_e32 v32, v32, v33, vcc
	v_rsq_f32_e32 v32, v32
	s_nop 0
	v_mul_f32_e32 v33, 0x45800000, v32
	v_cndmask_b32_e32 v32, v32, v33, vcc
	v_pk_mul_f32 v[28:29], v[28:29], v[32:33] op_sel_hi:[1,0]
	v_pk_mul_f32 v[30:31], v[30:31], v[32:33] op_sel_hi:[1,0]
	v_pk_mul_f32 v[36:37], v[26:27], v[32:33] op_sel_hi:[1,0]
	v_pk_mul_f32 v[26:27], v[24:25], v[32:33] op_sel_hi:[1,0]
	v_cvt_pk_bf16_f32 v24, v28, v29
	v_add_co_u32_e32 v28, vcc, s5, v160
	v_cvt_pk_bf16_f32 v25, v30, v31
	v_cvt_pk_bf16_f32 v26, v26, v27
	v_cvt_pk_bf16_f32 v27, v36, v37
	v_addc_co_u32_e32 v29, vcc, 0, v161, vcc
	global_store_dwordx4 v[28:29], v[24:27], off
	v_pk_mul_f32 v[22:23], v[22:23], v[32:33] op_sel_hi:[1,0]
	v_pk_mul_f32 v[20:21], v[20:21], v[32:33] op_sel_hi:[1,0]
	v_pk_mul_f32 v[24:25], v[18:19], v[32:33] op_sel_hi:[1,0]
	v_pk_mul_f32 v[18:19], v[16:17], v[32:33] op_sel_hi:[1,0]
	v_cvt_pk_bf16_f32 v16, v20, v21
	v_cvt_pk_bf16_f32 v17, v22, v23
	v_cvt_pk_bf16_f32 v18, v18, v19
	v_cvt_pk_bf16_f32 v19, v24, v25
	global_store_dwordx4 v[34:35], v[16:19], off offset:256
	s_nop 1
	v_mov_b32_e32 v16, v199
	s_mov_b32 s5, 0xb0000
	v_lshl_add_u64 v[18:19], v[160:161], 0, s[14:15]
	v_fmamk_f32 v16, v16, 0x3a800000, v187
	v_cmp_gt_f32_e32 vcc, s67, v16
	v_mul_f32_e32 v17, 0x4b800000, v16
	s_nop 0
	v_cndmask_b32_e32 v16, v16, v17, vcc
	v_rsq_f32_e32 v16, v16
	s_nop 0
	v_mul_f32_e32 v17, 0x45800000, v16
	v_cndmask_b32_e32 v16, v16, v17, vcc
	v_pk_mul_f32 v[12:13], v[12:13], v[16:17] op_sel_hi:[1,0]
	v_pk_mul_f32 v[14:15], v[14:15], v[16:17] op_sel_hi:[1,0]
	v_pk_mul_f32 v[20:21], v[10:11], v[16:17] op_sel_hi:[1,0]
	v_pk_mul_f32 v[10:11], v[8:9], v[16:17] op_sel_hi:[1,0]
	v_cvt_pk_bf16_f32 v8, v12, v13
	v_add_co_u32_e32 v12, vcc, s5, v160
	v_cvt_pk_bf16_f32 v9, v14, v15
	v_cvt_pk_bf16_f32 v10, v10, v11
	v_cvt_pk_bf16_f32 v11, v20, v21
	v_addc_co_u32_e32 v13, vcc, 0, v161, vcc
	global_store_dwordx4 v[12:13], v[8:11], off
	v_pk_mul_f32 v[6:7], v[6:7], v[16:17] op_sel_hi:[1,0]
	v_pk_mul_f32 v[4:5], v[4:5], v[16:17] op_sel_hi:[1,0]
	v_pk_mul_f32 v[8:9], v[2:3], v[16:17] op_sel_hi:[1,0]
	v_pk_mul_f32 v[2:3], v[0:1], v[16:17] op_sel_hi:[1,0]
	v_cvt_pk_bf16_f32 v0, v4, v5
	v_cvt_pk_bf16_f32 v1, v6, v7
	v_cvt_pk_bf16_f32 v2, v2, v3
	v_cvt_pk_bf16_f32 v3, v8, v9
	s_and_b64 vcc, exec, s[38:39]
	global_store_dwordx4 v[18:19], v[0:3], off offset:256
	s_cbranch_vccz .LBB0_492
	s_waitcnt vmcnt(0)
	s_cmpk_gt_u32 s36, 0xff
	s_cbranch_scc1 .LBB0_499
	s_barrier

; #define PG8_STAGE(bufoff, gbase, voff) do { _Pragma("unroll") for (int _i = 0; _i < 2; ++_i) \
;         __builtin_amdgcn_global_load_lds((const unsigned*)((const char*)(gbase) + (voff)[_i]), (PG8_LAS unsigned*)(lds + (bufoff) + ldsw + _i * 8192), 16, 0, 0); } while (0)
; #define PG8_LDA(dst, b, h) do { _Pragma("unroll") for (int m = 0; m < 4; ++m) _Pragma("unroll") for (int k = 0; k < 2; ++k) dst[m][k] = *(const PG8_LAS bf16x8*)(lds + PG8_SA(b, h) + aoff + m * 2048 + k * 1024); } while (0)
; #define PG8_LDB(dst, b, h) do { _Pragma("unroll") for (int n = 0; n < 2; ++n) _Pragma("unroll") for (int k = 0; k < 2; ++k) dst[n][k] = *(const PG8_LAS bf16x8*)(lds + PG8_SB(b, h) + boff + n * 2048 + k * 1024); } while (0)
; #define PG8_MMA(ai, bj, At, Bt) do { __builtin_amdgcn_s_setprio(1); _Pragma("unroll") for (int m = 0; m < 4; ++m) _Pragma("unroll") for (int n = 0; n < 2; ++n) _Pragma("unroll") for (int k = 0; k < 2; ++k) \
;         acc[ai][bj][m][n] = __builtin_amdgcn_mfma_f32_16x16x32_bf16(Bt[n][k], At[m][k], acc[ai][bj][m][n], 0, 0, 0); __builtin_amdgcn_s_setprio(0); } while (0)
; #define PG8_WAIT_L(n) asm volatile("s_waitcnt lgkmcnt(" #n ")" ::: "memory")
; #define PG8_BAR __builtin_amdgcn_s_barrier()
; #define PG8_SCHED __builtin_amdgcn_sched_barrier(0)
; template <class Epi, class Sched, bool STAMP = false>
; __device__ __forceinline__ void gemm_phase(PG8_LAS unsigned char* lds, const Gemm g, const Sched& S, const Epi& E, unsigned long long* stamps) {
;     ...
;             const bool last = (t == nt - 2);
;             const char* a1 = cA + (size_t)(t + 1) * kstep;
;             const char* a2 = last ? nA : cA + (size_t)(t + 2) * kstep; const char* b2 = last ? nB : cB + (size_t)(t + 2) * kstep;
;             const char* a3 = a2 + kstep; const char* b3 = b2 + kstep;
;             if (last && has_next) S.a_ready(nxt);
;             PG8_LDB(B0, 0, 0); PG8_SCHED; PG8_LDA(At, 0, 0); PG8_STAGE(PG8_SA(1, 1), a1 + hstep, voffA);
;             PG8_WAIT_L(8); PG8_BAR; PG8_WAIT_L(0); PG8_MMA(0, 0, At, B0); PG8_BAR; PG8_SCHED;
;             PG8_LDB(B1, 0, 1); PG8_STAGE(PG8_SB(0, 0), b2, voffB);
;             PG8_BAR; PG8_WAIT_L(0); PG8_MMA(0, 1, At, B1); PG8_BAR;
;             PG8_LDA(At, 0, 1); PG8_STAGE(PG8_SA(0, 0), a2, voffA);
;             PG8_BAR; PG8_WAIT_L(0); PG8_MMA(1, 0, At, B0); PG8_BAR; PG8_SCHED;
.LBB0_1183:
	s_add_u32 s30, s26, 0x100
	s_addc_u32 s31, s27, 0
	s_add_i32 s14, 0, 0x10000
	v_add_u32_e32 v161, s14, v158
	ds_read_b128 v[154:157], v161
	ds_read_b128 v[162:165], v161 offset:1024
	ds_read_b128 v[166:169], v161 offset:2048
	ds_read_b128 v[170:173], v161 offset:3072
	s_cmp_eq_u32 s65, 60
	s_cselect_b32 s37, s7, s31
	s_cselect_b32 s36, s23, s30
	s_cselect_b32 s35, s5, s64
	s_cselect_b32 s34, s62, s63
	v_lshl_add_u64 v[182:183], s[26:27], 0, v[150:151]
	s_add_i32 m0, s25, 0xc000
	ds_read_b128 v[174:177], v160
	ds_read_b128 v[178:181], v160 offset:1024
	ds_read_b128 v[192:195], v160 offset:2048
	ds_read_b128 v[196:199], v160 offset:3072
	ds_read_b128 v[200:203], v160 offset:4096
	ds_read_b128 v[204:207], v160 offset:5120
	ds_read_b128 v[208:211], v160 offset:6144
	ds_read_b128 v[212:215], v160 offset:7168
	global_load_lds_dwordx4 v[182:183], off
	v_lshl_add_u64 v[182:183], s[26:27], 0, v[152:153]
	s_add_i32 m0, s25, 0xe000
	s_nop 0
	global_load_lds_dwordx4 v[182:183], off
	s_waitcnt lgkmcnt(8)
	s_barrier
	s_waitcnt lgkmcnt(0)
	s_waitcnt lgkmcnt(0)
	v_mfma_f32_16x16x32_bf16 v[124:127], v[154:157], v[174:177], v[124:127]
	v_mfma_f32_16x16x32_bf16 v[120:123], v[166:169], v[174:177], v[120:123]
	v_mfma_f32_16x16x32_bf16 v[108:111], v[154:157], v[192:195], v[108:111]
	v_mfma_f32_16x16x32_bf16 v[104:107], v[166:169], v[192:195], v[104:107]
	v_mfma_f32_16x16x32_bf16 v[92:95], v[154:157], v[200:203], v[92:95]
	v_mfma_f32_16x16x32_bf16 v[88:91], v[166:169], v[200:203], v[88:91]
	v_mfma_f32_16x16x32_bf16 v[76:79], v[154:157], v[208:211], v[76:79]
	v_mfma_f32_16x16x32_bf16 v[72:75], v[166:169], v[208:211], v[72:75]
	v_mfma_f32_16x16x32_bf16 v[124:127], v[162:165], v[178:181], v[124:127]
	v_mfma_f32_16x16x32_bf16 v[120:123], v[170:173], v[178:181], v[120:123]
	v_mfma_f32_16x16x32_bf16 v[108:111], v[162:165], v[196:199], v[108:111]
	v_mfma_f32_16x16x32_bf16 v[104:107], v[170:173], v[196:199], v[104:107]
	v_mfma_f32_16x16x32_bf16 v[92:95], v[162:165], v[204:207], v[92:95]
	v_mfma_f32_16x16x32_bf16 v[88:91], v[170:173], v[204:207], v[88:91]
	v_mfma_f32_16x16x32_bf16 v[76:79], v[162:165], v[212:215], v[76:79]
	v_mfma_f32_16x16x32_bf16 v[72:75], v[170:173], v[212:215], v[72:75]
	s_barrier
	s_add_i32 s16, 0, 0x14000
	s_add_i32 s14, s14, s49
	v_add_u32_e32 v161, s16, v158
	v_lshl_add_u64 v[182:183], s[34:35], 0, v[128:129]
	s_mov_b32 m0, s14
	ds_read_b128 v[216:219], v161
	ds_read_b128 v[220:223], v161 offset:1024
	ds_read_b128 v[224:227], v161 offset:2048
	ds_read_b128 v[228:231], v161 offset:3072
	global_load_lds_dwordx4 v[182:183], off
	v_lshl_add_u64 v[232:233], s[34:35], 0, v[148:149]
	s_add_i32 m0, s14, 0x2000
	s_nop 0
	global_load_lds_dwordx4 v[232:233], off
	s_barrier
	s_waitcnt lgkmcnt(0)
	s_waitcnt lgkmcnt(0)
	v_mfma_f32_16x16x32_bf16 v[116:119], v[216:219], v[174:177], v[116:119]
	v_mfma_f32_16x16x32_bf16 v[112:115], v[224:227], v[174:177], v[112:115]
	v_mfma_f32_16x16x32_bf16 v[100:103], v[216:219], v[192:195], v[100:103]
	v_mfma_f32_16x16x32_bf16 v[96:99], v[224:227], v[192:195], v[96:99]
	v_mfma_f32_16x16x32_bf16 v[84:87], v[216:219], v[200:203], v[84:87]
	v_mfma_f32_16x16x32_bf16 v[80:83], v[224:227], v[200:203], v[80:83]
	v_mfma_f32_16x16x32_bf16 v[68:71], v[216:219], v[208:211], v[68:71]
	v_mfma_f32_16x16x32_bf16 v[64:67], v[224:227], v[208:211], v[64:67]
	v_mfma_f32_16x16x32_bf16 v[116:119], v[220:223], v[178:181], v[116:119]
	v_mfma_f32_16x16x32_bf16 v[112:115], v[228:231], v[178:181], v[112:115]
	v_mfma_f32_16x16x32_bf16 v[100:103], v[220:223], v[196:199], v[100:103]
	v_mfma_f32_16x16x32_bf16 v[96:99], v[228:231], v[196:199], v[96:99]
	v_mfma_f32_16x16x32_bf16 v[84:87], v[220:223], v[204:207], v[84:87]
	v_mfma_f32_16x16x32_bf16 v[80:83], v[228:231], v[204:207], v[80:83]
	v_mfma_f32_16x16x32_bf16 v[68:71], v[220:223], v[212:215], v[68:71]
	v_mfma_f32_16x16x32_bf16 v[64:67], v[228:231], v[212:215], v[64:67]
	s_mov_b32 m0, s25
	v_lshl_add_u64 v[234:235], s[36:37], 0, v[128:129]
	s_barrier
	ds_read_b128 v[174:177], v160 offset:16384
	ds_read_b128 v[178:181], v160 offset:17408
	ds_read_b128 v[192:195], v160 offset:18432
	ds_read_b128 v[196:199], v160 offset:19456
	ds_read_b128 v[200:203], v160 offset:20480
	ds_read_b128 v[204:207], v160 offset:21504
	ds_read_b128 v[208:211], v160 offset:22528
	ds_read_b128 v[212:215], v160 offset:23552
	global_load_lds_dwordx4 v[234:235], off
	v_lshl_add_u64 v[236:237], s[36:37], 0, v[148:149]
	s_mov_b32 m0, s53
	s_nop 0
	global_load_lds_dwordx4 v[236:237], off
	s_barrier
	s_waitcnt lgkmcnt(0)
	s_waitcnt lgkmcnt(0)
	v_mfma_f32_16x16x32_bf16 v[60:63], v[154:157], v[174:177], v[60:63]
	v_mfma_f32_16x16x32_bf16 v[56:59], v[166:169], v[174:177], v[56:59]
	v_mfma_f32_16x16x32_bf16 v[44:47], v[154:157], v[192:195], v[44:47]
	v_mfma_f32_16x16x32_bf16 v[40:43], v[166:169], v[192:195], v[40:43]
	v_mfma_f32_16x16x32_bf16 v[28:31], v[154:157], v[200:203], v[28:31]
	v_mfma_f32_16x16x32_bf16 v[24:27], v[166:169], v[200:203], v[24:27]
	v_mfma_f32_16x16x32_bf16 v[12:15], v[154:157], v[208:211], v[12:15]
	v_mfma_f32_16x16x32_bf16 v[8:11], v[166:169], v[208:211], v[8:11]
	v_mfma_f32_16x16x32_bf16 v[60:63], v[162:165], v[178:181], v[60:63]
	v_mfma_f32_16x16x32_bf16 v[56:59], v[170:173], v[178:181], v[56:59]
	v_mfma_f32_16x16x32_bf16 v[44:47], v[162:165], v[196:199], v[44:47]
	v_mfma_f32_16x16x32_bf16 v[40:43], v[170:173], v[196:199], v[40:43]
	v_mfma_f32_16x16x32_bf16 v[28:31], v[162:165], v[204:207], v[28:31]
	v_mfma_f32_16x16x32_bf16 v[24:27], v[170:173], v[204:207], v[24:27]
	v_mfma_f32_16x16x32_bf16 v[12:15], v[162:165], v[212:215], v[12:15]
	v_mfma_f32_16x16x32_bf16 v[8:11], v[170:173], v[212:215], v[8:11]
	s_barrier
; #define PG8_STAGE(bufoff, gbase, voff) do { _Pragma("unroll") for (int _i = 0; _i < 2; ++_i) \
;         __builtin_amdgcn_global_load_lds((const unsigned*)((const char*)(gbase) + (voff)[_i]), (PG8_LAS unsigned*)(lds + (bufoff) + ldsw + _i * 8192), 16, 0, 0); } while (0)
; #define PG8_LDA(dst, b, h) do { _Pragma("unroll") for (int m = 0; m < 4; ++m) _Pragma("unroll") for (int k = 0; k < 2; ++k) dst[m][k] = *(const PG8_LAS bf16x8*)(lds + PG8_SA(b, h) + aoff + m * 2048 + k * 1024); } while (0)
; #define PG8_LDB(dst, b, h) do { _Pragma("unroll") for (int n = 0; n < 2; ++n) _Pragma("unroll") for (int k = 0; k < 2; ++k) dst[n][k] = *(const PG8_LAS bf16x8*)(lds + PG8_SB(b, h) + boff + n * 2048 + k * 1024); } while (0)
; #define PG8_MMA(ai, bj, At, Bt) do { __builtin_amdgcn_s_setprio(1); _Pragma("unroll") for (int m = 0; m < 4; ++m) _Pragma("unroll") for (int n = 0; n < 2; ++n) _Pragma("unroll") for (int k = 0; k < 2; ++k) \
;         acc[ai][bj][m][n] = __builtin_amdgcn_mfma_f32_16x16x32_bf16(Bt[n][k], At[m][k], acc[ai][bj][m][n], 0, 0, 0); __builtin_amdgcn_s_setprio(0); } while (0)
; #define PG8_WAIT_V(n) asm volatile("s_waitcnt vmcnt(" #n ")" ::: "memory")
; #define PG8_WAIT_L(n) asm volatile("s_waitcnt lgkmcnt(" #n ")" ::: "memory")
; #define PG8_BAR __builtin_amdgcn_s_barrier()
; #define PG8_SCHED __builtin_amdgcn_sched_barrier(0)
; template <class Epi, class Sched, bool STAMP = false>
; __device__ __forceinline__ void gemm_phase(PG8_LAS unsigned char* lds, const Gemm g, const Sched& S, const Epi& E, unsigned long long* stamps) {
;     ...
;             PG8_STAGE(PG8_SB(0, 1), b2 + hstep, voffB);
;             PG8_WAIT_V(6); PG8_BAR; PG8_MMA(1, 1, At, B1); PG8_BAR;
;             PG8_LDB(B0, 1, 0); PG8_SCHED; PG8_LDA(At, 1, 0); PG8_STAGE(PG8_SA(0, 1), a2 + hstep, voffA);
;             PG8_WAIT_L(8); PG8_BAR; PG8_WAIT_L(0); PG8_MMA(0, 0, At, B0); PG8_BAR; PG8_SCHED;
;             PG8_LDB(B1, 1, 1); PG8_STAGE(PG8_SB(1, 0), b3, voffB);
;             PG8_BAR; PG8_WAIT_L(0); PG8_MMA(0, 1, At, B1); PG8_BAR;
;             PG8_LDA(At, 1, 1); PG8_STAGE(PG8_SA(1, 0), a3, voffA);
	s_add_u32 s14, s34, 0x100000
	s_addc_u32 s15, s35, 0
	s_add_i32 s16, s16, s49
	v_lshl_add_u64 v[154:155], s[14:15], 0, v[128:129]
	s_mov_b32 m0, s16
	s_nop 0
	global_load_lds_dwordx4 v[154:155], off
	v_lshl_add_u64 v[154:155], s[14:15], 0, v[148:149]
	s_add_i32 m0, s16, 0x2000
	s_nop 0
	global_load_lds_dwordx4 v[154:155], off
	s_waitcnt vmcnt(6)
	s_barrier
	v_mfma_f32_16x16x32_bf16 v[52:55], v[216:219], v[174:177], v[52:55]
	v_mfma_f32_16x16x32_bf16 v[48:51], v[224:227], v[174:177], v[48:51]
	v_mfma_f32_16x16x32_bf16 v[36:39], v[216:219], v[192:195], v[36:39]
	v_mfma_f32_16x16x32_bf16 v[32:35], v[224:227], v[192:195], v[32:35]
	v_mfma_f32_16x16x32_bf16 v[20:23], v[216:219], v[200:203], v[20:23]
	v_mfma_f32_16x16x32_bf16 v[16:19], v[224:227], v[200:203], v[16:19]
	v_mfma_f32_16x16x32_bf16 v[4:7], v[216:219], v[208:211], v[4:7]
	v_mfma_f32_16x16x32_bf16 v[0:3], v[224:227], v[208:211], v[0:3]
	v_mfma_f32_16x16x32_bf16 v[52:55], v[220:223], v[178:181], v[52:55]
	v_mfma_f32_16x16x32_bf16 v[48:51], v[228:231], v[178:181], v[48:51]
	v_mfma_f32_16x16x32_bf16 v[36:39], v[220:223], v[196:199], v[36:39]
	v_mfma_f32_16x16x32_bf16 v[32:35], v[228:231], v[196:199], v[32:35]
	v_mfma_f32_16x16x32_bf16 v[20:23], v[220:223], v[204:207], v[20:23]
	v_mfma_f32_16x16x32_bf16 v[16:19], v[228:231], v[204:207], v[16:19]
	v_mfma_f32_16x16x32_bf16 v[4:7], v[220:223], v[212:215], v[4:7]
	v_mfma_f32_16x16x32_bf16 v[0:3], v[228:231], v[212:215], v[0:3]
	s_add_i32 s16, 0, 0x18000
	v_add_u32_e32 v161, s16, v158
	s_barrier
	ds_read_b128 v[154:157], v161
	ds_read_b128 v[162:165], v161 offset:1024
	ds_read_b128 v[166:169], v161 offset:2048
	ds_read_b128 v[170:173], v161 offset:3072
	s_add_u32 s14, s36, 0x100000
	s_addc_u32 s15, s37, 0
	s_mov_b32 m0, s56
	v_lshl_add_u64 v[216:217], s[14:15], 0, v[128:129]
	ds_read_b128 v[174:177], v160 offset:32768
	ds_read_b128 v[178:181], v160 offset:33792
	ds_read_b128 v[192:195], v160 offset:34816
	ds_read_b128 v[196:199], v160 offset:35840
	ds_read_b128 v[200:203], v160 offset:36864
	ds_read_b128 v[204:207], v160 offset:37888
	ds_read_b128 v[208:211], v160 offset:38912
	ds_read_b128 v[212:215], v160 offset:39936
	global_load_lds_dwordx4 v[216:217], off
	v_lshl_add_u64 v[216:217], s[14:15], 0, v[148:149]
	s_mov_b32 m0, s57
	s_nop 0
	global_load_lds_dwordx4 v[216:217], off
	s_waitcnt lgkmcnt(8)
	s_barrier
	s_waitcnt lgkmcnt(0)
	s_waitcnt lgkmcnt(0)
	v_mfma_f32_16x16x32_bf16 v[124:127], v[154:157], v[174:177], v[124:127]
	v_mfma_f32_16x16x32_bf16 v[120:123], v[166:169], v[174:177], v[120:123]
	v_mfma_f32_16x16x32_bf16 v[108:111], v[154:157], v[192:195], v[108:111]
	v_mfma_f32_16x16x32_bf16 v[104:107], v[166:169], v[192:195], v[104:107]
	v_mfma_f32_16x16x32_bf16 v[92:95], v[154:157], v[200:203], v[92:95]
	v_mfma_f32_16x16x32_bf16 v[88:91], v[166:169], v[200:203], v[88:91]
	v_mfma_f32_16x16x32_bf16 v[76:79], v[154:157], v[208:211], v[76:79]
	v_mfma_f32_16x16x32_bf16 v[72:75], v[166:169], v[208:211], v[72:75]
	v_mfma_f32_16x16x32_bf16 v[124:127], v[162:165], v[178:181], v[124:127]
	v_mfma_f32_16x16x32_bf16 v[120:123], v[170:173], v[178:181], v[120:123]
	v_mfma_f32_16x16x32_bf16 v[108:111], v[162:165], v[196:199], v[108:111]
	v_mfma_f32_16x16x32_bf16 v[104:107], v[170:173], v[196:199], v[104:107]
	v_mfma_f32_16x16x32_bf16 v[92:95], v[162:165], v[204:207], v[92:95]
	v_mfma_f32_16x16x32_bf16 v[88:91], v[170:173], v[204:207], v[88:91]
	v_mfma_f32_16x16x32_bf16 v[76:79], v[162:165], v[212:215], v[76:79]
	v_mfma_f32_16x16x32_bf16 v[72:75], v[170:173], v[212:215], v[72:75]
	s_barrier
	s_add_i32 s17, 0, 0x1c000
	s_add_i32 s14, s16, s49
	v_add_u32_e32 v161, s17, v158
	v_lshl_add_u64 v[182:183], v[182:183], 0, s[18:19]
	s_mov_b32 m0, s14
	ds_read_b128 v[216:219], v161
	ds_read_b128 v[220:223], v161 offset:1024
	ds_read_b128 v[224:227], v161 offset:2048
	ds_read_b128 v[228:231], v161 offset:3072
	global_load_lds_dwordx4 v[182:183], off
	v_lshl_add_u64 v[182:183], v[232:233], 0, s[18:19]
	s_add_i32 m0, s14, 0x2000
	s_nop 0
	global_load_lds_dwordx4 v[182:183], off
	s_barrier
	s_waitcnt lgkmcnt(0)
	s_waitcnt lgkmcnt(0)
	v_mfma_f32_16x16x32_bf16 v[116:119], v[216:219], v[174:177], v[116:119]
	v_mfma_f32_16x16x32_bf16 v[112:115], v[224:227], v[174:177], v[112:115]
	v_mfma_f32_16x16x32_bf16 v[100:103], v[216:219], v[192:195], v[100:103]
	v_mfma_f32_16x16x32_bf16 v[96:99], v[224:227], v[192:195], v[96:99]
	v_mfma_f32_16x16x32_bf16 v[84:87], v[216:219], v[200:203], v[84:87]
	v_mfma_f32_16x16x32_bf16 v[80:83], v[224:227], v[200:203], v[80:83]
	v_mfma_f32_16x16x32_bf16 v[68:71], v[216:219], v[208:211], v[68:71]
	v_mfma_f32_16x16x32_bf16 v[64:67], v[224:227], v[208:211], v[64:67]
	v_mfma_f32_16x16x32_bf16 v[116:119], v[220:223], v[178:181], v[116:119]
	v_mfma_f32_16x16x32_bf16 v[112:115], v[228:231], v[178:181], v[112:115]
	v_mfma_f32_16x16x32_bf16 v[100:103], v[220:223], v[196:199], v[100:103]
	v_mfma_f32_16x16x32_bf16 v[96:99], v[228:231], v[196:199], v[96:99]
	v_mfma_f32_16x16x32_bf16 v[84:87], v[220:223], v[204:207], v[84:87]
	v_mfma_f32_16x16x32_bf16 v[80:83], v[228:231], v[204:207], v[80:83]
	v_mfma_f32_16x16x32_bf16 v[68:71], v[220:223], v[212:215], v[68:71]
	v_mfma_f32_16x16x32_bf16 v[64:67], v[228:231], v[212:215], v[64:67]
	s_mov_b32 m0, s59
	v_lshl_add_u64 v[182:183], v[234:235], 0, s[18:19]
	s_barrier
	ds_read_b128 v[174:177], v160 offset:49152
	ds_read_b128 v[178:181], v160 offset:50176
	ds_read_b128 v[192:195], v160 offset:51200
	ds_read_b128 v[196:199], v160 offset:52224
	ds_read_b128 v[200:203], v160 offset:53248
	ds_read_b128 v[204:207], v160 offset:54272
	ds_read_b128 v[208:211], v160 offset:55296
	ds_read_b128 v[212:215], v160 offset:56320
	global_load_lds_dwordx4 v[182:183], off
	v_lshl_add_u64 v[182:183], v[236:237], 0, s[18:19]
	s_mov_b32 m0, s60
	s_nop 0
	global_load_lds_dwordx4 v[182:183], off
	s_barrier
; __device__ __forceinline__ unsigned cvt_pk_bf16(float lo, float hi) { const f32x2_cv v = {lo, hi}; const bf16x2_cv b = __builtin_convertvector(v, bf16x2_cv); return __builtin_bit_cast(unsigned, b); }
; #define PG8_STAGE(bufoff, gbase, voff) do { _Pragma("unroll") for (int _i = 0; _i < 2; ++_i) \
;         __builtin_amdgcn_global_load_lds((const unsigned*)((const char*)(gbase) + (voff)[_i]), (PG8_LAS unsigned*)(lds + (bufoff) + ldsw + _i * 8192), 16, 0, 0); } while (0)
; #define PG8_WAIT_V(n) asm volatile("s_waitcnt vmcnt(" #n ")" ::: "memory")
; #define PG8_BAR __builtin_amdgcn_s_barrier()
; template <class Epi, class Sched, bool STAMP = false>
; __device__ __forceinline__ void gemm_phase(PG8_LAS unsigned char* lds, const Gemm g, const Sched& S, const Epi& E, unsigned long long* stamps) {
;     ...
;             PG8_BAR; PG8_WAIT_L(0); PG8_MMA(1, 0, At, B0); PG8_BAR; PG8_SCHED;
;             PG8_STAGE(PG8_SB(1, 1), b3 + hstep, voffB);
;             PG8_WAIT_V(6); PG8_BAR; PG8_MMA(1, 1, At, B1); PG8_BAR;
;     __device__ __forceinline__ void operator()(const f32x4 (&acc)[2][2][4][2], const pg8::Unit& u, int wr, int wc, int fr, int fq) const {
;         const int row0 = u.pm * 256 + wr * 64 + fr, col0 = u.pn * 256 + wc * 32 + 4 * fq;
; #pragma unroll
;         for (int ai = 0; ai < 2; ++ai)
; #pragma unroll
;             for (int m = 0; m < 4; ++m) {
;                 const int row = row0 + ai * 128 + m * 16;
;                 float* xp = X + (size_t)row * 1024 + col0; bf16_t* bp = XB + (size_t)row * 1024 + col0;
;                 const float* xi = Xp0 ? (row < T_P ? Xp0 + (size_t)row * 1024 + col0 : Xs0 + (size_t)(row - T_P) * 1024 + col0) : xp;
;                 float ss = 0.f;
; #pragma unroll
;                 for (int bj = 0; bj < 2; ++bj)
; #pragma unroll
;                     for (int n = 0; n < 2; ++n) {
;                         f32x4 xv = *(const f32x4*)(xi + bj * 128 + n * 16) + acc[ai][bj][m][n];
;                         *(f32x4*)(xp + bj * 128 + n * 16) = xv;
;                         ss += (xv[0] * xv[0] + xv[1] * xv[1]) + (xv[2] * xv[2] + xv[3] * xv[3]);
;                         u32x2 w; w.x = cvt_pk_bf16(xv[0], xv[1]); w.y = cvt_pk_bf16(xv[2], xv[3]);
;                         *(u32x2*)(bp + bj * 128 + n * 16) = w; }
;                 ss += __shfl_xor(ss, 16); ss += __shfl_xor(ss, 32);
;                 if (fq == 0) atomicAdd(rowss_out + row, ss); }
	s_waitcnt lgkmcnt(0)
	s_waitcnt lgkmcnt(0)
	v_mfma_f32_16x16x32_bf16 v[60:63], v[154:157], v[174:177], v[60:63]
	v_mfma_f32_16x16x32_bf16 v[56:59], v[166:169], v[174:177], v[56:59]
	v_mfma_f32_16x16x32_bf16 v[44:47], v[154:157], v[192:195], v[44:47]
	v_mfma_f32_16x16x32_bf16 v[40:43], v[166:169], v[192:195], v[40:43]
	v_mfma_f32_16x16x32_bf16 v[28:31], v[154:157], v[200:203], v[28:31]
	v_mfma_f32_16x16x32_bf16 v[24:27], v[166:169], v[200:203], v[24:27]
	v_mfma_f32_16x16x32_bf16 v[12:15], v[154:157], v[208:211], v[12:15]
	v_mfma_f32_16x16x32_bf16 v[8:11], v[166:169], v[208:211], v[8:11]
	v_mfma_f32_16x16x32_bf16 v[60:63], v[162:165], v[178:181], v[60:63]
	v_mfma_f32_16x16x32_bf16 v[56:59], v[170:173], v[178:181], v[56:59]
	v_mfma_f32_16x16x32_bf16 v[44:47], v[162:165], v[196:199], v[44:47]
	v_mfma_f32_16x16x32_bf16 v[40:43], v[170:173], v[196:199], v[40:43]
	v_mfma_f32_16x16x32_bf16 v[28:31], v[162:165], v[204:207], v[28:31]
	v_mfma_f32_16x16x32_bf16 v[24:27], v[170:173], v[204:207], v[24:27]
	v_mfma_f32_16x16x32_bf16 v[12:15], v[162:165], v[212:215], v[12:15]
	v_mfma_f32_16x16x32_bf16 v[8:11], v[170:173], v[212:215], v[8:11]
	s_barrier
	s_add_u32 s14, s34, 0x100080
	s_addc_u32 s15, s35, 0
	s_add_i32 s16, s17, s49
	v_lshl_add_u64 v[154:155], s[14:15], 0, v[128:129]
	s_mov_b32 m0, s16
	s_nop 0
	global_load_lds_dwordx4 v[154:155], off
	v_lshl_add_u64 v[154:155], s[14:15], 0, v[148:149]
	s_add_i32 m0, s16, 0x2000
	s_nop 0
	global_load_lds_dwordx4 v[154:155], off
	s_waitcnt vmcnt(6)
	s_barrier
	v_mfma_f32_16x16x32_bf16 v[52:55], v[216:219], v[174:177], v[52:55]
	v_mfma_f32_16x16x32_bf16 v[48:51], v[224:227], v[174:177], v[48:51]
	v_mfma_f32_16x16x32_bf16 v[36:39], v[216:219], v[192:195], v[36:39]
	v_mfma_f32_16x16x32_bf16 v[32:35], v[224:227], v[192:195], v[32:35]
	v_mfma_f32_16x16x32_bf16 v[20:23], v[216:219], v[200:203], v[20:23]
	v_mfma_f32_16x16x32_bf16 v[16:19], v[224:227], v[200:203], v[16:19]
	v_mfma_f32_16x16x32_bf16 v[4:7], v[216:219], v[208:211], v[4:7]
	v_mfma_f32_16x16x32_bf16 v[0:3], v[224:227], v[208:211], v[0:3]
	v_mfma_f32_16x16x32_bf16 v[52:55], v[220:223], v[178:181], v[52:55]
	v_mfma_f32_16x16x32_bf16 v[48:51], v[228:231], v[178:181], v[48:51]
	v_mfma_f32_16x16x32_bf16 v[36:39], v[220:223], v[196:199], v[36:39]
	v_mfma_f32_16x16x32_bf16 v[32:35], v[228:231], v[196:199], v[32:35]
	v_mfma_f32_16x16x32_bf16 v[20:23], v[220:223], v[204:207], v[20:23]
	v_mfma_f32_16x16x32_bf16 v[16:19], v[228:231], v[204:207], v[16:19]
	v_mfma_f32_16x16x32_bf16 v[4:7], v[220:223], v[212:215], v[4:7]
	v_mfma_f32_16x16x32_bf16 v[0:3], v[228:231], v[212:215], v[0:3]
	s_add_i32 s65, s65, 2
	s_add_u32 s63, s63, 0x100
	s_addc_u32 s64, s64, 0
	s_cmp_gt_u32 s65, 61
	s_mov_b64 s[26:27], s[30:31]
	s_barrier
	s_cbranch_scc0 .LBB0_1183
	v_lshl_add_u32 v156, s22, 8, v139
	v_ashrrev_i32_e32 v157, 31, v156
	v_lshl_or_b32 v154, s24, 8, v159
	v_lshlrev_b64 v[162:163], 12, v[156:157]
	v_ashrrev_i32_e32 v155, 31, v154
	v_lshl_add_u64 v[162:163], s[84:85], 0, v[162:163]
	v_lshl_add_u64 v[170:171], v[154:155], 2, v[162:163]
	global_load_dwordx4 v[192:195], v[170:171], off
	global_load_dwordx4 v[196:199], v[170:171], off offset:64
	global_load_dwordx4 v[200:203], v[170:171], off offset:512
	global_load_dwordx4 v[204:207], v[170:171], off offset:576
	v_add_co_u32_e32 v224, vcc, 0x10000, v170
	s_nop 1
	v_addc_co_u32_e32 v225, vcc, 0, v171, vcc
	global_load_dwordx4 v[208:211], v[224:225], off
	global_load_dwordx4 v[212:215], v[224:225], off offset:64
	global_load_dwordx4 v[216:219], v[224:225], off offset:512
	global_load_dwordx4 v[220:223], v[224:225], off offset:576
	v_lshlrev_b64 v[166:167], 11, v[156:157]
	v_lshl_add_u64 v[166:167], s[0:1], 0, v[166:167]
	v_lshl_add_u64 v[172:173], v[154:155], 1, v[166:167]
	v_xor_b32_e32 v161, 32, v189
	s_waitcnt vmcnt(4)
	v_mov_b32_e32 v162, v192
	v_mov_b32_e32 v163, v193
	v_mov_b32_e32 v164, v194
	v_mov_b32_e32 v165, v195
	v_pk_add_f32 v[126:127], v[126:127], v[164:165]
	v_pk_add_f32 v[124:125], v[124:125], v[162:163]
	v_cvt_pk_bf16_f32 v163, v126, v127
	v_cvt_pk_bf16_f32 v162, v124, v125
	global_store_dwordx4 v[170:171], v[124:127], off
	global_store_dwordx2 v[172:173], v[162:163], off
	s_nop 1
	v_mov_b32_e32 v162, v196
	v_mov_b32_e32 v163, v197
	v_mov_b32_e32 v164, v198
	v_mov_b32_e32 v165, v199
	v_pk_add_f32 v[122:123], v[122:123], v[164:165]
	v_pk_add_f32 v[120:121], v[120:121], v[162:163]
	v_cvt_pk_bf16_f32 v163, v122, v123
	v_cvt_pk_bf16_f32 v162, v120, v121
	global_store_dwordx4 v[170:171], v[120:123], off offset:64
	global_store_dwordx2 v[172:173], v[162:163], off offset:32
	s_nop 1
	v_mov_b32_e32 v162, v200
	v_mov_b32_e32 v163, v201
	v_mov_b32_e32 v164, v202
	v_mov_b32_e32 v165, v203
	v_pk_add_f32 v[164:165], v[118:119], v[164:165]
	v_pk_add_f32 v[162:163], v[116:117], v[162:163]
	v_cvt_pk_bf16_f32 v117, v164, v165
	v_cvt_pk_bf16_f32 v116, v162, v163
	global_store_dwordx4 v[170:171], v[162:165], off offset:512
	global_store_dwordx2 v[172:173], v[116:117], off offset:256
	s_nop 1
	v_mov_b32_e32 v166, v204
	v_mov_b32_e32 v167, v205
	v_mov_b32_e32 v168, v206
	v_mov_b32_e32 v169, v207
	v_mul_f32_e32 v118, v125, v125
	v_mul_f32_e32 v119, v127, v127
	v_fmac_f32_e32 v118, v124, v124
	v_fmac_f32_e32 v119, v126, v126
	v_add_f32_e32 v118, v118, v119
	v_mul_f32_e32 v119, v121, v121
	v_mul_f32_e32 v121, v123, v123
	v_fmac_f32_e32 v119, v120, v120
	v_fmac_f32_e32 v121, v122, v122
	v_add_f32_e32 v119, v119, v121
	v_add_f32_e32 v118, v118, v119
	v_mul_f32_e32 v119, v163, v163
	v_mul_f32_e32 v120, v165, v165
	v_fmac_f32_e32 v119, v162, v162
	v_fmac_f32_e32 v120, v164, v164
	v_add_f32_e32 v119, v119, v120
	v_and_b32_e32 v117, 64, v189
	v_add_f32_e32 v122, v118, v119
	v_xor_b32_e32 v116, 16, v189
	v_add_u32_e32 v117, 64, v117
	v_cmp_lt_i32_e32 vcc, v116, v117
	v_pk_add_f32 v[120:121], v[114:115], v[168:169]
	v_pk_add_f32 v[118:119], v[112:113], v[166:167]
	v_mul_f32_e32 v113, v121, v121
	v_mul_f32_e32 v112, v119, v119
	v_fmac_f32_e32 v112, v118, v118
	v_fmac_f32_e32 v113, v120, v120
	v_cndmask_b32_e32 v116, v189, v116, vcc
	v_add_f32_e32 v112, v112, v113
	v_lshlrev_b32_e32 v116, 2, v116
	v_add_f32_e32 v112, v122, v112
	ds_bpermute_b32 v113, v116, v112
	v_cmp_lt_i32_e32 vcc, v161, v117
	global_store_dwordx4 v[170:171], v[118:121], off offset:576
	s_waitcnt lgkmcnt(0)
	v_add_f32_e32 v115, v112, v113
	v_cndmask_b32_e32 v114, v189, v161, vcc
	v_lshlrev_b32_e32 v114, 2, v114
	ds_bpermute_b32 v117, v114, v115
	v_cvt_pk_bf16_f32 v112, v118, v119
	v_cvt_pk_bf16_f32 v113, v120, v121
	global_store_dwordx2 v[172:173], v[112:113], off offset:288
	v_lshl_add_u64 v[112:113], v[156:157], 2, s[2:3]
	s_and_saveexec_b64 s[22:23], s[38:39]
	s_cbranch_execz .LBB0_1186
	s_waitcnt lgkmcnt(0)
	v_add_f32_e32 v115, v115, v117
	global_atomic_add_f32 v[112:113], v115, off

; #define PG8_STAGE(bufoff, gbase, voff) do { _Pragma("unroll") for (int _i = 0; _i < 2; ++_i) \
;         __builtin_amdgcn_global_load_lds((const unsigned*)((const char*)(gbase) + (voff)[_i]), (PG8_LAS unsigned*)(lds + (bufoff) + ldsw + _i * 8192), 16, 0, 0); } while (0)
; #define PG8_LDA(dst, b, h) do { _Pragma("unroll") for (int m = 0; m < 4; ++m) _Pragma("unroll") for (int k = 0; k < 2; ++k) dst[m][k] = *(const PG8_LAS bf16x8*)(lds + PG8_SA(b, h) + aoff + m * 2048 + k * 1024); } while (0)
; #define PG8_LDB(dst, b, h) do { _Pragma("unroll") for (int n = 0; n < 2; ++n) _Pragma("unroll") for (int k = 0; k < 2; ++k) dst[n][k] = *(const PG8_LAS bf16x8*)(lds + PG8_SB(b, h) + boff + n * 2048 + k * 1024); } while (0)
; #define PG8_MMA(ai, bj, At, Bt) do { __builtin_amdgcn_s_setprio(1); _Pragma("unroll") for (int m = 0; m < 4; ++m) _Pragma("unroll") for (int n = 0; n < 2; ++n) _Pragma("unroll") for (int k = 0; k < 2; ++k) \
;         acc[ai][bj][m][n] = __builtin_amdgcn_mfma_f32_16x16x32_bf16(Bt[n][k], At[m][k], acc[ai][bj][m][n], 0, 0, 0); __builtin_amdgcn_s_setprio(0); } while (0)
; #define PG8_WAIT_L(n) asm volatile("s_waitcnt lgkmcnt(" #n ")" ::: "memory")
; #define PG8_BAR __builtin_amdgcn_s_barrier()
; #define PG8_SCHED __builtin_amdgcn_sched_barrier(0)
; template <class Epi, class Sched, bool STAMP = false>
; __device__ __forceinline__ void gemm_phase(PG8_LAS unsigned char* lds, const Gemm g, const Sched& S, const Epi& E, unsigned long long* stamps) {
;     ...
;             const bool last = (t == nt - 2);
;             const char* a1 = cA + (size_t)(t + 1) * kstep;
;             const char* a2 = last ? nA : cA + (size_t)(t + 2) * kstep; const char* b2 = last ? nB : cB + (size_t)(t + 2) * kstep;
;             const char* a3 = a2 + kstep; const char* b3 = b2 + kstep;
;             if (last && has_next) S.a_ready(nxt);
;             PG8_LDB(B0, 0, 0); PG8_SCHED; PG8_LDA(At, 0, 0); PG8_STAGE(PG8_SA(1, 1), a1 + hstep, voffA);
;             PG8_WAIT_L(8); PG8_BAR; PG8_WAIT_L(0); PG8_MMA(0, 0, At, B0); PG8_BAR; PG8_SCHED;
;             PG8_LDB(B1, 0, 1); PG8_STAGE(PG8_SB(0, 0), b2, voffB);
;             PG8_BAR; PG8_WAIT_L(0); PG8_MMA(0, 1, At, B1); PG8_BAR;
;             PG8_LDA(At, 0, 1); PG8_STAGE(PG8_SA(0, 0), a2, voffA);
;             PG8_BAR; PG8_WAIT_L(0); PG8_MMA(1, 0, At, B0); PG8_BAR; PG8_SCHED;
.LBB0_1207:
	s_add_u32 s6, s4, 0x100
	s_addc_u32 s7, s5, 0
	s_cmp_lg_u32 s39, 4
	s_cselect_b32 s12, s6, 0
	s_cselect_b32 s13, s7, 0
	s_add_u32 s20, s2, s12
	s_addc_u32 s21, s3, s13
	s_add_i32 s14, 0, 0x10000
	v_add_u32_e32 v157, s14, v155
	ds_read_b128 v[158:161], v157
	ds_read_b128 v[162:165], v157 offset:1024
	ds_read_b128 v[166:169], v157 offset:2048
	ds_read_b128 v[170:173], v157 offset:3072
	s_add_u32 s12, s0, s12
	s_addc_u32 s13, s1, s13
	v_lshl_add_u64 v[182:183], v[150:151], 0, s[4:5]
	s_add_i32 m0, s27, 0xc000
	ds_read_b128 v[174:177], v156
	ds_read_b128 v[178:181], v156 offset:1024
	ds_read_b128 v[192:195], v156 offset:2048
	ds_read_b128 v[196:199], v156 offset:3072
	ds_read_b128 v[200:203], v156 offset:4096
	ds_read_b128 v[204:207], v156 offset:5120
	ds_read_b128 v[208:211], v156 offset:6144
	ds_read_b128 v[212:215], v156 offset:7168
	global_load_lds_dwordx4 v[182:183], off
	v_lshl_add_u64 v[182:183], v[152:153], 0, s[4:5]
	s_add_i32 m0, s27, 0xe000
	s_nop 0
	global_load_lds_dwordx4 v[182:183], off
	s_waitcnt lgkmcnt(8)
	s_barrier
	s_waitcnt lgkmcnt(0)
	s_waitcnt lgkmcnt(0)
	v_mfma_f32_16x16x32_bf16 v[124:127], v[158:161], v[174:177], v[124:127]
	v_mfma_f32_16x16x32_bf16 v[120:123], v[166:169], v[174:177], v[120:123]
	v_mfma_f32_16x16x32_bf16 v[116:119], v[158:161], v[192:195], v[116:119]
	v_mfma_f32_16x16x32_bf16 v[112:115], v[166:169], v[192:195], v[112:115]
	v_mfma_f32_16x16x32_bf16 v[104:107], v[158:161], v[200:203], v[104:107]
	v_mfma_f32_16x16x32_bf16 v[96:99], v[166:169], v[200:203], v[96:99]
	v_mfma_f32_16x16x32_bf16 v[88:91], v[158:161], v[208:211], v[88:91]
	v_mfma_f32_16x16x32_bf16 v[80:83], v[166:169], v[208:211], v[80:83]
	v_mfma_f32_16x16x32_bf16 v[124:127], v[162:165], v[178:181], v[124:127]
	v_mfma_f32_16x16x32_bf16 v[120:123], v[170:173], v[178:181], v[120:123]
	v_mfma_f32_16x16x32_bf16 v[116:119], v[162:165], v[196:199], v[116:119]
	v_mfma_f32_16x16x32_bf16 v[112:115], v[170:173], v[196:199], v[112:115]
	v_mfma_f32_16x16x32_bf16 v[104:107], v[162:165], v[204:207], v[104:107]
	v_mfma_f32_16x16x32_bf16 v[96:99], v[170:173], v[204:207], v[96:99]
	v_mfma_f32_16x16x32_bf16 v[88:91], v[162:165], v[212:215], v[88:91]
	v_mfma_f32_16x16x32_bf16 v[80:83], v[170:173], v[212:215], v[80:83]
	s_barrier
	s_add_i32 s15, 0, 0x14000
	s_add_i32 s4, s14, s26
	v_add_u32_e32 v157, s15, v155
	v_lshl_add_u64 v[182:183], s[12:13], 0, v[128:129]
	s_mov_b32 m0, s4
	ds_read_b128 v[216:219], v157
	ds_read_b128 v[220:223], v157 offset:1024
	ds_read_b128 v[224:227], v157 offset:2048
	ds_read_b128 v[228:231], v157 offset:3072
	global_load_lds_dwordx4 v[182:183], off
	v_lshl_add_u64 v[232:233], s[12:13], 0, v[148:149]
	s_add_i32 m0, s4, 0x2000
	s_nop 0
	global_load_lds_dwordx4 v[232:233], off
	s_barrier
	s_waitcnt lgkmcnt(0)
	s_waitcnt lgkmcnt(0)
	v_mfma_f32_16x16x32_bf16 v[108:111], v[216:219], v[174:177], v[108:111]
	v_mfma_f32_16x16x32_bf16 v[100:103], v[224:227], v[174:177], v[100:103]
	v_mfma_f32_16x16x32_bf16 v[92:95], v[216:219], v[192:195], v[92:95]
	v_mfma_f32_16x16x32_bf16 v[84:87], v[224:227], v[192:195], v[84:87]
	v_mfma_f32_16x16x32_bf16 v[76:79], v[216:219], v[200:203], v[76:79]
	v_mfma_f32_16x16x32_bf16 v[72:75], v[224:227], v[200:203], v[72:75]
	v_mfma_f32_16x16x32_bf16 v[68:71], v[216:219], v[208:211], v[68:71]
	v_mfma_f32_16x16x32_bf16 v[64:67], v[224:227], v[208:211], v[64:67]
	v_mfma_f32_16x16x32_bf16 v[108:111], v[220:223], v[178:181], v[108:111]
	v_mfma_f32_16x16x32_bf16 v[100:103], v[228:231], v[178:181], v[100:103]
	v_mfma_f32_16x16x32_bf16 v[92:95], v[220:223], v[196:199], v[92:95]
	v_mfma_f32_16x16x32_bf16 v[84:87], v[228:231], v[196:199], v[84:87]
	v_mfma_f32_16x16x32_bf16 v[76:79], v[220:223], v[204:207], v[76:79]
	v_mfma_f32_16x16x32_bf16 v[72:75], v[228:231], v[204:207], v[72:75]
	v_mfma_f32_16x16x32_bf16 v[68:71], v[220:223], v[212:215], v[68:71]
	v_mfma_f32_16x16x32_bf16 v[64:67], v[228:231], v[212:215], v[64:67]
	s_mov_b32 m0, s27
	v_lshl_add_u64 v[234:235], s[20:21], 0, v[128:129]
	s_barrier
	ds_read_b128 v[174:177], v156 offset:16384
	ds_read_b128 v[178:181], v156 offset:17408
	ds_read_b128 v[192:195], v156 offset:18432
	ds_read_b128 v[196:199], v156 offset:19456
	ds_read_b128 v[200:203], v156 offset:20480
	ds_read_b128 v[204:207], v156 offset:21504
	ds_read_b128 v[208:211], v156 offset:22528
	ds_read_b128 v[212:215], v156 offset:23552
	global_load_lds_dwordx4 v[234:235], off
	v_lshl_add_u64 v[236:237], s[20:21], 0, v[148:149]
	s_mov_b32 m0, s30
	s_nop 0
	global_load_lds_dwordx4 v[236:237], off
	s_barrier
	s_waitcnt lgkmcnt(0)
	s_waitcnt lgkmcnt(0)
	v_mfma_f32_16x16x32_bf16 v[60:63], v[158:161], v[174:177], v[60:63]
	v_mfma_f32_16x16x32_bf16 v[56:59], v[166:169], v[174:177], v[56:59]
	v_mfma_f32_16x16x32_bf16 v[52:55], v[158:161], v[192:195], v[52:55]
	v_mfma_f32_16x16x32_bf16 v[48:51], v[166:169], v[192:195], v[48:51]
	v_mfma_f32_16x16x32_bf16 v[36:39], v[158:161], v[200:203], v[36:39]
	v_mfma_f32_16x16x32_bf16 v[32:35], v[166:169], v[200:203], v[32:35]
	v_mfma_f32_16x16x32_bf16 v[20:23], v[158:161], v[208:211], v[20:23]
	v_mfma_f32_16x16x32_bf16 v[16:19], v[166:169], v[208:211], v[16:19]
	v_mfma_f32_16x16x32_bf16 v[60:63], v[162:165], v[178:181], v[60:63]
	v_mfma_f32_16x16x32_bf16 v[56:59], v[170:173], v[178:181], v[56:59]
	v_mfma_f32_16x16x32_bf16 v[52:55], v[162:165], v[196:199], v[52:55]
	v_mfma_f32_16x16x32_bf16 v[48:51], v[170:173], v[196:199], v[48:51]
	v_mfma_f32_16x16x32_bf16 v[36:39], v[162:165], v[204:207], v[36:39]
	v_mfma_f32_16x16x32_bf16 v[32:35], v[170:173], v[204:207], v[32:35]
	v_mfma_f32_16x16x32_bf16 v[20:23], v[162:165], v[212:215], v[20:23]
	v_mfma_f32_16x16x32_bf16 v[16:19], v[170:173], v[212:215], v[16:19]
	s_barrier
; #define PG8_STAGE(bufoff, gbase, voff) do { _Pragma("unroll") for (int _i = 0; _i < 2; ++_i) \
;         __builtin_amdgcn_global_load_lds((const unsigned*)((const char*)(gbase) + (voff)[_i]), (PG8_LAS unsigned*)(lds + (bufoff) + ldsw + _i * 8192), 16, 0, 0); } while (0)
; #define PG8_LDA(dst, b, h) do { _Pragma("unroll") for (int m = 0; m < 4; ++m) _Pragma("unroll") for (int k = 0; k < 2; ++k) dst[m][k] = *(const PG8_LAS bf16x8*)(lds + PG8_SA(b, h) + aoff + m * 2048 + k * 1024); } while (0)
; #define PG8_LDB(dst, b, h) do { _Pragma("unroll") for (int n = 0; n < 2; ++n) _Pragma("unroll") for (int k = 0; k < 2; ++k) dst[n][k] = *(const PG8_LAS bf16x8*)(lds + PG8_SB(b, h) + boff + n * 2048 + k * 1024); } while (0)
; #define PG8_MMA(ai, bj, At, Bt) do { __builtin_amdgcn_s_setprio(1); _Pragma("unroll") for (int m = 0; m < 4; ++m) _Pragma("unroll") for (int n = 0; n < 2; ++n) _Pragma("unroll") for (int k = 0; k < 2; ++k) \
;         acc[ai][bj][m][n] = __builtin_amdgcn_mfma_f32_16x16x32_bf16(Bt[n][k], At[m][k], acc[ai][bj][m][n], 0, 0, 0); __builtin_amdgcn_s_setprio(0); } while (0)
; #define PG8_WAIT_V(n) asm volatile("s_waitcnt vmcnt(" #n ")" ::: "memory")
; #define PG8_WAIT_L(n) asm volatile("s_waitcnt lgkmcnt(" #n ")" ::: "memory")
; #define PG8_BAR __builtin_amdgcn_s_barrier()
; #define PG8_SCHED __builtin_amdgcn_sched_barrier(0)
; template <class Epi, class Sched, bool STAMP = false>
; __device__ __forceinline__ void gemm_phase(PG8_LAS unsigned char* lds, const Gemm g, const Sched& S, const Epi& E, unsigned long long* stamps) {
;     ...
;             PG8_STAGE(PG8_SB(0, 1), b2 + hstep, voffB);
;             PG8_WAIT_V(6); PG8_BAR; PG8_MMA(1, 1, At, B1); PG8_BAR;
;             PG8_LDB(B0, 1, 0); PG8_SCHED; PG8_LDA(At, 1, 0); PG8_STAGE(PG8_SA(0, 1), a2 + hstep, voffA);
;             PG8_WAIT_L(8); PG8_BAR; PG8_WAIT_L(0); PG8_MMA(0, 0, At, B0); PG8_BAR; PG8_SCHED;
;             PG8_LDB(B1, 1, 1); PG8_STAGE(PG8_SB(1, 0), b3, voffB);
;             PG8_BAR; PG8_WAIT_L(0); PG8_MMA(0, 1, At, B1); PG8_BAR;
;             PG8_LDA(At, 1, 1); PG8_STAGE(PG8_SA(1, 0), a3, voffA);
	s_add_u32 s4, s12, 0x100000
	s_addc_u32 s5, s13, 0
	s_add_i32 s14, s15, s26
	v_lshl_add_u64 v[158:159], s[4:5], 0, v[128:129]
	s_mov_b32 m0, s14
	s_nop 0
	global_load_lds_dwordx4 v[158:159], off
	v_lshl_add_u64 v[158:159], s[4:5], 0, v[148:149]
	s_add_i32 m0, s14, 0x2000
	s_nop 0
	global_load_lds_dwordx4 v[158:159], off
	s_waitcnt vmcnt(6)
	s_barrier
	v_mfma_f32_16x16x32_bf16 v[44:47], v[216:219], v[174:177], v[44:47]
	v_mfma_f32_16x16x32_bf16 v[40:43], v[224:227], v[174:177], v[40:43]
	v_mfma_f32_16x16x32_bf16 v[28:31], v[216:219], v[192:195], v[28:31]
	v_mfma_f32_16x16x32_bf16 v[24:27], v[224:227], v[192:195], v[24:27]
	v_mfma_f32_16x16x32_bf16 v[12:15], v[216:219], v[200:203], v[12:15]
	v_mfma_f32_16x16x32_bf16 v[8:11], v[224:227], v[200:203], v[8:11]
	v_mfma_f32_16x16x32_bf16 v[4:7], v[216:219], v[208:211], v[4:7]
	v_mfma_f32_16x16x32_bf16 v[0:3], v[224:227], v[208:211], v[0:3]
	v_mfma_f32_16x16x32_bf16 v[44:47], v[220:223], v[178:181], v[44:47]
	v_mfma_f32_16x16x32_bf16 v[40:43], v[228:231], v[178:181], v[40:43]
	v_mfma_f32_16x16x32_bf16 v[28:31], v[220:223], v[196:199], v[28:31]
	v_mfma_f32_16x16x32_bf16 v[24:27], v[228:231], v[196:199], v[24:27]
	v_mfma_f32_16x16x32_bf16 v[12:15], v[220:223], v[204:207], v[12:15]
	v_mfma_f32_16x16x32_bf16 v[8:11], v[228:231], v[204:207], v[8:11]
	v_mfma_f32_16x16x32_bf16 v[4:7], v[220:223], v[212:215], v[4:7]
	v_mfma_f32_16x16x32_bf16 v[0:3], v[228:231], v[212:215], v[0:3]
	s_add_i32 s14, 0, 0x18000
	v_add_u32_e32 v157, s14, v155
	s_barrier
	ds_read_b128 v[158:161], v157
	ds_read_b128 v[162:165], v157 offset:1024
	ds_read_b128 v[166:169], v157 offset:2048
	ds_read_b128 v[170:173], v157 offset:3072
	s_add_u32 s4, s20, 0x100000
	s_addc_u32 s5, s21, 0
	s_mov_b32 m0, s31
	v_lshl_add_u64 v[216:217], s[4:5], 0, v[128:129]
	ds_read_b128 v[174:177], v156 offset:32768
	ds_read_b128 v[178:181], v156 offset:33792
	ds_read_b128 v[192:195], v156 offset:34816
	ds_read_b128 v[196:199], v156 offset:35840
	ds_read_b128 v[200:203], v156 offset:36864
	ds_read_b128 v[204:207], v156 offset:37888
	ds_read_b128 v[208:211], v156 offset:38912
	ds_read_b128 v[212:215], v156 offset:39936
	global_load_lds_dwordx4 v[216:217], off
	v_lshl_add_u64 v[216:217], s[4:5], 0, v[148:149]
	s_mov_b32 m0, s34
	s_nop 0
	global_load_lds_dwordx4 v[216:217], off
	s_waitcnt lgkmcnt(8)
	s_barrier
	s_waitcnt lgkmcnt(0)
	s_waitcnt lgkmcnt(0)
	v_mfma_f32_16x16x32_bf16 v[124:127], v[158:161], v[174:177], v[124:127]
	v_mfma_f32_16x16x32_bf16 v[120:123], v[166:169], v[174:177], v[120:123]
	v_mfma_f32_16x16x32_bf16 v[116:119], v[158:161], v[192:195], v[116:119]
	v_mfma_f32_16x16x32_bf16 v[112:115], v[166:169], v[192:195], v[112:115]
	v_mfma_f32_16x16x32_bf16 v[104:107], v[158:161], v[200:203], v[104:107]
	v_mfma_f32_16x16x32_bf16 v[96:99], v[166:169], v[200:203], v[96:99]
	v_mfma_f32_16x16x32_bf16 v[88:91], v[158:161], v[208:211], v[88:91]
	v_mfma_f32_16x16x32_bf16 v[80:83], v[166:169], v[208:211], v[80:83]
	v_mfma_f32_16x16x32_bf16 v[124:127], v[162:165], v[178:181], v[124:127]
	v_mfma_f32_16x16x32_bf16 v[120:123], v[170:173], v[178:181], v[120:123]
	v_mfma_f32_16x16x32_bf16 v[116:119], v[162:165], v[196:199], v[116:119]
	v_mfma_f32_16x16x32_bf16 v[112:115], v[170:173], v[196:199], v[112:115]
	v_mfma_f32_16x16x32_bf16 v[104:107], v[162:165], v[204:207], v[104:107]
	v_mfma_f32_16x16x32_bf16 v[96:99], v[170:173], v[204:207], v[96:99]
	v_mfma_f32_16x16x32_bf16 v[88:91], v[162:165], v[212:215], v[88:91]
	v_mfma_f32_16x16x32_bf16 v[80:83], v[170:173], v[212:215], v[80:83]
	s_barrier
	s_add_i32 s15, 0, 0x1c000
	s_add_i32 s4, s14, s26
	v_add_u32_e32 v157, s15, v155
	v_lshl_add_u64 v[182:183], v[182:183], 0, s[18:19]
	s_mov_b32 m0, s4
	ds_read_b128 v[216:219], v157
	ds_read_b128 v[220:223], v157 offset:1024
	ds_read_b128 v[224:227], v157 offset:2048
	ds_read_b128 v[228:231], v157 offset:3072
	global_load_lds_dwordx4 v[182:183], off
	v_lshl_add_u64 v[182:183], v[232:233], 0, s[18:19]
	s_add_i32 m0, s4, 0x2000
	s_nop 0
	global_load_lds_dwordx4 v[182:183], off
	s_barrier
	s_waitcnt lgkmcnt(0)
	s_waitcnt lgkmcnt(0)
	v_mfma_f32_16x16x32_bf16 v[108:111], v[216:219], v[174:177], v[108:111]
	v_mfma_f32_16x16x32_bf16 v[100:103], v[224:227], v[174:177], v[100:103]
	v_mfma_f32_16x16x32_bf16 v[92:95], v[216:219], v[192:195], v[92:95]
	v_mfma_f32_16x16x32_bf16 v[84:87], v[224:227], v[192:195], v[84:87]
	v_mfma_f32_16x16x32_bf16 v[76:79], v[216:219], v[200:203], v[76:79]
	v_mfma_f32_16x16x32_bf16 v[72:75], v[224:227], v[200:203], v[72:75]
	v_mfma_f32_16x16x32_bf16 v[68:71], v[216:219], v[208:211], v[68:71]
	v_mfma_f32_16x16x32_bf16 v[64:67], v[224:227], v[208:211], v[64:67]
	v_mfma_f32_16x16x32_bf16 v[108:111], v[220:223], v[178:181], v[108:111]
	v_mfma_f32_16x16x32_bf16 v[100:103], v[228:231], v[178:181], v[100:103]
	v_mfma_f32_16x16x32_bf16 v[92:95], v[220:223], v[196:199], v[92:95]
	v_mfma_f32_16x16x32_bf16 v[84:87], v[228:231], v[196:199], v[84:87]
	v_mfma_f32_16x16x32_bf16 v[76:79], v[220:223], v[204:207], v[76:79]
	v_mfma_f32_16x16x32_bf16 v[72:75], v[228:231], v[204:207], v[72:75]
	v_mfma_f32_16x16x32_bf16 v[68:71], v[220:223], v[212:215], v[68:71]
	v_mfma_f32_16x16x32_bf16 v[64:67], v[228:231], v[212:215], v[64:67]
	s_mov_b32 m0, s37
	v_lshl_add_u64 v[182:183], v[234:235], 0, s[18:19]
	s_barrier
	ds_read_b128 v[174:177], v156 offset:49152
	ds_read_b128 v[178:181], v156 offset:50176
	ds_read_b128 v[192:195], v156 offset:51200
	ds_read_b128 v[196:199], v156 offset:52224
	ds_read_b128 v[200:203], v156 offset:53248
	ds_read_b128 v[204:207], v156 offset:54272
	ds_read_b128 v[208:211], v156 offset:55296
	ds_read_b128 v[212:215], v156 offset:56320
	global_load_lds_dwordx4 v[182:183], off
	v_lshl_add_u64 v[182:183], v[236:237], 0, s[18:19]
	s_mov_b32 m0, s38
	s_nop 0
	global_load_lds_dwordx4 v[182:183], off
	s_barrier
; #define PG8_STAGE(bufoff, gbase, voff) do { _Pragma("unroll") for (int _i = 0; _i < 2; ++_i) \
;         __builtin_amdgcn_global_load_lds((const unsigned*)((const char*)(gbase) + (voff)[_i]), (PG8_LAS unsigned*)(lds + (bufoff) + ldsw + _i * 8192), 16, 0, 0); } while (0)
; #define PG8_MMA(ai, bj, At, Bt) do { __builtin_amdgcn_s_setprio(1); _Pragma("unroll") for (int m = 0; m < 4; ++m) _Pragma("unroll") for (int n = 0; n < 2; ++n) _Pragma("unroll") for (int k = 0; k < 2; ++k) \
;         acc[ai][bj][m][n] = __builtin_amdgcn_mfma_f32_16x16x32_bf16(Bt[n][k], At[m][k], acc[ai][bj][m][n], 0, 0, 0); __builtin_amdgcn_s_setprio(0); } while (0)
; #define PG8_WAIT_V(n) asm volatile("s_waitcnt vmcnt(" #n ")" ::: "memory")
; #define PG8_WAIT_L(n) asm volatile("s_waitcnt lgkmcnt(" #n ")" ::: "memory")
; #define PG8_BAR __builtin_amdgcn_s_barrier()
; #define PG8_SCHED __builtin_amdgcn_sched_barrier(0)
; template <class Epi, class Sched, bool STAMP = false>
; __device__ __forceinline__ void gemm_phase(PG8_LAS unsigned char* lds, const Gemm g, const Sched& S, const Epi& E, unsigned long long* stamps) {
;     ...
;             PG8_BAR; PG8_WAIT_L(0); PG8_MMA(1, 0, At, B0); PG8_BAR; PG8_SCHED;
;             PG8_STAGE(PG8_SB(1, 1), b3 + hstep, voffB);
;             PG8_WAIT_V(6); PG8_BAR; PG8_MMA(1, 1, At, B1); PG8_BAR;
;     __device__ __forceinline__ void operator()(const f32x4 (&acc)[2][2][4][2], const pg8::Unit& u, int wr, int wc, int fr, int fq) const {
;         const int row0 = (u.pm - 64) * 256 + wr * 64 + fr, col0 = u.pn * 256 + wc * 32 + 4 * fq;
; #pragma unroll
;         for (int ai = 0; ai < 2; ++ai)
; #pragma unroll
;             for (int m = 0; m < 4; ++m) { float* xp = PART + (size_t)(row0 + ai * 128 + m * 16) * ldp + col0;
; #pragma unroll
;                 for (int bj = 0; bj < 2; ++bj)
; #pragma unroll
;                     for (int n = 0; n < 2; ++n) *(f32x4*)(xp + bj * 128 + n * 16) = acc[ai][bj][m][n]; }
;     }
	s_waitcnt lgkmcnt(0)
	s_waitcnt lgkmcnt(0)
	v_mfma_f32_16x16x32_bf16 v[60:63], v[158:161], v[174:177], v[60:63]
	v_mfma_f32_16x16x32_bf16 v[56:59], v[166:169], v[174:177], v[56:59]
	v_mfma_f32_16x16x32_bf16 v[52:55], v[158:161], v[192:195], v[52:55]
	v_mfma_f32_16x16x32_bf16 v[48:51], v[166:169], v[192:195], v[48:51]
	v_mfma_f32_16x16x32_bf16 v[36:39], v[158:161], v[200:203], v[36:39]
	v_mfma_f32_16x16x32_bf16 v[32:35], v[166:169], v[200:203], v[32:35]
	v_mfma_f32_16x16x32_bf16 v[20:23], v[158:161], v[208:211], v[20:23]
	v_mfma_f32_16x16x32_bf16 v[16:19], v[166:169], v[208:211], v[16:19]
	v_mfma_f32_16x16x32_bf16 v[60:63], v[162:165], v[178:181], v[60:63]
	v_mfma_f32_16x16x32_bf16 v[56:59], v[170:173], v[178:181], v[56:59]
	v_mfma_f32_16x16x32_bf16 v[52:55], v[162:165], v[196:199], v[52:55]
	v_mfma_f32_16x16x32_bf16 v[48:51], v[170:173], v[196:199], v[48:51]
	v_mfma_f32_16x16x32_bf16 v[36:39], v[162:165], v[204:207], v[36:39]
	v_mfma_f32_16x16x32_bf16 v[32:35], v[170:173], v[204:207], v[32:35]
	v_mfma_f32_16x16x32_bf16 v[20:23], v[162:165], v[212:215], v[20:23]
	v_mfma_f32_16x16x32_bf16 v[16:19], v[170:173], v[212:215], v[16:19]
	s_barrier
	s_add_u32 s4, s12, 0x100080
	s_addc_u32 s5, s13, 0
	s_add_i32 s12, s15, s26
	v_lshl_add_u64 v[158:159], s[4:5], 0, v[128:129]
	s_mov_b32 m0, s12
	s_nop 0
	global_load_lds_dwordx4 v[158:159], off
	v_lshl_add_u64 v[158:159], s[4:5], 0, v[148:149]
	s_add_i32 m0, s12, 0x2000
	s_nop 0
	global_load_lds_dwordx4 v[158:159], off
	s_waitcnt vmcnt(6)
	s_barrier
	v_mfma_f32_16x16x32_bf16 v[44:47], v[216:219], v[174:177], v[44:47]
	v_mfma_f32_16x16x32_bf16 v[40:43], v[224:227], v[174:177], v[40:43]
	v_mfma_f32_16x16x32_bf16 v[28:31], v[216:219], v[192:195], v[28:31]
	v_mfma_f32_16x16x32_bf16 v[24:27], v[224:227], v[192:195], v[24:27]
	v_mfma_f32_16x16x32_bf16 v[12:15], v[216:219], v[200:203], v[12:15]
	v_mfma_f32_16x16x32_bf16 v[8:11], v[224:227], v[200:203], v[8:11]
	v_mfma_f32_16x16x32_bf16 v[4:7], v[216:219], v[208:211], v[4:7]
	v_mfma_f32_16x16x32_bf16 v[0:3], v[224:227], v[208:211], v[0:3]
	v_mfma_f32_16x16x32_bf16 v[44:47], v[220:223], v[178:181], v[44:47]
	v_mfma_f32_16x16x32_bf16 v[40:43], v[228:231], v[178:181], v[40:43]
	v_mfma_f32_16x16x32_bf16 v[28:31], v[220:223], v[196:199], v[28:31]
	v_mfma_f32_16x16x32_bf16 v[24:27], v[228:231], v[196:199], v[24:27]
	v_mfma_f32_16x16x32_bf16 v[12:15], v[220:223], v[204:207], v[12:15]
	v_mfma_f32_16x16x32_bf16 v[8:11], v[228:231], v[204:207], v[8:11]
	v_mfma_f32_16x16x32_bf16 v[4:7], v[220:223], v[212:215], v[4:7]
	v_mfma_f32_16x16x32_bf16 v[0:3], v[228:231], v[212:215], v[0:3]
	s_add_i32 s39, s39, 2
	s_cmp_gt_u32 s39, 5
	s_mov_b64 s[4:5], s[6:7]
	s_barrier
	s_cbranch_scc0 .LBB0_1207
	s_lshl_b32 s0, s25, 22
	s_add_u32 s0, s10, s0
	s_addc_u32 s1, s42, 0
	s_add_u32 s0, s0, 0xdd00000
	s_addc_u32 s1, s1, 0
	s_lshl_b32 s2, s24, 8
	s_add_i32 s2, s2, s35
	v_add_u32_e32 v150, s2, v154
	v_add_u32_e32 v148, 0xffffc000, v150
	s_lshl_b32 s2, s23, 8
	v_lshl_or_b32 v128, v139, 2, s2
	v_ashrrev_i32_e32 v149, 31, v148
	v_or_b32_e32 v128, s36, v128
	v_lshlrev_b64 v[148:149], 12, v[148:149]
	v_lshl_add_u64 v[148:149], s[0:1], 0, v[148:149]
	v_lshlrev_b32_e32 v128, 2, v128
	v_lshl_add_u64 v[148:149], v[148:149], 0, v[128:129]
	global_store_dwordx4 v[148:149], v[124:127], off
	global_store_dwordx4 v[148:149], v[120:123], off offset:64
	global_store_dwordx4 v[148:149], v[108:111], off offset:512
	global_store_dwordx4 v[148:149], v[100:103], off offset:576
	s_cmpk_lt_u32 s22, 0x100
	v_readlane_b32 s39, v242, 28
	v_add_u32_e32 v100, 0xffffc010, v150
	v_ashrrev_i32_e32 v101, 31, v100
	v_lshlrev_b64 v[100:101], 12, v[100:101]
	v_lshl_add_u64 v[100:101], s[0:1], 0, v[100:101]
	v_lshl_add_u64 v[100:101], v[100:101], 0, v[128:129]
	global_store_dwordx4 v[100:101], v[116:119], off
	global_store_dwordx4 v[100:101], v[112:115], off offset:64
	global_store_dwordx4 v[100:101], v[92:95], off offset:512
	global_store_dwordx4 v[100:101], v[84:87], off offset:576
	s_mov_b32 s38, 0x1ffff
	s_nop 0
	v_add_u32_e32 v84, 0xffffc020, v150
	v_ashrrev_i32_e32 v85, 31, v84
	v_lshlrev_b64 v[84:85], 12, v[84:85]
	v_lshl_add_u64 v[84:85], s[0:1], 0, v[84:85]
	v_lshl_add_u64 v[84:85], v[84:85], 0, v[128:129]
	global_store_dwordx4 v[84:85], v[104:107], off
	global_store_dwordx4 v[84:85], v[96:99], off offset:64
	global_store_dwordx4 v[84:85], v[76:79], off offset:512
	global_store_dwordx4 v[84:85], v[72:75], off offset:576
	s_nop 1
	v_add_u32_e32 v72, 0xffffc030, v150
	v_ashrrev_i32_e32 v73, 31, v72
	v_lshlrev_b64 v[72:73], 12, v[72:73]
	v_lshl_add_u64 v[72:73], s[0:1], 0, v[72:73]
	v_lshl_add_u64 v[72:73], v[72:73], 0, v[128:129]
	s_mov_b64 s[0:1], 0x80000
	global_store_dwordx4 v[72:73], v[88:91], off
	global_store_dwordx4 v[72:73], v[80:83], off offset:64
	global_store_dwordx4 v[72:73], v[68:71], off offset:512
	global_store_dwordx4 v[72:73], v[64:67], off offset:576
	s_nop 1
	v_lshl_add_u64 v[64:65], v[148:149], 0, s[0:1]
	s_mov_b32 s0, 0x80000
	v_add_co_u32_e32 v66, vcc, s0, v148
	s_mov_b64 s[0:1], 0x90000
	s_nop 0
	v_addc_co_u32_e32 v67, vcc, 0, v149, vcc
	global_store_dwordx4 v[66:67], v[60:63], off
	global_store_dwordx4 v[64:65], v[56:59], off offset:64
	global_store_dwordx4 v[64:65], v[44:47], off offset:512
	global_store_dwordx4 v[64:65], v[40:43], off offset:576
	s_nop 1
	v_lshl_add_u64 v[40:41], v[148:149], 0, s[0:1]
	s_mov_b32 s0, 0x90000
	v_add_co_u32_e32 v42, vcc, s0, v148
	s_mov_b64 s[0:1], 0xa0000
	s_nop 0
	v_addc_co_u32_e32 v43, vcc, 0, v149, vcc
	global_store_dwordx4 v[42:43], v[52:55], off
	global_store_dwordx4 v[40:41], v[48:51], off offset:64
	global_store_dwordx4 v[40:41], v[28:31], off offset:512
	global_store_dwordx4 v[40:41], v[24:27], off offset:576
	s_nop 1
	v_lshl_add_u64 v[24:25], v[148:149], 0, s[0:1]
	s_mov_b32 s0, 0xa0000
	v_add_co_u32_e32 v26, vcc, s0, v148
	s_mov_b64 s[0:1], 0xb0000
	s_nop 0
	v_addc_co_u32_e32 v27, vcc, 0, v149, vcc
	global_store_dwordx4 v[26:27], v[36:39], off
	global_store_dwordx4 v[24:25], v[32:35], off offset:64
	global_store_dwordx4 v[24:25], v[12:15], off offset:512
	global_store_dwordx4 v[24:25], v[8:11], off offset:576
	s_nop 1
	v_add_co_u32_e32 v10, vcc, 0xb0000, v148
	v_lshl_add_u64 v[8:9], v[148:149], 0, s[0:1]
	s_nop 0
	v_addc_co_u32_e32 v11, vcc, 0, v149, vcc
	global_store_dwordx4 v[10:11], v[20:23], off
	global_store_dwordx4 v[8:9], v[16:19], off offset:64
	global_store_dwordx4 v[8:9], v[4:7], off offset:512
	global_store_dwordx4 v[8:9], v[0:3], off offset:576
	s_waitcnt vmcnt(0)
	s_cbranch_scc0 .LBB0_1210
	s_barrier

; #define PG8_STAGE(bufoff, gbase, voff) do { _Pragma("unroll") for (int _i = 0; _i < 2; ++_i) \
;         __builtin_amdgcn_global_load_lds((const unsigned*)((const char*)(gbase) + (voff)[_i]), (PG8_LAS unsigned*)(lds + (bufoff) + ldsw + _i * 8192), 16, 0, 0); } while (0)
; #define PG8_LDA(dst, b, h) do { _Pragma("unroll") for (int m = 0; m < 4; ++m) _Pragma("unroll") for (int k = 0; k < 2; ++k) dst[m][k] = *(const PG8_LAS bf16x8*)(lds + PG8_SA(b, h) + aoff + m * 2048 + k * 1024); } while (0)
; #define PG8_LDB(dst, b, h) do { _Pragma("unroll") for (int n = 0; n < 2; ++n) _Pragma("unroll") for (int k = 0; k < 2; ++k) dst[n][k] = *(const PG8_LAS bf16x8*)(lds + PG8_SB(b, h) + boff + n * 2048 + k * 1024); } while (0)
; #define PG8_MMA(ai, bj, At, Bt) do { __builtin_amdgcn_s_setprio(1); _Pragma("unroll") for (int m = 0; m < 4; ++m) _Pragma("unroll") for (int n = 0; n < 2; ++n) _Pragma("unroll") for (int k = 0; k < 2; ++k) \
;         acc[ai][bj][m][n] = __builtin_amdgcn_mfma_f32_16x16x32_bf16(Bt[n][k], At[m][k], acc[ai][bj][m][n], 0, 0, 0); __builtin_amdgcn_s_setprio(0); } while (0)
; #define PG8_WAIT_L(n) asm volatile("s_waitcnt lgkmcnt(" #n ")" ::: "memory")
; #define PG8_BAR __builtin_amdgcn_s_barrier()
; #define PG8_SCHED __builtin_amdgcn_sched_barrier(0)
; template <class Epi, class Sched, bool STAMP = false>
; __device__ __forceinline__ void gemm_phase(PG8_LAS unsigned char* lds, const Gemm g, const Sched& S, const Epi& E, unsigned long long* stamps) {
;     ...
;             const bool last = (t == nt - 2);
;             const char* a1 = cA + (size_t)(t + 1) * kstep;
;             const char* a2 = last ? nA : cA + (size_t)(t + 2) * kstep; const char* b2 = last ? nB : cB + (size_t)(t + 2) * kstep;
;             const char* a3 = a2 + kstep; const char* b3 = b2 + kstep;
;             if (last && has_next) S.a_ready(nxt);
;             PG8_LDB(B0, 0, 0); PG8_SCHED; PG8_LDA(At, 0, 0); PG8_STAGE(PG8_SA(1, 1), a1 + hstep, voffA);
;             PG8_WAIT_L(8); PG8_BAR; PG8_WAIT_L(0); PG8_MMA(0, 0, At, B0); PG8_BAR; PG8_SCHED;
;             PG8_LDB(B1, 0, 1); PG8_STAGE(PG8_SB(0, 0), b2, voffB);
;             PG8_BAR; PG8_WAIT_L(0); PG8_MMA(0, 1, At, B1); PG8_BAR;
;             PG8_LDA(At, 0, 1); PG8_STAGE(PG8_SA(0, 0), a2, voffA);
;             PG8_BAR; PG8_WAIT_L(0); PG8_MMA(1, 0, At, B0); PG8_BAR; PG8_SCHED;
.LBB0_1340:
	s_add_u32 s14, s24, 0xfffc0080
	s_addc_u32 s15, s25, -1
	s_add_i32 s16, 0, 0x10000
	v_add_u32_e32 v169, s16, v166
	ds_read_b128 v[158:161], v169
	ds_read_b128 v[162:165], v169 offset:1024
	ds_read_b128 v[170:173], v169 offset:2048
	ds_read_b128 v[174:177], v169 offset:3072
	s_cmp_eq_u32 s61, 12
	s_cselect_b32 s31, s7, s15
	s_cselect_b32 s30, s57, s14
	s_cselect_b32 s27, s5, s60
	s_cselect_b32 s26, s58, s59
	v_lshl_add_u64 v[182:183], s[24:25], 0, v[154:155]
	s_add_i32 m0, s23, 0xc000
	ds_read_b128 v[178:181], v168
	ds_read_b128 v[192:195], v168 offset:1024
	ds_read_b128 v[196:199], v168 offset:2048
	ds_read_b128 v[200:203], v168 offset:3072
	ds_read_b128 v[204:207], v168 offset:4096
	ds_read_b128 v[208:211], v168 offset:5120
	ds_read_b128 v[212:215], v168 offset:6144
	ds_read_b128 v[216:219], v168 offset:7168
	global_load_lds_dwordx4 v[182:183], off
	v_lshl_add_u64 v[182:183], s[24:25], 0, v[156:157]
	s_add_i32 m0, s23, 0xe000
	s_nop 0
	global_load_lds_dwordx4 v[182:183], off
	s_waitcnt lgkmcnt(8)
	s_barrier
	s_waitcnt lgkmcnt(0)
	s_waitcnt lgkmcnt(0)
	v_mfma_f32_16x16x32_bf16 v[124:127], v[158:161], v[178:181], v[124:127]
	v_mfma_f32_16x16x32_bf16 v[120:123], v[170:173], v[178:181], v[120:123]
	v_mfma_f32_16x16x32_bf16 v[108:111], v[158:161], v[196:199], v[108:111]
	v_mfma_f32_16x16x32_bf16 v[104:107], v[170:173], v[196:199], v[104:107]
	v_mfma_f32_16x16x32_bf16 v[92:95], v[158:161], v[204:207], v[92:95]
	v_mfma_f32_16x16x32_bf16 v[88:91], v[170:173], v[204:207], v[88:91]
	v_mfma_f32_16x16x32_bf16 v[76:79], v[158:161], v[212:215], v[76:79]
	v_mfma_f32_16x16x32_bf16 v[72:75], v[170:173], v[212:215], v[72:75]
	v_mfma_f32_16x16x32_bf16 v[124:127], v[162:165], v[192:195], v[124:127]
	v_mfma_f32_16x16x32_bf16 v[120:123], v[174:177], v[192:195], v[120:123]
	v_mfma_f32_16x16x32_bf16 v[108:111], v[162:165], v[200:203], v[108:111]
	v_mfma_f32_16x16x32_bf16 v[104:107], v[174:177], v[200:203], v[104:107]
	v_mfma_f32_16x16x32_bf16 v[92:95], v[162:165], v[208:211], v[92:95]
	v_mfma_f32_16x16x32_bf16 v[88:91], v[174:177], v[208:211], v[88:91]
	v_mfma_f32_16x16x32_bf16 v[76:79], v[162:165], v[216:219], v[76:79]
	v_mfma_f32_16x16x32_bf16 v[72:75], v[174:177], v[216:219], v[72:75]
	s_barrier
	s_add_i32 s17, 0, 0x14000
	s_add_i32 s14, s16, s43
	v_add_u32_e32 v169, s17, v166
	v_lshl_add_u64 v[182:183], s[26:27], 0, v[128:129]
	s_mov_b32 m0, s14
	ds_read_b128 v[220:223], v169
	ds_read_b128 v[224:227], v169 offset:1024
	ds_read_b128 v[228:231], v169 offset:2048
	ds_read_b128 v[232:235], v169 offset:3072
	global_load_lds_dwordx4 v[182:183], off
	v_lshl_add_u64 v[236:237], s[26:27], 0, v[148:149]
	s_add_i32 m0, s14, 0x2000
	s_nop 0
	global_load_lds_dwordx4 v[236:237], off
	s_barrier
	s_waitcnt lgkmcnt(0)
	s_waitcnt lgkmcnt(0)
	v_mfma_f32_16x16x32_bf16 v[116:119], v[220:223], v[178:181], v[116:119]
	v_mfma_f32_16x16x32_bf16 v[112:115], v[228:231], v[178:181], v[112:115]
	v_mfma_f32_16x16x32_bf16 v[100:103], v[220:223], v[196:199], v[100:103]
	v_mfma_f32_16x16x32_bf16 v[96:99], v[228:231], v[196:199], v[96:99]
	v_mfma_f32_16x16x32_bf16 v[84:87], v[220:223], v[204:207], v[84:87]
	v_mfma_f32_16x16x32_bf16 v[80:83], v[228:231], v[204:207], v[80:83]
	v_mfma_f32_16x16x32_bf16 v[68:71], v[220:223], v[212:215], v[68:71]
	v_mfma_f32_16x16x32_bf16 v[64:67], v[228:231], v[212:215], v[64:67]
	v_mfma_f32_16x16x32_bf16 v[116:119], v[224:227], v[192:195], v[116:119]
	v_mfma_f32_16x16x32_bf16 v[112:115], v[232:235], v[192:195], v[112:115]
	v_mfma_f32_16x16x32_bf16 v[100:103], v[224:227], v[200:203], v[100:103]
	v_mfma_f32_16x16x32_bf16 v[96:99], v[232:235], v[200:203], v[96:99]
	v_mfma_f32_16x16x32_bf16 v[84:87], v[224:227], v[208:211], v[84:87]
	v_mfma_f32_16x16x32_bf16 v[80:83], v[232:235], v[208:211], v[80:83]
	v_mfma_f32_16x16x32_bf16 v[68:71], v[224:227], v[216:219], v[68:71]
	v_mfma_f32_16x16x32_bf16 v[64:67], v[232:235], v[216:219], v[64:67]
	s_mov_b32 m0, s23
	v_lshl_add_u64 v[238:239], s[30:31], 0, v[152:153]
	s_barrier
	ds_read_b128 v[178:181], v168 offset:16384
	ds_read_b128 v[192:195], v168 offset:17408
	ds_read_b128 v[196:199], v168 offset:18432
	ds_read_b128 v[200:203], v168 offset:19456
	ds_read_b128 v[204:207], v168 offset:20480
	ds_read_b128 v[208:211], v168 offset:21504
	ds_read_b128 v[212:215], v168 offset:22528
	ds_read_b128 v[216:219], v168 offset:23552
	global_load_lds_dwordx4 v[238:239], off
	v_lshl_add_u64 v[240:241], s[30:31], 0, v[150:151]
	s_mov_b32 m0, s45
	s_nop 0
	global_load_lds_dwordx4 v[240:241], off
	s_barrier
	s_waitcnt lgkmcnt(0)
	s_waitcnt lgkmcnt(0)
	v_mfma_f32_16x16x32_bf16 v[60:63], v[158:161], v[178:181], v[60:63]
	v_mfma_f32_16x16x32_bf16 v[56:59], v[170:173], v[178:181], v[56:59]
	v_mfma_f32_16x16x32_bf16 v[44:47], v[158:161], v[196:199], v[44:47]
	v_mfma_f32_16x16x32_bf16 v[40:43], v[170:173], v[196:199], v[40:43]
	v_mfma_f32_16x16x32_bf16 v[28:31], v[158:161], v[204:207], v[28:31]
	v_mfma_f32_16x16x32_bf16 v[24:27], v[170:173], v[204:207], v[24:27]
	v_mfma_f32_16x16x32_bf16 v[12:15], v[158:161], v[212:215], v[12:15]
	v_mfma_f32_16x16x32_bf16 v[8:11], v[170:173], v[212:215], v[8:11]
	v_mfma_f32_16x16x32_bf16 v[60:63], v[162:165], v[192:195], v[60:63]
	v_mfma_f32_16x16x32_bf16 v[56:59], v[174:177], v[192:195], v[56:59]
	v_mfma_f32_16x16x32_bf16 v[44:47], v[162:165], v[200:203], v[44:47]
	v_mfma_f32_16x16x32_bf16 v[40:43], v[174:177], v[200:203], v[40:43]
	v_mfma_f32_16x16x32_bf16 v[28:31], v[162:165], v[208:211], v[28:31]
	v_mfma_f32_16x16x32_bf16 v[24:27], v[174:177], v[208:211], v[24:27]
	v_mfma_f32_16x16x32_bf16 v[12:15], v[162:165], v[216:219], v[12:15]
	v_mfma_f32_16x16x32_bf16 v[8:11], v[174:177], v[216:219], v[8:11]
	s_barrier
; #define PG8_STAGE(bufoff, gbase, voff) do { _Pragma("unroll") for (int _i = 0; _i < 2; ++_i) \
;         __builtin_amdgcn_global_load_lds((const unsigned*)((const char*)(gbase) + (voff)[_i]), (PG8_LAS unsigned*)(lds + (bufoff) + ldsw + _i * 8192), 16, 0, 0); } while (0)
; #define PG8_LDA(dst, b, h) do { _Pragma("unroll") for (int m = 0; m < 4; ++m) _Pragma("unroll") for (int k = 0; k < 2; ++k) dst[m][k] = *(const PG8_LAS bf16x8*)(lds + PG8_SA(b, h) + aoff + m * 2048 + k * 1024); } while (0)
; #define PG8_LDB(dst, b, h) do { _Pragma("unroll") for (int n = 0; n < 2; ++n) _Pragma("unroll") for (int k = 0; k < 2; ++k) dst[n][k] = *(const PG8_LAS bf16x8*)(lds + PG8_SB(b, h) + boff + n * 2048 + k * 1024); } while (0)
; #define PG8_MMA(ai, bj, At, Bt) do { __builtin_amdgcn_s_setprio(1); _Pragma("unroll") for (int m = 0; m < 4; ++m) _Pragma("unroll") for (int n = 0; n < 2; ++n) _Pragma("unroll") for (int k = 0; k < 2; ++k) \
;         acc[ai][bj][m][n] = __builtin_amdgcn_mfma_f32_16x16x32_bf16(Bt[n][k], At[m][k], acc[ai][bj][m][n], 0, 0, 0); __builtin_amdgcn_s_setprio(0); } while (0)
; #define PG8_WAIT_V(n) asm volatile("s_waitcnt vmcnt(" #n ")" ::: "memory")
; #define PG8_WAIT_L(n) asm volatile("s_waitcnt lgkmcnt(" #n ")" ::: "memory")
; #define PG8_BAR __builtin_amdgcn_s_barrier()
; #define PG8_SCHED __builtin_amdgcn_sched_barrier(0)
; template <class Epi, class Sched, bool STAMP = false>
; __device__ __forceinline__ void gemm_phase(PG8_LAS unsigned char* lds, const Gemm g, const Sched& S, const Epi& E, unsigned long long* stamps) {
;     ...
;             PG8_STAGE(PG8_SB(0, 1), b2 + hstep, voffB);
;             PG8_WAIT_V(6); PG8_BAR; PG8_MMA(1, 1, At, B1); PG8_BAR;
;             PG8_LDB(B0, 1, 0); PG8_SCHED; PG8_LDA(At, 1, 0); PG8_STAGE(PG8_SA(0, 1), a2 + hstep, voffA);
;             PG8_WAIT_L(8); PG8_BAR; PG8_WAIT_L(0); PG8_MMA(0, 0, At, B0); PG8_BAR; PG8_SCHED;
;             PG8_LDB(B1, 1, 1); PG8_STAGE(PG8_SB(1, 0), b3, voffB);
;             PG8_BAR; PG8_WAIT_L(0); PG8_MMA(0, 1, At, B1); PG8_BAR;
;             PG8_LDA(At, 1, 1); PG8_STAGE(PG8_SA(1, 0), a3, voffA);
	s_add_u32 s14, s26, 0x40000
	s_addc_u32 s15, s27, 0
	s_add_i32 s16, s17, s43
	v_lshl_add_u64 v[158:159], s[14:15], 0, v[128:129]
	s_mov_b32 m0, s16
	s_nop 0
	global_load_lds_dwordx4 v[158:159], off
	v_lshl_add_u64 v[158:159], s[14:15], 0, v[148:149]
	s_add_i32 m0, s16, 0x2000
	s_nop 0
	global_load_lds_dwordx4 v[158:159], off
	s_waitcnt vmcnt(6)
	s_barrier
	v_mfma_f32_16x16x32_bf16 v[52:55], v[220:223], v[178:181], v[52:55]
	v_mfma_f32_16x16x32_bf16 v[48:51], v[228:231], v[178:181], v[48:51]
	v_mfma_f32_16x16x32_bf16 v[36:39], v[220:223], v[196:199], v[36:39]
	v_mfma_f32_16x16x32_bf16 v[32:35], v[228:231], v[196:199], v[32:35]
	v_mfma_f32_16x16x32_bf16 v[20:23], v[220:223], v[204:207], v[20:23]
	v_mfma_f32_16x16x32_bf16 v[16:19], v[228:231], v[204:207], v[16:19]
	v_mfma_f32_16x16x32_bf16 v[4:7], v[220:223], v[212:215], v[4:7]
	v_mfma_f32_16x16x32_bf16 v[0:3], v[228:231], v[212:215], v[0:3]
	v_mfma_f32_16x16x32_bf16 v[52:55], v[224:227], v[192:195], v[52:55]
	v_mfma_f32_16x16x32_bf16 v[48:51], v[232:235], v[192:195], v[48:51]
	v_mfma_f32_16x16x32_bf16 v[36:39], v[224:227], v[200:203], v[36:39]
	v_mfma_f32_16x16x32_bf16 v[32:35], v[232:235], v[200:203], v[32:35]
	v_mfma_f32_16x16x32_bf16 v[20:23], v[224:227], v[208:211], v[20:23]
	v_mfma_f32_16x16x32_bf16 v[16:19], v[232:235], v[208:211], v[16:19]
	v_mfma_f32_16x16x32_bf16 v[4:7], v[224:227], v[216:219], v[4:7]
	v_mfma_f32_16x16x32_bf16 v[0:3], v[232:235], v[216:219], v[0:3]
	s_add_i32 s16, 0, 0x18000
	v_add_u32_e32 v169, s16, v166
	s_barrier
	ds_read_b128 v[158:161], v169
	ds_read_b128 v[162:165], v169 offset:1024
	ds_read_b128 v[170:173], v169 offset:2048
	ds_read_b128 v[174:177], v169 offset:3072
	s_add_u32 s14, s30, 0x40000
	s_addc_u32 s15, s31, 0
	s_mov_b32 m0, s46
	v_lshl_add_u64 v[220:221], s[14:15], 0, v[152:153]
	ds_read_b128 v[178:181], v168 offset:32768
	ds_read_b128 v[192:195], v168 offset:33792
	ds_read_b128 v[196:199], v168 offset:34816
	ds_read_b128 v[200:203], v168 offset:35840
	ds_read_b128 v[204:207], v168 offset:36864
	ds_read_b128 v[208:211], v168 offset:37888
	ds_read_b128 v[212:215], v168 offset:38912
	ds_read_b128 v[216:219], v168 offset:39936
	global_load_lds_dwordx4 v[220:221], off
	v_lshl_add_u64 v[220:221], s[14:15], 0, v[150:151]
	s_mov_b32 m0, s47
	s_nop 0
	global_load_lds_dwordx4 v[220:221], off
	s_waitcnt lgkmcnt(8)
	s_barrier
	s_waitcnt lgkmcnt(0)
	s_waitcnt lgkmcnt(0)
	v_mfma_f32_16x16x32_bf16 v[124:127], v[158:161], v[178:181], v[124:127]
	v_mfma_f32_16x16x32_bf16 v[120:123], v[170:173], v[178:181], v[120:123]
	v_mfma_f32_16x16x32_bf16 v[108:111], v[158:161], v[196:199], v[108:111]
	v_mfma_f32_16x16x32_bf16 v[104:107], v[170:173], v[196:199], v[104:107]
	v_mfma_f32_16x16x32_bf16 v[92:95], v[158:161], v[204:207], v[92:95]
	v_mfma_f32_16x16x32_bf16 v[88:91], v[170:173], v[204:207], v[88:91]
	v_mfma_f32_16x16x32_bf16 v[76:79], v[158:161], v[212:215], v[76:79]
	v_mfma_f32_16x16x32_bf16 v[72:75], v[170:173], v[212:215], v[72:75]
	v_mfma_f32_16x16x32_bf16 v[124:127], v[162:165], v[192:195], v[124:127]
	v_mfma_f32_16x16x32_bf16 v[120:123], v[174:177], v[192:195], v[120:123]
	v_mfma_f32_16x16x32_bf16 v[108:111], v[162:165], v[200:203], v[108:111]
	v_mfma_f32_16x16x32_bf16 v[104:107], v[174:177], v[200:203], v[104:107]
	v_mfma_f32_16x16x32_bf16 v[92:95], v[162:165], v[208:211], v[92:95]
	v_mfma_f32_16x16x32_bf16 v[88:91], v[174:177], v[208:211], v[88:91]
	v_mfma_f32_16x16x32_bf16 v[76:79], v[162:165], v[216:219], v[76:79]
	v_mfma_f32_16x16x32_bf16 v[72:75], v[174:177], v[216:219], v[72:75]
	s_barrier
	s_add_i32 s17, 0, 0x1c000
	s_add_i32 s14, s16, s43
	v_add_u32_e32 v169, s17, v166
	v_lshl_add_u64 v[182:183], v[182:183], 0, s[18:19]
	s_mov_b32 m0, s14
	ds_read_b128 v[220:223], v169
	ds_read_b128 v[224:227], v169 offset:1024
	ds_read_b128 v[228:231], v169 offset:2048
	ds_read_b128 v[232:235], v169 offset:3072
	global_load_lds_dwordx4 v[182:183], off
	v_lshl_add_u64 v[182:183], v[236:237], 0, s[18:19]
	s_add_i32 m0, s14, 0x2000
	s_nop 0
	global_load_lds_dwordx4 v[182:183], off
	s_barrier
	s_waitcnt lgkmcnt(0)
	s_waitcnt lgkmcnt(0)
	v_mfma_f32_16x16x32_bf16 v[116:119], v[220:223], v[178:181], v[116:119]
	v_mfma_f32_16x16x32_bf16 v[112:115], v[228:231], v[178:181], v[112:115]
	v_mfma_f32_16x16x32_bf16 v[100:103], v[220:223], v[196:199], v[100:103]
	v_mfma_f32_16x16x32_bf16 v[96:99], v[228:231], v[196:199], v[96:99]
	v_mfma_f32_16x16x32_bf16 v[84:87], v[220:223], v[204:207], v[84:87]
	v_mfma_f32_16x16x32_bf16 v[80:83], v[228:231], v[204:207], v[80:83]
	v_mfma_f32_16x16x32_bf16 v[68:71], v[220:223], v[212:215], v[68:71]
	v_mfma_f32_16x16x32_bf16 v[64:67], v[228:231], v[212:215], v[64:67]
	v_mfma_f32_16x16x32_bf16 v[116:119], v[224:227], v[192:195], v[116:119]
	v_mfma_f32_16x16x32_bf16 v[112:115], v[232:235], v[192:195], v[112:115]
	v_mfma_f32_16x16x32_bf16 v[100:103], v[224:227], v[200:203], v[100:103]
	v_mfma_f32_16x16x32_bf16 v[96:99], v[232:235], v[200:203], v[96:99]
	v_mfma_f32_16x16x32_bf16 v[84:87], v[224:227], v[208:211], v[84:87]
	v_mfma_f32_16x16x32_bf16 v[80:83], v[232:235], v[208:211], v[80:83]
	v_mfma_f32_16x16x32_bf16 v[68:71], v[224:227], v[216:219], v[68:71]
	v_mfma_f32_16x16x32_bf16 v[64:67], v[232:235], v[216:219], v[64:67]
	s_mov_b32 m0, s48
	v_lshl_add_u64 v[182:183], v[238:239], 0, s[18:19]
	s_barrier
	ds_read_b128 v[178:181], v168 offset:49152
	ds_read_b128 v[192:195], v168 offset:50176
	ds_read_b128 v[196:199], v168 offset:51200
	ds_read_b128 v[200:203], v168 offset:52224
	ds_read_b128 v[204:207], v168 offset:53248
	ds_read_b128 v[208:211], v168 offset:54272
	ds_read_b128 v[212:215], v168 offset:55296
	ds_read_b128 v[216:219], v168 offset:56320
	global_load_lds_dwordx4 v[182:183], off
	v_lshl_add_u64 v[182:183], v[240:241], 0, s[18:19]
	s_mov_b32 m0, s49
	s_nop 0
	global_load_lds_dwordx4 v[182:183], off
	s_barrier
; __device__ __forceinline__ unsigned cvt_pk_bf16(float lo, float hi) { const f32x2_cv v = {lo, hi}; const bf16x2_cv b = __builtin_convertvector(v, bf16x2_cv); return __builtin_bit_cast(unsigned, b); }
; #define PG8_STAGE(bufoff, gbase, voff) do { _Pragma("unroll") for (int _i = 0; _i < 2; ++_i) \
;         __builtin_amdgcn_global_load_lds((const unsigned*)((const char*)(gbase) + (voff)[_i]), (PG8_LAS unsigned*)(lds + (bufoff) + ldsw + _i * 8192), 16, 0, 0); } while (0)
; #define PG8_MMA(ai, bj, At, Bt) do { __builtin_amdgcn_s_setprio(1); _Pragma("unroll") for (int m = 0; m < 4; ++m) _Pragma("unroll") for (int n = 0; n < 2; ++n) _Pragma("unroll") for (int k = 0; k < 2; ++k) \
;         acc[ai][bj][m][n] = __builtin_amdgcn_mfma_f32_16x16x32_bf16(Bt[n][k], At[m][k], acc[ai][bj][m][n], 0, 0, 0); __builtin_amdgcn_s_setprio(0); } while (0)
; template <class Epi, class Sched, bool STAMP = false>
; __device__ __forceinline__ void gemm_phase(PG8_LAS unsigned char* lds, const Gemm g, const Sched& S, const Epi& E, unsigned long long* stamps) {
;     ...
;             PG8_BAR; PG8_WAIT_L(0); PG8_MMA(1, 0, At, B0); PG8_BAR; PG8_SCHED;
;             PG8_STAGE(PG8_SB(1, 1), b3 + hstep, voffB);
;             PG8_WAIT_V(6); PG8_BAR; PG8_MMA(1, 1, At, B1); PG8_BAR;
;     __device__ __forceinline__ void operator()(const f32x4 (&acc)[2][2][4][2], const pg8::Unit& u, int wr, int wc, int fr, int fq) const {
;         const int row0 = u.pm * 256 + wr * 64 + fr, col0 = u.pn * 256 + wc * 32 + 8 * fq;
; #pragma unroll
;         for (int ai = 0; ai < 2; ++ai)
; #pragma unroll
;             for (int m = 0; m < 4; ++m) {
;                 const int row = row0 + ai * 128 + m * 16;
;                 const float s = (MODE == 2) ? 1.0f : rstd_of(rowss, row);
;                 bf16_t* rowp = O + (size_t)row * ldc + col0;
; #pragma unroll
;                 for (int bj = 0; bj < 2; ++bj) {
;                     f32x4 v0 = acc[ai][bj][m][0] * s, v1 = acc[ai][bj][m][1] * s;
;                     if (MODE == 1) {
; #pragma unroll
;                         for (int j = 0; j < 4; ++j) { const float a = fmaxf(v0[j], 0.f), b = fmaxf(v1[j], 0.f); v0[j] = a * a; v1[j] = b * b; } }
;                     u32x4 w; w.x = cvt_pk_bf16(v0[0], v0[1]); w.y = cvt_pk_bf16(v0[2], v0[3]); w.z = cvt_pk_bf16(v1[0], v1[1]); w.w = cvt_pk_bf16(v1[2], v1[3]);
;                     *(u32x4*)(rowp + bj * 128) = w; } }
;     }
	s_waitcnt lgkmcnt(0)
	s_waitcnt lgkmcnt(0)
	v_mfma_f32_16x16x32_bf16 v[60:63], v[158:161], v[178:181], v[60:63]
	v_mfma_f32_16x16x32_bf16 v[56:59], v[170:173], v[178:181], v[56:59]
	v_mfma_f32_16x16x32_bf16 v[44:47], v[158:161], v[196:199], v[44:47]
	v_mfma_f32_16x16x32_bf16 v[40:43], v[170:173], v[196:199], v[40:43]
	v_mfma_f32_16x16x32_bf16 v[28:31], v[158:161], v[204:207], v[28:31]
	v_mfma_f32_16x16x32_bf16 v[24:27], v[170:173], v[204:207], v[24:27]
	v_mfma_f32_16x16x32_bf16 v[12:15], v[158:161], v[212:215], v[12:15]
	v_mfma_f32_16x16x32_bf16 v[8:11], v[170:173], v[212:215], v[8:11]
	v_mfma_f32_16x16x32_bf16 v[60:63], v[162:165], v[192:195], v[60:63]
	v_mfma_f32_16x16x32_bf16 v[56:59], v[174:177], v[192:195], v[56:59]
	v_mfma_f32_16x16x32_bf16 v[44:47], v[162:165], v[200:203], v[44:47]
	v_mfma_f32_16x16x32_bf16 v[40:43], v[174:177], v[200:203], v[40:43]
	v_mfma_f32_16x16x32_bf16 v[28:31], v[162:165], v[208:211], v[28:31]
	v_mfma_f32_16x16x32_bf16 v[24:27], v[174:177], v[208:211], v[24:27]
	v_mfma_f32_16x16x32_bf16 v[12:15], v[162:165], v[216:219], v[12:15]
	v_mfma_f32_16x16x32_bf16 v[8:11], v[174:177], v[216:219], v[8:11]
	s_barrier
	s_add_u32 s14, s26, 0x40080
	s_addc_u32 s15, s27, 0
	s_add_i32 s16, s17, s43
	v_lshl_add_u64 v[158:159], s[14:15], 0, v[128:129]
	s_mov_b32 m0, s16
	s_nop 0
	global_load_lds_dwordx4 v[158:159], off
	v_lshl_add_u64 v[158:159], s[14:15], 0, v[148:149]
	s_add_i32 m0, s16, 0x2000
	s_nop 0
	global_load_lds_dwordx4 v[158:159], off
	s_waitcnt vmcnt(6)
	s_barrier
	v_mfma_f32_16x16x32_bf16 v[52:55], v[220:223], v[178:181], v[52:55]
	v_mfma_f32_16x16x32_bf16 v[48:51], v[228:231], v[178:181], v[48:51]
	v_mfma_f32_16x16x32_bf16 v[36:39], v[220:223], v[196:199], v[36:39]
	v_mfma_f32_16x16x32_bf16 v[32:35], v[228:231], v[196:199], v[32:35]
	v_mfma_f32_16x16x32_bf16 v[20:23], v[220:223], v[204:207], v[20:23]
	v_mfma_f32_16x16x32_bf16 v[16:19], v[228:231], v[204:207], v[16:19]
	v_mfma_f32_16x16x32_bf16 v[4:7], v[220:223], v[212:215], v[4:7]
	v_mfma_f32_16x16x32_bf16 v[0:3], v[228:231], v[212:215], v[0:3]
	v_mfma_f32_16x16x32_bf16 v[52:55], v[224:227], v[192:195], v[52:55]
	v_mfma_f32_16x16x32_bf16 v[48:51], v[232:235], v[192:195], v[48:51]
	v_mfma_f32_16x16x32_bf16 v[36:39], v[224:227], v[200:203], v[36:39]
	v_mfma_f32_16x16x32_bf16 v[32:35], v[232:235], v[200:203], v[32:35]
	v_mfma_f32_16x16x32_bf16 v[20:23], v[224:227], v[208:211], v[20:23]
	v_mfma_f32_16x16x32_bf16 v[16:19], v[232:235], v[208:211], v[16:19]
	v_mfma_f32_16x16x32_bf16 v[4:7], v[224:227], v[216:219], v[4:7]
	v_mfma_f32_16x16x32_bf16 v[0:3], v[232:235], v[216:219], v[0:3]
	s_add_i32 s61, s61, 2
	s_add_u32 s24, s24, 0x100
	s_addc_u32 s25, s25, 0
	s_add_u32 s59, s59, 0x100
	s_addc_u32 s60, s60, 0
	s_cmp_gt_u32 s61, 13
	s_barrier
	s_cbranch_scc0 .LBB0_1340
	v_lshl_add_u32 v162, s22, 8, v139
	v_ashrrev_i32_e32 v163, 31, v162
	v_lshl_add_u64 v[158:159], v[162:163], 2, s[0:1]
	global_load_dword v164, v[158:159], off
	global_load_dword v231, v[158:159], off offset:64
	global_load_dword v232, v[158:159], off offset:128
	global_load_dword v233, v[158:159], off offset:192
	global_load_dword v234, v[158:159], off offset:512
	global_load_dword v235, v[158:159], off offset:576
	global_load_dword v236, v[158:159], off offset:640
	global_load_dword v237, v[158:159], off offset:704
	v_lshl_or_b32 v160, s56, 8, v167
	v_ashrrev_i32_e32 v161, 31, v160
	s_mov_b32 s5, 0x80000
	s_mov_b64 s[14:15], 0x80000
	s_mov_b32 s56, s4
	s_mov_b32 s22, s6
	s_mov_b64 s[26:27], s[20:21]
	s_mov_b64 s[24:25], s[12:13]
	s_waitcnt vmcnt(0)
	v_fmamk_f32 v164, v164, 0x3a800000, v187
	v_cmp_gt_f32_e32 vcc, s67, v164
	v_mul_f32_e32 v165, 0x4b800000, v164
	s_nop 0
	v_cndmask_b32_e32 v164, v164, v165, vcc
	v_rsq_f32_e32 v164, v164
	s_nop 0
	v_mul_f32_e32 v165, 0x45800000, v164
	v_cndmask_b32_e32 v170, v164, v165, vcc
	v_lshlrev_b64 v[164:165], 12, v[162:163]
	v_lshl_add_u64 v[172:173], s[2:3], 0, v[164:165]
	v_lshlrev_b64 v[164:165], 1, v[160:161]
	v_lshl_add_u64 v[160:161], v[172:173], 0, v[164:165]
	v_pk_mul_f32 v[126:127], v[126:127], v[170:171] op_sel_hi:[1,0]
	v_pk_mul_f32 v[124:125], v[124:125], v[170:171] op_sel_hi:[1,0]
	v_pk_mul_f32 v[172:173], v[122:123], v[170:171] op_sel_hi:[1,0]
	v_pk_mul_f32 v[122:123], v[120:121], v[170:171] op_sel_hi:[1,0]
	v_cvt_pk_bf16_f32 v120, v124, v125
	v_cvt_pk_bf16_f32 v121, v126, v127
	v_cvt_pk_bf16_f32 v122, v122, v123
	v_cvt_pk_bf16_f32 v123, v172, v173
	global_store_dwordx4 v[160:161], v[120:123], off
	v_pk_mul_f32 v[118:119], v[118:119], v[170:171] op_sel_hi:[1,0]
	v_pk_mul_f32 v[116:117], v[116:117], v[170:171] op_sel_hi:[1,0]
	v_pk_mul_f32 v[120:121], v[114:115], v[170:171] op_sel_hi:[1,0]
	v_pk_mul_f32 v[114:115], v[112:113], v[170:171] op_sel_hi:[1,0]
	v_cvt_pk_bf16_f32 v112, v116, v117
	v_cvt_pk_bf16_f32 v113, v118, v119
	v_cvt_pk_bf16_f32 v114, v114, v115
	v_cvt_pk_bf16_f32 v115, v120, v121
	global_store_dwordx4 v[160:161], v[112:115], off offset:256
	s_nop 1
	v_mov_b32_e32 v114, v231
	s_nop 0
	v_or_b32_e32 v112, 16, v162
	v_ashrrev_i32_e32 v113, 31, v112
	v_lshlrev_b64 v[112:113], 12, v[112:113]
	v_lshl_add_u64 v[112:113], s[2:3], 0, v[112:113]
	v_lshl_add_u64 v[112:113], v[112:113], 0, v[164:165]
	v_fmamk_f32 v114, v114, 0x3a800000, v187
	v_cmp_gt_f32_e32 vcc, s67, v114
	v_mul_f32_e32 v115, 0x4b800000, v114
	s_nop 0
	v_cndmask_b32_e32 v114, v114, v115, vcc
	v_rsq_f32_e32 v114, v114
	s_nop 0
	v_mul_f32_e32 v115, 0x45800000, v114
	v_cndmask_b32_e32 v114, v114, v115, vcc
	v_pk_mul_f32 v[110:111], v[110:111], v[114:115] op_sel_hi:[1,0]
	v_pk_mul_f32 v[108:109], v[108:109], v[114:115] op_sel_hi:[1,0]
	v_pk_mul_f32 v[116:117], v[106:107], v[114:115] op_sel_hi:[1,0]
; __device__ __forceinline__ unsigned cvt_pk_bf16(float lo, float hi) { const f32x2_cv v = {lo, hi}; const bf16x2_cv b = __builtin_convertvector(v, bf16x2_cv); return __builtin_bit_cast(unsigned, b); }
; __device__ __forceinline__ float rstd_of(const float* rowss, int row) { return rsqrtf(rowss[row] * (1.0f / 1024.0f) + 1e-6f); }
;     __device__ __forceinline__ void operator()(const f32x4 (&acc)[2][2][4][2], const pg8::Unit& u, int wr, int wc, int fr, int fq) const {
;         const int row0 = u.pm * 256 + wr * 64 + fr, col0 = u.pn * 256 + wc * 32 + 8 * fq;
; #pragma unroll
;         for (int ai = 0; ai < 2; ++ai)
; #pragma unroll
;             for (int m = 0; m < 4; ++m) {
;                 const int row = row0 + ai * 128 + m * 16;
;                 const float s = (MODE == 2) ? 1.0f : rstd_of(rowss, row);
;                 bf16_t* rowp = O + (size_t)row * ldc + col0;
; #pragma unroll
;                 for (int bj = 0; bj < 2; ++bj) {
;                     f32x4 v0 = acc[ai][bj][m][0] * s, v1 = acc[ai][bj][m][1] * s;
;                     if (MODE == 1) {
; #pragma unroll
;                         for (int j = 0; j < 4; ++j) { const float a = fmaxf(v0[j], 0.f), b = fmaxf(v1[j], 0.f); v0[j] = a * a; v1[j] = b * b; } }
;                     u32x4 w; w.x = cvt_pk_bf16(v0[0], v0[1]); w.y = cvt_pk_bf16(v0[2], v0[3]); w.z = cvt_pk_bf16(v1[0], v1[1]); w.w = cvt_pk_bf16(v1[2], v1[3]);
;                     *(u32x4*)(rowp + bj * 128) = w; } }
;     }
	v_pk_mul_f32 v[106:107], v[104:105], v[114:115] op_sel_hi:[1,0]
	v_cvt_pk_bf16_f32 v104, v108, v109
	v_cvt_pk_bf16_f32 v105, v110, v111
	v_cvt_pk_bf16_f32 v106, v106, v107
	v_cvt_pk_bf16_f32 v107, v116, v117
	global_store_dwordx4 v[112:113], v[104:107], off
	v_pk_mul_f32 v[102:103], v[102:103], v[114:115] op_sel_hi:[1,0]
	v_pk_mul_f32 v[100:101], v[100:101], v[114:115] op_sel_hi:[1,0]
	v_pk_mul_f32 v[104:105], v[98:99], v[114:115] op_sel_hi:[1,0]
	v_pk_mul_f32 v[98:99], v[96:97], v[114:115] op_sel_hi:[1,0]
	v_cvt_pk_bf16_f32 v96, v100, v101
	v_cvt_pk_bf16_f32 v97, v102, v103
	v_cvt_pk_bf16_f32 v98, v98, v99
	v_cvt_pk_bf16_f32 v99, v104, v105
	global_store_dwordx4 v[112:113], v[96:99], off offset:256
	s_nop 1
	v_mov_b32_e32 v98, v232
	s_nop 0
	v_or_b32_e32 v96, 32, v162
	v_ashrrev_i32_e32 v97, 31, v96
	v_lshlrev_b64 v[96:97], 12, v[96:97]
	v_lshl_add_u64 v[96:97], s[2:3], 0, v[96:97]
	v_lshl_add_u64 v[96:97], v[96:97], 0, v[164:165]
	v_fmamk_f32 v98, v98, 0x3a800000, v187
	v_cmp_gt_f32_e32 vcc, s67, v98
	v_mul_f32_e32 v99, 0x4b800000, v98
	s_nop 0
	v_cndmask_b32_e32 v98, v98, v99, vcc
	v_rsq_f32_e32 v98, v98
	s_nop 0
	v_mul_f32_e32 v99, 0x45800000, v98
	v_cndmask_b32_e32 v98, v98, v99, vcc
	v_pk_mul_f32 v[94:95], v[94:95], v[98:99] op_sel_hi:[1,0]
	v_pk_mul_f32 v[92:93], v[92:93], v[98:99] op_sel_hi:[1,0]
	v_pk_mul_f32 v[100:101], v[90:91], v[98:99] op_sel_hi:[1,0]
	v_pk_mul_f32 v[90:91], v[88:89], v[98:99] op_sel_hi:[1,0]
	v_cvt_pk_bf16_f32 v88, v92, v93
	v_cvt_pk_bf16_f32 v89, v94, v95
	v_cvt_pk_bf16_f32 v90, v90, v91
	v_cvt_pk_bf16_f32 v91, v100, v101
	global_store_dwordx4 v[96:97], v[88:91], off
	v_pk_mul_f32 v[86:87], v[86:87], v[98:99] op_sel_hi:[1,0]
	v_pk_mul_f32 v[84:85], v[84:85], v[98:99] op_sel_hi:[1,0]
	v_pk_mul_f32 v[88:89], v[82:83], v[98:99] op_sel_hi:[1,0]
	v_pk_mul_f32 v[82:83], v[80:81], v[98:99] op_sel_hi:[1,0]
	v_cvt_pk_bf16_f32 v80, v84, v85
	v_cvt_pk_bf16_f32 v81, v86, v87
	v_cvt_pk_bf16_f32 v82, v82, v83
	v_cvt_pk_bf16_f32 v83, v88, v89
	global_store_dwordx4 v[96:97], v[80:83], off offset:256
	s_nop 1
	v_mov_b32_e32 v82, v233
	s_nop 0
	v_or_b32_e32 v80, 48, v162
	v_ashrrev_i32_e32 v81, 31, v80
	v_lshlrev_b64 v[80:81], 12, v[80:81]
	v_lshl_add_u64 v[80:81], s[2:3], 0, v[80:81]
	v_lshl_add_u64 v[80:81], v[80:81], 0, v[164:165]
	v_fmamk_f32 v82, v82, 0x3a800000, v187
	v_cmp_gt_f32_e32 vcc, s67, v82
	v_mul_f32_e32 v83, 0x4b800000, v82
	s_nop 0
	v_cndmask_b32_e32 v82, v82, v83, vcc
	v_rsq_f32_e32 v82, v82
	s_nop 0
	v_mul_f32_e32 v83, 0x45800000, v82
	v_cndmask_b32_e32 v82, v82, v83, vcc
	v_pk_mul_f32 v[78:79], v[78:79], v[82:83] op_sel_hi:[1,0]
	v_pk_mul_f32 v[76:77], v[76:77], v[82:83] op_sel_hi:[1,0]
	v_pk_mul_f32 v[84:85], v[74:75], v[82:83] op_sel_hi:[1,0]
	v_pk_mul_f32 v[74:75], v[72:73], v[82:83] op_sel_hi:[1,0]
	v_cvt_pk_bf16_f32 v72, v76, v77
	v_cvt_pk_bf16_f32 v73, v78, v79
	v_cvt_pk_bf16_f32 v74, v74, v75
	v_cvt_pk_bf16_f32 v75, v84, v85
	global_store_dwordx4 v[80:81], v[72:75], off
	v_pk_mul_f32 v[70:71], v[70:71], v[82:83] op_sel_hi:[1,0]
	v_pk_mul_f32 v[68:69], v[68:69], v[82:83] op_sel_hi:[1,0]
	v_pk_mul_f32 v[72:73], v[66:67], v[82:83] op_sel_hi:[1,0]
	v_pk_mul_f32 v[66:67], v[64:65], v[82:83] op_sel_hi:[1,0]
	v_cvt_pk_bf16_f32 v64, v68, v69
	v_cvt_pk_bf16_f32 v65, v70, v71
	v_cvt_pk_bf16_f32 v66, v66, v67
	v_cvt_pk_bf16_f32 v67, v72, v73
	global_store_dwordx4 v[80:81], v[64:67], off offset:256
	s_nop 1
	v_mov_b32_e32 v64, v234
	s_nop 0
	v_lshl_add_u64 v[66:67], v[160:161], 0, s[14:15]
	s_mov_b64 s[14:15], 0x90000
	v_fmamk_f32 v64, v64, 0x3a800000, v187
	v_cmp_gt_f32_e32 vcc, s67, v64
	v_mul_f32_e32 v65, 0x4b800000, v64
	s_nop 0
	v_cndmask_b32_e32 v64, v64, v65, vcc
	v_rsq_f32_e32 v64, v64
	s_nop 0
	v_mul_f32_e32 v65, 0x45800000, v64
	v_cndmask_b32_e32 v64, v64, v65, vcc
	v_pk_mul_f32 v[60:61], v[60:61], v[64:65] op_sel_hi:[1,0]
	v_pk_mul_f32 v[62:63], v[62:63], v[64:65] op_sel_hi:[1,0]
	v_pk_mul_f32 v[68:69], v[58:59], v[64:65] op_sel_hi:[1,0]
	v_pk_mul_f32 v[58:59], v[56:57], v[64:65] op_sel_hi:[1,0]
	v_cvt_pk_bf16_f32 v56, v60, v61
	v_add_co_u32_e32 v60, vcc, s5, v160
	v_cvt_pk_bf16_f32 v57, v62, v63
	v_cvt_pk_bf16_f32 v58, v58, v59
	v_cvt_pk_bf16_f32 v59, v68, v69
	v_addc_co_u32_e32 v61, vcc, 0, v161, vcc
	global_store_dwordx4 v[60:61], v[56:59], off
	v_pk_mul_f32 v[54:55], v[54:55], v[64:65] op_sel_hi:[1,0]
	v_pk_mul_f32 v[52:53], v[52:53], v[64:65] op_sel_hi:[1,0]
; __device__ __forceinline__ unsigned cvt_pk_bf16(float lo, float hi) { const f32x2_cv v = {lo, hi}; const bf16x2_cv b = __builtin_convertvector(v, bf16x2_cv); return __builtin_bit_cast(unsigned, b); }
; #define PG8_WAIT_V(n) asm volatile("s_waitcnt vmcnt(" #n ")" ::: "memory")
; #define PG8_BAR __builtin_amdgcn_s_barrier()
; __device__ __forceinline__ float rstd_of(const float* rowss, int row) { return rsqrtf(rowss[row] * (1.0f / 1024.0f) + 1e-6f); }
; template <class Epi, class Sched, bool STAMP = false>
; __device__ __forceinline__ void gemm_phase(PG8_LAS unsigned char* lds, const Gemm g, const Sched& S, const Epi& E, unsigned long long* stamps) {
;     ...
;         if (!has_next) break;
; #pragma unroll
;         for (int a = 0; a < 2; ++a)
; #pragma unroll
;             for (int b = 0; b < 2; ++b)
; #pragma unroll
;                 for (int m = 0; m < 4; ++m)
; #pragma unroll
;                     for (int n = 0; n < 2; ++n) acc[a][b][m][n] = (f32x4){0.f, 0.f, 0.f, 0.f};
;         cur = nxt; cA = nA; cB = nB; ++ui;
;     }
;     PG8_WAIT_V(0);
;     if (wr == 0) PG8_BAR;
;     PG8_BAR;
;     __device__ __forceinline__ void operator()(const f32x4 (&acc)[2][2][4][2], const pg8::Unit& u, int wr, int wc, int fr, int fq) const {
;     ...
;             for (int m = 0; m < 4; ++m) {
;                 const int row = row0 + ai * 128 + m * 16;
;                 const float s = (MODE == 2) ? 1.0f : rstd_of(rowss, row);
;                 bf16_t* rowp = O + (size_t)row * ldc + col0;
; #pragma unroll
;                 for (int bj = 0; bj < 2; ++bj) {
;                     f32x4 v0 = acc[ai][bj][m][0] * s, v1 = acc[ai][bj][m][1] * s;
;                     if (MODE == 1) {
; #pragma unroll
;                         for (int j = 0; j < 4; ++j) { const float a = fmaxf(v0[j], 0.f), b = fmaxf(v1[j], 0.f); v0[j] = a * a; v1[j] = b * b; } }
;                     u32x4 w; w.x = cvt_pk_bf16(v0[0], v0[1]); w.y = cvt_pk_bf16(v0[2], v0[3]); w.z = cvt_pk_bf16(v1[0], v1[1]); w.w = cvt_pk_bf16(v1[2], v1[3]);
;                     *(u32x4*)(rowp + bj * 128) = w; } }
;     }
	v_pk_mul_f32 v[56:57], v[50:51], v[64:65] op_sel_hi:[1,0]
	v_pk_mul_f32 v[50:51], v[48:49], v[64:65] op_sel_hi:[1,0]
	v_cvt_pk_bf16_f32 v48, v52, v53
	v_cvt_pk_bf16_f32 v49, v54, v55
	v_cvt_pk_bf16_f32 v50, v50, v51
	v_cvt_pk_bf16_f32 v51, v56, v57
	global_store_dwordx4 v[66:67], v[48:51], off offset:256
	s_nop 1
	v_mov_b32_e32 v48, v235
	s_mov_b32 s5, 0x90000
	v_lshl_add_u64 v[50:51], v[160:161], 0, s[14:15]
	s_mov_b64 s[14:15], 0xa0000
	v_fmamk_f32 v48, v48, 0x3a800000, v187
	v_cmp_gt_f32_e32 vcc, s67, v48
	v_mul_f32_e32 v49, 0x4b800000, v48
	s_nop 0
	v_cndmask_b32_e32 v48, v48, v49, vcc
	v_rsq_f32_e32 v48, v48
	s_nop 0
	v_mul_f32_e32 v49, 0x45800000, v48
	v_cndmask_b32_e32 v48, v48, v49, vcc
	v_pk_mul_f32 v[44:45], v[44:45], v[48:49] op_sel_hi:[1,0]
	v_pk_mul_f32 v[46:47], v[46:47], v[48:49] op_sel_hi:[1,0]
	v_pk_mul_f32 v[52:53], v[42:43], v[48:49] op_sel_hi:[1,0]
	v_pk_mul_f32 v[42:43], v[40:41], v[48:49] op_sel_hi:[1,0]
	v_cvt_pk_bf16_f32 v40, v44, v45
	v_add_co_u32_e32 v44, vcc, s5, v160
	v_cvt_pk_bf16_f32 v41, v46, v47
	v_cvt_pk_bf16_f32 v42, v42, v43
	v_cvt_pk_bf16_f32 v43, v52, v53
	v_addc_co_u32_e32 v45, vcc, 0, v161, vcc
	global_store_dwordx4 v[44:45], v[40:43], off
	v_pk_mul_f32 v[38:39], v[38:39], v[48:49] op_sel_hi:[1,0]
	v_pk_mul_f32 v[36:37], v[36:37], v[48:49] op_sel_hi:[1,0]
	v_pk_mul_f32 v[40:41], v[34:35], v[48:49] op_sel_hi:[1,0]
	v_pk_mul_f32 v[34:35], v[32:33], v[48:49] op_sel_hi:[1,0]
	v_cvt_pk_bf16_f32 v32, v36, v37
	v_cvt_pk_bf16_f32 v33, v38, v39
	v_cvt_pk_bf16_f32 v34, v34, v35
	v_cvt_pk_bf16_f32 v35, v40, v41
	global_store_dwordx4 v[50:51], v[32:35], off offset:256
	s_nop 1
	v_mov_b32_e32 v32, v236
	s_mov_b32 s5, 0xa0000
	v_lshl_add_u64 v[34:35], v[160:161], 0, s[14:15]
	s_mov_b64 s[14:15], 0xb0000
	v_fmamk_f32 v32, v32, 0x3a800000, v187
	v_cmp_gt_f32_e32 vcc, s67, v32
	v_mul_f32_e32 v33, 0x4b800000, v32
	s_nop 0
	v_cndmask_b32_e32 v32, v32, v33, vcc
	v_rsq_f32_e32 v32, v32
	s_nop 0
	v_mul_f32_e32 v33, 0x45800000, v32
	v_cndmask_b32_e32 v32, v32, v33, vcc
	v_pk_mul_f32 v[28:29], v[28:29], v[32:33] op_sel_hi:[1,0]
	v_pk_mul_f32 v[30:31], v[30:31], v[32:33] op_sel_hi:[1,0]
	v_pk_mul_f32 v[36:37], v[26:27], v[32:33] op_sel_hi:[1,0]
	v_pk_mul_f32 v[26:27], v[24:25], v[32:33] op_sel_hi:[1,0]
	v_cvt_pk_bf16_f32 v24, v28, v29
	v_add_co_u32_e32 v28, vcc, s5, v160
	v_cvt_pk_bf16_f32 v25, v30, v31
	v_cvt_pk_bf16_f32 v26, v26, v27
	v_cvt_pk_bf16_f32 v27, v36, v37
	v_addc_co_u32_e32 v29, vcc, 0, v161, vcc
	global_store_dwordx4 v[28:29], v[24:27], off
	v_pk_mul_f32 v[22:23], v[22:23], v[32:33] op_sel_hi:[1,0]
	v_pk_mul_f32 v[20:21], v[20:21], v[32:33] op_sel_hi:[1,0]
	v_pk_mul_f32 v[24:25], v[18:19], v[32:33] op_sel_hi:[1,0]
	v_pk_mul_f32 v[18:19], v[16:17], v[32:33] op_sel_hi:[1,0]
	v_cvt_pk_bf16_f32 v16, v20, v21
	v_cvt_pk_bf16_f32 v17, v22, v23
	v_cvt_pk_bf16_f32 v18, v18, v19
	v_cvt_pk_bf16_f32 v19, v24, v25
	global_store_dwordx4 v[34:35], v[16:19], off offset:256
	s_nop 1
	v_mov_b32_e32 v16, v237
	s_mov_b32 s5, 0xb0000
	v_lshl_add_u64 v[18:19], v[160:161], 0, s[14:15]
	v_fmamk_f32 v16, v16, 0x3a800000, v187
	v_cmp_gt_f32_e32 vcc, s67, v16
	v_mul_f32_e32 v17, 0x4b800000, v16
	s_nop 0
	v_cndmask_b32_e32 v16, v16, v17, vcc
	v_rsq_f32_e32 v16, v16
	s_nop 0
	v_mul_f32_e32 v17, 0x45800000, v16
	v_cndmask_b32_e32 v16, v16, v17, vcc
	v_pk_mul_f32 v[12:13], v[12:13], v[16:17] op_sel_hi:[1,0]
	v_pk_mul_f32 v[14:15], v[14:15], v[16:17] op_sel_hi:[1,0]
	v_pk_mul_f32 v[20:21], v[10:11], v[16:17] op_sel_hi:[1,0]
	v_pk_mul_f32 v[10:11], v[8:9], v[16:17] op_sel_hi:[1,0]
	v_cvt_pk_bf16_f32 v8, v12, v13
	v_add_co_u32_e32 v12, vcc, s5, v160
	v_cvt_pk_bf16_f32 v9, v14, v15
	v_cvt_pk_bf16_f32 v10, v10, v11
	v_cvt_pk_bf16_f32 v11, v20, v21
	v_addc_co_u32_e32 v13, vcc, 0, v161, vcc
	global_store_dwordx4 v[12:13], v[8:11], off
	v_pk_mul_f32 v[6:7], v[6:7], v[16:17] op_sel_hi:[1,0]
	v_pk_mul_f32 v[4:5], v[4:5], v[16:17] op_sel_hi:[1,0]
	v_pk_mul_f32 v[8:9], v[2:3], v[16:17] op_sel_hi:[1,0]
	v_pk_mul_f32 v[2:3], v[0:1], v[16:17] op_sel_hi:[1,0]
	v_cvt_pk_bf16_f32 v0, v4, v5
	v_cvt_pk_bf16_f32 v1, v6, v7
	v_cvt_pk_bf16_f32 v2, v2, v3
	v_cvt_pk_bf16_f32 v3, v8, v9
	s_and_b64 vcc, exec, s[38:39]
	global_store_dwordx4 v[18:19], v[0:3], off offset:256
	s_cbranch_vccz .LBB0_1337
	s_waitcnt vmcnt(0)
	s_cmpk_gt_u32 s42, 0xff
	s_cbranch_scc1 .LBB0_1344
	s_barrier

; #define PG8_STAGE(bufoff, gbase, voff) do { _Pragma("unroll") for (int _i = 0; _i < 2; ++_i) \
;         __builtin_amdgcn_global_load_lds((const unsigned*)((const char*)(gbase) + (voff)[_i]), (PG8_LAS unsigned*)(lds + (bufoff) + ldsw + _i * 8192), 16, 0, 0); } while (0)
; #define PG8_LDA(dst, b, h) do { _Pragma("unroll") for (int m = 0; m < 4; ++m) _Pragma("unroll") for (int k = 0; k < 2; ++k) dst[m][k] = *(const PG8_LAS bf16x8*)(lds + PG8_SA(b, h) + aoff + m * 2048 + k * 1024); } while (0)
; #define PG8_LDB(dst, b, h) do { _Pragma("unroll") for (int n = 0; n < 2; ++n) _Pragma("unroll") for (int k = 0; k < 2; ++k) dst[n][k] = *(const PG8_LAS bf16x8*)(lds + PG8_SB(b, h) + boff + n * 2048 + k * 1024); } while (0)
; template <class Epi, class Sched, bool STAMP = false>
; __device__ __forceinline__ void gemm_phase(PG8_LAS unsigned char* lds, const Gemm g, const Sched& S, const Epi& E, unsigned long long* stamps) {
;     ...
;         for (int t = 0; t < nt; t += 2) {
;             const bool last = (t == nt - 2);
;             const char* a1 = cA + (size_t)(t + 1) * kstep;
;             const char* a2 = last ? nA : cA + (size_t)(t + 2) * kstep; const char* b2 = last ? nB : cB + (size_t)(t + 2) * kstep;
;             const char* a3 = a2 + kstep; const char* b3 = b2 + kstep;
;             if (last && has_next) S.a_ready(nxt);
;             PG8_LDB(B0, 0, 0); PG8_SCHED; PG8_LDA(At, 0, 0); PG8_STAGE(PG8_SA(1, 1), a1 + hstep, voffA);
;             PG8_WAIT_L(8); PG8_BAR; PG8_WAIT_L(0); PG8_MMA(0, 0, At, B0); PG8_BAR; PG8_SCHED;
;             PG8_LDB(B1, 0, 1); PG8_STAGE(PG8_SB(0, 0), b2, voffB);
;             PG8_BAR; PG8_WAIT_L(0); PG8_MMA(0, 1, At, B1); PG8_BAR;
;             PG8_LDA(At, 0, 1); PG8_STAGE(PG8_SA(0, 0), a2, voffA);
;             PG8_BAR; PG8_WAIT_L(0); PG8_MMA(1, 0, At, B0); PG8_BAR; PG8_SCHED;
; __device__ __forceinline__ void run_rw_sample_tasks(LAS unsigned char* lds, unsigned char* ws) {
;     const int t = bidx(); OneUnit S; S.valid = t < 128; const int u = (t >> 2) & 31, sl = t & 3; S.pm = 64 + (u >> 3); S.pn = u & 7;
;     pg8::Gemm g; g.A = (const bf16_t*)(ws + OFF_XB) + sl * 256; g.Bt = (const bf16_t*)(ws + OFF_WRW) + sl * 256; g.M = T_ALL; g.N = 2048; g.K = 256; g.ld = 1024;
;     EpiPartial EA; EA.PART = (float*)(ws + OFF_GPART) + (size_t)sl * 1024 * 2048; EA.ldp = 2048;
;     pg8::gemm_phase<EpiPartial, OneUnit, false>(lds, g, S, EA, nullptr);
.LBB0_1349:
	s_add_i32 s15, s14, 0x100
	s_and_b64 s[16:17], s[24:25], exec
	s_cselect_b32 s15, 0, s15
	s_cselect_b32 s16, 0, 0
	s_add_u32 s36, s12, s15
	s_addc_u32 s37, s13, s16
	s_add_i32 s25, 0, 0x10000
	s_add_u32 s38, s6, s15
	s_addc_u32 s39, s7, s16
	s_add_u32 s40, s20, s14
	s_addc_u32 s41, s21, 0
	s_add_i32 s63, s25, s46
	s_add_i32 m0, s10, 0xc000
	s_add_i32 s64, s10, 0xe000
	s_add_i32 s62, 0, 0x14000
	s_add_i32 s61, s63, 0x2000
	s_add_u32 s30, s38, 0x40000
	v_add_u32_e32 v153, s25, v151
	s_addc_u32 s31, s39, 0
	s_add_i32 s52, s62, s46
	ds_read_b128 v[154:157], v153
	ds_read_b128 v[158:161], v153 offset:1024
	ds_read_b128 v[162:165], v153 offset:2048
	ds_read_b128 v[166:169], v153 offset:3072
	s_add_i32 s29, s52, 0x2000
	s_add_i32 s17, 0, 0x18000
	s_add_u32 s26, s36, 0x40000
	s_addc_u32 s27, s37, 0
	s_add_i32 s16, s17, s46
	s_add_i32 s15, 0, 0x1c000
	s_add_i32 s14, s16, 0x2000
	s_add_u32 s24, s38, 0x40080
	s_addc_u32 s25, s39, 0
	s_add_i32 s60, s15, s46
	s_add_i32 s59, s60, 0x2000
	v_lshl_add_u64 v[182:183], s[40:41], 0, v[128:129]
	v_lshl_add_u64 v[182:183], v[182:183], 0, s[18:19]
	ds_read_b128 v[170:173], v152
	ds_read_b128 v[174:177], v152 offset:1024
	ds_read_b128 v[178:181], v152 offset:2048
	ds_read_b128 v[192:195], v152 offset:3072
	ds_read_b128 v[196:199], v152 offset:4096
	ds_read_b128 v[200:203], v152 offset:5120
	ds_read_b128 v[204:207], v152 offset:6144
	ds_read_b128 v[208:211], v152 offset:7168
	global_load_lds_dwordx4 v[182:183], off
	v_lshl_add_u64 v[182:183], s[40:41], 0, v[148:149]
	v_lshl_add_u64 v[182:183], v[182:183], 0, s[18:19]
	s_mov_b32 m0, s64
	s_nop 0
	global_load_lds_dwordx4 v[182:183], off
	s_waitcnt lgkmcnt(8)
	s_barrier
	s_waitcnt lgkmcnt(0)
	s_waitcnt lgkmcnt(0)
	v_mfma_f32_16x16x32_bf16 v[124:127], v[154:157], v[170:173], v[124:127]
	v_mfma_f32_16x16x32_bf16 v[120:123], v[162:165], v[170:173], v[120:123]
	v_mfma_f32_16x16x32_bf16 v[116:119], v[154:157], v[178:181], v[116:119]
	v_mfma_f32_16x16x32_bf16 v[112:115], v[162:165], v[178:181], v[112:115]
	v_mfma_f32_16x16x32_bf16 v[104:107], v[154:157], v[196:199], v[104:107]
	v_mfma_f32_16x16x32_bf16 v[96:99], v[162:165], v[196:199], v[96:99]
	v_mfma_f32_16x16x32_bf16 v[88:91], v[154:157], v[204:207], v[88:91]
	v_mfma_f32_16x16x32_bf16 v[80:83], v[162:165], v[204:207], v[80:83]
	v_mfma_f32_16x16x32_bf16 v[124:127], v[158:161], v[174:177], v[124:127]
	v_mfma_f32_16x16x32_bf16 v[120:123], v[166:169], v[174:177], v[120:123]
	v_mfma_f32_16x16x32_bf16 v[116:119], v[158:161], v[192:195], v[116:119]
	v_mfma_f32_16x16x32_bf16 v[112:115], v[166:169], v[192:195], v[112:115]
	v_mfma_f32_16x16x32_bf16 v[104:107], v[158:161], v[200:203], v[104:107]
	v_mfma_f32_16x16x32_bf16 v[96:99], v[166:169], v[200:203], v[96:99]
	v_mfma_f32_16x16x32_bf16 v[88:91], v[158:161], v[208:211], v[88:91]
	v_mfma_f32_16x16x32_bf16 v[80:83], v[166:169], v[208:211], v[80:83]
	s_barrier
	s_mov_b32 m0, s63
	v_add_u32_e32 v153, s62, v151
	v_lshl_add_u64 v[182:183], s[38:39], 0, v[128:129]
	ds_read_b128 v[212:215], v153
	ds_read_b128 v[216:219], v153 offset:1024
	ds_read_b128 v[220:223], v153 offset:2048
	ds_read_b128 v[224:227], v153 offset:3072
	global_load_lds_dwordx4 v[182:183], off
	v_lshl_add_u64 v[228:229], s[38:39], 0, v[148:149]
	s_mov_b32 m0, s61
	s_nop 0
	global_load_lds_dwordx4 v[228:229], off
	s_barrier
	s_waitcnt lgkmcnt(0)
	s_waitcnt lgkmcnt(0)
	v_mfma_f32_16x16x32_bf16 v[108:111], v[212:215], v[170:173], v[108:111]
	v_mfma_f32_16x16x32_bf16 v[100:103], v[220:223], v[170:173], v[100:103]
	v_mfma_f32_16x16x32_bf16 v[92:95], v[212:215], v[178:181], v[92:95]
	v_mfma_f32_16x16x32_bf16 v[84:87], v[220:223], v[178:181], v[84:87]
	v_mfma_f32_16x16x32_bf16 v[76:79], v[212:215], v[196:199], v[76:79]
	v_mfma_f32_16x16x32_bf16 v[72:75], v[220:223], v[196:199], v[72:75]
	v_mfma_f32_16x16x32_bf16 v[68:71], v[212:215], v[204:207], v[68:71]
	v_mfma_f32_16x16x32_bf16 v[64:67], v[220:223], v[204:207], v[64:67]
	v_mfma_f32_16x16x32_bf16 v[108:111], v[216:219], v[174:177], v[108:111]
	v_mfma_f32_16x16x32_bf16 v[100:103], v[224:227], v[174:177], v[100:103]
	v_mfma_f32_16x16x32_bf16 v[92:95], v[216:219], v[192:195], v[92:95]
	v_mfma_f32_16x16x32_bf16 v[84:87], v[224:227], v[192:195], v[84:87]
	v_mfma_f32_16x16x32_bf16 v[76:79], v[216:219], v[200:203], v[76:79]
	v_mfma_f32_16x16x32_bf16 v[72:75], v[224:227], v[200:203], v[72:75]
	v_mfma_f32_16x16x32_bf16 v[68:71], v[216:219], v[208:211], v[68:71]
	v_mfma_f32_16x16x32_bf16 v[64:67], v[224:227], v[208:211], v[64:67]
	s_mov_b32 m0, s10
	v_lshl_add_u64 v[230:231], s[36:37], 0, v[128:129]
	s_barrier
	ds_read_b128 v[170:173], v152 offset:16384
	ds_read_b128 v[174:177], v152 offset:17408
	ds_read_b128 v[178:181], v152 offset:18432
	ds_read_b128 v[192:195], v152 offset:19456
	ds_read_b128 v[196:199], v152 offset:20480
	ds_read_b128 v[200:203], v152 offset:21504
	ds_read_b128 v[204:207], v152 offset:22528
	ds_read_b128 v[208:211], v152 offset:23552
	global_load_lds_dwordx4 v[230:231], off
	v_lshl_add_u64 v[232:233], s[36:37], 0, v[148:149]
	s_mov_b32 m0, s47
	s_nop 0
	global_load_lds_dwordx4 v[232:233], off
	s_barrier
; #define PG8_STAGE(bufoff, gbase, voff) do { _Pragma("unroll") for (int _i = 0; _i < 2; ++_i) \
;         __builtin_amdgcn_global_load_lds((const unsigned*)((const char*)(gbase) + (voff)[_i]), (PG8_LAS unsigned*)(lds + (bufoff) + ldsw + _i * 8192), 16, 0, 0); } while (0)
; #define PG8_LDA(dst, b, h) do { _Pragma("unroll") for (int m = 0; m < 4; ++m) _Pragma("unroll") for (int k = 0; k < 2; ++k) dst[m][k] = *(const PG8_LAS bf16x8*)(lds + PG8_SA(b, h) + aoff + m * 2048 + k * 1024); } while (0)
; #define PG8_LDB(dst, b, h) do { _Pragma("unroll") for (int n = 0; n < 2; ++n) _Pragma("unroll") for (int k = 0; k < 2; ++k) dst[n][k] = *(const PG8_LAS bf16x8*)(lds + PG8_SB(b, h) + boff + n * 2048 + k * 1024); } while (0)
; #define PG8_MMA(ai, bj, At, Bt) do { __builtin_amdgcn_s_setprio(1); _Pragma("unroll") for (int m = 0; m < 4; ++m) _Pragma("unroll") for (int n = 0; n < 2; ++n) _Pragma("unroll") for (int k = 0; k < 2; ++k) \
;         acc[ai][bj][m][n] = __builtin_amdgcn_mfma_f32_16x16x32_bf16(Bt[n][k], At[m][k], acc[ai][bj][m][n], 0, 0, 0); __builtin_amdgcn_s_setprio(0); } while (0)
; #define PG8_WAIT_V(n) asm volatile("s_waitcnt vmcnt(" #n ")" ::: "memory")
; #define PG8_WAIT_L(n) asm volatile("s_waitcnt lgkmcnt(" #n ")" ::: "memory")
; #define PG8_BAR __builtin_amdgcn_s_barrier()
; #define PG8_SCHED __builtin_amdgcn_sched_barrier(0)
; template <class Epi, class Sched, bool STAMP = false>
; __device__ __forceinline__ void gemm_phase(PG8_LAS unsigned char* lds, const Gemm g, const Sched& S, const Epi& E, unsigned long long* stamps) {
;     ...
;             PG8_BAR; PG8_WAIT_L(0); PG8_MMA(1, 0, At, B0); PG8_BAR; PG8_SCHED;
;             PG8_STAGE(PG8_SB(0, 1), b2 + hstep, voffB);
;             PG8_WAIT_V(6); PG8_BAR; PG8_MMA(1, 1, At, B1); PG8_BAR;
;             PG8_LDB(B0, 1, 0); PG8_SCHED; PG8_LDA(At, 1, 0); PG8_STAGE(PG8_SA(0, 1), a2 + hstep, voffA);
;             PG8_WAIT_L(8); PG8_BAR; PG8_WAIT_L(0); PG8_MMA(0, 0, At, B0); PG8_BAR; PG8_SCHED;
;             PG8_LDB(B1, 1, 1); PG8_STAGE(PG8_SB(1, 0), b3, voffB);
;             PG8_BAR; PG8_WAIT_L(0); PG8_MMA(0, 1, At, B1); PG8_BAR;
	s_waitcnt lgkmcnt(0)
	s_waitcnt lgkmcnt(0)
	v_mfma_f32_16x16x32_bf16 v[60:63], v[154:157], v[170:173], v[60:63]
	v_mfma_f32_16x16x32_bf16 v[56:59], v[162:165], v[170:173], v[56:59]
	v_mfma_f32_16x16x32_bf16 v[52:55], v[154:157], v[178:181], v[52:55]
	v_mfma_f32_16x16x32_bf16 v[48:51], v[162:165], v[178:181], v[48:51]
	v_mfma_f32_16x16x32_bf16 v[36:39], v[154:157], v[196:199], v[36:39]
	v_mfma_f32_16x16x32_bf16 v[32:35], v[162:165], v[196:199], v[32:35]
	v_mfma_f32_16x16x32_bf16 v[20:23], v[154:157], v[204:207], v[20:23]
	v_mfma_f32_16x16x32_bf16 v[16:19], v[162:165], v[204:207], v[16:19]
	v_mfma_f32_16x16x32_bf16 v[60:63], v[158:161], v[174:177], v[60:63]
	v_mfma_f32_16x16x32_bf16 v[56:59], v[166:169], v[174:177], v[56:59]
	v_mfma_f32_16x16x32_bf16 v[52:55], v[158:161], v[192:195], v[52:55]
	v_mfma_f32_16x16x32_bf16 v[48:51], v[166:169], v[192:195], v[48:51]
	v_mfma_f32_16x16x32_bf16 v[36:39], v[158:161], v[200:203], v[36:39]
	v_mfma_f32_16x16x32_bf16 v[32:35], v[166:169], v[200:203], v[32:35]
	v_mfma_f32_16x16x32_bf16 v[20:23], v[158:161], v[208:211], v[20:23]
	v_mfma_f32_16x16x32_bf16 v[16:19], v[166:169], v[208:211], v[16:19]
	s_barrier
	s_mov_b32 m0, s52
	v_lshl_add_u64 v[154:155], s[30:31], 0, v[128:129]
	global_load_lds_dwordx4 v[154:155], off
	v_lshl_add_u64 v[154:155], s[30:31], 0, v[148:149]
	s_mov_b32 m0, s29
	s_nop 0
	global_load_lds_dwordx4 v[154:155], off
	s_waitcnt vmcnt(6)
	s_barrier
	v_mfma_f32_16x16x32_bf16 v[44:47], v[212:215], v[170:173], v[44:47]
	v_mfma_f32_16x16x32_bf16 v[40:43], v[220:223], v[170:173], v[40:43]
	v_mfma_f32_16x16x32_bf16 v[28:31], v[212:215], v[178:181], v[28:31]
	v_mfma_f32_16x16x32_bf16 v[24:27], v[220:223], v[178:181], v[24:27]
	v_mfma_f32_16x16x32_bf16 v[12:15], v[212:215], v[196:199], v[12:15]
	v_mfma_f32_16x16x32_bf16 v[8:11], v[220:223], v[196:199], v[8:11]
	v_mfma_f32_16x16x32_bf16 v[4:7], v[212:215], v[204:207], v[4:7]
	v_mfma_f32_16x16x32_bf16 v[0:3], v[220:223], v[204:207], v[0:3]
	v_mfma_f32_16x16x32_bf16 v[44:47], v[216:219], v[174:177], v[44:47]
	v_mfma_f32_16x16x32_bf16 v[40:43], v[224:227], v[174:177], v[40:43]
	v_mfma_f32_16x16x32_bf16 v[28:31], v[216:219], v[192:195], v[28:31]
	v_mfma_f32_16x16x32_bf16 v[24:27], v[224:227], v[192:195], v[24:27]
	v_mfma_f32_16x16x32_bf16 v[12:15], v[216:219], v[200:203], v[12:15]
	v_mfma_f32_16x16x32_bf16 v[8:11], v[224:227], v[200:203], v[8:11]
	v_mfma_f32_16x16x32_bf16 v[4:7], v[216:219], v[208:211], v[4:7]
	v_mfma_f32_16x16x32_bf16 v[0:3], v[224:227], v[208:211], v[0:3]
	v_add_u32_e32 v153, s17, v151
	s_barrier
	ds_read_b128 v[154:157], v153
	ds_read_b128 v[158:161], v153 offset:1024
	ds_read_b128 v[162:165], v153 offset:2048
	ds_read_b128 v[166:169], v153 offset:3072
	s_mov_b32 m0, s48
	v_lshl_add_u64 v[212:213], s[26:27], 0, v[128:129]
	ds_read_b128 v[170:173], v152 offset:32768
	ds_read_b128 v[174:177], v152 offset:33792
	ds_read_b128 v[178:181], v152 offset:34816
	ds_read_b128 v[192:195], v152 offset:35840
	ds_read_b128 v[196:199], v152 offset:36864
	ds_read_b128 v[200:203], v152 offset:37888
	ds_read_b128 v[204:207], v152 offset:38912
	ds_read_b128 v[208:211], v152 offset:39936
	global_load_lds_dwordx4 v[212:213], off
	v_lshl_add_u64 v[212:213], s[26:27], 0, v[148:149]
	s_mov_b32 m0, s49
	s_nop 0
	global_load_lds_dwordx4 v[212:213], off
	s_waitcnt lgkmcnt(8)
	s_barrier
	s_waitcnt lgkmcnt(0)
	s_waitcnt lgkmcnt(0)
	v_mfma_f32_16x16x32_bf16 v[124:127], v[154:157], v[170:173], v[124:127]
	v_mfma_f32_16x16x32_bf16 v[120:123], v[162:165], v[170:173], v[120:123]
	v_mfma_f32_16x16x32_bf16 v[116:119], v[154:157], v[178:181], v[116:119]
	v_mfma_f32_16x16x32_bf16 v[112:115], v[162:165], v[178:181], v[112:115]
	v_mfma_f32_16x16x32_bf16 v[104:107], v[154:157], v[196:199], v[104:107]
	v_mfma_f32_16x16x32_bf16 v[96:99], v[162:165], v[196:199], v[96:99]
	v_mfma_f32_16x16x32_bf16 v[88:91], v[154:157], v[204:207], v[88:91]
	v_mfma_f32_16x16x32_bf16 v[80:83], v[162:165], v[204:207], v[80:83]
	v_mfma_f32_16x16x32_bf16 v[124:127], v[158:161], v[174:177], v[124:127]
	v_mfma_f32_16x16x32_bf16 v[120:123], v[166:169], v[174:177], v[120:123]
	v_mfma_f32_16x16x32_bf16 v[116:119], v[158:161], v[192:195], v[116:119]
	v_mfma_f32_16x16x32_bf16 v[112:115], v[166:169], v[192:195], v[112:115]
	v_mfma_f32_16x16x32_bf16 v[104:107], v[158:161], v[200:203], v[104:107]
	v_mfma_f32_16x16x32_bf16 v[96:99], v[166:169], v[200:203], v[96:99]
	v_mfma_f32_16x16x32_bf16 v[88:91], v[158:161], v[208:211], v[88:91]
	v_mfma_f32_16x16x32_bf16 v[80:83], v[166:169], v[208:211], v[80:83]
	s_barrier
	s_mov_b32 m0, s16
	v_add_u32_e32 v153, s15, v151
	v_lshl_add_u64 v[182:183], v[182:183], 0, s[18:19]
	ds_read_b128 v[212:215], v153
	ds_read_b128 v[216:219], v153 offset:1024
	ds_read_b128 v[220:223], v153 offset:2048
	ds_read_b128 v[224:227], v153 offset:3072
	global_load_lds_dwordx4 v[182:183], off
	v_lshl_add_u64 v[182:183], v[228:229], 0, s[18:19]
	s_mov_b32 m0, s14
	s_nop 0
	global_load_lds_dwordx4 v[182:183], off
	s_barrier
	s_waitcnt lgkmcnt(0)
	s_waitcnt lgkmcnt(0)
	v_mfma_f32_16x16x32_bf16 v[108:111], v[212:215], v[170:173], v[108:111]
	v_mfma_f32_16x16x32_bf16 v[100:103], v[220:223], v[170:173], v[100:103]
	v_mfma_f32_16x16x32_bf16 v[92:95], v[212:215], v[178:181], v[92:95]
	v_mfma_f32_16x16x32_bf16 v[84:87], v[220:223], v[178:181], v[84:87]
	v_mfma_f32_16x16x32_bf16 v[76:79], v[212:215], v[196:199], v[76:79]
	v_mfma_f32_16x16x32_bf16 v[72:75], v[220:223], v[196:199], v[72:75]
	v_mfma_f32_16x16x32_bf16 v[68:71], v[212:215], v[204:207], v[68:71]
	v_mfma_f32_16x16x32_bf16 v[64:67], v[220:223], v[204:207], v[64:67]
	v_mfma_f32_16x16x32_bf16 v[108:111], v[216:219], v[174:177], v[108:111]
	v_mfma_f32_16x16x32_bf16 v[100:103], v[224:227], v[174:177], v[100:103]
	v_mfma_f32_16x16x32_bf16 v[92:95], v[216:219], v[192:195], v[92:95]
	v_mfma_f32_16x16x32_bf16 v[84:87], v[224:227], v[192:195], v[84:87]
	v_mfma_f32_16x16x32_bf16 v[76:79], v[216:219], v[200:203], v[76:79]
	v_mfma_f32_16x16x32_bf16 v[72:75], v[224:227], v[200:203], v[72:75]
	v_mfma_f32_16x16x32_bf16 v[68:71], v[216:219], v[208:211], v[68:71]
	v_mfma_f32_16x16x32_bf16 v[64:67], v[224:227], v[208:211], v[64:67]
	s_mov_b32 m0, s57
	v_lshl_add_u64 v[182:183], v[230:231], 0, s[18:19]
	s_barrier
; #define PG8_STAGE(bufoff, gbase, voff) do { _Pragma("unroll") for (int _i = 0; _i < 2; ++_i) \
;         __builtin_amdgcn_global_load_lds((const unsigned*)((const char*)(gbase) + (voff)[_i]), (PG8_LAS unsigned*)(lds + (bufoff) + ldsw + _i * 8192), 16, 0, 0); } while (0)
; #define PG8_LDA(dst, b, h) do { _Pragma("unroll") for (int m = 0; m < 4; ++m) _Pragma("unroll") for (int k = 0; k < 2; ++k) dst[m][k] = *(const PG8_LAS bf16x8*)(lds + PG8_SA(b, h) + aoff + m * 2048 + k * 1024); } while (0)
; #define PG8_MMA(ai, bj, At, Bt) do { __builtin_amdgcn_s_setprio(1); _Pragma("unroll") for (int m = 0; m < 4; ++m) _Pragma("unroll") for (int n = 0; n < 2; ++n) _Pragma("unroll") for (int k = 0; k < 2; ++k) \
;         acc[ai][bj][m][n] = __builtin_amdgcn_mfma_f32_16x16x32_bf16(Bt[n][k], At[m][k], acc[ai][bj][m][n], 0, 0, 0); __builtin_amdgcn_s_setprio(0); } while (0)
; #define PG8_WAIT_V(n) asm volatile("s_waitcnt vmcnt(" #n ")" ::: "memory")
; #define PG8_WAIT_L(n) asm volatile("s_waitcnt lgkmcnt(" #n ")" ::: "memory")
; #define PG8_BAR __builtin_amdgcn_s_barrier()
; #define PG8_SCHED __builtin_amdgcn_sched_barrier(0)
; template <class Epi, class Sched, bool STAMP = false>
; __device__ __forceinline__ void gemm_phase(PG8_LAS unsigned char* lds, const Gemm g, const Sched& S, const Epi& E, unsigned long long* stamps) {
;     ...
;             PG8_LDA(At, 1, 1); PG8_STAGE(PG8_SA(1, 0), a3, voffA);
;             PG8_BAR; PG8_WAIT_L(0); PG8_MMA(1, 0, At, B0); PG8_BAR; PG8_SCHED;
;             PG8_STAGE(PG8_SB(1, 1), b3 + hstep, voffB);
;             PG8_WAIT_V(6); PG8_BAR; PG8_MMA(1, 1, At, B1); PG8_BAR;
;     __device__ __forceinline__ void operator()(const f32x4 (&acc)[2][2][4][2], const pg8::Unit& u, int wr, int wc, int fr, int fq) const {
;         const int row0 = (u.pm - 64) * 256 + wr * 64 + fr, col0 = u.pn * 256 + wc * 32 + 4 * fq;
; #pragma unroll
;         for (int ai = 0; ai < 2; ++ai)
; #pragma unroll
;             for (int m = 0; m < 4; ++m) { float* xp = PART + (size_t)(row0 + ai * 128 + m * 16) * ldp + col0;
; #pragma unroll
;                 for (int bj = 0; bj < 2; ++bj)
; #pragma unroll
;                     for (int n = 0; n < 2; ++n) *(f32x4*)(xp + bj * 128 + n * 16) = acc[ai][bj][m][n]; }
;     }
	ds_read_b128 v[170:173], v152 offset:49152
	ds_read_b128 v[174:177], v152 offset:50176
	ds_read_b128 v[178:181], v152 offset:51200
	ds_read_b128 v[192:195], v152 offset:52224
	ds_read_b128 v[196:199], v152 offset:53248
	ds_read_b128 v[200:203], v152 offset:54272
	ds_read_b128 v[204:207], v152 offset:55296
	ds_read_b128 v[208:211], v152 offset:56320
	global_load_lds_dwordx4 v[182:183], off
	v_lshl_add_u64 v[182:183], v[232:233], 0, s[18:19]
	s_mov_b32 m0, s58
	s_nop 0
	global_load_lds_dwordx4 v[182:183], off
	s_barrier
	s_waitcnt lgkmcnt(0)
	s_waitcnt lgkmcnt(0)
	v_mfma_f32_16x16x32_bf16 v[60:63], v[154:157], v[170:173], v[60:63]
	v_mfma_f32_16x16x32_bf16 v[56:59], v[162:165], v[170:173], v[56:59]
	v_mfma_f32_16x16x32_bf16 v[52:55], v[154:157], v[178:181], v[52:55]
	v_mfma_f32_16x16x32_bf16 v[48:51], v[162:165], v[178:181], v[48:51]
	v_mfma_f32_16x16x32_bf16 v[36:39], v[154:157], v[196:199], v[36:39]
	v_mfma_f32_16x16x32_bf16 v[32:35], v[162:165], v[196:199], v[32:35]
	v_mfma_f32_16x16x32_bf16 v[20:23], v[154:157], v[204:207], v[20:23]
	v_mfma_f32_16x16x32_bf16 v[16:19], v[162:165], v[204:207], v[16:19]
	v_mfma_f32_16x16x32_bf16 v[60:63], v[158:161], v[174:177], v[60:63]
	v_mfma_f32_16x16x32_bf16 v[56:59], v[166:169], v[174:177], v[56:59]
	v_mfma_f32_16x16x32_bf16 v[52:55], v[158:161], v[192:195], v[52:55]
	v_mfma_f32_16x16x32_bf16 v[48:51], v[166:169], v[192:195], v[48:51]
	v_mfma_f32_16x16x32_bf16 v[36:39], v[158:161], v[200:203], v[36:39]
	v_mfma_f32_16x16x32_bf16 v[32:35], v[166:169], v[200:203], v[32:35]
	v_mfma_f32_16x16x32_bf16 v[20:23], v[158:161], v[208:211], v[20:23]
	v_mfma_f32_16x16x32_bf16 v[16:19], v[166:169], v[208:211], v[16:19]
	s_barrier
	s_mov_b32 m0, s60
	v_lshl_add_u64 v[154:155], s[24:25], 0, v[128:129]
	global_load_lds_dwordx4 v[154:155], off
	v_lshl_add_u64 v[154:155], s[24:25], 0, v[148:149]
	s_mov_b32 m0, s59
	s_nop 0
	global_load_lds_dwordx4 v[154:155], off
	s_waitcnt vmcnt(6)
	s_barrier
	v_mfma_f32_16x16x32_bf16 v[44:47], v[212:215], v[170:173], v[44:47]
	v_mfma_f32_16x16x32_bf16 v[40:43], v[220:223], v[170:173], v[40:43]
	v_mfma_f32_16x16x32_bf16 v[28:31], v[212:215], v[178:181], v[28:31]
	v_mfma_f32_16x16x32_bf16 v[24:27], v[220:223], v[178:181], v[24:27]
	v_mfma_f32_16x16x32_bf16 v[12:15], v[212:215], v[196:199], v[12:15]
	v_mfma_f32_16x16x32_bf16 v[8:11], v[220:223], v[196:199], v[8:11]
	v_mfma_f32_16x16x32_bf16 v[4:7], v[212:215], v[204:207], v[4:7]
	v_mfma_f32_16x16x32_bf16 v[0:3], v[220:223], v[204:207], v[0:3]
	v_mfma_f32_16x16x32_bf16 v[44:47], v[216:219], v[174:177], v[44:47]
	v_mfma_f32_16x16x32_bf16 v[40:43], v[224:227], v[174:177], v[40:43]
	v_mfma_f32_16x16x32_bf16 v[28:31], v[216:219], v[192:195], v[28:31]
	v_mfma_f32_16x16x32_bf16 v[24:27], v[224:227], v[192:195], v[24:27]
	v_mfma_f32_16x16x32_bf16 v[12:15], v[216:219], v[200:203], v[12:15]
	v_mfma_f32_16x16x32_bf16 v[8:11], v[224:227], v[200:203], v[8:11]
	v_mfma_f32_16x16x32_bf16 v[4:7], v[216:219], v[208:211], v[4:7]
	v_mfma_f32_16x16x32_bf16 v[0:3], v[224:227], v[208:211], v[0:3]
	s_andn2_b64 vcc, exec, s[22:23]
	s_mov_b64 s[24:25], -1
	s_mov_b64 s[22:23], 0
	s_movk_i32 s14, 0x100
	s_barrier
	s_cbranch_vccz .LBB0_1349
	s_lshl_b32 s6, s45, 23
	s_add_u32 s6, s4, s6
	s_addc_u32 s7, s5, 0
	s_lshl_b32 s10, s44, 8
	s_add_i32 s10, s10, s53
	v_add_u32_e32 v150, s10, v150
	v_add_u32_e32 v148, 0xffffc000, v150
	s_lshl_b32 s10, s43, 8
	v_lshl_or_b32 v128, v139, 2, s10
	v_ashrrev_i32_e32 v149, 31, v148
	v_or_b32_e32 v128, s56, v128
	v_lshlrev_b64 v[148:149], 13, v[148:149]
	v_lshl_add_u64 v[148:149], s[6:7], 0, v[148:149]
	v_lshlrev_b32_e32 v128, 2, v128
	v_lshl_add_u64 v[148:149], v[148:149], 0, v[128:129]
	global_store_dwordx4 v[148:149], v[124:127], off
	global_store_dwordx4 v[148:149], v[120:123], off offset:64
	global_store_dwordx4 v[148:149], v[108:111], off offset:512
	global_store_dwordx4 v[148:149], v[100:103], off offset:576
	s_cmpk_lt_u32 s42, 0x100
	s_movk_i32 s58, 0xff60
	v_add_u32_e32 v100, 0xffffc010, v150
	v_ashrrev_i32_e32 v101, 31, v100
	v_lshlrev_b64 v[100:101], 13, v[100:101]
	v_lshl_add_u64 v[100:101], s[6:7], 0, v[100:101]
	v_lshl_add_u64 v[100:101], v[100:101], 0, v[128:129]
	global_store_dwordx4 v[100:101], v[116:119], off
	global_store_dwordx4 v[100:101], v[112:115], off offset:64
	global_store_dwordx4 v[100:101], v[92:95], off offset:512
	global_store_dwordx4 v[100:101], v[84:87], off offset:576
	s_nop 1
	v_add_u32_e32 v84, 0xffffc020, v150
	v_ashrrev_i32_e32 v85, 31, v84
	v_lshlrev_b64 v[84:85], 13, v[84:85]
	v_lshl_add_u64 v[84:85], s[6:7], 0, v[84:85]
	v_lshl_add_u64 v[84:85], v[84:85], 0, v[128:129]
	global_store_dwordx4 v[84:85], v[104:107], off
	global_store_dwordx4 v[84:85], v[96:99], off offset:64
	global_store_dwordx4 v[84:85], v[76:79], off offset:512
	global_store_dwordx4 v[84:85], v[72:75], off offset:576
	s_nop 1
	v_add_u32_e32 v72, 0xffffc030, v150
	v_ashrrev_i32_e32 v73, 31, v72
	v_lshlrev_b64 v[72:73], 13, v[72:73]
	v_lshl_add_u64 v[72:73], s[6:7], 0, v[72:73]
	v_lshl_add_u64 v[72:73], v[72:73], 0, v[128:129]
	s_mov_b64 s[6:7], 0x100000
	global_store_dwordx4 v[72:73], v[88:91], off
	global_store_dwordx4 v[72:73], v[80:83], off offset:64
	global_store_dwordx4 v[72:73], v[68:71], off offset:512
	global_store_dwordx4 v[72:73], v[64:67], off offset:576
	s_nop 1
	v_lshl_add_u64 v[64:65], v[148:149], 0, s[6:7]
	s_mov_b32 s6, 0x100000
	v_add_co_u32_e32 v66, vcc, s6, v148
	s_mov_b64 s[6:7], 0x120000
	s_nop 0
	v_addc_co_u32_e32 v67, vcc, 0, v149, vcc
	global_store_dwordx4 v[66:67], v[60:63], off
	global_store_dwordx4 v[64:65], v[56:59], off offset:64
	global_store_dwordx4 v[64:65], v[44:47], off offset:512
	global_store_dwordx4 v[64:65], v[40:43], off offset:576
	s_nop 1
	v_lshl_add_u64 v[40:41], v[148:149], 0, s[6:7]
	s_mov_b32 s6, 0x120000
	v_add_co_u32_e32 v42, vcc, s6, v148
	s_mov_b64 s[6:7], 0x140000
	s_nop 0
	v_addc_co_u32_e32 v43, vcc, 0, v149, vcc
	global_store_dwordx4 v[42:43], v[52:55], off
	global_store_dwordx4 v[40:41], v[48:51], off offset:64
	global_store_dwordx4 v[40:41], v[28:31], off offset:512
	global_store_dwordx4 v[40:41], v[24:27], off offset:576
	s_nop 1
	v_lshl_add_u64 v[24:25], v[148:149], 0, s[6:7]
	s_mov_b32 s6, 0x140000
	v_add_co_u32_e32 v26, vcc, s6, v148
	s_mov_b64 s[6:7], 0x160000
	s_nop 0
	v_addc_co_u32_e32 v27, vcc, 0, v149, vcc
	global_store_dwordx4 v[26:27], v[36:39], off
	global_store_dwordx4 v[24:25], v[32:35], off offset:64
	global_store_dwordx4 v[24:25], v[12:15], off offset:512
	global_store_dwordx4 v[24:25], v[8:11], off offset:576
	s_nop 1
	v_add_co_u32_e32 v10, vcc, 0x160000, v148
	v_lshl_add_u64 v[8:9], v[148:149], 0, s[6:7]
	s_nop 0
	v_addc_co_u32_e32 v11, vcc, 0, v149, vcc
	global_store_dwordx4 v[10:11], v[20:23], off
	global_store_dwordx4 v[8:9], v[16:19], off offset:64
	global_store_dwordx4 v[8:9], v[4:7], off offset:512
	global_store_dwordx4 v[8:9], v[0:3], off offset:576
	s_waitcnt vmcnt(0)
	s_cbranch_scc0 .LBB0_1352
	s_barrier
